# attention fast path: next tile's K0 fragments are read from LDS right after the last MFMA of the current tile (both tiles complete in LDS since the last barrier: K/V LDS-DMA now issued at the start of
# speedup vs baseline: 1.0134x; 1.0046x over previous
.LBB0_847:
	s_cmp_gt_i32 s43, s84
	s_cbranch_scc1 .LBB0_858
	s_add_i32 s100, s43, 63
	s_cmp_le_i32 s100, s83
	s_cbranch_scc0 .Latt_slow_0
	s_cmp_eq_u32 s88, 1
	s_cbranch_scc1 .Latt_slot1_0
	s_cmp_eq_u32 s88, 2
	s_cbranch_scc1 .Latt_slot2_0
	s_cmp_lg_u32 s43, 0
	s_cbranch_scc1 .Latt_vstep_0s0
	ds_read_b128 v[206:209], v194
	ds_read_b128 v[210:213], v195
	ds_read_b128 v[214:217], v196
	ds_read_b128 v[238:241], v197
	ds_read_b128 v[242:245], v198
	ds_read_b128 v[250:253], v199
	ds_read_b128 v[222:225], v200
	ds_read_b128 v[226:229], v201
	v_bfe_u32 v246, v203, 2, 2
	v_bfe_u32 v247, v203, 5, 1
	v_lshl_or_b32 v247, v247, 2, v246
	v_and_b32_e32 v249, 3, v203
	v_and_b32_e32 v254, 16, v203
	v_lshl_or_b32 v249, v249, 2, v254
	v_lshlrev_b32_e32 v249, 1, v249
	v_lshl_add_u32 v247, v247, 9, v249
	v_add_u32_e32 v247, 0xc000, v247
	v_lshlrev_b32_e32 v246, 6, v246
	v_add_u32_e32 v205, v247, v246
	v_xor_b32_e32 v249, 64, v246
	v_add_u32_e32 v218, v247, v249
	v_xor_b32_e32 v249, 0x80, v246
	v_add_u32_e32 v219, v247, v249
	v_xor_b32_e32 v249, 0xc0, v246
	v_add_u32_e32 v221, v247, v249
	s_branch .Latt_vdone_0s0

.Latt_vdone_0s0:
	s_waitcnt lgkmcnt(7)
	v_mfma_f32_32x32x16_bf16 v[128:143], v[206:209], v[144:147], 0
	ds_read_b128 v[206:209], v194 offset:8192
	s_cmp_lg_u64 s[18:19], 0
	s_cbranch_scc1 .Latt_nd0_0s0
	s_sub_i32 s100, s88, 1
	s_cmp_eq_u32 s88, 0
	s_cselect_b32 s100, 2, s100
	s_lshl_b32 s101, s100, 14
	s_add_i32 m0, s85, s101
	s_nop 0
	global_load_lds_dwordx4 v178, s[14:15]
.Latt_nd0_0s0:
	s_waitcnt lgkmcnt(7)
	v_mfma_f32_32x32x16_bf16 v[128:143], v[210:213], v[148:151], v[128:143]
	ds_read_b128 v[210:213], v195 offset:8192
	s_cmp_lg_u64 s[18:19], 0
	s_cbranch_scc1 .Latt_nd1_0s0
	s_add_i32 m0, m0, 0x400
	s_nop 0
	global_load_lds_dwordx4 v180, s[14:15]
.Latt_nd1_0s0:
	s_waitcnt lgkmcnt(7)
	v_mfma_f32_32x32x16_bf16 v[128:143], v[214:217], v[152:155], v[128:143]
	ds_read_b128 v[214:217], v196 offset:8192
	s_cmp_lg_u64 s[18:19], 0
	s_cbranch_scc1 .Latt_nd2_0s0
	s_lshl_b32 s101, s100, 15
	s_add_i32 m0, s86, s101
	s_add_u32 s100, s14, 0x1000
	s_addc_u32 s101, s15, 0
	global_load_lds_dwordx4 v182, s[100:101]
.Latt_nd2_0s0:
	s_waitcnt lgkmcnt(7)
	v_mfma_f32_32x32x16_bf16 v[128:143], v[238:241], v[156:159], v[128:143]
	ds_read_b128 v[238:241], v197 offset:8192
	s_cmp_lg_u64 s[18:19], 0
	s_cbranch_scc1 .Latt_nd3_0s0
	s_add_i32 m0, m0, 0x400
	s_nop 0
	global_load_lds_dwordx4 v184, s[100:101]
.Latt_nd3_0s0:
	s_waitcnt lgkmcnt(7)
	v_mfma_f32_32x32x16_bf16 v[128:143], v[242:245], v[160:163], v[128:143]
	s_cmp_lg_u64 s[18:19], 0
	s_cbranch_scc1 .Latt_nd4_0s0
	s_add_i32 m0, m0, 0x400
	s_nop 0
	global_load_lds_dwordx4 v186, s[100:101]
.Latt_nd4_0s0:
	s_waitcnt lgkmcnt(6)
	v_mfma_f32_32x32x16_bf16 v[128:143], v[250:253], v[164:167], v[128:143]
	s_cmp_lg_u64 s[18:19], 0
	s_cbranch_scc1 .Latt_nd5_0s0
	s_add_i32 m0, m0, 0x400
	s_nop 0
	global_load_lds_dwordx4 v188, s[100:101]
.Latt_nd5_0s0:
	s_waitcnt lgkmcnt(5)
	v_mfma_f32_32x32x16_bf16 v[128:143], v[222:225], v[168:171], v[128:143]
	s_waitcnt lgkmcnt(4)
	v_mfma_f32_32x32x16_bf16 v[128:143], v[226:229], v[172:175], v[128:143]
	s_waitcnt lgkmcnt(3)
	v_mfma_f32_32x32x16_bf16 v[222:237], v[206:209], v[144:147], 0
	ds_read_b128 v[206:209], v198 offset:8192
	s_nop 8
	v_max3_f32 v246, v128, v129, v130
	v_max3_f32 v247, v131, v132, v133
	v_max3_f32 v246, v246, v134, v135
	v_max3_f32 v247, v247, v136, v137
	v_max3_f32 v246, v246, v138, v139
	v_max3_f32 v247, v247, v140, v141
	v_max3_f32 v246, v246, v142, v143
	s_waitcnt lgkmcnt(3)
	v_mfma_f32_32x32x16_bf16 v[222:237], v[210:213], v[148:151], v[222:237]
	ds_read_b128 v[210:213], v199 offset:8192
	v_max_f32_e32 v246, v246, v247
	v_mov_b32_e32 v247, v246
	v_add_f32_e32 v249, 0x41000000, v190
	s_nop 1
	v_permlane32_swap_b32_e32 v246, v247
	v_max_f32_e32 v246, v246, v247
	v_cmp_gt_f32_e32 vcc, v246, v249
	s_cbranch_vccz .Latt_nr0_0s0
	v_max_f32_e32 v246, v190, v246
	v_sub_f32_e32 v190, v190, v246
	v_exp_f32_e32 v190, v190
	s_nop 0
	v_pk_mul_f32 v[126:127], v[126:127], v[190:191] op_sel_hi:[1,0]
	v_pk_mul_f32 v[124:125], v[124:125], v[190:191] op_sel_hi:[1,0]
	v_pk_mul_f32 v[122:123], v[122:123], v[190:191] op_sel_hi:[1,0]
	v_pk_mul_f32 v[120:121], v[120:121], v[190:191] op_sel_hi:[1,0]
	v_pk_mul_f32 v[118:119], v[118:119], v[190:191] op_sel_hi:[1,0]
	v_pk_mul_f32 v[116:117], v[116:117], v[190:191] op_sel_hi:[1,0]
	v_pk_mul_f32 v[114:115], v[114:115], v[190:191] op_sel_hi:[1,0]
	v_pk_mul_f32 v[112:113], v[112:113], v[190:191] op_sel_hi:[1,0]
	v_pk_mul_f32 v[110:111], v[110:111], v[190:191] op_sel_hi:[1,0]
	v_pk_mul_f32 v[108:109], v[108:109], v[190:191] op_sel_hi:[1,0]
	v_pk_mul_f32 v[106:107], v[106:107], v[190:191] op_sel_hi:[1,0]
	v_pk_mul_f32 v[104:105], v[104:105], v[190:191] op_sel_hi:[1,0]
	v_pk_mul_f32 v[102:103], v[102:103], v[190:191] op_sel_hi:[1,0]
	v_pk_mul_f32 v[100:101], v[100:101], v[190:191] op_sel_hi:[1,0]
	v_pk_mul_f32 v[98:99], v[98:99], v[190:191] op_sel_hi:[1,0]
	v_pk_mul_f32 v[96:97], v[96:97], v[190:191] op_sel_hi:[1,0]
	v_pk_mul_f32 v[94:95], v[94:95], v[190:191] op_sel_hi:[1,0]
	v_pk_mul_f32 v[92:93], v[92:93], v[190:191] op_sel_hi:[1,0]
	v_pk_mul_f32 v[90:91], v[90:91], v[190:191] op_sel_hi:[1,0]
	v_pk_mul_f32 v[88:89], v[88:89], v[190:191] op_sel_hi:[1,0]
	v_pk_mul_f32 v[86:87], v[86:87], v[190:191] op_sel_hi:[1,0]
	v_pk_mul_f32 v[84:85], v[84:85], v[190:191] op_sel_hi:[1,0]
	v_pk_mul_f32 v[82:83], v[82:83], v[190:191] op_sel_hi:[1,0]
	v_pk_mul_f32 v[80:81], v[80:81], v[190:191] op_sel_hi:[1,0]
	v_pk_mul_f32 v[78:79], v[78:79], v[190:191] op_sel_hi:[1,0]
	v_pk_mul_f32 v[76:77], v[76:77], v[190:191] op_sel_hi:[1,0]
	v_pk_mul_f32 v[74:75], v[74:75], v[190:191] op_sel_hi:[1,0]
	v_pk_mul_f32 v[72:73], v[72:73], v[190:191] op_sel_hi:[1,0]
	v_pk_mul_f32 v[70:71], v[70:71], v[190:191] op_sel_hi:[1,0]
	v_pk_mul_f32 v[68:69], v[68:69], v[190:191] op_sel_hi:[1,0]
	v_pk_mul_f32 v[66:67], v[66:67], v[190:191] op_sel_hi:[1,0]
	v_pk_mul_f32 v[64:65], v[64:65], v[190:191] op_sel_hi:[1,0]
	v_pk_mul_f32 v[62:63], v[62:63], v[190:191] op_sel_hi:[1,0]
	v_pk_mul_f32 v[60:61], v[60:61], v[190:191] op_sel_hi:[1,0]
	v_pk_mul_f32 v[58:59], v[58:59], v[190:191] op_sel_hi:[1,0]
	v_pk_mul_f32 v[56:57], v[56:57], v[190:191] op_sel_hi:[1,0]
	v_pk_mul_f32 v[54:55], v[54:55], v[190:191] op_sel_hi:[1,0]
	v_pk_mul_f32 v[52:53], v[52:53], v[190:191] op_sel_hi:[1,0]
	v_pk_mul_f32 v[50:51], v[50:51], v[190:191] op_sel_hi:[1,0]
	v_pk_mul_f32 v[48:49], v[48:49], v[190:191] op_sel_hi:[1,0]
	v_pk_mul_f32 v[46:47], v[46:47], v[190:191] op_sel_hi:[1,0]
	v_pk_mul_f32 v[44:45], v[44:45], v[190:191] op_sel_hi:[1,0]
	v_pk_mul_f32 v[42:43], v[42:43], v[190:191] op_sel_hi:[1,0]
	v_pk_mul_f32 v[40:41], v[40:41], v[190:191] op_sel_hi:[1,0]
	v_pk_mul_f32 v[38:39], v[38:39], v[190:191] op_sel_hi:[1,0]
	v_pk_mul_f32 v[36:37], v[36:37], v[190:191] op_sel_hi:[1,0]
	v_pk_mul_f32 v[34:35], v[34:35], v[190:191] op_sel_hi:[1,0]
	v_pk_mul_f32 v[32:33], v[32:33], v[190:191] op_sel_hi:[1,0]
	v_pk_mul_f32 v[30:31], v[30:31], v[190:191] op_sel_hi:[1,0]
	v_pk_mul_f32 v[28:29], v[28:29], v[190:191] op_sel_hi:[1,0]
	v_pk_mul_f32 v[26:27], v[26:27], v[190:191] op_sel_hi:[1,0]
	v_pk_mul_f32 v[24:25], v[24:25], v[190:191] op_sel_hi:[1,0]
	v_pk_mul_f32 v[22:23], v[22:23], v[190:191] op_sel_hi:[1,0]
	v_pk_mul_f32 v[20:21], v[20:21], v[190:191] op_sel_hi:[1,0]
	v_pk_mul_f32 v[18:19], v[18:19], v[190:191] op_sel_hi:[1,0]
	v_pk_mul_f32 v[16:17], v[16:17], v[190:191] op_sel_hi:[1,0]
	v_pk_mul_f32 v[14:15], v[14:15], v[190:191] op_sel_hi:[1,0]
	v_pk_mul_f32 v[12:13], v[12:13], v[190:191] op_sel_hi:[1,0]
	v_pk_mul_f32 v[10:11], v[10:11], v[190:191] op_sel_hi:[1,0]
	v_pk_mul_f32 v[8:9], v[8:9], v[190:191] op_sel_hi:[1,0]
	v_pk_mul_f32 v[6:7], v[6:7], v[190:191] op_sel_hi:[1,0]
	v_pk_mul_f32 v[4:5], v[4:5], v[190:191] op_sel_hi:[1,0]
	v_pk_mul_f32 v[2:3], v[2:3], v[190:191] op_sel_hi:[1,0]
	v_pk_mul_f32 v[0:1], v[0:1], v[190:191] op_sel_hi:[1,0]
	v_mul_f32_e32 v202, v202, v190
	v_mov_b32_e32 v190, v246
.Latt_nr0_0s0:
	s_waitcnt lgkmcnt(3)
	v_mfma_f32_32x32x16_bf16 v[222:237], v[214:217], v[152:155], v[222:237]
	ds_read_b128 v[214:217], v200 offset:8192
	v_sub_f32_e32 v128, v128, v190
	v_exp_f32_e32 v128, v128
	v_sub_f32_e32 v129, v129, v190
	v_exp_f32_e32 v129, v129
	v_sub_f32_e32 v130, v130, v190
	s_waitcnt lgkmcnt(3)
	v_mfma_f32_32x32x16_bf16 v[222:237], v[238:241], v[156:159], v[222:237]
	ds_read_b128 v[238:241], v201 offset:8192
	v_add_f32_e32 v254, 0, v128
	v_exp_f32_e32 v130, v130
	v_sub_f32_e32 v131, v131, v190
	v_add_f32_e32 v254, v129, v254
	v_exp_f32_e32 v131, v131
	s_waitcnt lgkmcnt(3)
	v_mfma_f32_32x32x16_bf16 v[222:237], v[206:209], v[160:163], v[222:237]
	ds_read_b64_tr_b16 v[206:207], v205
	ds_read_b64_tr_b16 v[208:209], v205 offset:4096
	v_sub_f32_e32 v132, v132, v190
	v_add_f32_e32 v254, v130, v254
	v_exp_f32_e32 v132, v132
	v_sub_f32_e32 v133, v133, v190
	v_add_f32_e32 v254, v131, v254
	s_waitcnt lgkmcnt(4)
	v_mfma_f32_32x32x16_bf16 v[222:237], v[210:213], v[164:167], v[222:237]
	ds_read_b64_tr_b16 v[210:211], v218
	ds_read_b64_tr_b16 v[212:213], v218 offset:4096
	v_exp_f32_e32 v133, v133
	v_sub_f32_e32 v134, v134, v190
	v_add_f32_e32 v254, v132, v254
	v_exp_f32_e32 v134, v134
	s_waitcnt lgkmcnt(5)
	v_mfma_f32_32x32x16_bf16 v[222:237], v[214:217], v[168:171], v[222:237]
	ds_read_b64_tr_b16 v[214:215], v219
	ds_read_b64_tr_b16 v[216:217], v219 offset:4096
	v_sub_f32_e32 v135, v135, v190
	v_add_f32_e32 v254, v133, v254
	v_exp_f32_e32 v135, v135
	s_nop 0
	s_waitcnt lgkmcnt(6)
	v_mfma_f32_32x32x16_bf16 v[222:237], v[238:241], v[172:175], v[222:237]
	ds_read_b64_tr_b16 v[238:239], v221
	ds_read_b64_tr_b16 v[240:241], v221 offset:4096
	v_cvt_pk_bf16_f32 v242, v128, v129
	v_cvt_pk_bf16_f32 v243, v130, v131
	v_cvt_pk_bf16_f32 v244, v132, v133
	v_cvt_pk_bf16_f32 v245, v134, v135
	s_nop 1
	s_waitcnt lgkmcnt(6)
	v_mfma_f32_32x32x16_bf16 v[112:127], v[206:209], v[242:245], v[112:127]
	ds_read_b64_tr_b16 v[206:207], v205 offset:256
	ds_read_b64_tr_b16 v[208:209], v205 offset:4352
	v_sub_f32_e32 v136, v136, v190
	v_add_f32_e32 v254, v134, v254
	v_exp_f32_e32 v136, v136
	v_sub_f32_e32 v137, v137, v190
	v_add_f32_e32 v254, v135, v254
	s_waitcnt lgkmcnt(6)
	v_mfma_f32_32x32x16_bf16 v[96:111], v[210:213], v[242:245], v[96:111]
	ds_read_b64_tr_b16 v[210:211], v218 offset:256
	ds_read_b64_tr_b16 v[212:213], v218 offset:4352
	v_exp_f32_e32 v137, v137
	v_sub_f32_e32 v138, v138, v190
	v_add_f32_e32 v254, v136, v254
	v_exp_f32_e32 v138, v138
	v_sub_f32_e32 v139, v139, v190
	s_waitcnt lgkmcnt(6)
	v_mfma_f32_32x32x16_bf16 v[80:95], v[214:217], v[242:245], v[80:95]
	ds_read_b64_tr_b16 v[214:215], v219 offset:256
	ds_read_b64_tr_b16 v[216:217], v219 offset:4352
	v_add_f32_e32 v254, v137, v254
	v_exp_f32_e32 v139, v139
	v_sub_f32_e32 v140, v140, v190
	v_add_f32_e32 v254, v138, v254
	s_waitcnt lgkmcnt(6)
	v_mfma_f32_32x32x16_bf16 v[64:79], v[238:241], v[242:245], v[64:79]
	ds_read_b64_tr_b16 v[238:239], v221 offset:256
	ds_read_b64_tr_b16 v[240:241], v221 offset:4352
	v_exp_f32_e32 v140, v140
	v_sub_f32_e32 v141, v141, v190
	v_add_f32_e32 v254, v139, v254
	v_exp_f32_e32 v141, v141
	s_waitcnt lgkmcnt(6)
	v_mfma_f32_32x32x16_bf16 v[48:63], v[206:209], v[242:245], v[48:63]
	ds_read_b64_tr_b16 v[206:207], v205 offset:8192
	ds_read_b64_tr_b16 v[208:209], v205 offset:12288
	v_sub_f32_e32 v142, v142, v190
	v_add_f32_e32 v254, v140, v254
	v_exp_f32_e32 v142, v142
	v_sub_f32_e32 v143, v143, v190
	s_waitcnt lgkmcnt(6)
	v_mfma_f32_32x32x16_bf16 v[32:47], v[210:213], v[242:245], v[32:47]
	ds_read_b64_tr_b16 v[210:211], v218 offset:8192
	ds_read_b64_tr_b16 v[212:213], v218 offset:12288
	v_add_f32_e32 v254, v141, v254
	v_exp_f32_e32 v143, v143
	v_add_f32_e32 v254, v142, v254
	v_add_f32_e32 v254, v143, v254
	s_waitcnt lgkmcnt(6)
	v_mfma_f32_32x32x16_bf16 v[16:31], v[214:217], v[242:245], v[16:31]
	ds_read_b64_tr_b16 v[214:215], v219 offset:8192
	ds_read_b64_tr_b16 v[216:217], v219 offset:12288
	v_cvt_pk_bf16_f32 v250, v136, v137
	v_cvt_pk_bf16_f32 v251, v138, v139
	v_cvt_pk_bf16_f32 v252, v140, v141
	v_cvt_pk_bf16_f32 v253, v142, v143
	v_add_f32_e32 v202, v202, v254
	s_waitcnt lgkmcnt(6)
	v_mfma_f32_32x32x16_bf16 v[0:15], v[238:241], v[242:245], v[0:15]
	ds_read_b64_tr_b16 v[238:239], v221 offset:8192
	ds_read_b64_tr_b16 v[240:241], v221 offset:12288
	ds_read_b64_tr_b16 v[128:129], v205 offset:8448
	ds_read_b64_tr_b16 v[130:131], v205 offset:12544
	s_waitcnt lgkmcnt(8)
	v_mfma_f32_32x32x16_bf16 v[112:127], v[206:209], v[250:253], v[112:127]
	ds_read_b64_tr_b16 v[206:207], v218 offset:8448
	ds_read_b64_tr_b16 v[208:209], v218 offset:12544
	v_max3_f32 v246, v222, v223, v224
	v_max3_f32 v247, v225, v226, v227
	v_max3_f32 v246, v246, v228, v229
	v_max3_f32 v247, v247, v230, v231
	v_max3_f32 v246, v246, v232, v233
	s_waitcnt lgkmcnt(8)
	v_mfma_f32_32x32x16_bf16 v[96:111], v[210:213], v[250:253], v[96:111]
	ds_read_b64_tr_b16 v[210:211], v219 offset:8448
	ds_read_b64_tr_b16 v[212:213], v219 offset:12544
	v_max3_f32 v247, v247, v234, v235
	v_max3_f32 v246, v246, v236, v237
	v_max_f32_e32 v246, v246, v247
	v_mov_b32_e32 v247, v246
	v_add_f32_e32 v249, 0x41000000, v190
	s_waitcnt lgkmcnt(8)
	v_mfma_f32_32x32x16_bf16 v[80:95], v[214:217], v[250:253], v[80:95]
	ds_read_b64_tr_b16 v[214:215], v221 offset:8448
	ds_read_b64_tr_b16 v[216:217], v221 offset:12544
	s_nop 1
	v_permlane32_swap_b32_e32 v246, v247
	v_max_f32_e32 v246, v246, v247
	v_cmp_gt_f32_e32 vcc, v246, v249
	s_cbranch_vccnz .Latt_rs1_0s0
	s_waitcnt lgkmcnt(8)
	v_mfma_f32_32x32x16_bf16 v[64:79], v[238:241], v[250:253], v[64:79]
	ds_read_b64_tr_b16 v[238:239], v205 offset:16384
	ds_read_b64_tr_b16 v[240:241], v205 offset:20480
	v_sub_f32_e32 v222, v222, v190
	v_exp_f32_e32 v222, v222
	v_sub_f32_e32 v223, v223, v190
	v_exp_f32_e32 v223, v223
	v_sub_f32_e32 v224, v224, v190
	v_add_f32_e32 v254, 0, v222
	s_waitcnt lgkmcnt(8)
	v_mfma_f32_32x32x16_bf16 v[48:63], v[128:131], v[250:253], v[48:63]
	ds_read_b64_tr_b16 v[128:129], v218 offset:16384
	ds_read_b64_tr_b16 v[130:131], v218 offset:20480
	v_exp_f32_e32 v224, v224
	v_sub_f32_e32 v225, v225, v190
	v_add_f32_e32 v254, v223, v254
	v_exp_f32_e32 v225, v225
	v_sub_f32_e32 v226, v226, v190
	v_add_f32_e32 v254, v224, v254
	s_waitcnt lgkmcnt(8)
	v_mfma_f32_32x32x16_bf16 v[32:47], v[206:209], v[250:253], v[32:47]
	ds_read_b64_tr_b16 v[206:207], v219 offset:16384
	ds_read_b64_tr_b16 v[208:209], v219 offset:20480
	v_exp_f32_e32 v226, v226
	v_sub_f32_e32 v227, v227, v190
	v_add_f32_e32 v254, v225, v254
	v_exp_f32_e32 v227, v227
	v_sub_f32_e32 v228, v228, v190
	s_waitcnt lgkmcnt(8)
	v_mfma_f32_32x32x16_bf16 v[16:31], v[210:213], v[250:253], v[16:31]
	ds_read_b64_tr_b16 v[210:211], v221 offset:16384
	ds_read_b64_tr_b16 v[212:213], v221 offset:20480
	v_add_f32_e32 v254, v226, v254
	v_exp_f32_e32 v228, v228
	v_sub_f32_e32 v229, v229, v190
	v_add_f32_e32 v254, v227, v254
	v_exp_f32_e32 v229, v229
	s_waitcnt lgkmcnt(8)
	v_mfma_f32_32x32x16_bf16 v[0:15], v[214:217], v[250:253], v[0:15]
	ds_read_b64_tr_b16 v[214:215], v205 offset:16640
	ds_read_b64_tr_b16 v[216:217], v205 offset:20736
	s_nop 0
	v_cvt_pk_bf16_f32 v242, v222, v223
	v_cvt_pk_bf16_f32 v243, v224, v225
	v_cvt_pk_bf16_f32 v244, v226, v227
	v_cvt_pk_bf16_f32 v245, v228, v229
	s_nop 1
	s_waitcnt lgkmcnt(8)
	v_mfma_f32_32x32x16_bf16 v[112:127], v[238:241], v[242:245], v[112:127]
	ds_read_b64_tr_b16 v[238:239], v218 offset:16640
	ds_read_b64_tr_b16 v[240:241], v218 offset:20736
	v_sub_f32_e32 v230, v230, v190
	v_add_f32_e32 v254, v228, v254
	v_exp_f32_e32 v230, v230
	v_sub_f32_e32 v231, v231, v190
	v_add_f32_e32 v254, v229, v254
	s_waitcnt lgkmcnt(8)
	v_mfma_f32_32x32x16_bf16 v[96:111], v[128:131], v[242:245], v[96:111]
	ds_read_b64_tr_b16 v[128:129], v219 offset:16640
	ds_read_b64_tr_b16 v[130:131], v219 offset:20736
	v_exp_f32_e32 v231, v231
	v_sub_f32_e32 v232, v232, v190
	v_add_f32_e32 v254, v230, v254
	v_exp_f32_e32 v232, v232
	v_sub_f32_e32 v233, v233, v190
	s_waitcnt lgkmcnt(8)
	v_mfma_f32_32x32x16_bf16 v[80:95], v[206:209], v[242:245], v[80:95]
	ds_read_b64_tr_b16 v[206:207], v221 offset:16640
	ds_read_b64_tr_b16 v[208:209], v221 offset:20736
	v_add_f32_e32 v254, v231, v254
	v_exp_f32_e32 v233, v233
	v_sub_f32_e32 v234, v234, v190
	v_add_f32_e32 v254, v232, v254
	s_waitcnt lgkmcnt(8)
	v_mfma_f32_32x32x16_bf16 v[64:79], v[210:213], v[242:245], v[64:79]
	ds_read_b64_tr_b16 v[210:211], v205 offset:24576
	ds_read_b64_tr_b16 v[212:213], v205 offset:28672
	v_exp_f32_e32 v234, v234
	v_sub_f32_e32 v235, v235, v190
	v_add_f32_e32 v254, v233, v254
	v_exp_f32_e32 v235, v235
	s_waitcnt lgkmcnt(8)
	v_mfma_f32_32x32x16_bf16 v[48:63], v[214:217], v[242:245], v[48:63]
	ds_read_b64_tr_b16 v[214:215], v218 offset:24576
	ds_read_b64_tr_b16 v[216:217], v218 offset:28672
	v_sub_f32_e32 v236, v236, v190
	v_add_f32_e32 v254, v234, v254
	v_exp_f32_e32 v236, v236
	v_sub_f32_e32 v237, v237, v190
	s_waitcnt lgkmcnt(8)
	v_mfma_f32_32x32x16_bf16 v[32:47], v[238:241], v[242:245], v[32:47]
	ds_read_b64_tr_b16 v[238:239], v219 offset:24576
	ds_read_b64_tr_b16 v[240:241], v219 offset:28672
	v_add_f32_e32 v254, v235, v254
	v_exp_f32_e32 v237, v237
	v_add_f32_e32 v254, v236, v254
	v_add_f32_e32 v254, v237, v254
	s_waitcnt lgkmcnt(8)
	v_mfma_f32_32x32x16_bf16 v[16:31], v[128:131], v[242:245], v[16:31]
	ds_read_b64_tr_b16 v[128:129], v221 offset:24576
	ds_read_b64_tr_b16 v[130:131], v221 offset:28672
	v_cvt_pk_bf16_f32 v250, v230, v231
	v_cvt_pk_bf16_f32 v251, v232, v233
	v_cvt_pk_bf16_f32 v252, v234, v235
	v_cvt_pk_bf16_f32 v253, v236, v237
	v_add_f32_e32 v202, v202, v254
	s_waitcnt lgkmcnt(8)
	v_mfma_f32_32x32x16_bf16 v[0:15], v[206:209], v[242:245], v[0:15]
	ds_read_b64_tr_b16 v[206:207], v205 offset:24832
	ds_read_b64_tr_b16 v[208:209], v205 offset:28928
	s_waitcnt lgkmcnt(8)
	v_mfma_f32_32x32x16_bf16 v[112:127], v[210:213], v[250:253], v[112:127]
	ds_read_b64_tr_b16 v[210:211], v218 offset:24832
	ds_read_b64_tr_b16 v[212:213], v218 offset:28928
	s_waitcnt lgkmcnt(8)
	v_mfma_f32_32x32x16_bf16 v[96:111], v[214:217], v[250:253], v[96:111]
	ds_read_b64_tr_b16 v[214:215], v219 offset:24832
	ds_read_b64_tr_b16 v[216:217], v219 offset:28928
	s_waitcnt lgkmcnt(8)
	v_mfma_f32_32x32x16_bf16 v[80:95], v[238:241], v[250:253], v[80:95]
	ds_read_b64_tr_b16 v[238:239], v221 offset:24832
	ds_read_b64_tr_b16 v[240:241], v221 offset:28928
	s_waitcnt lgkmcnt(8)
	v_mfma_f32_32x32x16_bf16 v[64:79], v[128:131], v[250:253], v[64:79]
	s_waitcnt lgkmcnt(6)
	v_mfma_f32_32x32x16_bf16 v[48:63], v[206:209], v[250:253], v[48:63]
	s_waitcnt lgkmcnt(4)
	v_mfma_f32_32x32x16_bf16 v[32:47], v[210:213], v[250:253], v[32:47]
	s_waitcnt lgkmcnt(2)
	v_mfma_f32_32x32x16_bf16 v[16:31], v[214:217], v[250:253], v[16:31]
	s_waitcnt lgkmcnt(0)
	v_mfma_f32_32x32x16_bf16 v[0:15], v[238:241], v[250:253], v[0:15]
	ds_read_b128 v[206:209], v194 offset:16384
	ds_read_b128 v[210:213], v195 offset:16384
	ds_read_b128 v[214:217], v196 offset:16384
	ds_read_b128 v[238:241], v197 offset:16384
	ds_read_b128 v[242:245], v198 offset:16384
	ds_read_b128 v[250:253], v199 offset:16384
	ds_read_b128 v[222:225], v200 offset:16384
	ds_read_b128 v[226:229], v201 offset:16384
	s_branch .Latt_end_0
.Latt_rs1_0s0:
	s_waitcnt lgkmcnt(8)
	v_mfma_f32_32x32x16_bf16 v[64:79], v[238:241], v[250:253], v[64:79]
	ds_read_b64_tr_b16 v[238:239], v205 offset:16384
	ds_read_b64_tr_b16 v[240:241], v205 offset:20480
	s_waitcnt lgkmcnt(8)
	v_mfma_f32_32x32x16_bf16 v[48:63], v[128:131], v[250:253], v[48:63]
	ds_read_b64_tr_b16 v[128:129], v218 offset:16384
	ds_read_b64_tr_b16 v[130:131], v218 offset:20480
	s_waitcnt lgkmcnt(8)
	v_mfma_f32_32x32x16_bf16 v[32:47], v[206:209], v[250:253], v[32:47]
	ds_read_b64_tr_b16 v[206:207], v219 offset:16384
	ds_read_b64_tr_b16 v[208:209], v219 offset:20480
	s_waitcnt lgkmcnt(8)
	v_mfma_f32_32x32x16_bf16 v[16:31], v[210:213], v[250:253], v[16:31]
	ds_read_b64_tr_b16 v[210:211], v221 offset:16384
	ds_read_b64_tr_b16 v[212:213], v221 offset:20480
	s_waitcnt lgkmcnt(8)
	v_mfma_f32_32x32x16_bf16 v[0:15], v[214:217], v[250:253], v[0:15]
	ds_read_b64_tr_b16 v[214:215], v205 offset:16640
	ds_read_b64_tr_b16 v[216:217], v205 offset:20736
	s_nop 11
	v_max_f32_e32 v246, v190, v246
	v_sub_f32_e32 v190, v190, v246
	v_exp_f32_e32 v190, v190
	s_nop 0
	v_pk_mul_f32 v[126:127], v[126:127], v[190:191] op_sel_hi:[1,0]
	v_pk_mul_f32 v[124:125], v[124:125], v[190:191] op_sel_hi:[1,0]
	v_pk_mul_f32 v[122:123], v[122:123], v[190:191] op_sel_hi:[1,0]
	v_pk_mul_f32 v[120:121], v[120:121], v[190:191] op_sel_hi:[1,0]
	v_pk_mul_f32 v[118:119], v[118:119], v[190:191] op_sel_hi:[1,0]
	v_pk_mul_f32 v[116:117], v[116:117], v[190:191] op_sel_hi:[1,0]
	v_pk_mul_f32 v[114:115], v[114:115], v[190:191] op_sel_hi:[1,0]
	v_pk_mul_f32 v[112:113], v[112:113], v[190:191] op_sel_hi:[1,0]
	v_pk_mul_f32 v[110:111], v[110:111], v[190:191] op_sel_hi:[1,0]
	v_pk_mul_f32 v[108:109], v[108:109], v[190:191] op_sel_hi:[1,0]
	v_pk_mul_f32 v[106:107], v[106:107], v[190:191] op_sel_hi:[1,0]
	v_pk_mul_f32 v[104:105], v[104:105], v[190:191] op_sel_hi:[1,0]
	v_pk_mul_f32 v[102:103], v[102:103], v[190:191] op_sel_hi:[1,0]
	v_pk_mul_f32 v[100:101], v[100:101], v[190:191] op_sel_hi:[1,0]
	v_pk_mul_f32 v[98:99], v[98:99], v[190:191] op_sel_hi:[1,0]
	v_pk_mul_f32 v[96:97], v[96:97], v[190:191] op_sel_hi:[1,0]
	v_pk_mul_f32 v[94:95], v[94:95], v[190:191] op_sel_hi:[1,0]
	v_pk_mul_f32 v[92:93], v[92:93], v[190:191] op_sel_hi:[1,0]
	v_pk_mul_f32 v[90:91], v[90:91], v[190:191] op_sel_hi:[1,0]
	v_pk_mul_f32 v[88:89], v[88:89], v[190:191] op_sel_hi:[1,0]
	v_pk_mul_f32 v[86:87], v[86:87], v[190:191] op_sel_hi:[1,0]
	v_pk_mul_f32 v[84:85], v[84:85], v[190:191] op_sel_hi:[1,0]
	v_pk_mul_f32 v[82:83], v[82:83], v[190:191] op_sel_hi:[1,0]
	v_pk_mul_f32 v[80:81], v[80:81], v[190:191] op_sel_hi:[1,0]
	v_pk_mul_f32 v[78:79], v[78:79], v[190:191] op_sel_hi:[1,0]
	v_pk_mul_f32 v[76:77], v[76:77], v[190:191] op_sel_hi:[1,0]
	v_pk_mul_f32 v[74:75], v[74:75], v[190:191] op_sel_hi:[1,0]
	v_pk_mul_f32 v[72:73], v[72:73], v[190:191] op_sel_hi:[1,0]
	v_pk_mul_f32 v[70:71], v[70:71], v[190:191] op_sel_hi:[1,0]
	v_pk_mul_f32 v[68:69], v[68:69], v[190:191] op_sel_hi:[1,0]
	v_pk_mul_f32 v[66:67], v[66:67], v[190:191] op_sel_hi:[1,0]
	v_pk_mul_f32 v[64:65], v[64:65], v[190:191] op_sel_hi:[1,0]
	v_pk_mul_f32 v[62:63], v[62:63], v[190:191] op_sel_hi:[1,0]
	v_pk_mul_f32 v[60:61], v[60:61], v[190:191] op_sel_hi:[1,0]
	v_pk_mul_f32 v[58:59], v[58:59], v[190:191] op_sel_hi:[1,0]
	v_pk_mul_f32 v[56:57], v[56:57], v[190:191] op_sel_hi:[1,0]
	v_pk_mul_f32 v[54:55], v[54:55], v[190:191] op_sel_hi:[1,0]
	v_pk_mul_f32 v[52:53], v[52:53], v[190:191] op_sel_hi:[1,0]
	v_pk_mul_f32 v[50:51], v[50:51], v[190:191] op_sel_hi:[1,0]
	v_pk_mul_f32 v[48:49], v[48:49], v[190:191] op_sel_hi:[1,0]
	v_pk_mul_f32 v[46:47], v[46:47], v[190:191] op_sel_hi:[1,0]
	v_pk_mul_f32 v[44:45], v[44:45], v[190:191] op_sel_hi:[1,0]
	v_pk_mul_f32 v[42:43], v[42:43], v[190:191] op_sel_hi:[1,0]
	v_pk_mul_f32 v[40:41], v[40:41], v[190:191] op_sel_hi:[1,0]
	v_pk_mul_f32 v[38:39], v[38:39], v[190:191] op_sel_hi:[1,0]
	v_pk_mul_f32 v[36:37], v[36:37], v[190:191] op_sel_hi:[1,0]
	v_pk_mul_f32 v[34:35], v[34:35], v[190:191] op_sel_hi:[1,0]
	v_pk_mul_f32 v[32:33], v[32:33], v[190:191] op_sel_hi:[1,0]
	v_pk_mul_f32 v[30:31], v[30:31], v[190:191] op_sel_hi:[1,0]
	v_pk_mul_f32 v[28:29], v[28:29], v[190:191] op_sel_hi:[1,0]
	v_pk_mul_f32 v[26:27], v[26:27], v[190:191] op_sel_hi:[1,0]
	v_pk_mul_f32 v[24:25], v[24:25], v[190:191] op_sel_hi:[1,0]
	v_pk_mul_f32 v[22:23], v[22:23], v[190:191] op_sel_hi:[1,0]
	v_pk_mul_f32 v[20:21], v[20:21], v[190:191] op_sel_hi:[1,0]
	v_pk_mul_f32 v[18:19], v[18:19], v[190:191] op_sel_hi:[1,0]
	v_pk_mul_f32 v[16:17], v[16:17], v[190:191] op_sel_hi:[1,0]
	v_pk_mul_f32 v[14:15], v[14:15], v[190:191] op_sel_hi:[1,0]
	v_pk_mul_f32 v[12:13], v[12:13], v[190:191] op_sel_hi:[1,0]
	v_pk_mul_f32 v[10:11], v[10:11], v[190:191] op_sel_hi:[1,0]
	v_pk_mul_f32 v[8:9], v[8:9], v[190:191] op_sel_hi:[1,0]
	v_pk_mul_f32 v[6:7], v[6:7], v[190:191] op_sel_hi:[1,0]
	v_pk_mul_f32 v[4:5], v[4:5], v[190:191] op_sel_hi:[1,0]
	v_pk_mul_f32 v[2:3], v[2:3], v[190:191] op_sel_hi:[1,0]
	v_pk_mul_f32 v[0:1], v[0:1], v[190:191] op_sel_hi:[1,0]
	v_mul_f32_e32 v202, v202, v190
	v_mov_b32_e32 v190, v246
	v_sub_f32_e32 v222, v222, v190
	v_exp_f32_e32 v222, v222
	v_sub_f32_e32 v223, v223, v190
	v_exp_f32_e32 v223, v223
	v_sub_f32_e32 v224, v224, v190
	v_add_f32_e32 v254, 0, v222
	v_exp_f32_e32 v224, v224
	v_sub_f32_e32 v225, v225, v190
	v_add_f32_e32 v254, v223, v254
	v_exp_f32_e32 v225, v225
	v_sub_f32_e32 v226, v226, v190
	v_add_f32_e32 v254, v224, v254
	v_exp_f32_e32 v226, v226
	v_sub_f32_e32 v227, v227, v190
	v_add_f32_e32 v254, v225, v254
	v_exp_f32_e32 v227, v227
	v_sub_f32_e32 v228, v228, v190
	v_add_f32_e32 v254, v226, v254
	v_exp_f32_e32 v228, v228
	v_sub_f32_e32 v229, v229, v190
	v_add_f32_e32 v254, v227, v254
	v_exp_f32_e32 v229, v229
	v_sub_f32_e32 v230, v230, v190
	v_add_f32_e32 v254, v228, v254
	v_exp_f32_e32 v230, v230
	v_sub_f32_e32 v231, v231, v190
	v_add_f32_e32 v254, v229, v254
	v_exp_f32_e32 v231, v231
	v_sub_f32_e32 v232, v232, v190
	v_add_f32_e32 v254, v230, v254
	v_exp_f32_e32 v232, v232
	v_sub_f32_e32 v233, v233, v190
	v_add_f32_e32 v254, v231, v254
	v_exp_f32_e32 v233, v233
	v_sub_f32_e32 v234, v234, v190
	v_add_f32_e32 v254, v232, v254
	v_exp_f32_e32 v234, v234
	v_sub_f32_e32 v235, v235, v190
	v_add_f32_e32 v254, v233, v254
	v_exp_f32_e32 v235, v235
	v_sub_f32_e32 v236, v236, v190
	v_add_f32_e32 v254, v234, v254
	v_exp_f32_e32 v236, v236
	v_sub_f32_e32 v237, v237, v190
	v_add_f32_e32 v254, v235, v254
	v_exp_f32_e32 v237, v237
	v_add_f32_e32 v254, v236, v254
	v_add_f32_e32 v254, v237, v254
	v_cvt_pk_bf16_f32 v242, v222, v223
	v_cvt_pk_bf16_f32 v243, v224, v225
	v_cvt_pk_bf16_f32 v244, v226, v227
	v_cvt_pk_bf16_f32 v245, v228, v229
	v_cvt_pk_bf16_f32 v250, v230, v231
	v_cvt_pk_bf16_f32 v251, v232, v233
	v_cvt_pk_bf16_f32 v252, v234, v235
	v_cvt_pk_bf16_f32 v253, v236, v237
	v_add_f32_e32 v202, v202, v254
	s_nop 1
	s_waitcnt lgkmcnt(8)
	v_mfma_f32_32x32x16_bf16 v[112:127], v[238:241], v[242:245], v[112:127]
	ds_read_b64_tr_b16 v[238:239], v218 offset:16640
	ds_read_b64_tr_b16 v[240:241], v218 offset:20736
	s_waitcnt lgkmcnt(8)
	v_mfma_f32_32x32x16_bf16 v[96:111], v[128:131], v[242:245], v[96:111]
	ds_read_b64_tr_b16 v[222:223], v219 offset:16640
	ds_read_b64_tr_b16 v[224:225], v219 offset:20736
	s_waitcnt lgkmcnt(8)
	v_mfma_f32_32x32x16_bf16 v[80:95], v[206:209], v[242:245], v[80:95]
	ds_read_b64_tr_b16 v[206:207], v221 offset:16640
	ds_read_b64_tr_b16 v[208:209], v221 offset:20736
	s_waitcnt lgkmcnt(8)
	v_mfma_f32_32x32x16_bf16 v[64:79], v[210:213], v[242:245], v[64:79]
	ds_read_b64_tr_b16 v[210:211], v205 offset:24576
	ds_read_b64_tr_b16 v[212:213], v205 offset:28672
	s_waitcnt lgkmcnt(8)
	v_mfma_f32_32x32x16_bf16 v[48:63], v[214:217], v[242:245], v[48:63]
	ds_read_b64_tr_b16 v[214:215], v218 offset:24576
	ds_read_b64_tr_b16 v[216:217], v218 offset:28672
	s_waitcnt lgkmcnt(8)
	v_mfma_f32_32x32x16_bf16 v[32:47], v[238:241], v[242:245], v[32:47]
	ds_read_b64_tr_b16 v[238:239], v219 offset:24576
	ds_read_b64_tr_b16 v[240:241], v219 offset:28672
	s_waitcnt lgkmcnt(8)
	v_mfma_f32_32x32x16_bf16 v[16:31], v[222:225], v[242:245], v[16:31]
	ds_read_b64_tr_b16 v[222:223], v221 offset:24576
	ds_read_b64_tr_b16 v[224:225], v221 offset:28672
	s_waitcnt lgkmcnt(8)
	v_mfma_f32_32x32x16_bf16 v[0:15], v[206:209], v[242:245], v[0:15]
	ds_read_b64_tr_b16 v[206:207], v205 offset:24832
	ds_read_b64_tr_b16 v[208:209], v205 offset:28928
	s_waitcnt lgkmcnt(8)
	v_mfma_f32_32x32x16_bf16 v[112:127], v[210:213], v[250:253], v[112:127]
	ds_read_b64_tr_b16 v[210:211], v218 offset:24832
	ds_read_b64_tr_b16 v[212:213], v218 offset:28928
	s_waitcnt lgkmcnt(8)
	v_mfma_f32_32x32x16_bf16 v[96:111], v[214:217], v[250:253], v[96:111]
	ds_read_b64_tr_b16 v[214:215], v219 offset:24832
	ds_read_b64_tr_b16 v[216:217], v219 offset:28928
	s_waitcnt lgkmcnt(8)
	v_mfma_f32_32x32x16_bf16 v[80:95], v[238:241], v[250:253], v[80:95]
	ds_read_b64_tr_b16 v[238:239], v221 offset:24832
	ds_read_b64_tr_b16 v[240:241], v221 offset:28928
	s_waitcnt lgkmcnt(8)
	v_mfma_f32_32x32x16_bf16 v[64:79], v[222:225], v[250:253], v[64:79]
	s_waitcnt lgkmcnt(6)
	v_mfma_f32_32x32x16_bf16 v[48:63], v[206:209], v[250:253], v[48:63]
	s_waitcnt lgkmcnt(4)
	v_mfma_f32_32x32x16_bf16 v[32:47], v[210:213], v[250:253], v[32:47]
	s_waitcnt lgkmcnt(2)
	v_mfma_f32_32x32x16_bf16 v[16:31], v[214:217], v[250:253], v[16:31]
	s_waitcnt lgkmcnt(0)
	v_mfma_f32_32x32x16_bf16 v[0:15], v[238:241], v[250:253], v[0:15]
	ds_read_b128 v[206:209], v194 offset:16384
	ds_read_b128 v[210:213], v195 offset:16384
	ds_read_b128 v[214:217], v196 offset:16384
	ds_read_b128 v[238:241], v197 offset:16384
	ds_read_b128 v[242:245], v198 offset:16384
	ds_read_b128 v[250:253], v199 offset:16384
	ds_read_b128 v[222:225], v200 offset:16384
	ds_read_b128 v[226:229], v201 offset:16384
	s_branch .Latt_end_0
.Latt_slow_0s0:
.Latt_slot1_0:
	v_add_u32_e32 v205, 0x8000, v205
	v_add_u32_e32 v218, 0x8000, v218
	v_add_u32_e32 v219, 0x8000, v219
	v_add_u32_e32 v221, 0x8000, v221
	s_waitcnt lgkmcnt(7)
	v_mfma_f32_32x32x16_bf16 v[128:143], v[206:209], v[144:147], 0
	ds_read_b128 v[206:209], v194 offset:24576
	s_cmp_lg_u64 s[18:19], 0
	s_cbranch_scc1 .Latt_nd0_0s1
	s_sub_i32 s100, s88, 1
	s_cmp_eq_u32 s88, 0
	s_cselect_b32 s100, 2, s100
	s_lshl_b32 s101, s100, 14
	s_add_i32 m0, s85, s101
	s_nop 0
	global_load_lds_dwordx4 v178, s[14:15]
.Latt_nd0_0s1:
	s_waitcnt lgkmcnt(7)
	v_mfma_f32_32x32x16_bf16 v[128:143], v[210:213], v[148:151], v[128:143]
	ds_read_b128 v[210:213], v195 offset:24576
	s_cmp_lg_u64 s[18:19], 0
	s_cbranch_scc1 .Latt_nd1_0s1
	s_add_i32 m0, m0, 0x400
	s_nop 0
	global_load_lds_dwordx4 v180, s[14:15]
.Latt_nd1_0s1:
	s_waitcnt lgkmcnt(7)
	v_mfma_f32_32x32x16_bf16 v[128:143], v[214:217], v[152:155], v[128:143]
	ds_read_b128 v[214:217], v196 offset:24576
	s_cmp_lg_u64 s[18:19], 0
	s_cbranch_scc1 .Latt_nd2_0s1
	s_lshl_b32 s101, s100, 15
	s_add_i32 m0, s86, s101
	s_add_u32 s100, s14, 0x1000
	s_addc_u32 s101, s15, 0
	global_load_lds_dwordx4 v182, s[100:101]
.Latt_nd2_0s1:
	s_waitcnt lgkmcnt(7)
	v_mfma_f32_32x32x16_bf16 v[128:143], v[238:241], v[156:159], v[128:143]
	ds_read_b128 v[238:241], v197 offset:24576
	s_cmp_lg_u64 s[18:19], 0
	s_cbranch_scc1 .Latt_nd3_0s1
	s_add_i32 m0, m0, 0x400
	s_nop 0
	global_load_lds_dwordx4 v184, s[100:101]

.Latt_nd5_0s1:
	s_waitcnt lgkmcnt(5)
	v_mfma_f32_32x32x16_bf16 v[128:143], v[222:225], v[168:171], v[128:143]
	s_waitcnt lgkmcnt(4)
	v_mfma_f32_32x32x16_bf16 v[128:143], v[226:229], v[172:175], v[128:143]
	s_waitcnt lgkmcnt(3)
	v_mfma_f32_32x32x16_bf16 v[222:237], v[206:209], v[144:147], 0
	ds_read_b128 v[206:209], v198 offset:24576
	s_nop 8
	v_max3_f32 v246, v128, v129, v130
	v_max3_f32 v247, v131, v132, v133
	v_max3_f32 v246, v246, v134, v135
	v_max3_f32 v247, v247, v136, v137
	v_max3_f32 v246, v246, v138, v139
	v_max3_f32 v247, v247, v140, v141
	v_max3_f32 v246, v246, v142, v143
	s_waitcnt lgkmcnt(3)
	v_mfma_f32_32x32x16_bf16 v[222:237], v[210:213], v[148:151], v[222:237]
	ds_read_b128 v[210:213], v199 offset:24576
	v_max_f32_e32 v246, v246, v247
	v_mov_b32_e32 v247, v246
	v_add_f32_e32 v249, 0x41000000, v190
	s_nop 1
	v_permlane32_swap_b32_e32 v246, v247
	v_max_f32_e32 v246, v246, v247
	v_cmp_gt_f32_e32 vcc, v246, v249
	s_cbranch_vccz .Latt_nr0_0s1
	v_max_f32_e32 v246, v190, v246
	v_sub_f32_e32 v190, v190, v246
	v_exp_f32_e32 v190, v190
	s_nop 0
	v_pk_mul_f32 v[126:127], v[126:127], v[190:191] op_sel_hi:[1,0]
	v_pk_mul_f32 v[124:125], v[124:125], v[190:191] op_sel_hi:[1,0]
	v_pk_mul_f32 v[122:123], v[122:123], v[190:191] op_sel_hi:[1,0]
	v_pk_mul_f32 v[120:121], v[120:121], v[190:191] op_sel_hi:[1,0]
	v_pk_mul_f32 v[118:119], v[118:119], v[190:191] op_sel_hi:[1,0]
	v_pk_mul_f32 v[116:117], v[116:117], v[190:191] op_sel_hi:[1,0]
	v_pk_mul_f32 v[114:115], v[114:115], v[190:191] op_sel_hi:[1,0]
	v_pk_mul_f32 v[112:113], v[112:113], v[190:191] op_sel_hi:[1,0]
	v_pk_mul_f32 v[110:111], v[110:111], v[190:191] op_sel_hi:[1,0]
	v_pk_mul_f32 v[108:109], v[108:109], v[190:191] op_sel_hi:[1,0]
	v_pk_mul_f32 v[106:107], v[106:107], v[190:191] op_sel_hi:[1,0]
	v_pk_mul_f32 v[104:105], v[104:105], v[190:191] op_sel_hi:[1,0]
	v_pk_mul_f32 v[102:103], v[102:103], v[190:191] op_sel_hi:[1,0]
	v_pk_mul_f32 v[100:101], v[100:101], v[190:191] op_sel_hi:[1,0]
	v_pk_mul_f32 v[98:99], v[98:99], v[190:191] op_sel_hi:[1,0]
	v_pk_mul_f32 v[96:97], v[96:97], v[190:191] op_sel_hi:[1,0]
	v_pk_mul_f32 v[94:95], v[94:95], v[190:191] op_sel_hi:[1,0]
	v_pk_mul_f32 v[92:93], v[92:93], v[190:191] op_sel_hi:[1,0]
	v_pk_mul_f32 v[90:91], v[90:91], v[190:191] op_sel_hi:[1,0]
	v_pk_mul_f32 v[88:89], v[88:89], v[190:191] op_sel_hi:[1,0]
	v_pk_mul_f32 v[86:87], v[86:87], v[190:191] op_sel_hi:[1,0]
	v_pk_mul_f32 v[84:85], v[84:85], v[190:191] op_sel_hi:[1,0]
	v_pk_mul_f32 v[82:83], v[82:83], v[190:191] op_sel_hi:[1,0]
	v_pk_mul_f32 v[80:81], v[80:81], v[190:191] op_sel_hi:[1,0]
	v_pk_mul_f32 v[78:79], v[78:79], v[190:191] op_sel_hi:[1,0]
	v_pk_mul_f32 v[76:77], v[76:77], v[190:191] op_sel_hi:[1,0]
	v_pk_mul_f32 v[74:75], v[74:75], v[190:191] op_sel_hi:[1,0]
	v_pk_mul_f32 v[72:73], v[72:73], v[190:191] op_sel_hi:[1,0]
	v_pk_mul_f32 v[70:71], v[70:71], v[190:191] op_sel_hi:[1,0]
	v_pk_mul_f32 v[68:69], v[68:69], v[190:191] op_sel_hi:[1,0]
	v_pk_mul_f32 v[66:67], v[66:67], v[190:191] op_sel_hi:[1,0]
	v_pk_mul_f32 v[64:65], v[64:65], v[190:191] op_sel_hi:[1,0]
	v_pk_mul_f32 v[62:63], v[62:63], v[190:191] op_sel_hi:[1,0]
	v_pk_mul_f32 v[60:61], v[60:61], v[190:191] op_sel_hi:[1,0]
	v_pk_mul_f32 v[58:59], v[58:59], v[190:191] op_sel_hi:[1,0]
	v_pk_mul_f32 v[56:57], v[56:57], v[190:191] op_sel_hi:[1,0]
	v_pk_mul_f32 v[54:55], v[54:55], v[190:191] op_sel_hi:[1,0]
	v_pk_mul_f32 v[52:53], v[52:53], v[190:191] op_sel_hi:[1,0]
	v_pk_mul_f32 v[50:51], v[50:51], v[190:191] op_sel_hi:[1,0]
	v_pk_mul_f32 v[48:49], v[48:49], v[190:191] op_sel_hi:[1,0]
	v_pk_mul_f32 v[46:47], v[46:47], v[190:191] op_sel_hi:[1,0]
	v_pk_mul_f32 v[44:45], v[44:45], v[190:191] op_sel_hi:[1,0]
	v_pk_mul_f32 v[42:43], v[42:43], v[190:191] op_sel_hi:[1,0]
	v_pk_mul_f32 v[40:41], v[40:41], v[190:191] op_sel_hi:[1,0]
	v_pk_mul_f32 v[38:39], v[38:39], v[190:191] op_sel_hi:[1,0]
	v_pk_mul_f32 v[36:37], v[36:37], v[190:191] op_sel_hi:[1,0]
	v_pk_mul_f32 v[34:35], v[34:35], v[190:191] op_sel_hi:[1,0]
	v_pk_mul_f32 v[32:33], v[32:33], v[190:191] op_sel_hi:[1,0]
	v_pk_mul_f32 v[30:31], v[30:31], v[190:191] op_sel_hi:[1,0]
	v_pk_mul_f32 v[28:29], v[28:29], v[190:191] op_sel_hi:[1,0]
	v_pk_mul_f32 v[26:27], v[26:27], v[190:191] op_sel_hi:[1,0]
	v_pk_mul_f32 v[24:25], v[24:25], v[190:191] op_sel_hi:[1,0]
	v_pk_mul_f32 v[22:23], v[22:23], v[190:191] op_sel_hi:[1,0]
	v_pk_mul_f32 v[20:21], v[20:21], v[190:191] op_sel_hi:[1,0]
	v_pk_mul_f32 v[18:19], v[18:19], v[190:191] op_sel_hi:[1,0]
	v_pk_mul_f32 v[16:17], v[16:17], v[190:191] op_sel_hi:[1,0]
	v_pk_mul_f32 v[14:15], v[14:15], v[190:191] op_sel_hi:[1,0]
	v_pk_mul_f32 v[12:13], v[12:13], v[190:191] op_sel_hi:[1,0]
	v_pk_mul_f32 v[10:11], v[10:11], v[190:191] op_sel_hi:[1,0]
	v_pk_mul_f32 v[8:9], v[8:9], v[190:191] op_sel_hi:[1,0]
	v_pk_mul_f32 v[6:7], v[6:7], v[190:191] op_sel_hi:[1,0]
	v_pk_mul_f32 v[4:5], v[4:5], v[190:191] op_sel_hi:[1,0]
	v_pk_mul_f32 v[2:3], v[2:3], v[190:191] op_sel_hi:[1,0]
	v_pk_mul_f32 v[0:1], v[0:1], v[190:191] op_sel_hi:[1,0]
	v_mul_f32_e32 v202, v202, v190
	v_mov_b32_e32 v190, v246
.Latt_nr0_0s1:
	s_waitcnt lgkmcnt(3)
	v_mfma_f32_32x32x16_bf16 v[222:237], v[214:217], v[152:155], v[222:237]
	ds_read_b128 v[214:217], v200 offset:24576
	v_sub_f32_e32 v128, v128, v190
	v_exp_f32_e32 v128, v128
	v_sub_f32_e32 v129, v129, v190
	v_exp_f32_e32 v129, v129
	v_sub_f32_e32 v130, v130, v190
	s_waitcnt lgkmcnt(3)
	v_mfma_f32_32x32x16_bf16 v[222:237], v[238:241], v[156:159], v[222:237]
	ds_read_b128 v[238:241], v201 offset:24576
	v_add_f32_e32 v254, 0, v128
	v_exp_f32_e32 v130, v130
	v_sub_f32_e32 v131, v131, v190
	v_add_f32_e32 v254, v129, v254
	v_exp_f32_e32 v131, v131
	s_waitcnt lgkmcnt(3)
	v_mfma_f32_32x32x16_bf16 v[222:237], v[206:209], v[160:163], v[222:237]
	ds_read_b64_tr_b16 v[206:207], v205
	ds_read_b64_tr_b16 v[208:209], v205 offset:4096
	v_sub_f32_e32 v132, v132, v190
	v_add_f32_e32 v254, v130, v254
	v_exp_f32_e32 v132, v132
	v_sub_f32_e32 v133, v133, v190
	v_add_f32_e32 v254, v131, v254
	s_waitcnt lgkmcnt(4)
	v_mfma_f32_32x32x16_bf16 v[222:237], v[210:213], v[164:167], v[222:237]
	ds_read_b64_tr_b16 v[210:211], v218
	ds_read_b64_tr_b16 v[212:213], v218 offset:4096
	v_exp_f32_e32 v133, v133
	v_sub_f32_e32 v134, v134, v190
	v_add_f32_e32 v254, v132, v254
	v_exp_f32_e32 v134, v134
	s_waitcnt lgkmcnt(5)
	v_mfma_f32_32x32x16_bf16 v[222:237], v[214:217], v[168:171], v[222:237]
	ds_read_b64_tr_b16 v[214:215], v219
	ds_read_b64_tr_b16 v[216:217], v219 offset:4096
	v_sub_f32_e32 v135, v135, v190
	v_add_f32_e32 v254, v133, v254
	v_exp_f32_e32 v135, v135
	s_nop 0
	s_waitcnt lgkmcnt(6)
	v_mfma_f32_32x32x16_bf16 v[222:237], v[238:241], v[172:175], v[222:237]
	ds_read_b64_tr_b16 v[238:239], v221
	ds_read_b64_tr_b16 v[240:241], v221 offset:4096
	v_cvt_pk_bf16_f32 v242, v128, v129
	v_cvt_pk_bf16_f32 v243, v130, v131
	v_cvt_pk_bf16_f32 v244, v132, v133
	v_cvt_pk_bf16_f32 v245, v134, v135
	s_nop 1
	s_waitcnt lgkmcnt(6)
	v_mfma_f32_32x32x16_bf16 v[112:127], v[206:209], v[242:245], v[112:127]
	ds_read_b64_tr_b16 v[206:207], v205 offset:256
	ds_read_b64_tr_b16 v[208:209], v205 offset:4352
	v_sub_f32_e32 v136, v136, v190
	v_add_f32_e32 v254, v134, v254
	v_exp_f32_e32 v136, v136
	v_sub_f32_e32 v137, v137, v190
	v_add_f32_e32 v254, v135, v254
	s_waitcnt lgkmcnt(6)
	v_mfma_f32_32x32x16_bf16 v[96:111], v[210:213], v[242:245], v[96:111]
	ds_read_b64_tr_b16 v[210:211], v218 offset:256
	ds_read_b64_tr_b16 v[212:213], v218 offset:4352
	v_exp_f32_e32 v137, v137
	v_sub_f32_e32 v138, v138, v190
	v_add_f32_e32 v254, v136, v254
	v_exp_f32_e32 v138, v138
	v_sub_f32_e32 v139, v139, v190
	s_waitcnt lgkmcnt(6)
	v_mfma_f32_32x32x16_bf16 v[80:95], v[214:217], v[242:245], v[80:95]
	ds_read_b64_tr_b16 v[214:215], v219 offset:256
	ds_read_b64_tr_b16 v[216:217], v219 offset:4352
	v_add_f32_e32 v254, v137, v254
	v_exp_f32_e32 v139, v139
	v_sub_f32_e32 v140, v140, v190
	v_add_f32_e32 v254, v138, v254
	s_waitcnt lgkmcnt(6)
	v_mfma_f32_32x32x16_bf16 v[64:79], v[238:241], v[242:245], v[64:79]
	ds_read_b64_tr_b16 v[238:239], v221 offset:256
	ds_read_b64_tr_b16 v[240:241], v221 offset:4352
	v_exp_f32_e32 v140, v140
	v_sub_f32_e32 v141, v141, v190
	v_add_f32_e32 v254, v139, v254
	v_exp_f32_e32 v141, v141
	s_waitcnt lgkmcnt(6)
	v_mfma_f32_32x32x16_bf16 v[48:63], v[206:209], v[242:245], v[48:63]
	ds_read_b64_tr_b16 v[206:207], v205 offset:8192
	ds_read_b64_tr_b16 v[208:209], v205 offset:12288
	v_sub_f32_e32 v142, v142, v190
	v_add_f32_e32 v254, v140, v254
	v_exp_f32_e32 v142, v142
	v_sub_f32_e32 v143, v143, v190
	s_waitcnt lgkmcnt(6)
	v_mfma_f32_32x32x16_bf16 v[32:47], v[210:213], v[242:245], v[32:47]
	ds_read_b64_tr_b16 v[210:211], v218 offset:8192
	ds_read_b64_tr_b16 v[212:213], v218 offset:12288
	v_add_f32_e32 v254, v141, v254
	v_exp_f32_e32 v143, v143
	v_add_f32_e32 v254, v142, v254
	v_add_f32_e32 v254, v143, v254
	s_waitcnt lgkmcnt(6)
	v_mfma_f32_32x32x16_bf16 v[16:31], v[214:217], v[242:245], v[16:31]
	ds_read_b64_tr_b16 v[214:215], v219 offset:8192
	ds_read_b64_tr_b16 v[216:217], v219 offset:12288
	v_cvt_pk_bf16_f32 v250, v136, v137
	v_cvt_pk_bf16_f32 v251, v138, v139
	v_cvt_pk_bf16_f32 v252, v140, v141
	v_cvt_pk_bf16_f32 v253, v142, v143
	v_add_f32_e32 v202, v202, v254
	s_waitcnt lgkmcnt(6)
	v_mfma_f32_32x32x16_bf16 v[0:15], v[238:241], v[242:245], v[0:15]
	ds_read_b64_tr_b16 v[238:239], v221 offset:8192
	ds_read_b64_tr_b16 v[240:241], v221 offset:12288
	ds_read_b64_tr_b16 v[128:129], v205 offset:8448
	ds_read_b64_tr_b16 v[130:131], v205 offset:12544
	s_waitcnt lgkmcnt(8)
	v_mfma_f32_32x32x16_bf16 v[112:127], v[206:209], v[250:253], v[112:127]
	ds_read_b64_tr_b16 v[206:207], v218 offset:8448
	ds_read_b64_tr_b16 v[208:209], v218 offset:12544
	v_max3_f32 v246, v222, v223, v224
	v_max3_f32 v247, v225, v226, v227
	v_max3_f32 v246, v246, v228, v229
	v_max3_f32 v247, v247, v230, v231
	v_max3_f32 v246, v246, v232, v233
	s_waitcnt lgkmcnt(8)
	v_mfma_f32_32x32x16_bf16 v[96:111], v[210:213], v[250:253], v[96:111]
	ds_read_b64_tr_b16 v[210:211], v219 offset:8448
	ds_read_b64_tr_b16 v[212:213], v219 offset:12544
	v_max3_f32 v247, v247, v234, v235
	v_max3_f32 v246, v246, v236, v237
	v_max_f32_e32 v246, v246, v247
	v_mov_b32_e32 v247, v246
	v_add_f32_e32 v249, 0x41000000, v190
	s_waitcnt lgkmcnt(8)
	v_mfma_f32_32x32x16_bf16 v[80:95], v[214:217], v[250:253], v[80:95]
	ds_read_b64_tr_b16 v[214:215], v221 offset:8448
	ds_read_b64_tr_b16 v[216:217], v221 offset:12544
	s_nop 1
	v_permlane32_swap_b32_e32 v246, v247
	v_max_f32_e32 v246, v246, v247
	v_cmp_gt_f32_e32 vcc, v246, v249
	s_cbranch_vccnz .Latt_rs1_0s1
	s_waitcnt lgkmcnt(8)
	v_mfma_f32_32x32x16_bf16 v[64:79], v[238:241], v[250:253], v[64:79]
	ds_read_b64_tr_b16 v[238:239], v205 offset:16384
	ds_read_b64_tr_b16 v[240:241], v205 offset:20480
	v_sub_f32_e32 v222, v222, v190
	v_exp_f32_e32 v222, v222
	v_sub_f32_e32 v223, v223, v190
	v_exp_f32_e32 v223, v223
	v_sub_f32_e32 v224, v224, v190
	v_add_f32_e32 v254, 0, v222
	s_waitcnt lgkmcnt(8)
	v_mfma_f32_32x32x16_bf16 v[48:63], v[128:131], v[250:253], v[48:63]
	ds_read_b64_tr_b16 v[128:129], v218 offset:16384
	ds_read_b64_tr_b16 v[130:131], v218 offset:20480
	v_exp_f32_e32 v224, v224
	v_sub_f32_e32 v225, v225, v190
	v_add_f32_e32 v254, v223, v254
	v_exp_f32_e32 v225, v225
	v_sub_f32_e32 v226, v226, v190
	v_add_f32_e32 v254, v224, v254
	s_waitcnt lgkmcnt(8)
	v_mfma_f32_32x32x16_bf16 v[32:47], v[206:209], v[250:253], v[32:47]
	ds_read_b64_tr_b16 v[206:207], v219 offset:16384
	ds_read_b64_tr_b16 v[208:209], v219 offset:20480
	v_exp_f32_e32 v226, v226
	v_sub_f32_e32 v227, v227, v190
	v_add_f32_e32 v254, v225, v254
	v_exp_f32_e32 v227, v227
	v_sub_f32_e32 v228, v228, v190
	s_waitcnt lgkmcnt(8)
	v_mfma_f32_32x32x16_bf16 v[16:31], v[210:213], v[250:253], v[16:31]
	ds_read_b64_tr_b16 v[210:211], v221 offset:16384
	ds_read_b64_tr_b16 v[212:213], v221 offset:20480
	v_add_f32_e32 v254, v226, v254
	v_exp_f32_e32 v228, v228
	v_sub_f32_e32 v229, v229, v190
	v_add_f32_e32 v254, v227, v254
	v_exp_f32_e32 v229, v229
	s_waitcnt lgkmcnt(8)
	v_mfma_f32_32x32x16_bf16 v[0:15], v[214:217], v[250:253], v[0:15]
	ds_read_b64_tr_b16 v[214:215], v205 offset:16640
	ds_read_b64_tr_b16 v[216:217], v205 offset:20736
	s_nop 0
	v_cvt_pk_bf16_f32 v242, v222, v223
	v_cvt_pk_bf16_f32 v243, v224, v225
	v_cvt_pk_bf16_f32 v244, v226, v227
	v_cvt_pk_bf16_f32 v245, v228, v229
	s_nop 1
	s_waitcnt lgkmcnt(8)
	v_mfma_f32_32x32x16_bf16 v[112:127], v[238:241], v[242:245], v[112:127]
	ds_read_b64_tr_b16 v[238:239], v218 offset:16640
	ds_read_b64_tr_b16 v[240:241], v218 offset:20736
	v_sub_f32_e32 v230, v230, v190
	v_add_f32_e32 v254, v228, v254
	v_exp_f32_e32 v230, v230
	v_sub_f32_e32 v231, v231, v190
	v_add_f32_e32 v254, v229, v254
	s_waitcnt lgkmcnt(8)
	v_mfma_f32_32x32x16_bf16 v[96:111], v[128:131], v[242:245], v[96:111]
	ds_read_b64_tr_b16 v[128:129], v219 offset:16640
	ds_read_b64_tr_b16 v[130:131], v219 offset:20736
	v_exp_f32_e32 v231, v231
	v_sub_f32_e32 v232, v232, v190
	v_add_f32_e32 v254, v230, v254
	v_exp_f32_e32 v232, v232
	v_sub_f32_e32 v233, v233, v190
	s_waitcnt lgkmcnt(8)
	v_mfma_f32_32x32x16_bf16 v[80:95], v[206:209], v[242:245], v[80:95]
	ds_read_b64_tr_b16 v[206:207], v221 offset:16640
	ds_read_b64_tr_b16 v[208:209], v221 offset:20736
	v_add_f32_e32 v254, v231, v254
	v_exp_f32_e32 v233, v233
	v_sub_f32_e32 v234, v234, v190
	v_add_f32_e32 v254, v232, v254
	s_waitcnt lgkmcnt(8)
	v_mfma_f32_32x32x16_bf16 v[64:79], v[210:213], v[242:245], v[64:79]
	ds_read_b64_tr_b16 v[210:211], v205 offset:24576
	ds_read_b64_tr_b16 v[212:213], v205 offset:28672
	v_exp_f32_e32 v234, v234
	v_sub_f32_e32 v235, v235, v190
	v_add_f32_e32 v254, v233, v254
	v_exp_f32_e32 v235, v235
	s_waitcnt lgkmcnt(8)
	v_mfma_f32_32x32x16_bf16 v[48:63], v[214:217], v[242:245], v[48:63]
	ds_read_b64_tr_b16 v[214:215], v218 offset:24576
	ds_read_b64_tr_b16 v[216:217], v218 offset:28672
	v_sub_f32_e32 v236, v236, v190
	v_add_f32_e32 v254, v234, v254
	v_exp_f32_e32 v236, v236
	v_sub_f32_e32 v237, v237, v190
	s_waitcnt lgkmcnt(8)
	v_mfma_f32_32x32x16_bf16 v[32:47], v[238:241], v[242:245], v[32:47]
	ds_read_b64_tr_b16 v[238:239], v219 offset:24576
	ds_read_b64_tr_b16 v[240:241], v219 offset:28672
	v_add_f32_e32 v254, v235, v254
	v_exp_f32_e32 v237, v237
	v_add_f32_e32 v254, v236, v254
	v_add_f32_e32 v254, v237, v254
	s_waitcnt lgkmcnt(8)
	v_mfma_f32_32x32x16_bf16 v[16:31], v[128:131], v[242:245], v[16:31]
	ds_read_b64_tr_b16 v[128:129], v221 offset:24576
	ds_read_b64_tr_b16 v[130:131], v221 offset:28672
	v_cvt_pk_bf16_f32 v250, v230, v231
	v_cvt_pk_bf16_f32 v251, v232, v233
	v_cvt_pk_bf16_f32 v252, v234, v235
	v_cvt_pk_bf16_f32 v253, v236, v237
	v_add_f32_e32 v202, v202, v254
	s_waitcnt lgkmcnt(8)
	v_mfma_f32_32x32x16_bf16 v[0:15], v[206:209], v[242:245], v[0:15]
	ds_read_b64_tr_b16 v[206:207], v205 offset:24832
	ds_read_b64_tr_b16 v[208:209], v205 offset:28928
	s_waitcnt lgkmcnt(8)
	v_mfma_f32_32x32x16_bf16 v[112:127], v[210:213], v[250:253], v[112:127]
	ds_read_b64_tr_b16 v[210:211], v218 offset:24832
	ds_read_b64_tr_b16 v[212:213], v218 offset:28928
	s_waitcnt lgkmcnt(8)
	v_mfma_f32_32x32x16_bf16 v[96:111], v[214:217], v[250:253], v[96:111]
	ds_read_b64_tr_b16 v[214:215], v219 offset:24832
	ds_read_b64_tr_b16 v[216:217], v219 offset:28928
	s_waitcnt lgkmcnt(8)
	v_mfma_f32_32x32x16_bf16 v[80:95], v[238:241], v[250:253], v[80:95]
	ds_read_b64_tr_b16 v[238:239], v221 offset:24832
	ds_read_b64_tr_b16 v[240:241], v221 offset:28928
	s_waitcnt lgkmcnt(8)
	v_mfma_f32_32x32x16_bf16 v[64:79], v[128:131], v[250:253], v[64:79]
	s_waitcnt lgkmcnt(6)
	v_mfma_f32_32x32x16_bf16 v[48:63], v[206:209], v[250:253], v[48:63]
	s_waitcnt lgkmcnt(4)
	v_mfma_f32_32x32x16_bf16 v[32:47], v[210:213], v[250:253], v[32:47]
	s_waitcnt lgkmcnt(2)
	v_mfma_f32_32x32x16_bf16 v[16:31], v[214:217], v[250:253], v[16:31]
	s_waitcnt lgkmcnt(0)
	v_mfma_f32_32x32x16_bf16 v[0:15], v[238:241], v[250:253], v[0:15]
	ds_read_b128 v[206:209], v194 offset:32768
	ds_read_b128 v[210:213], v195 offset:32768
	ds_read_b128 v[214:217], v196 offset:32768
	ds_read_b128 v[238:241], v197 offset:32768
	ds_read_b128 v[242:245], v198 offset:32768
	ds_read_b128 v[250:253], v199 offset:32768
	ds_read_b128 v[222:225], v200 offset:32768
	ds_read_b128 v[226:229], v201 offset:32768
	s_branch .Latt_end_0
.Latt_rs1_0s1:
	s_waitcnt lgkmcnt(8)
	v_mfma_f32_32x32x16_bf16 v[64:79], v[238:241], v[250:253], v[64:79]
	ds_read_b64_tr_b16 v[238:239], v205 offset:16384
	ds_read_b64_tr_b16 v[240:241], v205 offset:20480
	s_waitcnt lgkmcnt(8)
	v_mfma_f32_32x32x16_bf16 v[48:63], v[128:131], v[250:253], v[48:63]
	ds_read_b64_tr_b16 v[128:129], v218 offset:16384
	ds_read_b64_tr_b16 v[130:131], v218 offset:20480
	s_waitcnt lgkmcnt(8)
	v_mfma_f32_32x32x16_bf16 v[32:47], v[206:209], v[250:253], v[32:47]
	ds_read_b64_tr_b16 v[206:207], v219 offset:16384
	ds_read_b64_tr_b16 v[208:209], v219 offset:20480
	s_waitcnt lgkmcnt(8)
	v_mfma_f32_32x32x16_bf16 v[16:31], v[210:213], v[250:253], v[16:31]
	ds_read_b64_tr_b16 v[210:211], v221 offset:16384
	ds_read_b64_tr_b16 v[212:213], v221 offset:20480
	s_waitcnt lgkmcnt(8)
	v_mfma_f32_32x32x16_bf16 v[0:15], v[214:217], v[250:253], v[0:15]
	ds_read_b64_tr_b16 v[214:215], v205 offset:16640
	ds_read_b64_tr_b16 v[216:217], v205 offset:20736
	s_nop 11
	v_max_f32_e32 v246, v190, v246
	v_sub_f32_e32 v190, v190, v246
	v_exp_f32_e32 v190, v190
	s_nop 0
	v_pk_mul_f32 v[126:127], v[126:127], v[190:191] op_sel_hi:[1,0]
	v_pk_mul_f32 v[124:125], v[124:125], v[190:191] op_sel_hi:[1,0]
	v_pk_mul_f32 v[122:123], v[122:123], v[190:191] op_sel_hi:[1,0]
	v_pk_mul_f32 v[120:121], v[120:121], v[190:191] op_sel_hi:[1,0]
	v_pk_mul_f32 v[118:119], v[118:119], v[190:191] op_sel_hi:[1,0]
	v_pk_mul_f32 v[116:117], v[116:117], v[190:191] op_sel_hi:[1,0]
	v_pk_mul_f32 v[114:115], v[114:115], v[190:191] op_sel_hi:[1,0]
	v_pk_mul_f32 v[112:113], v[112:113], v[190:191] op_sel_hi:[1,0]
	v_pk_mul_f32 v[110:111], v[110:111], v[190:191] op_sel_hi:[1,0]
	v_pk_mul_f32 v[108:109], v[108:109], v[190:191] op_sel_hi:[1,0]
	v_pk_mul_f32 v[106:107], v[106:107], v[190:191] op_sel_hi:[1,0]
	v_pk_mul_f32 v[104:105], v[104:105], v[190:191] op_sel_hi:[1,0]
	v_pk_mul_f32 v[102:103], v[102:103], v[190:191] op_sel_hi:[1,0]
	v_pk_mul_f32 v[100:101], v[100:101], v[190:191] op_sel_hi:[1,0]
	v_pk_mul_f32 v[98:99], v[98:99], v[190:191] op_sel_hi:[1,0]
	v_pk_mul_f32 v[96:97], v[96:97], v[190:191] op_sel_hi:[1,0]
	v_pk_mul_f32 v[94:95], v[94:95], v[190:191] op_sel_hi:[1,0]
	v_pk_mul_f32 v[92:93], v[92:93], v[190:191] op_sel_hi:[1,0]
	v_pk_mul_f32 v[90:91], v[90:91], v[190:191] op_sel_hi:[1,0]
	v_pk_mul_f32 v[88:89], v[88:89], v[190:191] op_sel_hi:[1,0]
	v_pk_mul_f32 v[86:87], v[86:87], v[190:191] op_sel_hi:[1,0]
	v_pk_mul_f32 v[84:85], v[84:85], v[190:191] op_sel_hi:[1,0]
	v_pk_mul_f32 v[82:83], v[82:83], v[190:191] op_sel_hi:[1,0]
	v_pk_mul_f32 v[80:81], v[80:81], v[190:191] op_sel_hi:[1,0]
	v_pk_mul_f32 v[78:79], v[78:79], v[190:191] op_sel_hi:[1,0]
	v_pk_mul_f32 v[76:77], v[76:77], v[190:191] op_sel_hi:[1,0]
	v_pk_mul_f32 v[74:75], v[74:75], v[190:191] op_sel_hi:[1,0]
	v_pk_mul_f32 v[72:73], v[72:73], v[190:191] op_sel_hi:[1,0]
	v_pk_mul_f32 v[70:71], v[70:71], v[190:191] op_sel_hi:[1,0]
	v_pk_mul_f32 v[68:69], v[68:69], v[190:191] op_sel_hi:[1,0]
	v_pk_mul_f32 v[66:67], v[66:67], v[190:191] op_sel_hi:[1,0]
	v_pk_mul_f32 v[64:65], v[64:65], v[190:191] op_sel_hi:[1,0]
	v_pk_mul_f32 v[62:63], v[62:63], v[190:191] op_sel_hi:[1,0]
	v_pk_mul_f32 v[60:61], v[60:61], v[190:191] op_sel_hi:[1,0]
	v_pk_mul_f32 v[58:59], v[58:59], v[190:191] op_sel_hi:[1,0]
	v_pk_mul_f32 v[56:57], v[56:57], v[190:191] op_sel_hi:[1,0]
	v_pk_mul_f32 v[54:55], v[54:55], v[190:191] op_sel_hi:[1,0]
	v_pk_mul_f32 v[52:53], v[52:53], v[190:191] op_sel_hi:[1,0]
	v_pk_mul_f32 v[50:51], v[50:51], v[190:191] op_sel_hi:[1,0]
	v_pk_mul_f32 v[48:49], v[48:49], v[190:191] op_sel_hi:[1,0]
	v_pk_mul_f32 v[46:47], v[46:47], v[190:191] op_sel_hi:[1,0]
	v_pk_mul_f32 v[44:45], v[44:45], v[190:191] op_sel_hi:[1,0]
	v_pk_mul_f32 v[42:43], v[42:43], v[190:191] op_sel_hi:[1,0]
	v_pk_mul_f32 v[40:41], v[40:41], v[190:191] op_sel_hi:[1,0]
	v_pk_mul_f32 v[38:39], v[38:39], v[190:191] op_sel_hi:[1,0]
	v_pk_mul_f32 v[36:37], v[36:37], v[190:191] op_sel_hi:[1,0]
	v_pk_mul_f32 v[34:35], v[34:35], v[190:191] op_sel_hi:[1,0]
	v_pk_mul_f32 v[32:33], v[32:33], v[190:191] op_sel_hi:[1,0]
	v_pk_mul_f32 v[30:31], v[30:31], v[190:191] op_sel_hi:[1,0]
	v_pk_mul_f32 v[28:29], v[28:29], v[190:191] op_sel_hi:[1,0]
	v_pk_mul_f32 v[26:27], v[26:27], v[190:191] op_sel_hi:[1,0]
	v_pk_mul_f32 v[24:25], v[24:25], v[190:191] op_sel_hi:[1,0]
	v_pk_mul_f32 v[22:23], v[22:23], v[190:191] op_sel_hi:[1,0]
	v_pk_mul_f32 v[20:21], v[20:21], v[190:191] op_sel_hi:[1,0]
	v_pk_mul_f32 v[18:19], v[18:19], v[190:191] op_sel_hi:[1,0]
	v_pk_mul_f32 v[16:17], v[16:17], v[190:191] op_sel_hi:[1,0]
	v_pk_mul_f32 v[14:15], v[14:15], v[190:191] op_sel_hi:[1,0]
	v_pk_mul_f32 v[12:13], v[12:13], v[190:191] op_sel_hi:[1,0]
	v_pk_mul_f32 v[10:11], v[10:11], v[190:191] op_sel_hi:[1,0]
	v_pk_mul_f32 v[8:9], v[8:9], v[190:191] op_sel_hi:[1,0]
	v_pk_mul_f32 v[6:7], v[6:7], v[190:191] op_sel_hi:[1,0]
	v_pk_mul_f32 v[4:5], v[4:5], v[190:191] op_sel_hi:[1,0]
	v_pk_mul_f32 v[2:3], v[2:3], v[190:191] op_sel_hi:[1,0]
	v_pk_mul_f32 v[0:1], v[0:1], v[190:191] op_sel_hi:[1,0]
	v_mul_f32_e32 v202, v202, v190
	v_mov_b32_e32 v190, v246
	v_sub_f32_e32 v222, v222, v190
	v_exp_f32_e32 v222, v222
	v_sub_f32_e32 v223, v223, v190
	v_exp_f32_e32 v223, v223
	v_sub_f32_e32 v224, v224, v190
	v_add_f32_e32 v254, 0, v222
	v_exp_f32_e32 v224, v224
	v_sub_f32_e32 v225, v225, v190
	v_add_f32_e32 v254, v223, v254
	v_exp_f32_e32 v225, v225
	v_sub_f32_e32 v226, v226, v190
	v_add_f32_e32 v254, v224, v254
	v_exp_f32_e32 v226, v226
	v_sub_f32_e32 v227, v227, v190
	v_add_f32_e32 v254, v225, v254
	v_exp_f32_e32 v227, v227
	v_sub_f32_e32 v228, v228, v190
	v_add_f32_e32 v254, v226, v254
	v_exp_f32_e32 v228, v228
	v_sub_f32_e32 v229, v229, v190
	v_add_f32_e32 v254, v227, v254
	v_exp_f32_e32 v229, v229
	v_sub_f32_e32 v230, v230, v190
	v_add_f32_e32 v254, v228, v254
	v_exp_f32_e32 v230, v230
	v_sub_f32_e32 v231, v231, v190
	v_add_f32_e32 v254, v229, v254
	v_exp_f32_e32 v231, v231
	v_sub_f32_e32 v232, v232, v190
	v_add_f32_e32 v254, v230, v254
	v_exp_f32_e32 v232, v232
	v_sub_f32_e32 v233, v233, v190
	v_add_f32_e32 v254, v231, v254
	v_exp_f32_e32 v233, v233
	v_sub_f32_e32 v234, v234, v190
	v_add_f32_e32 v254, v232, v254
	v_exp_f32_e32 v234, v234
	v_sub_f32_e32 v235, v235, v190
	v_add_f32_e32 v254, v233, v254
	v_exp_f32_e32 v235, v235
	v_sub_f32_e32 v236, v236, v190
	v_add_f32_e32 v254, v234, v254
	v_exp_f32_e32 v236, v236
	v_sub_f32_e32 v237, v237, v190
	v_add_f32_e32 v254, v235, v254
	v_exp_f32_e32 v237, v237
	v_add_f32_e32 v254, v236, v254
	v_add_f32_e32 v254, v237, v254
	v_cvt_pk_bf16_f32 v242, v222, v223
	v_cvt_pk_bf16_f32 v243, v224, v225
	v_cvt_pk_bf16_f32 v244, v226, v227
	v_cvt_pk_bf16_f32 v245, v228, v229
	v_cvt_pk_bf16_f32 v250, v230, v231
	v_cvt_pk_bf16_f32 v251, v232, v233
	v_cvt_pk_bf16_f32 v252, v234, v235
	v_cvt_pk_bf16_f32 v253, v236, v237
	v_add_f32_e32 v202, v202, v254
	s_nop 1
	s_waitcnt lgkmcnt(8)
	v_mfma_f32_32x32x16_bf16 v[112:127], v[238:241], v[242:245], v[112:127]
	ds_read_b64_tr_b16 v[238:239], v218 offset:16640
	ds_read_b64_tr_b16 v[240:241], v218 offset:20736
	s_waitcnt lgkmcnt(8)
	v_mfma_f32_32x32x16_bf16 v[96:111], v[128:131], v[242:245], v[96:111]
	ds_read_b64_tr_b16 v[222:223], v219 offset:16640
	ds_read_b64_tr_b16 v[224:225], v219 offset:20736
	s_waitcnt lgkmcnt(8)
	v_mfma_f32_32x32x16_bf16 v[80:95], v[206:209], v[242:245], v[80:95]
	ds_read_b64_tr_b16 v[206:207], v221 offset:16640
	ds_read_b64_tr_b16 v[208:209], v221 offset:20736
	s_waitcnt lgkmcnt(8)
	v_mfma_f32_32x32x16_bf16 v[64:79], v[210:213], v[242:245], v[64:79]
	ds_read_b64_tr_b16 v[210:211], v205 offset:24576
	ds_read_b64_tr_b16 v[212:213], v205 offset:28672
	s_waitcnt lgkmcnt(8)
	v_mfma_f32_32x32x16_bf16 v[48:63], v[214:217], v[242:245], v[48:63]
	ds_read_b64_tr_b16 v[214:215], v218 offset:24576
	ds_read_b64_tr_b16 v[216:217], v218 offset:28672
	s_waitcnt lgkmcnt(8)
	v_mfma_f32_32x32x16_bf16 v[32:47], v[238:241], v[242:245], v[32:47]
	ds_read_b64_tr_b16 v[238:239], v219 offset:24576
	ds_read_b64_tr_b16 v[240:241], v219 offset:28672
	s_waitcnt lgkmcnt(8)
	v_mfma_f32_32x32x16_bf16 v[16:31], v[222:225], v[242:245], v[16:31]
	ds_read_b64_tr_b16 v[222:223], v221 offset:24576
	ds_read_b64_tr_b16 v[224:225], v221 offset:28672
	s_waitcnt lgkmcnt(8)
	v_mfma_f32_32x32x16_bf16 v[0:15], v[206:209], v[242:245], v[0:15]
	ds_read_b64_tr_b16 v[206:207], v205 offset:24832
	ds_read_b64_tr_b16 v[208:209], v205 offset:28928
	s_waitcnt lgkmcnt(8)
	v_mfma_f32_32x32x16_bf16 v[112:127], v[210:213], v[250:253], v[112:127]
	ds_read_b64_tr_b16 v[210:211], v218 offset:24832
	ds_read_b64_tr_b16 v[212:213], v218 offset:28928
	s_waitcnt lgkmcnt(8)
	v_mfma_f32_32x32x16_bf16 v[96:111], v[214:217], v[250:253], v[96:111]
	ds_read_b64_tr_b16 v[214:215], v219 offset:24832
	ds_read_b64_tr_b16 v[216:217], v219 offset:28928
	s_waitcnt lgkmcnt(8)
	v_mfma_f32_32x32x16_bf16 v[80:95], v[238:241], v[250:253], v[80:95]
	ds_read_b64_tr_b16 v[238:239], v221 offset:24832
	ds_read_b64_tr_b16 v[240:241], v221 offset:28928
	s_waitcnt lgkmcnt(8)
	v_mfma_f32_32x32x16_bf16 v[64:79], v[222:225], v[250:253], v[64:79]
	s_waitcnt lgkmcnt(6)
	v_mfma_f32_32x32x16_bf16 v[48:63], v[206:209], v[250:253], v[48:63]
	s_waitcnt lgkmcnt(4)
	v_mfma_f32_32x32x16_bf16 v[32:47], v[210:213], v[250:253], v[32:47]
	s_waitcnt lgkmcnt(2)
	v_mfma_f32_32x32x16_bf16 v[16:31], v[214:217], v[250:253], v[16:31]
	s_waitcnt lgkmcnt(0)
	v_mfma_f32_32x32x16_bf16 v[0:15], v[238:241], v[250:253], v[0:15]
	ds_read_b128 v[206:209], v194 offset:32768
	ds_read_b128 v[210:213], v195 offset:32768
	ds_read_b128 v[214:217], v196 offset:32768
	ds_read_b128 v[238:241], v197 offset:32768
	ds_read_b128 v[242:245], v198 offset:32768
	ds_read_b128 v[250:253], v199 offset:32768
	ds_read_b128 v[222:225], v200 offset:32768
	ds_read_b128 v[226:229], v201 offset:32768
	s_branch .Latt_end_0
.Latt_slow_0s1:
.Latt_slot2_0:
	v_add_u32_e32 v205, 0x8000, v205
	v_add_u32_e32 v218, 0x8000, v218
	v_add_u32_e32 v219, 0x8000, v219
	v_add_u32_e32 v221, 0x8000, v221
	s_waitcnt lgkmcnt(7)
	v_mfma_f32_32x32x16_bf16 v[128:143], v[206:209], v[144:147], 0
	ds_read_b128 v[206:209], v194 offset:40960
	s_cmp_lg_u64 s[18:19], 0
	s_cbranch_scc1 .Latt_nd0_0s2
	s_sub_i32 s100, s88, 1
	s_cmp_eq_u32 s88, 0
	s_cselect_b32 s100, 2, s100
	s_lshl_b32 s101, s100, 14
	s_add_i32 m0, s85, s101
	s_nop 0
	global_load_lds_dwordx4 v178, s[14:15]
.Latt_nd0_0s2:
	s_waitcnt lgkmcnt(7)
	v_mfma_f32_32x32x16_bf16 v[128:143], v[210:213], v[148:151], v[128:143]
	ds_read_b128 v[210:213], v195 offset:40960
	s_cmp_lg_u64 s[18:19], 0
	s_cbranch_scc1 .Latt_nd1_0s2
	s_add_i32 m0, m0, 0x400
	s_nop 0
	global_load_lds_dwordx4 v180, s[14:15]
.Latt_nd1_0s2:
	s_waitcnt lgkmcnt(7)
	v_mfma_f32_32x32x16_bf16 v[128:143], v[214:217], v[152:155], v[128:143]
	ds_read_b128 v[214:217], v196 offset:40960
	s_cmp_lg_u64 s[18:19], 0
	s_cbranch_scc1 .Latt_nd2_0s2
	s_lshl_b32 s101, s100, 15
	s_add_i32 m0, s86, s101
	s_add_u32 s100, s14, 0x1000
	s_addc_u32 s101, s15, 0
	global_load_lds_dwordx4 v182, s[100:101]
.Latt_nd2_0s2:
	s_waitcnt lgkmcnt(7)
	v_mfma_f32_32x32x16_bf16 v[128:143], v[238:241], v[156:159], v[128:143]
	ds_read_b128 v[238:241], v197 offset:40960
	s_cmp_lg_u64 s[18:19], 0
	s_cbranch_scc1 .Latt_nd3_0s2
	s_add_i32 m0, m0, 0x400
	s_nop 0
	global_load_lds_dwordx4 v184, s[100:101]

.Latt_nd5_0s2:
	s_waitcnt lgkmcnt(5)
	v_mfma_f32_32x32x16_bf16 v[128:143], v[222:225], v[168:171], v[128:143]
	s_waitcnt lgkmcnt(4)
	v_mfma_f32_32x32x16_bf16 v[128:143], v[226:229], v[172:175], v[128:143]
	s_waitcnt lgkmcnt(3)
	v_mfma_f32_32x32x16_bf16 v[222:237], v[206:209], v[144:147], 0
	ds_read_b128 v[206:209], v198 offset:40960
	s_nop 8
	v_max3_f32 v246, v128, v129, v130
	v_max3_f32 v247, v131, v132, v133
	v_max3_f32 v246, v246, v134, v135
	v_max3_f32 v247, v247, v136, v137
	v_max3_f32 v246, v246, v138, v139
	v_max3_f32 v247, v247, v140, v141
	v_max3_f32 v246, v246, v142, v143
	s_waitcnt lgkmcnt(3)
	v_mfma_f32_32x32x16_bf16 v[222:237], v[210:213], v[148:151], v[222:237]
	ds_read_b128 v[210:213], v199 offset:40960
	v_max_f32_e32 v246, v246, v247
	v_mov_b32_e32 v247, v246
	v_add_f32_e32 v249, 0x41000000, v190
	s_nop 1
	v_permlane32_swap_b32_e32 v246, v247
	v_max_f32_e32 v246, v246, v247
	v_cmp_gt_f32_e32 vcc, v246, v249
	s_cbranch_vccz .Latt_nr0_0s2
	v_max_f32_e32 v246, v190, v246
	v_sub_f32_e32 v190, v190, v246
	v_exp_f32_e32 v190, v190
	s_nop 0
	v_pk_mul_f32 v[126:127], v[126:127], v[190:191] op_sel_hi:[1,0]
	v_pk_mul_f32 v[124:125], v[124:125], v[190:191] op_sel_hi:[1,0]
	v_pk_mul_f32 v[122:123], v[122:123], v[190:191] op_sel_hi:[1,0]
	v_pk_mul_f32 v[120:121], v[120:121], v[190:191] op_sel_hi:[1,0]
	v_pk_mul_f32 v[118:119], v[118:119], v[190:191] op_sel_hi:[1,0]
	v_pk_mul_f32 v[116:117], v[116:117], v[190:191] op_sel_hi:[1,0]
	v_pk_mul_f32 v[114:115], v[114:115], v[190:191] op_sel_hi:[1,0]
	v_pk_mul_f32 v[112:113], v[112:113], v[190:191] op_sel_hi:[1,0]
	v_pk_mul_f32 v[110:111], v[110:111], v[190:191] op_sel_hi:[1,0]
	v_pk_mul_f32 v[108:109], v[108:109], v[190:191] op_sel_hi:[1,0]
	v_pk_mul_f32 v[106:107], v[106:107], v[190:191] op_sel_hi:[1,0]
	v_pk_mul_f32 v[104:105], v[104:105], v[190:191] op_sel_hi:[1,0]
	v_pk_mul_f32 v[102:103], v[102:103], v[190:191] op_sel_hi:[1,0]
	v_pk_mul_f32 v[100:101], v[100:101], v[190:191] op_sel_hi:[1,0]
	v_pk_mul_f32 v[98:99], v[98:99], v[190:191] op_sel_hi:[1,0]
	v_pk_mul_f32 v[96:97], v[96:97], v[190:191] op_sel_hi:[1,0]
	v_pk_mul_f32 v[94:95], v[94:95], v[190:191] op_sel_hi:[1,0]
	v_pk_mul_f32 v[92:93], v[92:93], v[190:191] op_sel_hi:[1,0]
	v_pk_mul_f32 v[90:91], v[90:91], v[190:191] op_sel_hi:[1,0]
	v_pk_mul_f32 v[88:89], v[88:89], v[190:191] op_sel_hi:[1,0]
	v_pk_mul_f32 v[86:87], v[86:87], v[190:191] op_sel_hi:[1,0]
	v_pk_mul_f32 v[84:85], v[84:85], v[190:191] op_sel_hi:[1,0]
	v_pk_mul_f32 v[82:83], v[82:83], v[190:191] op_sel_hi:[1,0]
	v_pk_mul_f32 v[80:81], v[80:81], v[190:191] op_sel_hi:[1,0]
	v_pk_mul_f32 v[78:79], v[78:79], v[190:191] op_sel_hi:[1,0]
	v_pk_mul_f32 v[76:77], v[76:77], v[190:191] op_sel_hi:[1,0]
	v_pk_mul_f32 v[74:75], v[74:75], v[190:191] op_sel_hi:[1,0]
	v_pk_mul_f32 v[72:73], v[72:73], v[190:191] op_sel_hi:[1,0]
	v_pk_mul_f32 v[70:71], v[70:71], v[190:191] op_sel_hi:[1,0]
	v_pk_mul_f32 v[68:69], v[68:69], v[190:191] op_sel_hi:[1,0]
	v_pk_mul_f32 v[66:67], v[66:67], v[190:191] op_sel_hi:[1,0]
	v_pk_mul_f32 v[64:65], v[64:65], v[190:191] op_sel_hi:[1,0]
	v_pk_mul_f32 v[62:63], v[62:63], v[190:191] op_sel_hi:[1,0]
	v_pk_mul_f32 v[60:61], v[60:61], v[190:191] op_sel_hi:[1,0]
	v_pk_mul_f32 v[58:59], v[58:59], v[190:191] op_sel_hi:[1,0]
	v_pk_mul_f32 v[56:57], v[56:57], v[190:191] op_sel_hi:[1,0]
	v_pk_mul_f32 v[54:55], v[54:55], v[190:191] op_sel_hi:[1,0]
	v_pk_mul_f32 v[52:53], v[52:53], v[190:191] op_sel_hi:[1,0]
	v_pk_mul_f32 v[50:51], v[50:51], v[190:191] op_sel_hi:[1,0]
	v_pk_mul_f32 v[48:49], v[48:49], v[190:191] op_sel_hi:[1,0]
	v_pk_mul_f32 v[46:47], v[46:47], v[190:191] op_sel_hi:[1,0]
	v_pk_mul_f32 v[44:45], v[44:45], v[190:191] op_sel_hi:[1,0]
	v_pk_mul_f32 v[42:43], v[42:43], v[190:191] op_sel_hi:[1,0]
	v_pk_mul_f32 v[40:41], v[40:41], v[190:191] op_sel_hi:[1,0]
	v_pk_mul_f32 v[38:39], v[38:39], v[190:191] op_sel_hi:[1,0]
	v_pk_mul_f32 v[36:37], v[36:37], v[190:191] op_sel_hi:[1,0]
	v_pk_mul_f32 v[34:35], v[34:35], v[190:191] op_sel_hi:[1,0]
	v_pk_mul_f32 v[32:33], v[32:33], v[190:191] op_sel_hi:[1,0]
	v_pk_mul_f32 v[30:31], v[30:31], v[190:191] op_sel_hi:[1,0]
	v_pk_mul_f32 v[28:29], v[28:29], v[190:191] op_sel_hi:[1,0]
	v_pk_mul_f32 v[26:27], v[26:27], v[190:191] op_sel_hi:[1,0]
	v_pk_mul_f32 v[24:25], v[24:25], v[190:191] op_sel_hi:[1,0]
	v_pk_mul_f32 v[22:23], v[22:23], v[190:191] op_sel_hi:[1,0]
	v_pk_mul_f32 v[20:21], v[20:21], v[190:191] op_sel_hi:[1,0]
	v_pk_mul_f32 v[18:19], v[18:19], v[190:191] op_sel_hi:[1,0]
	v_pk_mul_f32 v[16:17], v[16:17], v[190:191] op_sel_hi:[1,0]
	v_pk_mul_f32 v[14:15], v[14:15], v[190:191] op_sel_hi:[1,0]
	v_pk_mul_f32 v[12:13], v[12:13], v[190:191] op_sel_hi:[1,0]
	v_pk_mul_f32 v[10:11], v[10:11], v[190:191] op_sel_hi:[1,0]
	v_pk_mul_f32 v[8:9], v[8:9], v[190:191] op_sel_hi:[1,0]
	v_pk_mul_f32 v[6:7], v[6:7], v[190:191] op_sel_hi:[1,0]
	v_pk_mul_f32 v[4:5], v[4:5], v[190:191] op_sel_hi:[1,0]
	v_pk_mul_f32 v[2:3], v[2:3], v[190:191] op_sel_hi:[1,0]
	v_pk_mul_f32 v[0:1], v[0:1], v[190:191] op_sel_hi:[1,0]
	v_mul_f32_e32 v202, v202, v190
	v_mov_b32_e32 v190, v246
.Latt_nr0_0s2:
	s_waitcnt lgkmcnt(3)
	v_mfma_f32_32x32x16_bf16 v[222:237], v[214:217], v[152:155], v[222:237]
	ds_read_b128 v[214:217], v200 offset:40960
	v_sub_f32_e32 v128, v128, v190
	v_exp_f32_e32 v128, v128
	v_sub_f32_e32 v129, v129, v190
	v_exp_f32_e32 v129, v129
	v_sub_f32_e32 v130, v130, v190
	s_waitcnt lgkmcnt(3)
	v_mfma_f32_32x32x16_bf16 v[222:237], v[238:241], v[156:159], v[222:237]
	ds_read_b128 v[238:241], v201 offset:40960
	v_add_f32_e32 v254, 0, v128
	v_exp_f32_e32 v130, v130
	v_sub_f32_e32 v131, v131, v190
	v_add_f32_e32 v254, v129, v254
	v_exp_f32_e32 v131, v131
	s_waitcnt lgkmcnt(3)
	v_mfma_f32_32x32x16_bf16 v[222:237], v[206:209], v[160:163], v[222:237]
	ds_read_b64_tr_b16 v[206:207], v205
	ds_read_b64_tr_b16 v[208:209], v205 offset:4096
	v_sub_f32_e32 v132, v132, v190
	v_add_f32_e32 v254, v130, v254
	v_exp_f32_e32 v132, v132
	v_sub_f32_e32 v133, v133, v190
	v_add_f32_e32 v254, v131, v254
	s_waitcnt lgkmcnt(4)
	v_mfma_f32_32x32x16_bf16 v[222:237], v[210:213], v[164:167], v[222:237]
	ds_read_b64_tr_b16 v[210:211], v218
	ds_read_b64_tr_b16 v[212:213], v218 offset:4096
	v_exp_f32_e32 v133, v133
	v_sub_f32_e32 v134, v134, v190
	v_add_f32_e32 v254, v132, v254
	v_exp_f32_e32 v134, v134
	s_waitcnt lgkmcnt(5)
	v_mfma_f32_32x32x16_bf16 v[222:237], v[214:217], v[168:171], v[222:237]
	ds_read_b64_tr_b16 v[214:215], v219
	ds_read_b64_tr_b16 v[216:217], v219 offset:4096
	v_sub_f32_e32 v135, v135, v190
	v_add_f32_e32 v254, v133, v254
	v_exp_f32_e32 v135, v135
	s_nop 0
	s_waitcnt lgkmcnt(6)
	v_mfma_f32_32x32x16_bf16 v[222:237], v[238:241], v[172:175], v[222:237]
	ds_read_b64_tr_b16 v[238:239], v221
	ds_read_b64_tr_b16 v[240:241], v221 offset:4096
	v_cvt_pk_bf16_f32 v242, v128, v129
	v_cvt_pk_bf16_f32 v243, v130, v131
	v_cvt_pk_bf16_f32 v244, v132, v133
	v_cvt_pk_bf16_f32 v245, v134, v135
	s_nop 1
	s_waitcnt lgkmcnt(6)
	v_mfma_f32_32x32x16_bf16 v[112:127], v[206:209], v[242:245], v[112:127]
	ds_read_b64_tr_b16 v[206:207], v205 offset:256
	ds_read_b64_tr_b16 v[208:209], v205 offset:4352
	v_sub_f32_e32 v136, v136, v190
	v_add_f32_e32 v254, v134, v254
	v_exp_f32_e32 v136, v136
	v_sub_f32_e32 v137, v137, v190
	v_add_f32_e32 v254, v135, v254
	s_waitcnt lgkmcnt(6)
	v_mfma_f32_32x32x16_bf16 v[96:111], v[210:213], v[242:245], v[96:111]
	ds_read_b64_tr_b16 v[210:211], v218 offset:256
	ds_read_b64_tr_b16 v[212:213], v218 offset:4352
	v_exp_f32_e32 v137, v137
	v_sub_f32_e32 v138, v138, v190
	v_add_f32_e32 v254, v136, v254
	v_exp_f32_e32 v138, v138
	v_sub_f32_e32 v139, v139, v190
	s_waitcnt lgkmcnt(6)
	v_mfma_f32_32x32x16_bf16 v[80:95], v[214:217], v[242:245], v[80:95]
	ds_read_b64_tr_b16 v[214:215], v219 offset:256
	ds_read_b64_tr_b16 v[216:217], v219 offset:4352
	v_add_f32_e32 v254, v137, v254
	v_exp_f32_e32 v139, v139
	v_sub_f32_e32 v140, v140, v190
	v_add_f32_e32 v254, v138, v254
	s_waitcnt lgkmcnt(6)
	v_mfma_f32_32x32x16_bf16 v[64:79], v[238:241], v[242:245], v[64:79]
	ds_read_b64_tr_b16 v[238:239], v221 offset:256
	ds_read_b64_tr_b16 v[240:241], v221 offset:4352
	v_exp_f32_e32 v140, v140
	v_sub_f32_e32 v141, v141, v190
	v_add_f32_e32 v254, v139, v254
	v_exp_f32_e32 v141, v141
	s_waitcnt lgkmcnt(6)
	v_mfma_f32_32x32x16_bf16 v[48:63], v[206:209], v[242:245], v[48:63]
	ds_read_b64_tr_b16 v[206:207], v205 offset:8192
	ds_read_b64_tr_b16 v[208:209], v205 offset:12288
	v_sub_f32_e32 v142, v142, v190
	v_add_f32_e32 v254, v140, v254
	v_exp_f32_e32 v142, v142
	v_sub_f32_e32 v143, v143, v190
	s_waitcnt lgkmcnt(6)
	v_mfma_f32_32x32x16_bf16 v[32:47], v[210:213], v[242:245], v[32:47]
	ds_read_b64_tr_b16 v[210:211], v218 offset:8192
	ds_read_b64_tr_b16 v[212:213], v218 offset:12288
	v_add_f32_e32 v254, v141, v254
	v_exp_f32_e32 v143, v143
	v_add_f32_e32 v254, v142, v254
	v_add_f32_e32 v254, v143, v254
	s_waitcnt lgkmcnt(6)
	v_mfma_f32_32x32x16_bf16 v[16:31], v[214:217], v[242:245], v[16:31]
	ds_read_b64_tr_b16 v[214:215], v219 offset:8192
	ds_read_b64_tr_b16 v[216:217], v219 offset:12288
	v_cvt_pk_bf16_f32 v250, v136, v137
	v_cvt_pk_bf16_f32 v251, v138, v139
	v_cvt_pk_bf16_f32 v252, v140, v141
	v_cvt_pk_bf16_f32 v253, v142, v143
	v_add_f32_e32 v202, v202, v254
	s_waitcnt lgkmcnt(6)
	v_mfma_f32_32x32x16_bf16 v[0:15], v[238:241], v[242:245], v[0:15]
	ds_read_b64_tr_b16 v[238:239], v221 offset:8192
	ds_read_b64_tr_b16 v[240:241], v221 offset:12288
	ds_read_b64_tr_b16 v[128:129], v205 offset:8448
	ds_read_b64_tr_b16 v[130:131], v205 offset:12544
	s_waitcnt lgkmcnt(8)
	v_mfma_f32_32x32x16_bf16 v[112:127], v[206:209], v[250:253], v[112:127]
	ds_read_b64_tr_b16 v[206:207], v218 offset:8448
	ds_read_b64_tr_b16 v[208:209], v218 offset:12544
	v_max3_f32 v246, v222, v223, v224
	v_max3_f32 v247, v225, v226, v227
	v_max3_f32 v246, v246, v228, v229
	v_max3_f32 v247, v247, v230, v231
	v_max3_f32 v246, v246, v232, v233
	s_waitcnt lgkmcnt(8)
	v_mfma_f32_32x32x16_bf16 v[96:111], v[210:213], v[250:253], v[96:111]
	ds_read_b64_tr_b16 v[210:211], v219 offset:8448
	ds_read_b64_tr_b16 v[212:213], v219 offset:12544
	v_max3_f32 v247, v247, v234, v235
	v_max3_f32 v246, v246, v236, v237
	v_max_f32_e32 v246, v246, v247
	v_mov_b32_e32 v247, v246
	v_add_f32_e32 v249, 0x41000000, v190
	s_waitcnt lgkmcnt(8)
	v_mfma_f32_32x32x16_bf16 v[80:95], v[214:217], v[250:253], v[80:95]
	ds_read_b64_tr_b16 v[214:215], v221 offset:8448
	ds_read_b64_tr_b16 v[216:217], v221 offset:12544
	s_nop 1
	v_permlane32_swap_b32_e32 v246, v247
	v_max_f32_e32 v246, v246, v247
	v_cmp_gt_f32_e32 vcc, v246, v249
	s_cbranch_vccnz .Latt_rs1_0s2
	s_waitcnt lgkmcnt(8)
	v_mfma_f32_32x32x16_bf16 v[64:79], v[238:241], v[250:253], v[64:79]
	ds_read_b64_tr_b16 v[238:239], v205 offset:16384
	ds_read_b64_tr_b16 v[240:241], v205 offset:20480
	v_sub_f32_e32 v222, v222, v190
	v_exp_f32_e32 v222, v222
	v_sub_f32_e32 v223, v223, v190
	v_exp_f32_e32 v223, v223
	v_sub_f32_e32 v224, v224, v190
	v_add_f32_e32 v254, 0, v222
	s_waitcnt lgkmcnt(8)
	v_mfma_f32_32x32x16_bf16 v[48:63], v[128:131], v[250:253], v[48:63]
	ds_read_b64_tr_b16 v[128:129], v218 offset:16384
	ds_read_b64_tr_b16 v[130:131], v218 offset:20480
	v_exp_f32_e32 v224, v224
	v_sub_f32_e32 v225, v225, v190
	v_add_f32_e32 v254, v223, v254
	v_exp_f32_e32 v225, v225
	v_sub_f32_e32 v226, v226, v190
	v_add_f32_e32 v254, v224, v254
	s_waitcnt lgkmcnt(8)
	v_mfma_f32_32x32x16_bf16 v[32:47], v[206:209], v[250:253], v[32:47]
	ds_read_b64_tr_b16 v[206:207], v219 offset:16384
	ds_read_b64_tr_b16 v[208:209], v219 offset:20480
	v_exp_f32_e32 v226, v226
	v_sub_f32_e32 v227, v227, v190
	v_add_f32_e32 v254, v225, v254
	v_exp_f32_e32 v227, v227
	v_sub_f32_e32 v228, v228, v190
	s_waitcnt lgkmcnt(8)
	v_mfma_f32_32x32x16_bf16 v[16:31], v[210:213], v[250:253], v[16:31]
	ds_read_b64_tr_b16 v[210:211], v221 offset:16384
	ds_read_b64_tr_b16 v[212:213], v221 offset:20480
	v_add_f32_e32 v254, v226, v254
	v_exp_f32_e32 v228, v228
	v_sub_f32_e32 v229, v229, v190
	v_add_f32_e32 v254, v227, v254
	v_exp_f32_e32 v229, v229
	s_waitcnt lgkmcnt(8)
	v_mfma_f32_32x32x16_bf16 v[0:15], v[214:217], v[250:253], v[0:15]
	ds_read_b64_tr_b16 v[214:215], v205 offset:16640
	ds_read_b64_tr_b16 v[216:217], v205 offset:20736
	s_nop 0
	v_cvt_pk_bf16_f32 v242, v222, v223
	v_cvt_pk_bf16_f32 v243, v224, v225
	v_cvt_pk_bf16_f32 v244, v226, v227
	v_cvt_pk_bf16_f32 v245, v228, v229
	s_nop 1
	s_waitcnt lgkmcnt(8)
	v_mfma_f32_32x32x16_bf16 v[112:127], v[238:241], v[242:245], v[112:127]
	ds_read_b64_tr_b16 v[238:239], v218 offset:16640
	ds_read_b64_tr_b16 v[240:241], v218 offset:20736
	v_sub_f32_e32 v230, v230, v190
	v_add_f32_e32 v254, v228, v254
	v_exp_f32_e32 v230, v230
	v_sub_f32_e32 v231, v231, v190
	v_add_f32_e32 v254, v229, v254
	s_waitcnt lgkmcnt(8)
	v_mfma_f32_32x32x16_bf16 v[96:111], v[128:131], v[242:245], v[96:111]
	ds_read_b64_tr_b16 v[128:129], v219 offset:16640
	ds_read_b64_tr_b16 v[130:131], v219 offset:20736
	v_exp_f32_e32 v231, v231
	v_sub_f32_e32 v232, v232, v190
	v_add_f32_e32 v254, v230, v254
	v_exp_f32_e32 v232, v232
	v_sub_f32_e32 v233, v233, v190
	s_waitcnt lgkmcnt(8)
	v_mfma_f32_32x32x16_bf16 v[80:95], v[206:209], v[242:245], v[80:95]
	ds_read_b64_tr_b16 v[206:207], v221 offset:16640
	ds_read_b64_tr_b16 v[208:209], v221 offset:20736
	v_add_f32_e32 v254, v231, v254
	v_exp_f32_e32 v233, v233
	v_sub_f32_e32 v234, v234, v190
	v_add_f32_e32 v254, v232, v254
	s_waitcnt lgkmcnt(8)
	v_mfma_f32_32x32x16_bf16 v[64:79], v[210:213], v[242:245], v[64:79]
	ds_read_b64_tr_b16 v[210:211], v205 offset:24576
	ds_read_b64_tr_b16 v[212:213], v205 offset:28672
	v_exp_f32_e32 v234, v234
	v_sub_f32_e32 v235, v235, v190
	v_add_f32_e32 v254, v233, v254
	v_exp_f32_e32 v235, v235
	s_waitcnt lgkmcnt(8)
	v_mfma_f32_32x32x16_bf16 v[48:63], v[214:217], v[242:245], v[48:63]
	ds_read_b64_tr_b16 v[214:215], v218 offset:24576
	ds_read_b64_tr_b16 v[216:217], v218 offset:28672
	v_sub_f32_e32 v236, v236, v190
	v_add_f32_e32 v254, v234, v254
	v_exp_f32_e32 v236, v236
	v_sub_f32_e32 v237, v237, v190
	s_waitcnt lgkmcnt(8)
	v_mfma_f32_32x32x16_bf16 v[32:47], v[238:241], v[242:245], v[32:47]
	ds_read_b64_tr_b16 v[238:239], v219 offset:24576
	ds_read_b64_tr_b16 v[240:241], v219 offset:28672
	v_add_f32_e32 v254, v235, v254
	v_exp_f32_e32 v237, v237
	v_add_f32_e32 v254, v236, v254
	v_add_f32_e32 v254, v237, v254
	s_waitcnt lgkmcnt(8)
	v_mfma_f32_32x32x16_bf16 v[16:31], v[128:131], v[242:245], v[16:31]
	ds_read_b64_tr_b16 v[128:129], v221 offset:24576
	ds_read_b64_tr_b16 v[130:131], v221 offset:28672
	v_cvt_pk_bf16_f32 v250, v230, v231
	v_cvt_pk_bf16_f32 v251, v232, v233
	v_cvt_pk_bf16_f32 v252, v234, v235
	v_cvt_pk_bf16_f32 v253, v236, v237
	v_add_f32_e32 v202, v202, v254
	s_waitcnt lgkmcnt(8)
	v_mfma_f32_32x32x16_bf16 v[0:15], v[206:209], v[242:245], v[0:15]
	ds_read_b64_tr_b16 v[206:207], v205 offset:24832
	ds_read_b64_tr_b16 v[208:209], v205 offset:28928
	s_waitcnt lgkmcnt(8)
	v_mfma_f32_32x32x16_bf16 v[112:127], v[210:213], v[250:253], v[112:127]
	ds_read_b64_tr_b16 v[210:211], v218 offset:24832
	ds_read_b64_tr_b16 v[212:213], v218 offset:28928
	s_waitcnt lgkmcnt(8)
	v_mfma_f32_32x32x16_bf16 v[96:111], v[214:217], v[250:253], v[96:111]
	ds_read_b64_tr_b16 v[214:215], v219 offset:24832
	ds_read_b64_tr_b16 v[216:217], v219 offset:28928
	s_waitcnt lgkmcnt(8)
	v_mfma_f32_32x32x16_bf16 v[80:95], v[238:241], v[250:253], v[80:95]
	ds_read_b64_tr_b16 v[238:239], v221 offset:24832
	ds_read_b64_tr_b16 v[240:241], v221 offset:28928
	s_waitcnt lgkmcnt(8)
	v_mfma_f32_32x32x16_bf16 v[64:79], v[128:131], v[250:253], v[64:79]
	s_waitcnt lgkmcnt(6)
	v_mfma_f32_32x32x16_bf16 v[48:63], v[206:209], v[250:253], v[48:63]
	s_waitcnt lgkmcnt(4)
	v_mfma_f32_32x32x16_bf16 v[32:47], v[210:213], v[250:253], v[32:47]
	s_waitcnt lgkmcnt(2)
	v_mfma_f32_32x32x16_bf16 v[16:31], v[214:217], v[250:253], v[16:31]
	s_waitcnt lgkmcnt(0)
	v_mfma_f32_32x32x16_bf16 v[0:15], v[238:241], v[250:253], v[0:15]
	ds_read_b128 v[206:209], v194
	ds_read_b128 v[210:213], v195
	ds_read_b128 v[214:217], v196
	ds_read_b128 v[238:241], v197
	ds_read_b128 v[242:245], v198
	ds_read_b128 v[250:253], v199
	ds_read_b128 v[222:225], v200
	ds_read_b128 v[226:229], v201
	s_branch .Latt_end_0
.Latt_rs1_0s2:
	s_waitcnt lgkmcnt(8)
	v_mfma_f32_32x32x16_bf16 v[64:79], v[238:241], v[250:253], v[64:79]
	ds_read_b64_tr_b16 v[238:239], v205 offset:16384
	ds_read_b64_tr_b16 v[240:241], v205 offset:20480
	s_waitcnt lgkmcnt(8)
	v_mfma_f32_32x32x16_bf16 v[48:63], v[128:131], v[250:253], v[48:63]
	ds_read_b64_tr_b16 v[128:129], v218 offset:16384
	ds_read_b64_tr_b16 v[130:131], v218 offset:20480
	s_waitcnt lgkmcnt(8)
	v_mfma_f32_32x32x16_bf16 v[32:47], v[206:209], v[250:253], v[32:47]
	ds_read_b64_tr_b16 v[206:207], v219 offset:16384
	ds_read_b64_tr_b16 v[208:209], v219 offset:20480
	s_waitcnt lgkmcnt(8)
	v_mfma_f32_32x32x16_bf16 v[16:31], v[210:213], v[250:253], v[16:31]
	ds_read_b64_tr_b16 v[210:211], v221 offset:16384
	ds_read_b64_tr_b16 v[212:213], v221 offset:20480
	s_waitcnt lgkmcnt(8)
	v_mfma_f32_32x32x16_bf16 v[0:15], v[214:217], v[250:253], v[0:15]
	ds_read_b64_tr_b16 v[214:215], v205 offset:16640
	ds_read_b64_tr_b16 v[216:217], v205 offset:20736
	s_nop 11
	v_max_f32_e32 v246, v190, v246
	v_sub_f32_e32 v190, v190, v246
	v_exp_f32_e32 v190, v190
	s_nop 0
	v_pk_mul_f32 v[126:127], v[126:127], v[190:191] op_sel_hi:[1,0]
	v_pk_mul_f32 v[124:125], v[124:125], v[190:191] op_sel_hi:[1,0]
	v_pk_mul_f32 v[122:123], v[122:123], v[190:191] op_sel_hi:[1,0]
	v_pk_mul_f32 v[120:121], v[120:121], v[190:191] op_sel_hi:[1,0]
	v_pk_mul_f32 v[118:119], v[118:119], v[190:191] op_sel_hi:[1,0]
	v_pk_mul_f32 v[116:117], v[116:117], v[190:191] op_sel_hi:[1,0]
	v_pk_mul_f32 v[114:115], v[114:115], v[190:191] op_sel_hi:[1,0]
	v_pk_mul_f32 v[112:113], v[112:113], v[190:191] op_sel_hi:[1,0]
	v_pk_mul_f32 v[110:111], v[110:111], v[190:191] op_sel_hi:[1,0]
	v_pk_mul_f32 v[108:109], v[108:109], v[190:191] op_sel_hi:[1,0]
	v_pk_mul_f32 v[106:107], v[106:107], v[190:191] op_sel_hi:[1,0]
	v_pk_mul_f32 v[104:105], v[104:105], v[190:191] op_sel_hi:[1,0]
	v_pk_mul_f32 v[102:103], v[102:103], v[190:191] op_sel_hi:[1,0]
	v_pk_mul_f32 v[100:101], v[100:101], v[190:191] op_sel_hi:[1,0]
	v_pk_mul_f32 v[98:99], v[98:99], v[190:191] op_sel_hi:[1,0]
	v_pk_mul_f32 v[96:97], v[96:97], v[190:191] op_sel_hi:[1,0]
	v_pk_mul_f32 v[94:95], v[94:95], v[190:191] op_sel_hi:[1,0]
	v_pk_mul_f32 v[92:93], v[92:93], v[190:191] op_sel_hi:[1,0]
	v_pk_mul_f32 v[90:91], v[90:91], v[190:191] op_sel_hi:[1,0]
	v_pk_mul_f32 v[88:89], v[88:89], v[190:191] op_sel_hi:[1,0]
	v_pk_mul_f32 v[86:87], v[86:87], v[190:191] op_sel_hi:[1,0]
	v_pk_mul_f32 v[84:85], v[84:85], v[190:191] op_sel_hi:[1,0]
	v_pk_mul_f32 v[82:83], v[82:83], v[190:191] op_sel_hi:[1,0]
	v_pk_mul_f32 v[80:81], v[80:81], v[190:191] op_sel_hi:[1,0]
	v_pk_mul_f32 v[78:79], v[78:79], v[190:191] op_sel_hi:[1,0]
	v_pk_mul_f32 v[76:77], v[76:77], v[190:191] op_sel_hi:[1,0]
	v_pk_mul_f32 v[74:75], v[74:75], v[190:191] op_sel_hi:[1,0]
	v_pk_mul_f32 v[72:73], v[72:73], v[190:191] op_sel_hi:[1,0]
	v_pk_mul_f32 v[70:71], v[70:71], v[190:191] op_sel_hi:[1,0]
	v_pk_mul_f32 v[68:69], v[68:69], v[190:191] op_sel_hi:[1,0]
	v_pk_mul_f32 v[66:67], v[66:67], v[190:191] op_sel_hi:[1,0]
	v_pk_mul_f32 v[64:65], v[64:65], v[190:191] op_sel_hi:[1,0]
	v_pk_mul_f32 v[62:63], v[62:63], v[190:191] op_sel_hi:[1,0]
	v_pk_mul_f32 v[60:61], v[60:61], v[190:191] op_sel_hi:[1,0]
	v_pk_mul_f32 v[58:59], v[58:59], v[190:191] op_sel_hi:[1,0]
	v_pk_mul_f32 v[56:57], v[56:57], v[190:191] op_sel_hi:[1,0]
	v_pk_mul_f32 v[54:55], v[54:55], v[190:191] op_sel_hi:[1,0]
	v_pk_mul_f32 v[52:53], v[52:53], v[190:191] op_sel_hi:[1,0]
	v_pk_mul_f32 v[50:51], v[50:51], v[190:191] op_sel_hi:[1,0]
	v_pk_mul_f32 v[48:49], v[48:49], v[190:191] op_sel_hi:[1,0]
	v_pk_mul_f32 v[46:47], v[46:47], v[190:191] op_sel_hi:[1,0]
	v_pk_mul_f32 v[44:45], v[44:45], v[190:191] op_sel_hi:[1,0]
	v_pk_mul_f32 v[42:43], v[42:43], v[190:191] op_sel_hi:[1,0]
	v_pk_mul_f32 v[40:41], v[40:41], v[190:191] op_sel_hi:[1,0]
	v_pk_mul_f32 v[38:39], v[38:39], v[190:191] op_sel_hi:[1,0]
	v_pk_mul_f32 v[36:37], v[36:37], v[190:191] op_sel_hi:[1,0]
	v_pk_mul_f32 v[34:35], v[34:35], v[190:191] op_sel_hi:[1,0]
	v_pk_mul_f32 v[32:33], v[32:33], v[190:191] op_sel_hi:[1,0]
	v_pk_mul_f32 v[30:31], v[30:31], v[190:191] op_sel_hi:[1,0]
	v_pk_mul_f32 v[28:29], v[28:29], v[190:191] op_sel_hi:[1,0]
	v_pk_mul_f32 v[26:27], v[26:27], v[190:191] op_sel_hi:[1,0]
	v_pk_mul_f32 v[24:25], v[24:25], v[190:191] op_sel_hi:[1,0]
	v_pk_mul_f32 v[22:23], v[22:23], v[190:191] op_sel_hi:[1,0]
	v_pk_mul_f32 v[20:21], v[20:21], v[190:191] op_sel_hi:[1,0]
	v_pk_mul_f32 v[18:19], v[18:19], v[190:191] op_sel_hi:[1,0]
	v_pk_mul_f32 v[16:17], v[16:17], v[190:191] op_sel_hi:[1,0]
	v_pk_mul_f32 v[14:15], v[14:15], v[190:191] op_sel_hi:[1,0]
	v_pk_mul_f32 v[12:13], v[12:13], v[190:191] op_sel_hi:[1,0]
	v_pk_mul_f32 v[10:11], v[10:11], v[190:191] op_sel_hi:[1,0]
	v_pk_mul_f32 v[8:9], v[8:9], v[190:191] op_sel_hi:[1,0]
	v_pk_mul_f32 v[6:7], v[6:7], v[190:191] op_sel_hi:[1,0]
	v_pk_mul_f32 v[4:5], v[4:5], v[190:191] op_sel_hi:[1,0]
	v_pk_mul_f32 v[2:3], v[2:3], v[190:191] op_sel_hi:[1,0]
	v_pk_mul_f32 v[0:1], v[0:1], v[190:191] op_sel_hi:[1,0]
	v_mul_f32_e32 v202, v202, v190
	v_mov_b32_e32 v190, v246
	v_sub_f32_e32 v222, v222, v190
	v_exp_f32_e32 v222, v222
	v_sub_f32_e32 v223, v223, v190
	v_exp_f32_e32 v223, v223
	v_sub_f32_e32 v224, v224, v190
	v_add_f32_e32 v254, 0, v222
	v_exp_f32_e32 v224, v224
	v_sub_f32_e32 v225, v225, v190
	v_add_f32_e32 v254, v223, v254
	v_exp_f32_e32 v225, v225
	v_sub_f32_e32 v226, v226, v190
	v_add_f32_e32 v254, v224, v254
	v_exp_f32_e32 v226, v226
	v_sub_f32_e32 v227, v227, v190
	v_add_f32_e32 v254, v225, v254
	v_exp_f32_e32 v227, v227
	v_sub_f32_e32 v228, v228, v190
	v_add_f32_e32 v254, v226, v254
	v_exp_f32_e32 v228, v228
	v_sub_f32_e32 v229, v229, v190
	v_add_f32_e32 v254, v227, v254
	v_exp_f32_e32 v229, v229
	v_sub_f32_e32 v230, v230, v190
	v_add_f32_e32 v254, v228, v254
	v_exp_f32_e32 v230, v230
	v_sub_f32_e32 v231, v231, v190
	v_add_f32_e32 v254, v229, v254
	v_exp_f32_e32 v231, v231
	v_sub_f32_e32 v232, v232, v190
	v_add_f32_e32 v254, v230, v254
	v_exp_f32_e32 v232, v232
	v_sub_f32_e32 v233, v233, v190
	v_add_f32_e32 v254, v231, v254
	v_exp_f32_e32 v233, v233
	v_sub_f32_e32 v234, v234, v190
	v_add_f32_e32 v254, v232, v254
	v_exp_f32_e32 v234, v234
	v_sub_f32_e32 v235, v235, v190
	v_add_f32_e32 v254, v233, v254
	v_exp_f32_e32 v235, v235
	v_sub_f32_e32 v236, v236, v190
	v_add_f32_e32 v254, v234, v254
	v_exp_f32_e32 v236, v236
	v_sub_f32_e32 v237, v237, v190
	v_add_f32_e32 v254, v235, v254
	v_exp_f32_e32 v237, v237
	v_add_f32_e32 v254, v236, v254
	v_add_f32_e32 v254, v237, v254
	v_cvt_pk_bf16_f32 v242, v222, v223
	v_cvt_pk_bf16_f32 v243, v224, v225
	v_cvt_pk_bf16_f32 v244, v226, v227
	v_cvt_pk_bf16_f32 v245, v228, v229
	v_cvt_pk_bf16_f32 v250, v230, v231
	v_cvt_pk_bf16_f32 v251, v232, v233
	v_cvt_pk_bf16_f32 v252, v234, v235
	v_cvt_pk_bf16_f32 v253, v236, v237
	v_add_f32_e32 v202, v202, v254
	s_nop 1
	s_waitcnt lgkmcnt(8)
	v_mfma_f32_32x32x16_bf16 v[112:127], v[238:241], v[242:245], v[112:127]
	ds_read_b64_tr_b16 v[238:239], v218 offset:16640
	ds_read_b64_tr_b16 v[240:241], v218 offset:20736
	s_waitcnt lgkmcnt(8)
	v_mfma_f32_32x32x16_bf16 v[96:111], v[128:131], v[242:245], v[96:111]
	ds_read_b64_tr_b16 v[222:223], v219 offset:16640
	ds_read_b64_tr_b16 v[224:225], v219 offset:20736
	s_waitcnt lgkmcnt(8)
	v_mfma_f32_32x32x16_bf16 v[80:95], v[206:209], v[242:245], v[80:95]
	ds_read_b64_tr_b16 v[206:207], v221 offset:16640
	ds_read_b64_tr_b16 v[208:209], v221 offset:20736
	s_waitcnt lgkmcnt(8)
	v_mfma_f32_32x32x16_bf16 v[64:79], v[210:213], v[242:245], v[64:79]
	ds_read_b64_tr_b16 v[210:211], v205 offset:24576
	ds_read_b64_tr_b16 v[212:213], v205 offset:28672
	s_waitcnt lgkmcnt(8)
	v_mfma_f32_32x32x16_bf16 v[48:63], v[214:217], v[242:245], v[48:63]
	ds_read_b64_tr_b16 v[214:215], v218 offset:24576
	ds_read_b64_tr_b16 v[216:217], v218 offset:28672
	s_waitcnt lgkmcnt(8)
	v_mfma_f32_32x32x16_bf16 v[32:47], v[238:241], v[242:245], v[32:47]
	ds_read_b64_tr_b16 v[238:239], v219 offset:24576
	ds_read_b64_tr_b16 v[240:241], v219 offset:28672
	s_waitcnt lgkmcnt(8)
	v_mfma_f32_32x32x16_bf16 v[16:31], v[222:225], v[242:245], v[16:31]
	ds_read_b64_tr_b16 v[222:223], v221 offset:24576
	ds_read_b64_tr_b16 v[224:225], v221 offset:28672
	s_waitcnt lgkmcnt(8)
	v_mfma_f32_32x32x16_bf16 v[0:15], v[206:209], v[242:245], v[0:15]
	ds_read_b64_tr_b16 v[206:207], v205 offset:24832
	ds_read_b64_tr_b16 v[208:209], v205 offset:28928
	s_waitcnt lgkmcnt(8)
	v_mfma_f32_32x32x16_bf16 v[112:127], v[210:213], v[250:253], v[112:127]
	ds_read_b64_tr_b16 v[210:211], v218 offset:24832
	ds_read_b64_tr_b16 v[212:213], v218 offset:28928
	s_waitcnt lgkmcnt(8)
	v_mfma_f32_32x32x16_bf16 v[96:111], v[214:217], v[250:253], v[96:111]
	ds_read_b64_tr_b16 v[214:215], v219 offset:24832
	ds_read_b64_tr_b16 v[216:217], v219 offset:28928
	s_waitcnt lgkmcnt(8)
	v_mfma_f32_32x32x16_bf16 v[80:95], v[238:241], v[250:253], v[80:95]
	ds_read_b64_tr_b16 v[238:239], v221 offset:24832
	ds_read_b64_tr_b16 v[240:241], v221 offset:28928
	s_waitcnt lgkmcnt(8)
	v_mfma_f32_32x32x16_bf16 v[64:79], v[222:225], v[250:253], v[64:79]
	s_waitcnt lgkmcnt(6)
	v_mfma_f32_32x32x16_bf16 v[48:63], v[206:209], v[250:253], v[48:63]
	s_waitcnt lgkmcnt(4)
	v_mfma_f32_32x32x16_bf16 v[32:47], v[210:213], v[250:253], v[32:47]
	s_waitcnt lgkmcnt(2)
	v_mfma_f32_32x32x16_bf16 v[16:31], v[214:217], v[250:253], v[16:31]
	s_waitcnt lgkmcnt(0)
	v_mfma_f32_32x32x16_bf16 v[0:15], v[238:241], v[250:253], v[0:15]
	ds_read_b128 v[206:209], v194
	ds_read_b128 v[210:213], v195
	ds_read_b128 v[214:217], v196
	ds_read_b128 v[238:241], v197
	ds_read_b128 v[242:245], v198
	ds_read_b128 v[250:253], v199
	ds_read_b128 v[222:225], v200
	ds_read_b128 v[226:229], v201
	s_branch .Latt_end_0
.Latt_slow_0s2:
.Latt_slow_0:
	s_waitcnt lgkmcnt(0)
	s_lshl_b32 s34, s88, 14
	s_add_i32 s35, s34, 0
	v_add_u32_e32 v206, s35, v194
	ds_read_b128 v[128:131], v206
	v_add_u32_e32 v207, s35, v195
	ds_read_b128 v[210:213], v207
	v_add_u32_e32 v208, s35, v196
	v_add_u32_e32 v209, s35, v197
	v_lshrrev_b32_e32 v204, 3, v203
	s_add_i32 s89, s43, 31
	v_and_or_b32 v205, v203, 31, s83
	s_cmp_le_i32 s89, s83
	s_waitcnt lgkmcnt(1)
	v_mfma_f32_32x32x16_bf16 v[128:143], v[128:131], v[144:147], 0
	ds_read_b128 v[214:217], v209
	s_waitcnt lgkmcnt(1)
	v_mfma_f32_32x32x16_bf16 v[128:143], v[210:213], v[148:151], v[128:143]
	ds_read_b128 v[210:213], v208
	s_waitcnt lgkmcnt(0)
	v_mfma_f32_32x32x16_bf16 v[128:143], v[210:213], v[152:155], v[128:143]
	v_add_u32_e32 v210, s35, v198
	v_add_u32_e32 v212, s35, v199
	v_add_u32_e32 v213, s35, v200
	v_and_b32_e32 v211, 4, v204
	ds_read_b128 v[222:225], v212
	v_mfma_f32_32x32x16_bf16 v[128:143], v[214:217], v[156:159], v[128:143]
	ds_read_b128 v[214:217], v210
	s_waitcnt lgkmcnt(0)
	v_mfma_f32_32x32x16_bf16 v[128:143], v[214:217], v[160:163], v[128:143]
	ds_read_b128 v[216:219], v213
	v_add_u32_e32 v214, s35, v201
	v_mfma_f32_32x32x16_bf16 v[128:143], v[222:225], v[164:167], v[128:143]
	ds_read_b128 v[222:225], v214
	s_waitcnt lgkmcnt(1)
	v_mfma_f32_32x32x16_bf16 v[128:143], v[216:219], v[168:171], v[128:143]
	s_waitcnt lgkmcnt(0)
	v_mfma_f32_32x32x16_bf16 v[128:143], v[222:225], v[172:175], v[128:143]
	s_cbranch_scc1 .LBB0_850
	v_add_u32_e32 v204, s43, v211
	v_cmp_lt_i32_e32 vcc, v204, v205
	v_add_u32_e32 v215, 2, v204
	s_nop 7
	v_cndmask_b32_e32 v129, v192, v129, vcc
	v_cmp_le_i32_e32 vcc, v204, v205
	s_nop 1
	v_cndmask_b32_e32 v128, v192, v128, vcc
	v_cmp_le_i32_e32 vcc, v215, v205
	v_add_u32_e32 v215, 3, v204
	s_nop 0
	v_cndmask_b32_e32 v130, v192, v130, vcc
	v_cmp_le_i32_e32 vcc, v215, v205
	v_add_u32_e32 v215, 8, v204
	s_nop 0
	v_cndmask_b32_e32 v131, v192, v131, vcc
	v_cmp_le_i32_e32 vcc, v215, v205
	v_add_u32_e32 v215, 9, v204
	s_nop 0
	v_cndmask_b32_e32 v132, v192, v132, vcc
	v_cmp_le_i32_e32 vcc, v215, v205
	v_add_u32_e32 v215, 10, v204
	s_nop 0
	v_cndmask_b32_e32 v133, v192, v133, vcc
	v_cmp_le_i32_e32 vcc, v215, v205
	v_add_u32_e32 v215, 11, v204
	s_nop 0
	v_cndmask_b32_e32 v134, v192, v134, vcc
	v_cmp_le_i32_e32 vcc, v215, v205
	v_add_u32_e32 v215, 16, v204
	s_nop 0
	v_cndmask_b32_e32 v135, v192, v135, vcc
	v_cmp_le_i32_e32 vcc, v215, v205
	v_add_u32_e32 v215, 17, v204
	s_nop 0
	v_cndmask_b32_e32 v136, v192, v136, vcc
	v_cmp_le_i32_e32 vcc, v215, v205
	v_add_u32_e32 v215, 18, v204
	s_nop 0
	v_cndmask_b32_e32 v137, v192, v137, vcc
	v_cmp_le_i32_e32 vcc, v215, v205
	v_add_u32_e32 v215, 19, v204
	s_nop 0
	v_cndmask_b32_e32 v138, v192, v138, vcc
	v_cmp_le_i32_e32 vcc, v215, v205
	v_add_u32_e32 v215, 24, v204
	s_nop 0
	v_cndmask_b32_e32 v139, v192, v139, vcc
	v_cmp_le_i32_e32 vcc, v215, v205
	v_add_u32_e32 v215, 25, v204
	s_nop 0
	v_cndmask_b32_e32 v140, v192, v140, vcc
	v_cmp_le_i32_e32 vcc, v215, v205
	v_add_u32_e32 v215, 26, v204
	v_add_u32_e32 v204, 27, v204
	v_cndmask_b32_e32 v141, v192, v141, vcc
	v_cmp_le_i32_e32 vcc, v215, v205
	s_nop 1
	v_cndmask_b32_e32 v142, v192, v142, vcc
	v_cmp_le_i32_e32 vcc, v204, v205
	s_nop 1
	v_cndmask_b32_e32 v143, v192, v143, vcc

.LBB0_857:
	v_sub_f32_e32 v128, v128, v190
	v_exp_f32_e32 v128, v128
	v_sub_f32_e32 v129, v129, v190
	v_exp_f32_e32 v129, v129
	v_sub_f32_e32 v130, v130, v190
	v_exp_f32_e32 v130, v130
	v_sub_f32_e32 v131, v131, v190
	v_exp_f32_e32 v131, v131
	v_sub_f32_e32 v132, v132, v190
	v_add_f32_e32 v205, 0, v128
	v_exp_f32_e32 v132, v132
	v_sub_f32_e32 v133, v133, v190
	v_add_f32_e32 v205, v129, v205
	v_exp_f32_e32 v133, v133
	v_sub_f32_e32 v134, v134, v190
	v_add_f32_e32 v205, v130, v205
	v_exp_f32_e32 v134, v134
	v_sub_f32_e32 v135, v135, v190
	v_add_f32_e32 v205, v131, v205
	v_exp_f32_e32 v135, v135
	v_sub_f32_e32 v136, v136, v190
	v_add_f32_e32 v205, v132, v205
	v_exp_f32_e32 v136, v136
	v_sub_f32_e32 v137, v137, v190
	v_add_f32_e32 v205, v133, v205
	v_exp_f32_e32 v137, v137
	v_sub_f32_e32 v138, v138, v190
	v_add_f32_e32 v205, v134, v205
	v_exp_f32_e32 v138, v138
	v_sub_f32_e32 v139, v139, v190
	v_add_f32_e32 v205, v135, v205
	v_exp_f32_e32 v139, v139
	v_sub_f32_e32 v140, v140, v190
	v_add_f32_e32 v205, v136, v205
	v_exp_f32_e32 v140, v140
	v_sub_f32_e32 v141, v141, v190
	v_add_f32_e32 v205, v137, v205
	v_exp_f32_e32 v141, v141
	v_sub_f32_e32 v142, v142, v190
	v_add_f32_e32 v205, v138, v205
	v_exp_f32_e32 v142, v142
	v_sub_f32_e32 v143, v143, v190
	v_add_f32_e32 v205, v139, v205
	v_exp_f32_e32 v143, v143
	v_add_f32_e32 v205, v140, v205
	v_add_f32_e32 v205, v141, v205
	v_add_f32_e32 v205, v142, v205
	v_add_u32_e32 v208, 0xc000, v216
	v_add_f32_e32 v216, v143, v205
	v_cvt_pk_bf16_f32 v128, v128, v129
	v_cvt_pk_bf16_f32 v129, v130, v131
	v_cvt_pk_bf16_f32 v130, v132, v133
	v_cvt_pk_bf16_f32 v131, v134, v135
	v_cvt_pk_bf16_f32 v132, v136, v137
	v_cvt_pk_bf16_f32 v133, v138, v139
	v_cvt_pk_bf16_f32 v134, v140, v141
	v_cvt_pk_bf16_f32 v135, v142, v143
	v_add_u32_e32 v219, v208, v204
	ds_read_b64_tr_b16 v[136:137], v219 offset:16384
	ds_read_b64_tr_b16 v[138:139], v219 offset:20480
	v_add_u32_e32 v203, v208, v203
	ds_read_b64_tr_b16 v[142:143], v219 offset:20736
	ds_read_b64_tr_b16 v[140:141], v219 offset:16640
	v_add_u32_e32 v217, v208, v217
	v_add_u32_e32 v218, v208, v218
	s_waitcnt lgkmcnt(2)
	v_mfma_f32_32x32x16_bf16 v[112:127], v[136:139], v[128:131], v[112:127]
	ds_read_b64_tr_b16 v[136:137], v203 offset:16384
	ds_read_b64_tr_b16 v[138:139], v203 offset:20480
	ds_read_b64_tr_b16 v[206:207], v203 offset:20736
	ds_read_b64_tr_b16 v[204:205], v203 offset:16640
	v_add_f32_e32 v202, v202, v216
	s_waitcnt lgkmcnt(2)
	v_mfma_f32_32x32x16_bf16 v[96:111], v[136:139], v[128:131], v[96:111]
	ds_read_b64_tr_b16 v[136:137], v217 offset:16384
	ds_read_b64_tr_b16 v[138:139], v217 offset:20480
	ds_read_b64_tr_b16 v[210:211], v217 offset:20736
	ds_read_b64_tr_b16 v[208:209], v217 offset:16640
	s_waitcnt lgkmcnt(2)
	v_mfma_f32_32x32x16_bf16 v[80:95], v[136:139], v[128:131], v[80:95]
	ds_read_b64_tr_b16 v[136:137], v218 offset:16384
	ds_read_b64_tr_b16 v[138:139], v218 offset:20480
	ds_read_b64_tr_b16 v[214:215], v218 offset:20736
	ds_read_b64_tr_b16 v[212:213], v218 offset:16640
	s_waitcnt lgkmcnt(2)
	v_mfma_f32_32x32x16_bf16 v[64:79], v[136:139], v[128:131], v[64:79]
	v_mfma_f32_32x32x16_bf16 v[48:63], v[140:143], v[128:131], v[48:63]
	v_mfma_f32_32x32x16_bf16 v[32:47], v[204:207], v[128:131], v[32:47]
	v_mfma_f32_32x32x16_bf16 v[16:31], v[208:211], v[128:131], v[16:31]
	s_waitcnt lgkmcnt(0)
	v_mfma_f32_32x32x16_bf16 v[0:15], v[212:215], v[128:131], v[0:15]
	ds_read_b64_tr_b16 v[128:129], v219 offset:24576
	ds_read_b64_tr_b16 v[130:131], v219 offset:28672
	ds_read_b64_tr_b16 v[138:139], v219 offset:28928
	ds_read_b64_tr_b16 v[136:137], v219 offset:24832
	s_waitcnt lgkmcnt(2)
	v_mfma_f32_32x32x16_bf16 v[112:127], v[128:131], v[132:135], v[112:127]
	ds_read_b64_tr_b16 v[128:129], v203 offset:24576
	ds_read_b64_tr_b16 v[130:131], v203 offset:28672
	ds_read_b64_tr_b16 v[142:143], v203 offset:28928
	ds_read_b64_tr_b16 v[140:141], v203 offset:24832
	s_waitcnt lgkmcnt(2)
	v_mfma_f32_32x32x16_bf16 v[96:111], v[128:131], v[132:135], v[96:111]
	ds_read_b64_tr_b16 v[128:129], v217 offset:24576
	ds_read_b64_tr_b16 v[130:131], v217 offset:28672
	ds_read_b64_tr_b16 v[206:207], v217 offset:28928
	ds_read_b64_tr_b16 v[204:205], v217 offset:24832
	s_waitcnt lgkmcnt(2)
	v_mfma_f32_32x32x16_bf16 v[80:95], v[128:131], v[132:135], v[80:95]
	ds_read_b64_tr_b16 v[128:129], v218 offset:24576
	ds_read_b64_tr_b16 v[130:131], v218 offset:28672
	ds_read_b64_tr_b16 v[210:211], v218 offset:28928
	ds_read_b64_tr_b16 v[208:209], v218 offset:24832
	s_waitcnt lgkmcnt(2)
	v_mfma_f32_32x32x16_bf16 v[64:79], v[128:131], v[132:135], v[64:79]
	v_mfma_f32_32x32x16_bf16 v[48:63], v[136:139], v[132:135], v[48:63]
	v_mfma_f32_32x32x16_bf16 v[32:47], v[140:143], v[132:135], v[32:47]
	v_mfma_f32_32x32x16_bf16 v[16:31], v[204:207], v[132:135], v[16:31]
	s_waitcnt lgkmcnt(0)
	v_mfma_f32_32x32x16_bf16 v[0:15], v[208:211], v[132:135], v[0:15]
.LBB0_858:
	s_waitcnt lgkmcnt(0)
.Latt_end_0:
	s_mov_b64 s[34:35], -1
	s_and_b64 vcc, exec, s[18:19]
	s_cbranch_vccz .LBB0_860
	s_waitcnt vmcnt(0)
	s_mov_b64 s[34:35], 0

.LBB0_866:
	s_cmp_gt_i32 s4, s84
	s_cbranch_scc1 .LBB0_877
	s_add_i32 s100, s4, 63
	s_cmp_le_i32 s100, s83
	s_cbranch_scc0 .Latt_slow_1
	s_cmp_eq_u32 s33, 1
	s_cbranch_scc1 .Latt_slot1_1
	s_cmp_eq_u32 s33, 2
	s_cbranch_scc1 .Latt_slot2_1
	s_cmp_lg_u32 s4, 0
	s_cbranch_scc1 .Latt_vstep_1s0
	ds_read_b128 v[206:209], v196
	ds_read_b128 v[210:213], v197
	ds_read_b128 v[214:217], v198
	ds_read_b128 v[238:241], v199
	ds_read_b128 v[242:245], v200
	ds_read_b128 v[250:253], v201
	ds_read_b128 v[222:225], v202
	ds_read_b128 v[226:229], v203
	v_bfe_u32 v246, v204, 2, 2
	v_bfe_u32 v247, v204, 5, 1
	v_lshl_or_b32 v247, v247, 2, v246
	v_and_b32_e32 v249, 3, v204
	v_and_b32_e32 v254, 16, v204
	v_lshl_or_b32 v249, v249, 2, v254
	v_lshlrev_b32_e32 v249, 1, v249
	v_lshl_add_u32 v247, v247, 9, v249
	v_add_u32_e32 v247, 0xc000, v247
	v_lshlrev_b32_e32 v246, 6, v246
	v_add_u32_e32 v205, v247, v246
	v_xor_b32_e32 v249, 64, v246
	v_add_u32_e32 v218, v247, v249
	v_xor_b32_e32 v249, 0x80, v246
	v_add_u32_e32 v219, v247, v249
	v_xor_b32_e32 v249, 0xc0, v246
	v_add_u32_e32 v221, v247, v249
	s_branch .Latt_vdone_1s0

.Latt_vdone_1s0:
	s_waitcnt lgkmcnt(7)
	v_mfma_f32_32x32x16_bf16 v[128:143], v[206:209], v[144:147], 0
	ds_read_b128 v[206:209], v196 offset:8192
	s_cmp_lg_u64 s[18:19], 0
	s_cbranch_scc1 .Latt_nd0_1s0
	s_sub_i32 s100, s33, 1
	s_cmp_eq_u32 s33, 0
	s_cselect_b32 s100, 2, s100
	s_lshl_b32 s101, s100, 14
	s_add_i32 m0, s85, s101
	s_nop 0
	global_load_lds_dwordx4 v178, s[12:13]
.Latt_nd0_1s0:
	s_waitcnt lgkmcnt(7)
	v_mfma_f32_32x32x16_bf16 v[128:143], v[210:213], v[148:151], v[128:143]
	ds_read_b128 v[210:213], v197 offset:8192
	s_cmp_lg_u64 s[18:19], 0
	s_cbranch_scc1 .Latt_nd1_1s0
	s_add_i32 m0, m0, 0x400
	s_nop 0
	global_load_lds_dwordx4 v180, s[12:13]
.Latt_nd1_1s0:
	s_waitcnt lgkmcnt(7)
	v_mfma_f32_32x32x16_bf16 v[128:143], v[214:217], v[152:155], v[128:143]
	ds_read_b128 v[214:217], v198 offset:8192
	s_cmp_lg_u64 s[18:19], 0
	s_cbranch_scc1 .Latt_nd2_1s0
	s_lshl_b32 s101, s100, 15
	s_add_i32 m0, s86, s101
	s_add_u32 s100, s12, 0xf00
	s_addc_u32 s101, s13, 0
	global_load_lds_dwordx4 v182, s[100:101]
.Latt_nd2_1s0:
	s_waitcnt lgkmcnt(7)
	v_mfma_f32_32x32x16_bf16 v[128:143], v[238:241], v[156:159], v[128:143]
	ds_read_b128 v[238:241], v199 offset:8192
	s_cmp_lg_u64 s[18:19], 0
	s_cbranch_scc1 .Latt_nd3_1s0
	s_add_i32 m0, m0, 0x400
	s_nop 0
	global_load_lds_dwordx4 v184, s[100:101]

.Latt_nd5_1s0:
	s_waitcnt lgkmcnt(5)
	v_mfma_f32_32x32x16_bf16 v[128:143], v[222:225], v[168:171], v[128:143]
	s_waitcnt lgkmcnt(4)
	v_mfma_f32_32x32x16_bf16 v[128:143], v[226:229], v[172:175], v[128:143]
	s_waitcnt lgkmcnt(3)
	v_mfma_f32_32x32x16_bf16 v[222:237], v[206:209], v[144:147], 0
	ds_read_b128 v[206:209], v200 offset:8192
	s_nop 8
	v_max3_f32 v246, v128, v129, v130
	v_max3_f32 v247, v131, v132, v133
	v_max3_f32 v246, v246, v134, v135
	v_max3_f32 v247, v247, v136, v137
	v_max3_f32 v246, v246, v138, v139
	v_max3_f32 v247, v247, v140, v141
	v_max3_f32 v246, v246, v142, v143
	s_waitcnt lgkmcnt(3)
	v_mfma_f32_32x32x16_bf16 v[222:237], v[210:213], v[148:151], v[222:237]
	ds_read_b128 v[210:213], v201 offset:8192
	v_max_f32_e32 v246, v246, v247
	v_mov_b32_e32 v247, v246
	v_add_f32_e32 v249, 0x41000000, v190
	s_nop 1
	v_permlane32_swap_b32_e32 v246, v247
	v_max_f32_e32 v246, v246, v247
	v_cmp_gt_f32_e32 vcc, v246, v249
	s_cbranch_vccz .Latt_nr0_1s0
	v_max_f32_e32 v246, v190, v246
	v_sub_f32_e32 v190, v190, v246
	v_exp_f32_e32 v190, v190
	s_nop 0
	v_pk_mul_f32 v[126:127], v[126:127], v[190:191] op_sel_hi:[1,0]
	v_pk_mul_f32 v[124:125], v[124:125], v[190:191] op_sel_hi:[1,0]
	v_pk_mul_f32 v[122:123], v[122:123], v[190:191] op_sel_hi:[1,0]
	v_pk_mul_f32 v[120:121], v[120:121], v[190:191] op_sel_hi:[1,0]
	v_pk_mul_f32 v[118:119], v[118:119], v[190:191] op_sel_hi:[1,0]
	v_pk_mul_f32 v[116:117], v[116:117], v[190:191] op_sel_hi:[1,0]
	v_pk_mul_f32 v[114:115], v[114:115], v[190:191] op_sel_hi:[1,0]
	v_pk_mul_f32 v[112:113], v[112:113], v[190:191] op_sel_hi:[1,0]
	v_pk_mul_f32 v[110:111], v[110:111], v[190:191] op_sel_hi:[1,0]
	v_pk_mul_f32 v[108:109], v[108:109], v[190:191] op_sel_hi:[1,0]
	v_pk_mul_f32 v[106:107], v[106:107], v[190:191] op_sel_hi:[1,0]
	v_pk_mul_f32 v[104:105], v[104:105], v[190:191] op_sel_hi:[1,0]
	v_pk_mul_f32 v[102:103], v[102:103], v[190:191] op_sel_hi:[1,0]
	v_pk_mul_f32 v[100:101], v[100:101], v[190:191] op_sel_hi:[1,0]
	v_pk_mul_f32 v[98:99], v[98:99], v[190:191] op_sel_hi:[1,0]
	v_pk_mul_f32 v[96:97], v[96:97], v[190:191] op_sel_hi:[1,0]
	v_pk_mul_f32 v[94:95], v[94:95], v[190:191] op_sel_hi:[1,0]
	v_pk_mul_f32 v[92:93], v[92:93], v[190:191] op_sel_hi:[1,0]
	v_pk_mul_f32 v[90:91], v[90:91], v[190:191] op_sel_hi:[1,0]
	v_pk_mul_f32 v[88:89], v[88:89], v[190:191] op_sel_hi:[1,0]
	v_pk_mul_f32 v[86:87], v[86:87], v[190:191] op_sel_hi:[1,0]
	v_pk_mul_f32 v[84:85], v[84:85], v[190:191] op_sel_hi:[1,0]
	v_pk_mul_f32 v[82:83], v[82:83], v[190:191] op_sel_hi:[1,0]
	v_pk_mul_f32 v[80:81], v[80:81], v[190:191] op_sel_hi:[1,0]
	v_pk_mul_f32 v[78:79], v[78:79], v[190:191] op_sel_hi:[1,0]
	v_pk_mul_f32 v[76:77], v[76:77], v[190:191] op_sel_hi:[1,0]
	v_pk_mul_f32 v[74:75], v[74:75], v[190:191] op_sel_hi:[1,0]
	v_pk_mul_f32 v[72:73], v[72:73], v[190:191] op_sel_hi:[1,0]
	v_pk_mul_f32 v[70:71], v[70:71], v[190:191] op_sel_hi:[1,0]
	v_pk_mul_f32 v[68:69], v[68:69], v[190:191] op_sel_hi:[1,0]
	v_pk_mul_f32 v[66:67], v[66:67], v[190:191] op_sel_hi:[1,0]
	v_pk_mul_f32 v[64:65], v[64:65], v[190:191] op_sel_hi:[1,0]
	v_pk_mul_f32 v[62:63], v[62:63], v[190:191] op_sel_hi:[1,0]
	v_pk_mul_f32 v[60:61], v[60:61], v[190:191] op_sel_hi:[1,0]
	v_pk_mul_f32 v[58:59], v[58:59], v[190:191] op_sel_hi:[1,0]
	v_pk_mul_f32 v[56:57], v[56:57], v[190:191] op_sel_hi:[1,0]
	v_pk_mul_f32 v[54:55], v[54:55], v[190:191] op_sel_hi:[1,0]
	v_pk_mul_f32 v[52:53], v[52:53], v[190:191] op_sel_hi:[1,0]
	v_pk_mul_f32 v[50:51], v[50:51], v[190:191] op_sel_hi:[1,0]
	v_pk_mul_f32 v[48:49], v[48:49], v[190:191] op_sel_hi:[1,0]
	v_pk_mul_f32 v[46:47], v[46:47], v[190:191] op_sel_hi:[1,0]
	v_pk_mul_f32 v[44:45], v[44:45], v[190:191] op_sel_hi:[1,0]
	v_pk_mul_f32 v[42:43], v[42:43], v[190:191] op_sel_hi:[1,0]
	v_pk_mul_f32 v[40:41], v[40:41], v[190:191] op_sel_hi:[1,0]
	v_pk_mul_f32 v[38:39], v[38:39], v[190:191] op_sel_hi:[1,0]
	v_pk_mul_f32 v[36:37], v[36:37], v[190:191] op_sel_hi:[1,0]
	v_pk_mul_f32 v[34:35], v[34:35], v[190:191] op_sel_hi:[1,0]
	v_pk_mul_f32 v[32:33], v[32:33], v[190:191] op_sel_hi:[1,0]
	v_pk_mul_f32 v[30:31], v[30:31], v[190:191] op_sel_hi:[1,0]
	v_pk_mul_f32 v[28:29], v[28:29], v[190:191] op_sel_hi:[1,0]
	v_pk_mul_f32 v[26:27], v[26:27], v[190:191] op_sel_hi:[1,0]
	v_pk_mul_f32 v[24:25], v[24:25], v[190:191] op_sel_hi:[1,0]
	v_pk_mul_f32 v[22:23], v[22:23], v[190:191] op_sel_hi:[1,0]
	v_pk_mul_f32 v[20:21], v[20:21], v[190:191] op_sel_hi:[1,0]
	v_pk_mul_f32 v[18:19], v[18:19], v[190:191] op_sel_hi:[1,0]
	v_pk_mul_f32 v[16:17], v[16:17], v[190:191] op_sel_hi:[1,0]
	v_pk_mul_f32 v[14:15], v[14:15], v[190:191] op_sel_hi:[1,0]
	v_pk_mul_f32 v[12:13], v[12:13], v[190:191] op_sel_hi:[1,0]
	v_pk_mul_f32 v[10:11], v[10:11], v[190:191] op_sel_hi:[1,0]
	v_pk_mul_f32 v[8:9], v[8:9], v[190:191] op_sel_hi:[1,0]
	v_pk_mul_f32 v[6:7], v[6:7], v[190:191] op_sel_hi:[1,0]
	v_pk_mul_f32 v[4:5], v[4:5], v[190:191] op_sel_hi:[1,0]
	v_pk_mul_f32 v[2:3], v[2:3], v[190:191] op_sel_hi:[1,0]
	v_pk_mul_f32 v[0:1], v[0:1], v[190:191] op_sel_hi:[1,0]
	v_mul_f32_e32 v195, v195, v190
	v_mov_b32_e32 v190, v246
.Latt_nr0_1s0:
	s_waitcnt lgkmcnt(3)
	v_mfma_f32_32x32x16_bf16 v[222:237], v[214:217], v[152:155], v[222:237]
	ds_read_b128 v[214:217], v202 offset:8192
	v_sub_f32_e32 v128, v128, v190
	v_exp_f32_e32 v128, v128
	v_sub_f32_e32 v129, v129, v190
	v_exp_f32_e32 v129, v129
	v_sub_f32_e32 v130, v130, v190
	s_waitcnt lgkmcnt(3)
	v_mfma_f32_32x32x16_bf16 v[222:237], v[238:241], v[156:159], v[222:237]
	ds_read_b128 v[238:241], v203 offset:8192
	v_add_f32_e32 v254, 0, v128
	v_exp_f32_e32 v130, v130
	v_sub_f32_e32 v131, v131, v190
	v_add_f32_e32 v254, v129, v254
	v_exp_f32_e32 v131, v131
	s_waitcnt lgkmcnt(3)
	v_mfma_f32_32x32x16_bf16 v[222:237], v[206:209], v[160:163], v[222:237]
	ds_read_b64_tr_b16 v[206:207], v205
	ds_read_b64_tr_b16 v[208:209], v205 offset:4096
	v_sub_f32_e32 v132, v132, v190
	v_add_f32_e32 v254, v130, v254
	v_exp_f32_e32 v132, v132
	v_sub_f32_e32 v133, v133, v190
	v_add_f32_e32 v254, v131, v254
	s_waitcnt lgkmcnt(4)
	v_mfma_f32_32x32x16_bf16 v[222:237], v[210:213], v[164:167], v[222:237]
	ds_read_b64_tr_b16 v[210:211], v218
	ds_read_b64_tr_b16 v[212:213], v218 offset:4096
	v_exp_f32_e32 v133, v133
	v_sub_f32_e32 v134, v134, v190
	v_add_f32_e32 v254, v132, v254
	v_exp_f32_e32 v134, v134
	s_waitcnt lgkmcnt(5)
	v_mfma_f32_32x32x16_bf16 v[222:237], v[214:217], v[168:171], v[222:237]
	ds_read_b64_tr_b16 v[214:215], v219
	ds_read_b64_tr_b16 v[216:217], v219 offset:4096
	v_sub_f32_e32 v135, v135, v190
	v_add_f32_e32 v254, v133, v254
	v_exp_f32_e32 v135, v135
	s_nop 0
	s_waitcnt lgkmcnt(6)
	v_mfma_f32_32x32x16_bf16 v[222:237], v[238:241], v[172:175], v[222:237]
	ds_read_b64_tr_b16 v[238:239], v221
	ds_read_b64_tr_b16 v[240:241], v221 offset:4096
	v_cvt_pk_bf16_f32 v242, v128, v129
	v_cvt_pk_bf16_f32 v243, v130, v131
	v_cvt_pk_bf16_f32 v244, v132, v133
	v_cvt_pk_bf16_f32 v245, v134, v135
	s_nop 1
	s_waitcnt lgkmcnt(6)
	v_mfma_f32_32x32x16_bf16 v[112:127], v[206:209], v[242:245], v[112:127]
	ds_read_b64_tr_b16 v[206:207], v205 offset:256
	ds_read_b64_tr_b16 v[208:209], v205 offset:4352
	v_sub_f32_e32 v136, v136, v190
	v_add_f32_e32 v254, v134, v254
	v_exp_f32_e32 v136, v136
	v_sub_f32_e32 v137, v137, v190
	v_add_f32_e32 v254, v135, v254
	s_waitcnt lgkmcnt(6)
	v_mfma_f32_32x32x16_bf16 v[96:111], v[210:213], v[242:245], v[96:111]
	ds_read_b64_tr_b16 v[210:211], v218 offset:256
	ds_read_b64_tr_b16 v[212:213], v218 offset:4352
	v_exp_f32_e32 v137, v137
	v_sub_f32_e32 v138, v138, v190
	v_add_f32_e32 v254, v136, v254
	v_exp_f32_e32 v138, v138
	v_sub_f32_e32 v139, v139, v190
	s_waitcnt lgkmcnt(6)
	v_mfma_f32_32x32x16_bf16 v[80:95], v[214:217], v[242:245], v[80:95]
	ds_read_b64_tr_b16 v[214:215], v219 offset:256
	ds_read_b64_tr_b16 v[216:217], v219 offset:4352
	v_add_f32_e32 v254, v137, v254
	v_exp_f32_e32 v139, v139
	v_sub_f32_e32 v140, v140, v190
	v_add_f32_e32 v254, v138, v254
	s_waitcnt lgkmcnt(6)
	v_mfma_f32_32x32x16_bf16 v[64:79], v[238:241], v[242:245], v[64:79]
	ds_read_b64_tr_b16 v[238:239], v221 offset:256
	ds_read_b64_tr_b16 v[240:241], v221 offset:4352
	v_exp_f32_e32 v140, v140
	v_sub_f32_e32 v141, v141, v190
	v_add_f32_e32 v254, v139, v254
	v_exp_f32_e32 v141, v141
	s_waitcnt lgkmcnt(6)
	v_mfma_f32_32x32x16_bf16 v[48:63], v[206:209], v[242:245], v[48:63]
	ds_read_b64_tr_b16 v[206:207], v205 offset:8192
	ds_read_b64_tr_b16 v[208:209], v205 offset:12288
	v_sub_f32_e32 v142, v142, v190
	v_add_f32_e32 v254, v140, v254
	v_exp_f32_e32 v142, v142
	v_sub_f32_e32 v143, v143, v190
	s_waitcnt lgkmcnt(6)
	v_mfma_f32_32x32x16_bf16 v[32:47], v[210:213], v[242:245], v[32:47]
	ds_read_b64_tr_b16 v[210:211], v218 offset:8192
	ds_read_b64_tr_b16 v[212:213], v218 offset:12288
	v_add_f32_e32 v254, v141, v254
	v_exp_f32_e32 v143, v143
	v_add_f32_e32 v254, v142, v254
	v_add_f32_e32 v254, v143, v254
	s_waitcnt lgkmcnt(6)
	v_mfma_f32_32x32x16_bf16 v[16:31], v[214:217], v[242:245], v[16:31]
	ds_read_b64_tr_b16 v[214:215], v219 offset:8192
	ds_read_b64_tr_b16 v[216:217], v219 offset:12288
	v_cvt_pk_bf16_f32 v250, v136, v137
	v_cvt_pk_bf16_f32 v251, v138, v139
	v_cvt_pk_bf16_f32 v252, v140, v141
	v_cvt_pk_bf16_f32 v253, v142, v143
	v_add_f32_e32 v195, v195, v254
	s_waitcnt lgkmcnt(6)
	v_mfma_f32_32x32x16_bf16 v[0:15], v[238:241], v[242:245], v[0:15]
	ds_read_b64_tr_b16 v[238:239], v221 offset:8192
	ds_read_b64_tr_b16 v[240:241], v221 offset:12288
	ds_read_b64_tr_b16 v[128:129], v205 offset:8448
	ds_read_b64_tr_b16 v[130:131], v205 offset:12544
	s_waitcnt lgkmcnt(8)
	v_mfma_f32_32x32x16_bf16 v[112:127], v[206:209], v[250:253], v[112:127]
	ds_read_b64_tr_b16 v[206:207], v218 offset:8448
	ds_read_b64_tr_b16 v[208:209], v218 offset:12544
	v_max3_f32 v246, v222, v223, v224
	v_max3_f32 v247, v225, v226, v227
	v_max3_f32 v246, v246, v228, v229
	v_max3_f32 v247, v247, v230, v231
	v_max3_f32 v246, v246, v232, v233
	s_waitcnt lgkmcnt(8)
	v_mfma_f32_32x32x16_bf16 v[96:111], v[210:213], v[250:253], v[96:111]
	ds_read_b64_tr_b16 v[210:211], v219 offset:8448
	ds_read_b64_tr_b16 v[212:213], v219 offset:12544
	v_max3_f32 v247, v247, v234, v235
	v_max3_f32 v246, v246, v236, v237
	v_max_f32_e32 v246, v246, v247
	v_mov_b32_e32 v247, v246
	v_add_f32_e32 v249, 0x41000000, v190
	s_waitcnt lgkmcnt(8)
	v_mfma_f32_32x32x16_bf16 v[80:95], v[214:217], v[250:253], v[80:95]
	ds_read_b64_tr_b16 v[214:215], v221 offset:8448
	ds_read_b64_tr_b16 v[216:217], v221 offset:12544
	s_nop 1
	v_permlane32_swap_b32_e32 v246, v247
	v_max_f32_e32 v246, v246, v247
	v_cmp_gt_f32_e32 vcc, v246, v249
	s_cbranch_vccnz .Latt_rs1_1s0
	s_waitcnt lgkmcnt(8)
	v_mfma_f32_32x32x16_bf16 v[64:79], v[238:241], v[250:253], v[64:79]
	ds_read_b64_tr_b16 v[238:239], v205 offset:16384
	ds_read_b64_tr_b16 v[240:241], v205 offset:20480
	v_sub_f32_e32 v222, v222, v190
	v_exp_f32_e32 v222, v222
	v_sub_f32_e32 v223, v223, v190
	v_exp_f32_e32 v223, v223
	v_sub_f32_e32 v224, v224, v190
	v_add_f32_e32 v254, 0, v222
	s_waitcnt lgkmcnt(8)
	v_mfma_f32_32x32x16_bf16 v[48:63], v[128:131], v[250:253], v[48:63]
	ds_read_b64_tr_b16 v[128:129], v218 offset:16384
	ds_read_b64_tr_b16 v[130:131], v218 offset:20480
	v_exp_f32_e32 v224, v224
	v_sub_f32_e32 v225, v225, v190
	v_add_f32_e32 v254, v223, v254
	v_exp_f32_e32 v225, v225
	v_sub_f32_e32 v226, v226, v190
	v_add_f32_e32 v254, v224, v254
	s_waitcnt lgkmcnt(8)
	v_mfma_f32_32x32x16_bf16 v[32:47], v[206:209], v[250:253], v[32:47]
	ds_read_b64_tr_b16 v[206:207], v219 offset:16384
	ds_read_b64_tr_b16 v[208:209], v219 offset:20480
	v_exp_f32_e32 v226, v226
	v_sub_f32_e32 v227, v227, v190
	v_add_f32_e32 v254, v225, v254
	v_exp_f32_e32 v227, v227
	v_sub_f32_e32 v228, v228, v190
	s_waitcnt lgkmcnt(8)
	v_mfma_f32_32x32x16_bf16 v[16:31], v[210:213], v[250:253], v[16:31]
	ds_read_b64_tr_b16 v[210:211], v221 offset:16384
	ds_read_b64_tr_b16 v[212:213], v221 offset:20480
	v_add_f32_e32 v254, v226, v254
	v_exp_f32_e32 v228, v228
	v_sub_f32_e32 v229, v229, v190
	v_add_f32_e32 v254, v227, v254
	v_exp_f32_e32 v229, v229
	s_waitcnt lgkmcnt(8)
	v_mfma_f32_32x32x16_bf16 v[0:15], v[214:217], v[250:253], v[0:15]
	ds_read_b64_tr_b16 v[214:215], v205 offset:16640
	ds_read_b64_tr_b16 v[216:217], v205 offset:20736
	s_nop 0
	v_cvt_pk_bf16_f32 v242, v222, v223
	v_cvt_pk_bf16_f32 v243, v224, v225
	v_cvt_pk_bf16_f32 v244, v226, v227
	v_cvt_pk_bf16_f32 v245, v228, v229
	s_nop 1
	s_waitcnt lgkmcnt(8)
	v_mfma_f32_32x32x16_bf16 v[112:127], v[238:241], v[242:245], v[112:127]
	ds_read_b64_tr_b16 v[238:239], v218 offset:16640
	ds_read_b64_tr_b16 v[240:241], v218 offset:20736
	v_sub_f32_e32 v230, v230, v190
	v_add_f32_e32 v254, v228, v254
	v_exp_f32_e32 v230, v230
	v_sub_f32_e32 v231, v231, v190
	v_add_f32_e32 v254, v229, v254
	s_waitcnt lgkmcnt(8)
	v_mfma_f32_32x32x16_bf16 v[96:111], v[128:131], v[242:245], v[96:111]
	ds_read_b64_tr_b16 v[128:129], v219 offset:16640
	ds_read_b64_tr_b16 v[130:131], v219 offset:20736
	v_exp_f32_e32 v231, v231
	v_sub_f32_e32 v232, v232, v190
	v_add_f32_e32 v254, v230, v254
	v_exp_f32_e32 v232, v232
	v_sub_f32_e32 v233, v233, v190
	s_waitcnt lgkmcnt(8)
	v_mfma_f32_32x32x16_bf16 v[80:95], v[206:209], v[242:245], v[80:95]
	ds_read_b64_tr_b16 v[206:207], v221 offset:16640
	ds_read_b64_tr_b16 v[208:209], v221 offset:20736
	v_add_f32_e32 v254, v231, v254
	v_exp_f32_e32 v233, v233
	v_sub_f32_e32 v234, v234, v190
	v_add_f32_e32 v254, v232, v254
	s_waitcnt lgkmcnt(8)
	v_mfma_f32_32x32x16_bf16 v[64:79], v[210:213], v[242:245], v[64:79]
	ds_read_b64_tr_b16 v[210:211], v205 offset:24576
	ds_read_b64_tr_b16 v[212:213], v205 offset:28672
	v_exp_f32_e32 v234, v234
	v_sub_f32_e32 v235, v235, v190
	v_add_f32_e32 v254, v233, v254
	v_exp_f32_e32 v235, v235
	s_waitcnt lgkmcnt(8)
	v_mfma_f32_32x32x16_bf16 v[48:63], v[214:217], v[242:245], v[48:63]
	ds_read_b64_tr_b16 v[214:215], v218 offset:24576
	ds_read_b64_tr_b16 v[216:217], v218 offset:28672
	v_sub_f32_e32 v236, v236, v190
	v_add_f32_e32 v254, v234, v254
	v_exp_f32_e32 v236, v236
	v_sub_f32_e32 v237, v237, v190
	s_waitcnt lgkmcnt(8)
	v_mfma_f32_32x32x16_bf16 v[32:47], v[238:241], v[242:245], v[32:47]
	ds_read_b64_tr_b16 v[238:239], v219 offset:24576
	ds_read_b64_tr_b16 v[240:241], v219 offset:28672
	v_add_f32_e32 v254, v235, v254
	v_exp_f32_e32 v237, v237
	v_add_f32_e32 v254, v236, v254
	v_add_f32_e32 v254, v237, v254
	s_waitcnt lgkmcnt(8)
	v_mfma_f32_32x32x16_bf16 v[16:31], v[128:131], v[242:245], v[16:31]
	ds_read_b64_tr_b16 v[128:129], v221 offset:24576
	ds_read_b64_tr_b16 v[130:131], v221 offset:28672
	v_cvt_pk_bf16_f32 v250, v230, v231
	v_cvt_pk_bf16_f32 v251, v232, v233
	v_cvt_pk_bf16_f32 v252, v234, v235
	v_cvt_pk_bf16_f32 v253, v236, v237
	v_add_f32_e32 v195, v195, v254
	s_waitcnt lgkmcnt(8)
	v_mfma_f32_32x32x16_bf16 v[0:15], v[206:209], v[242:245], v[0:15]
	ds_read_b64_tr_b16 v[206:207], v205 offset:24832
	ds_read_b64_tr_b16 v[208:209], v205 offset:28928
	s_waitcnt lgkmcnt(8)
	v_mfma_f32_32x32x16_bf16 v[112:127], v[210:213], v[250:253], v[112:127]
	ds_read_b64_tr_b16 v[210:211], v218 offset:24832
	ds_read_b64_tr_b16 v[212:213], v218 offset:28928
	s_waitcnt lgkmcnt(8)
	v_mfma_f32_32x32x16_bf16 v[96:111], v[214:217], v[250:253], v[96:111]
	ds_read_b64_tr_b16 v[214:215], v219 offset:24832
	ds_read_b64_tr_b16 v[216:217], v219 offset:28928
	s_waitcnt lgkmcnt(8)
	v_mfma_f32_32x32x16_bf16 v[80:95], v[238:241], v[250:253], v[80:95]
	ds_read_b64_tr_b16 v[238:239], v221 offset:24832
	ds_read_b64_tr_b16 v[240:241], v221 offset:28928
	s_waitcnt lgkmcnt(8)
	v_mfma_f32_32x32x16_bf16 v[64:79], v[128:131], v[250:253], v[64:79]
	s_waitcnt lgkmcnt(6)
	v_mfma_f32_32x32x16_bf16 v[48:63], v[206:209], v[250:253], v[48:63]
	s_waitcnt lgkmcnt(4)
	v_mfma_f32_32x32x16_bf16 v[32:47], v[210:213], v[250:253], v[32:47]
	s_waitcnt lgkmcnt(2)
	v_mfma_f32_32x32x16_bf16 v[16:31], v[214:217], v[250:253], v[16:31]
	s_waitcnt lgkmcnt(0)
	v_mfma_f32_32x32x16_bf16 v[0:15], v[238:241], v[250:253], v[0:15]
	ds_read_b128 v[206:209], v196 offset:16384
	ds_read_b128 v[210:213], v197 offset:16384
	ds_read_b128 v[214:217], v198 offset:16384
	ds_read_b128 v[238:241], v199 offset:16384
	ds_read_b128 v[242:245], v200 offset:16384
	ds_read_b128 v[250:253], v201 offset:16384
	ds_read_b128 v[222:225], v202 offset:16384
	ds_read_b128 v[226:229], v203 offset:16384
	s_branch .Latt_end_1
.Latt_rs1_1s0:
	s_waitcnt lgkmcnt(8)
	v_mfma_f32_32x32x16_bf16 v[64:79], v[238:241], v[250:253], v[64:79]
	ds_read_b64_tr_b16 v[238:239], v205 offset:16384
	ds_read_b64_tr_b16 v[240:241], v205 offset:20480
	s_waitcnt lgkmcnt(8)
	v_mfma_f32_32x32x16_bf16 v[48:63], v[128:131], v[250:253], v[48:63]
	ds_read_b64_tr_b16 v[128:129], v218 offset:16384
	ds_read_b64_tr_b16 v[130:131], v218 offset:20480
	s_waitcnt lgkmcnt(8)
	v_mfma_f32_32x32x16_bf16 v[32:47], v[206:209], v[250:253], v[32:47]
	ds_read_b64_tr_b16 v[206:207], v219 offset:16384
	ds_read_b64_tr_b16 v[208:209], v219 offset:20480
	s_waitcnt lgkmcnt(8)
	v_mfma_f32_32x32x16_bf16 v[16:31], v[210:213], v[250:253], v[16:31]
	ds_read_b64_tr_b16 v[210:211], v221 offset:16384
	ds_read_b64_tr_b16 v[212:213], v221 offset:20480
	s_waitcnt lgkmcnt(8)
	v_mfma_f32_32x32x16_bf16 v[0:15], v[214:217], v[250:253], v[0:15]
	ds_read_b64_tr_b16 v[214:215], v205 offset:16640
	ds_read_b64_tr_b16 v[216:217], v205 offset:20736
	s_nop 11
	v_max_f32_e32 v246, v190, v246
	v_sub_f32_e32 v190, v190, v246
	v_exp_f32_e32 v190, v190
	s_nop 0
	v_pk_mul_f32 v[126:127], v[126:127], v[190:191] op_sel_hi:[1,0]
	v_pk_mul_f32 v[124:125], v[124:125], v[190:191] op_sel_hi:[1,0]
	v_pk_mul_f32 v[122:123], v[122:123], v[190:191] op_sel_hi:[1,0]
	v_pk_mul_f32 v[120:121], v[120:121], v[190:191] op_sel_hi:[1,0]
	v_pk_mul_f32 v[118:119], v[118:119], v[190:191] op_sel_hi:[1,0]
	v_pk_mul_f32 v[116:117], v[116:117], v[190:191] op_sel_hi:[1,0]
	v_pk_mul_f32 v[114:115], v[114:115], v[190:191] op_sel_hi:[1,0]
	v_pk_mul_f32 v[112:113], v[112:113], v[190:191] op_sel_hi:[1,0]
	v_pk_mul_f32 v[110:111], v[110:111], v[190:191] op_sel_hi:[1,0]
	v_pk_mul_f32 v[108:109], v[108:109], v[190:191] op_sel_hi:[1,0]
	v_pk_mul_f32 v[106:107], v[106:107], v[190:191] op_sel_hi:[1,0]
	v_pk_mul_f32 v[104:105], v[104:105], v[190:191] op_sel_hi:[1,0]
	v_pk_mul_f32 v[102:103], v[102:103], v[190:191] op_sel_hi:[1,0]
	v_pk_mul_f32 v[100:101], v[100:101], v[190:191] op_sel_hi:[1,0]
	v_pk_mul_f32 v[98:99], v[98:99], v[190:191] op_sel_hi:[1,0]
	v_pk_mul_f32 v[96:97], v[96:97], v[190:191] op_sel_hi:[1,0]
	v_pk_mul_f32 v[94:95], v[94:95], v[190:191] op_sel_hi:[1,0]
	v_pk_mul_f32 v[92:93], v[92:93], v[190:191] op_sel_hi:[1,0]
	v_pk_mul_f32 v[90:91], v[90:91], v[190:191] op_sel_hi:[1,0]
	v_pk_mul_f32 v[88:89], v[88:89], v[190:191] op_sel_hi:[1,0]
	v_pk_mul_f32 v[86:87], v[86:87], v[190:191] op_sel_hi:[1,0]
	v_pk_mul_f32 v[84:85], v[84:85], v[190:191] op_sel_hi:[1,0]
	v_pk_mul_f32 v[82:83], v[82:83], v[190:191] op_sel_hi:[1,0]
	v_pk_mul_f32 v[80:81], v[80:81], v[190:191] op_sel_hi:[1,0]
	v_pk_mul_f32 v[78:79], v[78:79], v[190:191] op_sel_hi:[1,0]
	v_pk_mul_f32 v[76:77], v[76:77], v[190:191] op_sel_hi:[1,0]
	v_pk_mul_f32 v[74:75], v[74:75], v[190:191] op_sel_hi:[1,0]
	v_pk_mul_f32 v[72:73], v[72:73], v[190:191] op_sel_hi:[1,0]
	v_pk_mul_f32 v[70:71], v[70:71], v[190:191] op_sel_hi:[1,0]
	v_pk_mul_f32 v[68:69], v[68:69], v[190:191] op_sel_hi:[1,0]
	v_pk_mul_f32 v[66:67], v[66:67], v[190:191] op_sel_hi:[1,0]
	v_pk_mul_f32 v[64:65], v[64:65], v[190:191] op_sel_hi:[1,0]
	v_pk_mul_f32 v[62:63], v[62:63], v[190:191] op_sel_hi:[1,0]
	v_pk_mul_f32 v[60:61], v[60:61], v[190:191] op_sel_hi:[1,0]
	v_pk_mul_f32 v[58:59], v[58:59], v[190:191] op_sel_hi:[1,0]
	v_pk_mul_f32 v[56:57], v[56:57], v[190:191] op_sel_hi:[1,0]
	v_pk_mul_f32 v[54:55], v[54:55], v[190:191] op_sel_hi:[1,0]
	v_pk_mul_f32 v[52:53], v[52:53], v[190:191] op_sel_hi:[1,0]
	v_pk_mul_f32 v[50:51], v[50:51], v[190:191] op_sel_hi:[1,0]
	v_pk_mul_f32 v[48:49], v[48:49], v[190:191] op_sel_hi:[1,0]
	v_pk_mul_f32 v[46:47], v[46:47], v[190:191] op_sel_hi:[1,0]
	v_pk_mul_f32 v[44:45], v[44:45], v[190:191] op_sel_hi:[1,0]
	v_pk_mul_f32 v[42:43], v[42:43], v[190:191] op_sel_hi:[1,0]
	v_pk_mul_f32 v[40:41], v[40:41], v[190:191] op_sel_hi:[1,0]
	v_pk_mul_f32 v[38:39], v[38:39], v[190:191] op_sel_hi:[1,0]
	v_pk_mul_f32 v[36:37], v[36:37], v[190:191] op_sel_hi:[1,0]
	v_pk_mul_f32 v[34:35], v[34:35], v[190:191] op_sel_hi:[1,0]
	v_pk_mul_f32 v[32:33], v[32:33], v[190:191] op_sel_hi:[1,0]
	v_pk_mul_f32 v[30:31], v[30:31], v[190:191] op_sel_hi:[1,0]
	v_pk_mul_f32 v[28:29], v[28:29], v[190:191] op_sel_hi:[1,0]
	v_pk_mul_f32 v[26:27], v[26:27], v[190:191] op_sel_hi:[1,0]
	v_pk_mul_f32 v[24:25], v[24:25], v[190:191] op_sel_hi:[1,0]
	v_pk_mul_f32 v[22:23], v[22:23], v[190:191] op_sel_hi:[1,0]
	v_pk_mul_f32 v[20:21], v[20:21], v[190:191] op_sel_hi:[1,0]
	v_pk_mul_f32 v[18:19], v[18:19], v[190:191] op_sel_hi:[1,0]
	v_pk_mul_f32 v[16:17], v[16:17], v[190:191] op_sel_hi:[1,0]
	v_pk_mul_f32 v[14:15], v[14:15], v[190:191] op_sel_hi:[1,0]
	v_pk_mul_f32 v[12:13], v[12:13], v[190:191] op_sel_hi:[1,0]
	v_pk_mul_f32 v[10:11], v[10:11], v[190:191] op_sel_hi:[1,0]
	v_pk_mul_f32 v[8:9], v[8:9], v[190:191] op_sel_hi:[1,0]
	v_pk_mul_f32 v[6:7], v[6:7], v[190:191] op_sel_hi:[1,0]
	v_pk_mul_f32 v[4:5], v[4:5], v[190:191] op_sel_hi:[1,0]
	v_pk_mul_f32 v[2:3], v[2:3], v[190:191] op_sel_hi:[1,0]
	v_pk_mul_f32 v[0:1], v[0:1], v[190:191] op_sel_hi:[1,0]
	v_mul_f32_e32 v195, v195, v190
	v_mov_b32_e32 v190, v246
	v_sub_f32_e32 v222, v222, v190
	v_exp_f32_e32 v222, v222
	v_sub_f32_e32 v223, v223, v190
	v_exp_f32_e32 v223, v223
	v_sub_f32_e32 v224, v224, v190
	v_add_f32_e32 v254, 0, v222
	v_exp_f32_e32 v224, v224
	v_sub_f32_e32 v225, v225, v190
	v_add_f32_e32 v254, v223, v254
	v_exp_f32_e32 v225, v225
	v_sub_f32_e32 v226, v226, v190
	v_add_f32_e32 v254, v224, v254
	v_exp_f32_e32 v226, v226
	v_sub_f32_e32 v227, v227, v190
	v_add_f32_e32 v254, v225, v254
	v_exp_f32_e32 v227, v227
	v_sub_f32_e32 v228, v228, v190
	v_add_f32_e32 v254, v226, v254
	v_exp_f32_e32 v228, v228
	v_sub_f32_e32 v229, v229, v190
	v_add_f32_e32 v254, v227, v254
	v_exp_f32_e32 v229, v229
	v_sub_f32_e32 v230, v230, v190
	v_add_f32_e32 v254, v228, v254
	v_exp_f32_e32 v230, v230
	v_sub_f32_e32 v231, v231, v190
	v_add_f32_e32 v254, v229, v254
	v_exp_f32_e32 v231, v231
	v_sub_f32_e32 v232, v232, v190
	v_add_f32_e32 v254, v230, v254
	v_exp_f32_e32 v232, v232
	v_sub_f32_e32 v233, v233, v190
	v_add_f32_e32 v254, v231, v254
	v_exp_f32_e32 v233, v233
	v_sub_f32_e32 v234, v234, v190
	v_add_f32_e32 v254, v232, v254
	v_exp_f32_e32 v234, v234
	v_sub_f32_e32 v235, v235, v190
	v_add_f32_e32 v254, v233, v254
	v_exp_f32_e32 v235, v235
	v_sub_f32_e32 v236, v236, v190
	v_add_f32_e32 v254, v234, v254
	v_exp_f32_e32 v236, v236
	v_sub_f32_e32 v237, v237, v190
	v_add_f32_e32 v254, v235, v254
	v_exp_f32_e32 v237, v237
	v_add_f32_e32 v254, v236, v254
	v_add_f32_e32 v254, v237, v254
	v_cvt_pk_bf16_f32 v242, v222, v223
	v_cvt_pk_bf16_f32 v243, v224, v225
	v_cvt_pk_bf16_f32 v244, v226, v227
	v_cvt_pk_bf16_f32 v245, v228, v229
	v_cvt_pk_bf16_f32 v250, v230, v231
	v_cvt_pk_bf16_f32 v251, v232, v233
	v_cvt_pk_bf16_f32 v252, v234, v235
	v_cvt_pk_bf16_f32 v253, v236, v237
	v_add_f32_e32 v195, v195, v254
	s_nop 1
	s_waitcnt lgkmcnt(8)
	v_mfma_f32_32x32x16_bf16 v[112:127], v[238:241], v[242:245], v[112:127]
	ds_read_b64_tr_b16 v[238:239], v218 offset:16640
	ds_read_b64_tr_b16 v[240:241], v218 offset:20736
	s_waitcnt lgkmcnt(8)
	v_mfma_f32_32x32x16_bf16 v[96:111], v[128:131], v[242:245], v[96:111]
	ds_read_b64_tr_b16 v[222:223], v219 offset:16640
	ds_read_b64_tr_b16 v[224:225], v219 offset:20736
	s_waitcnt lgkmcnt(8)
	v_mfma_f32_32x32x16_bf16 v[80:95], v[206:209], v[242:245], v[80:95]
	ds_read_b64_tr_b16 v[206:207], v221 offset:16640
	ds_read_b64_tr_b16 v[208:209], v221 offset:20736
	s_waitcnt lgkmcnt(8)
	v_mfma_f32_32x32x16_bf16 v[64:79], v[210:213], v[242:245], v[64:79]
	ds_read_b64_tr_b16 v[210:211], v205 offset:24576
	ds_read_b64_tr_b16 v[212:213], v205 offset:28672
	s_waitcnt lgkmcnt(8)
	v_mfma_f32_32x32x16_bf16 v[48:63], v[214:217], v[242:245], v[48:63]
	ds_read_b64_tr_b16 v[214:215], v218 offset:24576
	ds_read_b64_tr_b16 v[216:217], v218 offset:28672
	s_waitcnt lgkmcnt(8)
	v_mfma_f32_32x32x16_bf16 v[32:47], v[238:241], v[242:245], v[32:47]
	ds_read_b64_tr_b16 v[238:239], v219 offset:24576
	ds_read_b64_tr_b16 v[240:241], v219 offset:28672
	s_waitcnt lgkmcnt(8)
	v_mfma_f32_32x32x16_bf16 v[16:31], v[222:225], v[242:245], v[16:31]
	ds_read_b64_tr_b16 v[222:223], v221 offset:24576
	ds_read_b64_tr_b16 v[224:225], v221 offset:28672
	s_waitcnt lgkmcnt(8)
	v_mfma_f32_32x32x16_bf16 v[0:15], v[206:209], v[242:245], v[0:15]
	ds_read_b64_tr_b16 v[206:207], v205 offset:24832
	ds_read_b64_tr_b16 v[208:209], v205 offset:28928
	s_waitcnt lgkmcnt(8)
	v_mfma_f32_32x32x16_bf16 v[112:127], v[210:213], v[250:253], v[112:127]
	ds_read_b64_tr_b16 v[210:211], v218 offset:24832
	ds_read_b64_tr_b16 v[212:213], v218 offset:28928
	s_waitcnt lgkmcnt(8)
	v_mfma_f32_32x32x16_bf16 v[96:111], v[214:217], v[250:253], v[96:111]
	ds_read_b64_tr_b16 v[214:215], v219 offset:24832
	ds_read_b64_tr_b16 v[216:217], v219 offset:28928
	s_waitcnt lgkmcnt(8)
	v_mfma_f32_32x32x16_bf16 v[80:95], v[238:241], v[250:253], v[80:95]
	ds_read_b64_tr_b16 v[238:239], v221 offset:24832
	ds_read_b64_tr_b16 v[240:241], v221 offset:28928
	s_waitcnt lgkmcnt(8)
	v_mfma_f32_32x32x16_bf16 v[64:79], v[222:225], v[250:253], v[64:79]
	s_waitcnt lgkmcnt(6)
	v_mfma_f32_32x32x16_bf16 v[48:63], v[206:209], v[250:253], v[48:63]
	s_waitcnt lgkmcnt(4)
	v_mfma_f32_32x32x16_bf16 v[32:47], v[210:213], v[250:253], v[32:47]
	s_waitcnt lgkmcnt(2)
	v_mfma_f32_32x32x16_bf16 v[16:31], v[214:217], v[250:253], v[16:31]
	s_waitcnt lgkmcnt(0)
	v_mfma_f32_32x32x16_bf16 v[0:15], v[238:241], v[250:253], v[0:15]
	ds_read_b128 v[206:209], v196 offset:16384
	ds_read_b128 v[210:213], v197 offset:16384
	ds_read_b128 v[214:217], v198 offset:16384
	ds_read_b128 v[238:241], v199 offset:16384
	ds_read_b128 v[242:245], v200 offset:16384
	ds_read_b128 v[250:253], v201 offset:16384
	ds_read_b128 v[222:225], v202 offset:16384
	ds_read_b128 v[226:229], v203 offset:16384
	s_branch .Latt_end_1
.Latt_slow_1s0:
.Latt_slot1_1:
	v_add_u32_e32 v205, 0x8000, v205
	v_add_u32_e32 v218, 0x8000, v218
	v_add_u32_e32 v219, 0x8000, v219
	v_add_u32_e32 v221, 0x8000, v221
	s_waitcnt lgkmcnt(7)
	v_mfma_f32_32x32x16_bf16 v[128:143], v[206:209], v[144:147], 0
	ds_read_b128 v[206:209], v196 offset:24576
	s_cmp_lg_u64 s[18:19], 0
	s_cbranch_scc1 .Latt_nd0_1s1
	s_sub_i32 s100, s33, 1
	s_cmp_eq_u32 s33, 0
	s_cselect_b32 s100, 2, s100
	s_lshl_b32 s101, s100, 14
	s_add_i32 m0, s85, s101
	s_nop 0
	global_load_lds_dwordx4 v178, s[12:13]
.Latt_nd0_1s1:
	s_waitcnt lgkmcnt(7)
	v_mfma_f32_32x32x16_bf16 v[128:143], v[210:213], v[148:151], v[128:143]
	ds_read_b128 v[210:213], v197 offset:24576
	s_cmp_lg_u64 s[18:19], 0
	s_cbranch_scc1 .Latt_nd1_1s1
	s_add_i32 m0, m0, 0x400
	s_nop 0
	global_load_lds_dwordx4 v180, s[12:13]
.Latt_nd1_1s1:
	s_waitcnt lgkmcnt(7)
	v_mfma_f32_32x32x16_bf16 v[128:143], v[214:217], v[152:155], v[128:143]
	ds_read_b128 v[214:217], v198 offset:24576
	s_cmp_lg_u64 s[18:19], 0
	s_cbranch_scc1 .Latt_nd2_1s1
	s_lshl_b32 s101, s100, 15
	s_add_i32 m0, s86, s101
	s_add_u32 s100, s12, 0xf00
	s_addc_u32 s101, s13, 0
	global_load_lds_dwordx4 v182, s[100:101]
.Latt_nd2_1s1:
	s_waitcnt lgkmcnt(7)
	v_mfma_f32_32x32x16_bf16 v[128:143], v[238:241], v[156:159], v[128:143]
	ds_read_b128 v[238:241], v199 offset:24576
	s_cmp_lg_u64 s[18:19], 0
	s_cbranch_scc1 .Latt_nd3_1s1
	s_add_i32 m0, m0, 0x400
	s_nop 0
	global_load_lds_dwordx4 v184, s[100:101]

.Latt_nd5_1s1:
	s_waitcnt lgkmcnt(5)
	v_mfma_f32_32x32x16_bf16 v[128:143], v[222:225], v[168:171], v[128:143]
	s_waitcnt lgkmcnt(4)
	v_mfma_f32_32x32x16_bf16 v[128:143], v[226:229], v[172:175], v[128:143]
	s_waitcnt lgkmcnt(3)
	v_mfma_f32_32x32x16_bf16 v[222:237], v[206:209], v[144:147], 0
	ds_read_b128 v[206:209], v200 offset:24576
	s_nop 8
	v_max3_f32 v246, v128, v129, v130
	v_max3_f32 v247, v131, v132, v133
	v_max3_f32 v246, v246, v134, v135
	v_max3_f32 v247, v247, v136, v137
	v_max3_f32 v246, v246, v138, v139
	v_max3_f32 v247, v247, v140, v141
	v_max3_f32 v246, v246, v142, v143
	s_waitcnt lgkmcnt(3)
	v_mfma_f32_32x32x16_bf16 v[222:237], v[210:213], v[148:151], v[222:237]
	ds_read_b128 v[210:213], v201 offset:24576
	v_max_f32_e32 v246, v246, v247
	v_mov_b32_e32 v247, v246
	v_add_f32_e32 v249, 0x41000000, v190
	s_nop 1
	v_permlane32_swap_b32_e32 v246, v247
	v_max_f32_e32 v246, v246, v247
	v_cmp_gt_f32_e32 vcc, v246, v249
	s_cbranch_vccz .Latt_nr0_1s1
	v_max_f32_e32 v246, v190, v246
	v_sub_f32_e32 v190, v190, v246
	v_exp_f32_e32 v190, v190
	s_nop 0
	v_pk_mul_f32 v[126:127], v[126:127], v[190:191] op_sel_hi:[1,0]
	v_pk_mul_f32 v[124:125], v[124:125], v[190:191] op_sel_hi:[1,0]
	v_pk_mul_f32 v[122:123], v[122:123], v[190:191] op_sel_hi:[1,0]
	v_pk_mul_f32 v[120:121], v[120:121], v[190:191] op_sel_hi:[1,0]
	v_pk_mul_f32 v[118:119], v[118:119], v[190:191] op_sel_hi:[1,0]
	v_pk_mul_f32 v[116:117], v[116:117], v[190:191] op_sel_hi:[1,0]
	v_pk_mul_f32 v[114:115], v[114:115], v[190:191] op_sel_hi:[1,0]
	v_pk_mul_f32 v[112:113], v[112:113], v[190:191] op_sel_hi:[1,0]
	v_pk_mul_f32 v[110:111], v[110:111], v[190:191] op_sel_hi:[1,0]
	v_pk_mul_f32 v[108:109], v[108:109], v[190:191] op_sel_hi:[1,0]
	v_pk_mul_f32 v[106:107], v[106:107], v[190:191] op_sel_hi:[1,0]
	v_pk_mul_f32 v[104:105], v[104:105], v[190:191] op_sel_hi:[1,0]
	v_pk_mul_f32 v[102:103], v[102:103], v[190:191] op_sel_hi:[1,0]
	v_pk_mul_f32 v[100:101], v[100:101], v[190:191] op_sel_hi:[1,0]
	v_pk_mul_f32 v[98:99], v[98:99], v[190:191] op_sel_hi:[1,0]
	v_pk_mul_f32 v[96:97], v[96:97], v[190:191] op_sel_hi:[1,0]
	v_pk_mul_f32 v[94:95], v[94:95], v[190:191] op_sel_hi:[1,0]
	v_pk_mul_f32 v[92:93], v[92:93], v[190:191] op_sel_hi:[1,0]
	v_pk_mul_f32 v[90:91], v[90:91], v[190:191] op_sel_hi:[1,0]
	v_pk_mul_f32 v[88:89], v[88:89], v[190:191] op_sel_hi:[1,0]
	v_pk_mul_f32 v[86:87], v[86:87], v[190:191] op_sel_hi:[1,0]
	v_pk_mul_f32 v[84:85], v[84:85], v[190:191] op_sel_hi:[1,0]
	v_pk_mul_f32 v[82:83], v[82:83], v[190:191] op_sel_hi:[1,0]
	v_pk_mul_f32 v[80:81], v[80:81], v[190:191] op_sel_hi:[1,0]
	v_pk_mul_f32 v[78:79], v[78:79], v[190:191] op_sel_hi:[1,0]
	v_pk_mul_f32 v[76:77], v[76:77], v[190:191] op_sel_hi:[1,0]
	v_pk_mul_f32 v[74:75], v[74:75], v[190:191] op_sel_hi:[1,0]
	v_pk_mul_f32 v[72:73], v[72:73], v[190:191] op_sel_hi:[1,0]
	v_pk_mul_f32 v[70:71], v[70:71], v[190:191] op_sel_hi:[1,0]
	v_pk_mul_f32 v[68:69], v[68:69], v[190:191] op_sel_hi:[1,0]
	v_pk_mul_f32 v[66:67], v[66:67], v[190:191] op_sel_hi:[1,0]
	v_pk_mul_f32 v[64:65], v[64:65], v[190:191] op_sel_hi:[1,0]
	v_pk_mul_f32 v[62:63], v[62:63], v[190:191] op_sel_hi:[1,0]
	v_pk_mul_f32 v[60:61], v[60:61], v[190:191] op_sel_hi:[1,0]
	v_pk_mul_f32 v[58:59], v[58:59], v[190:191] op_sel_hi:[1,0]
	v_pk_mul_f32 v[56:57], v[56:57], v[190:191] op_sel_hi:[1,0]
	v_pk_mul_f32 v[54:55], v[54:55], v[190:191] op_sel_hi:[1,0]
	v_pk_mul_f32 v[52:53], v[52:53], v[190:191] op_sel_hi:[1,0]
	v_pk_mul_f32 v[50:51], v[50:51], v[190:191] op_sel_hi:[1,0]
	v_pk_mul_f32 v[48:49], v[48:49], v[190:191] op_sel_hi:[1,0]
	v_pk_mul_f32 v[46:47], v[46:47], v[190:191] op_sel_hi:[1,0]
	v_pk_mul_f32 v[44:45], v[44:45], v[190:191] op_sel_hi:[1,0]
	v_pk_mul_f32 v[42:43], v[42:43], v[190:191] op_sel_hi:[1,0]
	v_pk_mul_f32 v[40:41], v[40:41], v[190:191] op_sel_hi:[1,0]
	v_pk_mul_f32 v[38:39], v[38:39], v[190:191] op_sel_hi:[1,0]
	v_pk_mul_f32 v[36:37], v[36:37], v[190:191] op_sel_hi:[1,0]
	v_pk_mul_f32 v[34:35], v[34:35], v[190:191] op_sel_hi:[1,0]
	v_pk_mul_f32 v[32:33], v[32:33], v[190:191] op_sel_hi:[1,0]
	v_pk_mul_f32 v[30:31], v[30:31], v[190:191] op_sel_hi:[1,0]
	v_pk_mul_f32 v[28:29], v[28:29], v[190:191] op_sel_hi:[1,0]
	v_pk_mul_f32 v[26:27], v[26:27], v[190:191] op_sel_hi:[1,0]
	v_pk_mul_f32 v[24:25], v[24:25], v[190:191] op_sel_hi:[1,0]
	v_pk_mul_f32 v[22:23], v[22:23], v[190:191] op_sel_hi:[1,0]
	v_pk_mul_f32 v[20:21], v[20:21], v[190:191] op_sel_hi:[1,0]
	v_pk_mul_f32 v[18:19], v[18:19], v[190:191] op_sel_hi:[1,0]
	v_pk_mul_f32 v[16:17], v[16:17], v[190:191] op_sel_hi:[1,0]
	v_pk_mul_f32 v[14:15], v[14:15], v[190:191] op_sel_hi:[1,0]
	v_pk_mul_f32 v[12:13], v[12:13], v[190:191] op_sel_hi:[1,0]
	v_pk_mul_f32 v[10:11], v[10:11], v[190:191] op_sel_hi:[1,0]
	v_pk_mul_f32 v[8:9], v[8:9], v[190:191] op_sel_hi:[1,0]
	v_pk_mul_f32 v[6:7], v[6:7], v[190:191] op_sel_hi:[1,0]
	v_pk_mul_f32 v[4:5], v[4:5], v[190:191] op_sel_hi:[1,0]
	v_pk_mul_f32 v[2:3], v[2:3], v[190:191] op_sel_hi:[1,0]
	v_pk_mul_f32 v[0:1], v[0:1], v[190:191] op_sel_hi:[1,0]
	v_mul_f32_e32 v195, v195, v190
	v_mov_b32_e32 v190, v246
.Latt_nr0_1s1:
	s_waitcnt lgkmcnt(3)
	v_mfma_f32_32x32x16_bf16 v[222:237], v[214:217], v[152:155], v[222:237]
	ds_read_b128 v[214:217], v202 offset:24576
	v_sub_f32_e32 v128, v128, v190
	v_exp_f32_e32 v128, v128
	v_sub_f32_e32 v129, v129, v190
	v_exp_f32_e32 v129, v129
	v_sub_f32_e32 v130, v130, v190
	s_waitcnt lgkmcnt(3)
	v_mfma_f32_32x32x16_bf16 v[222:237], v[238:241], v[156:159], v[222:237]
	ds_read_b128 v[238:241], v203 offset:24576
	v_add_f32_e32 v254, 0, v128
	v_exp_f32_e32 v130, v130
	v_sub_f32_e32 v131, v131, v190
	v_add_f32_e32 v254, v129, v254
	v_exp_f32_e32 v131, v131
	s_waitcnt lgkmcnt(3)
	v_mfma_f32_32x32x16_bf16 v[222:237], v[206:209], v[160:163], v[222:237]
	ds_read_b64_tr_b16 v[206:207], v205
	ds_read_b64_tr_b16 v[208:209], v205 offset:4096
	v_sub_f32_e32 v132, v132, v190
	v_add_f32_e32 v254, v130, v254
	v_exp_f32_e32 v132, v132
	v_sub_f32_e32 v133, v133, v190
	v_add_f32_e32 v254, v131, v254
	s_waitcnt lgkmcnt(4)
	v_mfma_f32_32x32x16_bf16 v[222:237], v[210:213], v[164:167], v[222:237]
	ds_read_b64_tr_b16 v[210:211], v218
	ds_read_b64_tr_b16 v[212:213], v218 offset:4096
	v_exp_f32_e32 v133, v133
	v_sub_f32_e32 v134, v134, v190
	v_add_f32_e32 v254, v132, v254
	v_exp_f32_e32 v134, v134
	s_waitcnt lgkmcnt(5)
	v_mfma_f32_32x32x16_bf16 v[222:237], v[214:217], v[168:171], v[222:237]
	ds_read_b64_tr_b16 v[214:215], v219
	ds_read_b64_tr_b16 v[216:217], v219 offset:4096
	v_sub_f32_e32 v135, v135, v190
	v_add_f32_e32 v254, v133, v254
	v_exp_f32_e32 v135, v135
	s_nop 0
	s_waitcnt lgkmcnt(6)
	v_mfma_f32_32x32x16_bf16 v[222:237], v[238:241], v[172:175], v[222:237]
	ds_read_b64_tr_b16 v[238:239], v221
	ds_read_b64_tr_b16 v[240:241], v221 offset:4096
	v_cvt_pk_bf16_f32 v242, v128, v129
	v_cvt_pk_bf16_f32 v243, v130, v131
	v_cvt_pk_bf16_f32 v244, v132, v133
	v_cvt_pk_bf16_f32 v245, v134, v135
	s_nop 1
	s_waitcnt lgkmcnt(6)
	v_mfma_f32_32x32x16_bf16 v[112:127], v[206:209], v[242:245], v[112:127]
	ds_read_b64_tr_b16 v[206:207], v205 offset:256
	ds_read_b64_tr_b16 v[208:209], v205 offset:4352
	v_sub_f32_e32 v136, v136, v190
	v_add_f32_e32 v254, v134, v254
	v_exp_f32_e32 v136, v136
	v_sub_f32_e32 v137, v137, v190
	v_add_f32_e32 v254, v135, v254
	s_waitcnt lgkmcnt(6)
	v_mfma_f32_32x32x16_bf16 v[96:111], v[210:213], v[242:245], v[96:111]
	ds_read_b64_tr_b16 v[210:211], v218 offset:256
	ds_read_b64_tr_b16 v[212:213], v218 offset:4352
	v_exp_f32_e32 v137, v137
	v_sub_f32_e32 v138, v138, v190
	v_add_f32_e32 v254, v136, v254
	v_exp_f32_e32 v138, v138
	v_sub_f32_e32 v139, v139, v190
	s_waitcnt lgkmcnt(6)
	v_mfma_f32_32x32x16_bf16 v[80:95], v[214:217], v[242:245], v[80:95]
	ds_read_b64_tr_b16 v[214:215], v219 offset:256
	ds_read_b64_tr_b16 v[216:217], v219 offset:4352
	v_add_f32_e32 v254, v137, v254
	v_exp_f32_e32 v139, v139
	v_sub_f32_e32 v140, v140, v190
	v_add_f32_e32 v254, v138, v254
	s_waitcnt lgkmcnt(6)
	v_mfma_f32_32x32x16_bf16 v[64:79], v[238:241], v[242:245], v[64:79]
	ds_read_b64_tr_b16 v[238:239], v221 offset:256
	ds_read_b64_tr_b16 v[240:241], v221 offset:4352
	v_exp_f32_e32 v140, v140
	v_sub_f32_e32 v141, v141, v190
	v_add_f32_e32 v254, v139, v254
	v_exp_f32_e32 v141, v141
	s_waitcnt lgkmcnt(6)
	v_mfma_f32_32x32x16_bf16 v[48:63], v[206:209], v[242:245], v[48:63]
	ds_read_b64_tr_b16 v[206:207], v205 offset:8192
	ds_read_b64_tr_b16 v[208:209], v205 offset:12288
	v_sub_f32_e32 v142, v142, v190
	v_add_f32_e32 v254, v140, v254
	v_exp_f32_e32 v142, v142
	v_sub_f32_e32 v143, v143, v190
	s_waitcnt lgkmcnt(6)
	v_mfma_f32_32x32x16_bf16 v[32:47], v[210:213], v[242:245], v[32:47]
	ds_read_b64_tr_b16 v[210:211], v218 offset:8192
	ds_read_b64_tr_b16 v[212:213], v218 offset:12288
	v_add_f32_e32 v254, v141, v254
	v_exp_f32_e32 v143, v143
	v_add_f32_e32 v254, v142, v254
	v_add_f32_e32 v254, v143, v254
	s_waitcnt lgkmcnt(6)
	v_mfma_f32_32x32x16_bf16 v[16:31], v[214:217], v[242:245], v[16:31]
	ds_read_b64_tr_b16 v[214:215], v219 offset:8192
	ds_read_b64_tr_b16 v[216:217], v219 offset:12288
	v_cvt_pk_bf16_f32 v250, v136, v137
	v_cvt_pk_bf16_f32 v251, v138, v139
	v_cvt_pk_bf16_f32 v252, v140, v141
	v_cvt_pk_bf16_f32 v253, v142, v143
	v_add_f32_e32 v195, v195, v254
	s_waitcnt lgkmcnt(6)
	v_mfma_f32_32x32x16_bf16 v[0:15], v[238:241], v[242:245], v[0:15]
	ds_read_b64_tr_b16 v[238:239], v221 offset:8192
	ds_read_b64_tr_b16 v[240:241], v221 offset:12288
	ds_read_b64_tr_b16 v[128:129], v205 offset:8448
	ds_read_b64_tr_b16 v[130:131], v205 offset:12544
	s_waitcnt lgkmcnt(8)
	v_mfma_f32_32x32x16_bf16 v[112:127], v[206:209], v[250:253], v[112:127]
	ds_read_b64_tr_b16 v[206:207], v218 offset:8448
	ds_read_b64_tr_b16 v[208:209], v218 offset:12544
	v_max3_f32 v246, v222, v223, v224
	v_max3_f32 v247, v225, v226, v227
	v_max3_f32 v246, v246, v228, v229
	v_max3_f32 v247, v247, v230, v231
	v_max3_f32 v246, v246, v232, v233
	s_waitcnt lgkmcnt(8)
	v_mfma_f32_32x32x16_bf16 v[96:111], v[210:213], v[250:253], v[96:111]
	ds_read_b64_tr_b16 v[210:211], v219 offset:8448
	ds_read_b64_tr_b16 v[212:213], v219 offset:12544
	v_max3_f32 v247, v247, v234, v235
	v_max3_f32 v246, v246, v236, v237
	v_max_f32_e32 v246, v246, v247
	v_mov_b32_e32 v247, v246
	v_add_f32_e32 v249, 0x41000000, v190
	s_waitcnt lgkmcnt(8)
	v_mfma_f32_32x32x16_bf16 v[80:95], v[214:217], v[250:253], v[80:95]
	ds_read_b64_tr_b16 v[214:215], v221 offset:8448
	ds_read_b64_tr_b16 v[216:217], v221 offset:12544
	s_nop 1
	v_permlane32_swap_b32_e32 v246, v247
	v_max_f32_e32 v246, v246, v247
	v_cmp_gt_f32_e32 vcc, v246, v249
	s_cbranch_vccnz .Latt_rs1_1s1
	s_waitcnt lgkmcnt(8)
	v_mfma_f32_32x32x16_bf16 v[64:79], v[238:241], v[250:253], v[64:79]
	ds_read_b64_tr_b16 v[238:239], v205 offset:16384
	ds_read_b64_tr_b16 v[240:241], v205 offset:20480
	v_sub_f32_e32 v222, v222, v190
	v_exp_f32_e32 v222, v222
	v_sub_f32_e32 v223, v223, v190
	v_exp_f32_e32 v223, v223
	v_sub_f32_e32 v224, v224, v190
	v_add_f32_e32 v254, 0, v222
	s_waitcnt lgkmcnt(8)
	v_mfma_f32_32x32x16_bf16 v[48:63], v[128:131], v[250:253], v[48:63]
	ds_read_b64_tr_b16 v[128:129], v218 offset:16384
	ds_read_b64_tr_b16 v[130:131], v218 offset:20480
	v_exp_f32_e32 v224, v224
	v_sub_f32_e32 v225, v225, v190
	v_add_f32_e32 v254, v223, v254
	v_exp_f32_e32 v225, v225
	v_sub_f32_e32 v226, v226, v190
	v_add_f32_e32 v254, v224, v254
	s_waitcnt lgkmcnt(8)
	v_mfma_f32_32x32x16_bf16 v[32:47], v[206:209], v[250:253], v[32:47]
	ds_read_b64_tr_b16 v[206:207], v219 offset:16384
	ds_read_b64_tr_b16 v[208:209], v219 offset:20480
	v_exp_f32_e32 v226, v226
	v_sub_f32_e32 v227, v227, v190
	v_add_f32_e32 v254, v225, v254
	v_exp_f32_e32 v227, v227
	v_sub_f32_e32 v228, v228, v190
	s_waitcnt lgkmcnt(8)
	v_mfma_f32_32x32x16_bf16 v[16:31], v[210:213], v[250:253], v[16:31]
	ds_read_b64_tr_b16 v[210:211], v221 offset:16384
	ds_read_b64_tr_b16 v[212:213], v221 offset:20480
	v_add_f32_e32 v254, v226, v254
	v_exp_f32_e32 v228, v228
	v_sub_f32_e32 v229, v229, v190
	v_add_f32_e32 v254, v227, v254
	v_exp_f32_e32 v229, v229
	s_waitcnt lgkmcnt(8)
	v_mfma_f32_32x32x16_bf16 v[0:15], v[214:217], v[250:253], v[0:15]
	ds_read_b64_tr_b16 v[214:215], v205 offset:16640
	ds_read_b64_tr_b16 v[216:217], v205 offset:20736
	s_nop 0
	v_cvt_pk_bf16_f32 v242, v222, v223
	v_cvt_pk_bf16_f32 v243, v224, v225
	v_cvt_pk_bf16_f32 v244, v226, v227
	v_cvt_pk_bf16_f32 v245, v228, v229
	s_nop 1
	s_waitcnt lgkmcnt(8)
	v_mfma_f32_32x32x16_bf16 v[112:127], v[238:241], v[242:245], v[112:127]
	ds_read_b64_tr_b16 v[238:239], v218 offset:16640
	ds_read_b64_tr_b16 v[240:241], v218 offset:20736
	v_sub_f32_e32 v230, v230, v190
	v_add_f32_e32 v254, v228, v254
	v_exp_f32_e32 v230, v230
	v_sub_f32_e32 v231, v231, v190
	v_add_f32_e32 v254, v229, v254
	s_waitcnt lgkmcnt(8)
	v_mfma_f32_32x32x16_bf16 v[96:111], v[128:131], v[242:245], v[96:111]
	ds_read_b64_tr_b16 v[128:129], v219 offset:16640
	ds_read_b64_tr_b16 v[130:131], v219 offset:20736
	v_exp_f32_e32 v231, v231
	v_sub_f32_e32 v232, v232, v190
	v_add_f32_e32 v254, v230, v254
	v_exp_f32_e32 v232, v232
	v_sub_f32_e32 v233, v233, v190
	s_waitcnt lgkmcnt(8)
	v_mfma_f32_32x32x16_bf16 v[80:95], v[206:209], v[242:245], v[80:95]
	ds_read_b64_tr_b16 v[206:207], v221 offset:16640
	ds_read_b64_tr_b16 v[208:209], v221 offset:20736
	v_add_f32_e32 v254, v231, v254
	v_exp_f32_e32 v233, v233
	v_sub_f32_e32 v234, v234, v190
	v_add_f32_e32 v254, v232, v254
	s_waitcnt lgkmcnt(8)
	v_mfma_f32_32x32x16_bf16 v[64:79], v[210:213], v[242:245], v[64:79]
	ds_read_b64_tr_b16 v[210:211], v205 offset:24576
	ds_read_b64_tr_b16 v[212:213], v205 offset:28672
	v_exp_f32_e32 v234, v234
	v_sub_f32_e32 v235, v235, v190
	v_add_f32_e32 v254, v233, v254
	v_exp_f32_e32 v235, v235
	s_waitcnt lgkmcnt(8)
	v_mfma_f32_32x32x16_bf16 v[48:63], v[214:217], v[242:245], v[48:63]
	ds_read_b64_tr_b16 v[214:215], v218 offset:24576
	ds_read_b64_tr_b16 v[216:217], v218 offset:28672
	v_sub_f32_e32 v236, v236, v190
	v_add_f32_e32 v254, v234, v254
	v_exp_f32_e32 v236, v236
	v_sub_f32_e32 v237, v237, v190
	s_waitcnt lgkmcnt(8)
	v_mfma_f32_32x32x16_bf16 v[32:47], v[238:241], v[242:245], v[32:47]
	ds_read_b64_tr_b16 v[238:239], v219 offset:24576
	ds_read_b64_tr_b16 v[240:241], v219 offset:28672
	v_add_f32_e32 v254, v235, v254
	v_exp_f32_e32 v237, v237
	v_add_f32_e32 v254, v236, v254
	v_add_f32_e32 v254, v237, v254
	s_waitcnt lgkmcnt(8)
	v_mfma_f32_32x32x16_bf16 v[16:31], v[128:131], v[242:245], v[16:31]
	ds_read_b64_tr_b16 v[128:129], v221 offset:24576
	ds_read_b64_tr_b16 v[130:131], v221 offset:28672
	v_cvt_pk_bf16_f32 v250, v230, v231
	v_cvt_pk_bf16_f32 v251, v232, v233
	v_cvt_pk_bf16_f32 v252, v234, v235
	v_cvt_pk_bf16_f32 v253, v236, v237
	v_add_f32_e32 v195, v195, v254
	s_waitcnt lgkmcnt(8)
	v_mfma_f32_32x32x16_bf16 v[0:15], v[206:209], v[242:245], v[0:15]
	ds_read_b64_tr_b16 v[206:207], v205 offset:24832
	ds_read_b64_tr_b16 v[208:209], v205 offset:28928
	s_waitcnt lgkmcnt(8)
	v_mfma_f32_32x32x16_bf16 v[112:127], v[210:213], v[250:253], v[112:127]
	ds_read_b64_tr_b16 v[210:211], v218 offset:24832
	ds_read_b64_tr_b16 v[212:213], v218 offset:28928
	s_waitcnt lgkmcnt(8)
	v_mfma_f32_32x32x16_bf16 v[96:111], v[214:217], v[250:253], v[96:111]
	ds_read_b64_tr_b16 v[214:215], v219 offset:24832
	ds_read_b64_tr_b16 v[216:217], v219 offset:28928
	s_waitcnt lgkmcnt(8)
	v_mfma_f32_32x32x16_bf16 v[80:95], v[238:241], v[250:253], v[80:95]
	ds_read_b64_tr_b16 v[238:239], v221 offset:24832
	ds_read_b64_tr_b16 v[240:241], v221 offset:28928
	s_waitcnt lgkmcnt(8)
	v_mfma_f32_32x32x16_bf16 v[64:79], v[128:131], v[250:253], v[64:79]
	s_waitcnt lgkmcnt(6)
	v_mfma_f32_32x32x16_bf16 v[48:63], v[206:209], v[250:253], v[48:63]
	s_waitcnt lgkmcnt(4)
	v_mfma_f32_32x32x16_bf16 v[32:47], v[210:213], v[250:253], v[32:47]
	s_waitcnt lgkmcnt(2)
	v_mfma_f32_32x32x16_bf16 v[16:31], v[214:217], v[250:253], v[16:31]
	s_waitcnt lgkmcnt(0)
	v_mfma_f32_32x32x16_bf16 v[0:15], v[238:241], v[250:253], v[0:15]
	ds_read_b128 v[206:209], v196 offset:32768
	ds_read_b128 v[210:213], v197 offset:32768
	ds_read_b128 v[214:217], v198 offset:32768
	ds_read_b128 v[238:241], v199 offset:32768
	ds_read_b128 v[242:245], v200 offset:32768
	ds_read_b128 v[250:253], v201 offset:32768
	ds_read_b128 v[222:225], v202 offset:32768
	ds_read_b128 v[226:229], v203 offset:32768
	s_branch .Latt_end_1
.Latt_rs1_1s1:
	s_waitcnt lgkmcnt(8)
	v_mfma_f32_32x32x16_bf16 v[64:79], v[238:241], v[250:253], v[64:79]
	ds_read_b64_tr_b16 v[238:239], v205 offset:16384
	ds_read_b64_tr_b16 v[240:241], v205 offset:20480
	s_waitcnt lgkmcnt(8)
	v_mfma_f32_32x32x16_bf16 v[48:63], v[128:131], v[250:253], v[48:63]
	ds_read_b64_tr_b16 v[128:129], v218 offset:16384
	ds_read_b64_tr_b16 v[130:131], v218 offset:20480
	s_waitcnt lgkmcnt(8)
	v_mfma_f32_32x32x16_bf16 v[32:47], v[206:209], v[250:253], v[32:47]
	ds_read_b64_tr_b16 v[206:207], v219 offset:16384
	ds_read_b64_tr_b16 v[208:209], v219 offset:20480
	s_waitcnt lgkmcnt(8)
	v_mfma_f32_32x32x16_bf16 v[16:31], v[210:213], v[250:253], v[16:31]
	ds_read_b64_tr_b16 v[210:211], v221 offset:16384
	ds_read_b64_tr_b16 v[212:213], v221 offset:20480
	s_waitcnt lgkmcnt(8)
	v_mfma_f32_32x32x16_bf16 v[0:15], v[214:217], v[250:253], v[0:15]
	ds_read_b64_tr_b16 v[214:215], v205 offset:16640
	ds_read_b64_tr_b16 v[216:217], v205 offset:20736
	s_nop 11
	v_max_f32_e32 v246, v190, v246
	v_sub_f32_e32 v190, v190, v246
	v_exp_f32_e32 v190, v190
	s_nop 0
	v_pk_mul_f32 v[126:127], v[126:127], v[190:191] op_sel_hi:[1,0]
	v_pk_mul_f32 v[124:125], v[124:125], v[190:191] op_sel_hi:[1,0]
	v_pk_mul_f32 v[122:123], v[122:123], v[190:191] op_sel_hi:[1,0]
	v_pk_mul_f32 v[120:121], v[120:121], v[190:191] op_sel_hi:[1,0]
	v_pk_mul_f32 v[118:119], v[118:119], v[190:191] op_sel_hi:[1,0]
	v_pk_mul_f32 v[116:117], v[116:117], v[190:191] op_sel_hi:[1,0]
	v_pk_mul_f32 v[114:115], v[114:115], v[190:191] op_sel_hi:[1,0]
	v_pk_mul_f32 v[112:113], v[112:113], v[190:191] op_sel_hi:[1,0]
	v_pk_mul_f32 v[110:111], v[110:111], v[190:191] op_sel_hi:[1,0]
	v_pk_mul_f32 v[108:109], v[108:109], v[190:191] op_sel_hi:[1,0]
	v_pk_mul_f32 v[106:107], v[106:107], v[190:191] op_sel_hi:[1,0]
	v_pk_mul_f32 v[104:105], v[104:105], v[190:191] op_sel_hi:[1,0]
	v_pk_mul_f32 v[102:103], v[102:103], v[190:191] op_sel_hi:[1,0]
	v_pk_mul_f32 v[100:101], v[100:101], v[190:191] op_sel_hi:[1,0]
	v_pk_mul_f32 v[98:99], v[98:99], v[190:191] op_sel_hi:[1,0]
	v_pk_mul_f32 v[96:97], v[96:97], v[190:191] op_sel_hi:[1,0]
	v_pk_mul_f32 v[94:95], v[94:95], v[190:191] op_sel_hi:[1,0]
	v_pk_mul_f32 v[92:93], v[92:93], v[190:191] op_sel_hi:[1,0]
	v_pk_mul_f32 v[90:91], v[90:91], v[190:191] op_sel_hi:[1,0]
	v_pk_mul_f32 v[88:89], v[88:89], v[190:191] op_sel_hi:[1,0]
	v_pk_mul_f32 v[86:87], v[86:87], v[190:191] op_sel_hi:[1,0]
	v_pk_mul_f32 v[84:85], v[84:85], v[190:191] op_sel_hi:[1,0]
	v_pk_mul_f32 v[82:83], v[82:83], v[190:191] op_sel_hi:[1,0]
	v_pk_mul_f32 v[80:81], v[80:81], v[190:191] op_sel_hi:[1,0]
	v_pk_mul_f32 v[78:79], v[78:79], v[190:191] op_sel_hi:[1,0]
	v_pk_mul_f32 v[76:77], v[76:77], v[190:191] op_sel_hi:[1,0]
	v_pk_mul_f32 v[74:75], v[74:75], v[190:191] op_sel_hi:[1,0]
	v_pk_mul_f32 v[72:73], v[72:73], v[190:191] op_sel_hi:[1,0]
	v_pk_mul_f32 v[70:71], v[70:71], v[190:191] op_sel_hi:[1,0]
	v_pk_mul_f32 v[68:69], v[68:69], v[190:191] op_sel_hi:[1,0]
	v_pk_mul_f32 v[66:67], v[66:67], v[190:191] op_sel_hi:[1,0]
	v_pk_mul_f32 v[64:65], v[64:65], v[190:191] op_sel_hi:[1,0]
	v_pk_mul_f32 v[62:63], v[62:63], v[190:191] op_sel_hi:[1,0]
	v_pk_mul_f32 v[60:61], v[60:61], v[190:191] op_sel_hi:[1,0]
	v_pk_mul_f32 v[58:59], v[58:59], v[190:191] op_sel_hi:[1,0]
	v_pk_mul_f32 v[56:57], v[56:57], v[190:191] op_sel_hi:[1,0]
	v_pk_mul_f32 v[54:55], v[54:55], v[190:191] op_sel_hi:[1,0]
	v_pk_mul_f32 v[52:53], v[52:53], v[190:191] op_sel_hi:[1,0]
	v_pk_mul_f32 v[50:51], v[50:51], v[190:191] op_sel_hi:[1,0]
	v_pk_mul_f32 v[48:49], v[48:49], v[190:191] op_sel_hi:[1,0]
	v_pk_mul_f32 v[46:47], v[46:47], v[190:191] op_sel_hi:[1,0]
	v_pk_mul_f32 v[44:45], v[44:45], v[190:191] op_sel_hi:[1,0]
	v_pk_mul_f32 v[42:43], v[42:43], v[190:191] op_sel_hi:[1,0]
	v_pk_mul_f32 v[40:41], v[40:41], v[190:191] op_sel_hi:[1,0]
	v_pk_mul_f32 v[38:39], v[38:39], v[190:191] op_sel_hi:[1,0]
	v_pk_mul_f32 v[36:37], v[36:37], v[190:191] op_sel_hi:[1,0]
	v_pk_mul_f32 v[34:35], v[34:35], v[190:191] op_sel_hi:[1,0]
	v_pk_mul_f32 v[32:33], v[32:33], v[190:191] op_sel_hi:[1,0]
	v_pk_mul_f32 v[30:31], v[30:31], v[190:191] op_sel_hi:[1,0]
	v_pk_mul_f32 v[28:29], v[28:29], v[190:191] op_sel_hi:[1,0]
	v_pk_mul_f32 v[26:27], v[26:27], v[190:191] op_sel_hi:[1,0]
	v_pk_mul_f32 v[24:25], v[24:25], v[190:191] op_sel_hi:[1,0]
	v_pk_mul_f32 v[22:23], v[22:23], v[190:191] op_sel_hi:[1,0]
	v_pk_mul_f32 v[20:21], v[20:21], v[190:191] op_sel_hi:[1,0]
	v_pk_mul_f32 v[18:19], v[18:19], v[190:191] op_sel_hi:[1,0]
	v_pk_mul_f32 v[16:17], v[16:17], v[190:191] op_sel_hi:[1,0]
	v_pk_mul_f32 v[14:15], v[14:15], v[190:191] op_sel_hi:[1,0]
	v_pk_mul_f32 v[12:13], v[12:13], v[190:191] op_sel_hi:[1,0]
	v_pk_mul_f32 v[10:11], v[10:11], v[190:191] op_sel_hi:[1,0]
	v_pk_mul_f32 v[8:9], v[8:9], v[190:191] op_sel_hi:[1,0]
	v_pk_mul_f32 v[6:7], v[6:7], v[190:191] op_sel_hi:[1,0]
	v_pk_mul_f32 v[4:5], v[4:5], v[190:191] op_sel_hi:[1,0]
	v_pk_mul_f32 v[2:3], v[2:3], v[190:191] op_sel_hi:[1,0]
	v_pk_mul_f32 v[0:1], v[0:1], v[190:191] op_sel_hi:[1,0]
	v_mul_f32_e32 v195, v195, v190
	v_mov_b32_e32 v190, v246
	v_sub_f32_e32 v222, v222, v190
	v_exp_f32_e32 v222, v222
	v_sub_f32_e32 v223, v223, v190
	v_exp_f32_e32 v223, v223
	v_sub_f32_e32 v224, v224, v190
	v_add_f32_e32 v254, 0, v222
	v_exp_f32_e32 v224, v224
	v_sub_f32_e32 v225, v225, v190
	v_add_f32_e32 v254, v223, v254
	v_exp_f32_e32 v225, v225
	v_sub_f32_e32 v226, v226, v190
	v_add_f32_e32 v254, v224, v254
	v_exp_f32_e32 v226, v226
	v_sub_f32_e32 v227, v227, v190
	v_add_f32_e32 v254, v225, v254
	v_exp_f32_e32 v227, v227
	v_sub_f32_e32 v228, v228, v190
	v_add_f32_e32 v254, v226, v254
	v_exp_f32_e32 v228, v228
	v_sub_f32_e32 v229, v229, v190
	v_add_f32_e32 v254, v227, v254
	v_exp_f32_e32 v229, v229
	v_sub_f32_e32 v230, v230, v190
	v_add_f32_e32 v254, v228, v254
	v_exp_f32_e32 v230, v230
	v_sub_f32_e32 v231, v231, v190
	v_add_f32_e32 v254, v229, v254
	v_exp_f32_e32 v231, v231
	v_sub_f32_e32 v232, v232, v190
	v_add_f32_e32 v254, v230, v254
	v_exp_f32_e32 v232, v232
	v_sub_f32_e32 v233, v233, v190
	v_add_f32_e32 v254, v231, v254
	v_exp_f32_e32 v233, v233
	v_sub_f32_e32 v234, v234, v190
	v_add_f32_e32 v254, v232, v254
	v_exp_f32_e32 v234, v234
	v_sub_f32_e32 v235, v235, v190
	v_add_f32_e32 v254, v233, v254
	v_exp_f32_e32 v235, v235
	v_sub_f32_e32 v236, v236, v190
	v_add_f32_e32 v254, v234, v254
	v_exp_f32_e32 v236, v236
	v_sub_f32_e32 v237, v237, v190
	v_add_f32_e32 v254, v235, v254
	v_exp_f32_e32 v237, v237
	v_add_f32_e32 v254, v236, v254
	v_add_f32_e32 v254, v237, v254
	v_cvt_pk_bf16_f32 v242, v222, v223
	v_cvt_pk_bf16_f32 v243, v224, v225
	v_cvt_pk_bf16_f32 v244, v226, v227
	v_cvt_pk_bf16_f32 v245, v228, v229
	v_cvt_pk_bf16_f32 v250, v230, v231
	v_cvt_pk_bf16_f32 v251, v232, v233
	v_cvt_pk_bf16_f32 v252, v234, v235
	v_cvt_pk_bf16_f32 v253, v236, v237
	v_add_f32_e32 v195, v195, v254
	s_nop 1
	s_waitcnt lgkmcnt(8)
	v_mfma_f32_32x32x16_bf16 v[112:127], v[238:241], v[242:245], v[112:127]
	ds_read_b64_tr_b16 v[238:239], v218 offset:16640
	ds_read_b64_tr_b16 v[240:241], v218 offset:20736
	s_waitcnt lgkmcnt(8)
	v_mfma_f32_32x32x16_bf16 v[96:111], v[128:131], v[242:245], v[96:111]
	ds_read_b64_tr_b16 v[222:223], v219 offset:16640
	ds_read_b64_tr_b16 v[224:225], v219 offset:20736
	s_waitcnt lgkmcnt(8)
	v_mfma_f32_32x32x16_bf16 v[80:95], v[206:209], v[242:245], v[80:95]
	ds_read_b64_tr_b16 v[206:207], v221 offset:16640
	ds_read_b64_tr_b16 v[208:209], v221 offset:20736
	s_waitcnt lgkmcnt(8)
	v_mfma_f32_32x32x16_bf16 v[64:79], v[210:213], v[242:245], v[64:79]
	ds_read_b64_tr_b16 v[210:211], v205 offset:24576
	ds_read_b64_tr_b16 v[212:213], v205 offset:28672
	s_waitcnt lgkmcnt(8)
	v_mfma_f32_32x32x16_bf16 v[48:63], v[214:217], v[242:245], v[48:63]
	ds_read_b64_tr_b16 v[214:215], v218 offset:24576
	ds_read_b64_tr_b16 v[216:217], v218 offset:28672
	s_waitcnt lgkmcnt(8)
	v_mfma_f32_32x32x16_bf16 v[32:47], v[238:241], v[242:245], v[32:47]
	ds_read_b64_tr_b16 v[238:239], v219 offset:24576
	ds_read_b64_tr_b16 v[240:241], v219 offset:28672
	s_waitcnt lgkmcnt(8)
	v_mfma_f32_32x32x16_bf16 v[16:31], v[222:225], v[242:245], v[16:31]
	ds_read_b64_tr_b16 v[222:223], v221 offset:24576
	ds_read_b64_tr_b16 v[224:225], v221 offset:28672
	s_waitcnt lgkmcnt(8)
	v_mfma_f32_32x32x16_bf16 v[0:15], v[206:209], v[242:245], v[0:15]
	ds_read_b64_tr_b16 v[206:207], v205 offset:24832
	ds_read_b64_tr_b16 v[208:209], v205 offset:28928
	s_waitcnt lgkmcnt(8)
	v_mfma_f32_32x32x16_bf16 v[112:127], v[210:213], v[250:253], v[112:127]
	ds_read_b64_tr_b16 v[210:211], v218 offset:24832
	ds_read_b64_tr_b16 v[212:213], v218 offset:28928
	s_waitcnt lgkmcnt(8)
	v_mfma_f32_32x32x16_bf16 v[96:111], v[214:217], v[250:253], v[96:111]
	ds_read_b64_tr_b16 v[214:215], v219 offset:24832
	ds_read_b64_tr_b16 v[216:217], v219 offset:28928
	s_waitcnt lgkmcnt(8)
	v_mfma_f32_32x32x16_bf16 v[80:95], v[238:241], v[250:253], v[80:95]
	ds_read_b64_tr_b16 v[238:239], v221 offset:24832
	ds_read_b64_tr_b16 v[240:241], v221 offset:28928
	s_waitcnt lgkmcnt(8)
	v_mfma_f32_32x32x16_bf16 v[64:79], v[222:225], v[250:253], v[64:79]
	s_waitcnt lgkmcnt(6)
	v_mfma_f32_32x32x16_bf16 v[48:63], v[206:209], v[250:253], v[48:63]
	s_waitcnt lgkmcnt(4)
	v_mfma_f32_32x32x16_bf16 v[32:47], v[210:213], v[250:253], v[32:47]
	s_waitcnt lgkmcnt(2)
	v_mfma_f32_32x32x16_bf16 v[16:31], v[214:217], v[250:253], v[16:31]
	s_waitcnt lgkmcnt(0)
	v_mfma_f32_32x32x16_bf16 v[0:15], v[238:241], v[250:253], v[0:15]
	ds_read_b128 v[206:209], v196 offset:32768
	ds_read_b128 v[210:213], v197 offset:32768
	ds_read_b128 v[214:217], v198 offset:32768
	ds_read_b128 v[238:241], v199 offset:32768
	ds_read_b128 v[242:245], v200 offset:32768
	ds_read_b128 v[250:253], v201 offset:32768
	ds_read_b128 v[222:225], v202 offset:32768
	ds_read_b128 v[226:229], v203 offset:32768
	s_branch .Latt_end_1
.Latt_slow_1s1:
.Latt_slot2_1:
	v_add_u32_e32 v205, 0x8000, v205
	v_add_u32_e32 v218, 0x8000, v218
	v_add_u32_e32 v219, 0x8000, v219
	v_add_u32_e32 v221, 0x8000, v221
	s_waitcnt lgkmcnt(7)
	v_mfma_f32_32x32x16_bf16 v[128:143], v[206:209], v[144:147], 0
	ds_read_b128 v[206:209], v196 offset:40960
	s_cmp_lg_u64 s[18:19], 0
	s_cbranch_scc1 .Latt_nd0_1s2
	s_sub_i32 s100, s33, 1
	s_cmp_eq_u32 s33, 0
	s_cselect_b32 s100, 2, s100
	s_lshl_b32 s101, s100, 14
	s_add_i32 m0, s85, s101
	s_nop 0
	global_load_lds_dwordx4 v178, s[12:13]
.Latt_nd0_1s2:
	s_waitcnt lgkmcnt(7)
	v_mfma_f32_32x32x16_bf16 v[128:143], v[210:213], v[148:151], v[128:143]
	ds_read_b128 v[210:213], v197 offset:40960
	s_cmp_lg_u64 s[18:19], 0
	s_cbranch_scc1 .Latt_nd1_1s2
	s_add_i32 m0, m0, 0x400
	s_nop 0
	global_load_lds_dwordx4 v180, s[12:13]
.Latt_nd1_1s2:
	s_waitcnt lgkmcnt(7)
	v_mfma_f32_32x32x16_bf16 v[128:143], v[214:217], v[152:155], v[128:143]
	ds_read_b128 v[214:217], v198 offset:40960
	s_cmp_lg_u64 s[18:19], 0
	s_cbranch_scc1 .Latt_nd2_1s2
	s_lshl_b32 s101, s100, 15
	s_add_i32 m0, s86, s101
	s_add_u32 s100, s12, 0xf00
	s_addc_u32 s101, s13, 0
	global_load_lds_dwordx4 v182, s[100:101]
.Latt_nd2_1s2:
	s_waitcnt lgkmcnt(7)
	v_mfma_f32_32x32x16_bf16 v[128:143], v[238:241], v[156:159], v[128:143]
	ds_read_b128 v[238:241], v199 offset:40960
	s_cmp_lg_u64 s[18:19], 0
	s_cbranch_scc1 .Latt_nd3_1s2
	s_add_i32 m0, m0, 0x400
	s_nop 0
	global_load_lds_dwordx4 v184, s[100:101]

.Latt_nd5_1s2:
	s_waitcnt lgkmcnt(5)
	v_mfma_f32_32x32x16_bf16 v[128:143], v[222:225], v[168:171], v[128:143]
	s_waitcnt lgkmcnt(4)
	v_mfma_f32_32x32x16_bf16 v[128:143], v[226:229], v[172:175], v[128:143]
	s_waitcnt lgkmcnt(3)
	v_mfma_f32_32x32x16_bf16 v[222:237], v[206:209], v[144:147], 0
	ds_read_b128 v[206:209], v200 offset:40960
	s_nop 8
	v_max3_f32 v246, v128, v129, v130
	v_max3_f32 v247, v131, v132, v133
	v_max3_f32 v246, v246, v134, v135
	v_max3_f32 v247, v247, v136, v137
	v_max3_f32 v246, v246, v138, v139
	v_max3_f32 v247, v247, v140, v141
	v_max3_f32 v246, v246, v142, v143
	s_waitcnt lgkmcnt(3)
	v_mfma_f32_32x32x16_bf16 v[222:237], v[210:213], v[148:151], v[222:237]
	ds_read_b128 v[210:213], v201 offset:40960
	v_max_f32_e32 v246, v246, v247
	v_mov_b32_e32 v247, v246
	v_add_f32_e32 v249, 0x41000000, v190
	s_nop 1
	v_permlane32_swap_b32_e32 v246, v247
	v_max_f32_e32 v246, v246, v247
	v_cmp_gt_f32_e32 vcc, v246, v249
	s_cbranch_vccz .Latt_nr0_1s2
	v_max_f32_e32 v246, v190, v246
	v_sub_f32_e32 v190, v190, v246
	v_exp_f32_e32 v190, v190
	s_nop 0
	v_pk_mul_f32 v[126:127], v[126:127], v[190:191] op_sel_hi:[1,0]
	v_pk_mul_f32 v[124:125], v[124:125], v[190:191] op_sel_hi:[1,0]
	v_pk_mul_f32 v[122:123], v[122:123], v[190:191] op_sel_hi:[1,0]
	v_pk_mul_f32 v[120:121], v[120:121], v[190:191] op_sel_hi:[1,0]
	v_pk_mul_f32 v[118:119], v[118:119], v[190:191] op_sel_hi:[1,0]
	v_pk_mul_f32 v[116:117], v[116:117], v[190:191] op_sel_hi:[1,0]
	v_pk_mul_f32 v[114:115], v[114:115], v[190:191] op_sel_hi:[1,0]
	v_pk_mul_f32 v[112:113], v[112:113], v[190:191] op_sel_hi:[1,0]
	v_pk_mul_f32 v[110:111], v[110:111], v[190:191] op_sel_hi:[1,0]
	v_pk_mul_f32 v[108:109], v[108:109], v[190:191] op_sel_hi:[1,0]
	v_pk_mul_f32 v[106:107], v[106:107], v[190:191] op_sel_hi:[1,0]
	v_pk_mul_f32 v[104:105], v[104:105], v[190:191] op_sel_hi:[1,0]
	v_pk_mul_f32 v[102:103], v[102:103], v[190:191] op_sel_hi:[1,0]
	v_pk_mul_f32 v[100:101], v[100:101], v[190:191] op_sel_hi:[1,0]
	v_pk_mul_f32 v[98:99], v[98:99], v[190:191] op_sel_hi:[1,0]
	v_pk_mul_f32 v[96:97], v[96:97], v[190:191] op_sel_hi:[1,0]
	v_pk_mul_f32 v[94:95], v[94:95], v[190:191] op_sel_hi:[1,0]
	v_pk_mul_f32 v[92:93], v[92:93], v[190:191] op_sel_hi:[1,0]
	v_pk_mul_f32 v[90:91], v[90:91], v[190:191] op_sel_hi:[1,0]
	v_pk_mul_f32 v[88:89], v[88:89], v[190:191] op_sel_hi:[1,0]
	v_pk_mul_f32 v[86:87], v[86:87], v[190:191] op_sel_hi:[1,0]
	v_pk_mul_f32 v[84:85], v[84:85], v[190:191] op_sel_hi:[1,0]
	v_pk_mul_f32 v[82:83], v[82:83], v[190:191] op_sel_hi:[1,0]
	v_pk_mul_f32 v[80:81], v[80:81], v[190:191] op_sel_hi:[1,0]
	v_pk_mul_f32 v[78:79], v[78:79], v[190:191] op_sel_hi:[1,0]
	v_pk_mul_f32 v[76:77], v[76:77], v[190:191] op_sel_hi:[1,0]
	v_pk_mul_f32 v[74:75], v[74:75], v[190:191] op_sel_hi:[1,0]
	v_pk_mul_f32 v[72:73], v[72:73], v[190:191] op_sel_hi:[1,0]
	v_pk_mul_f32 v[70:71], v[70:71], v[190:191] op_sel_hi:[1,0]
	v_pk_mul_f32 v[68:69], v[68:69], v[190:191] op_sel_hi:[1,0]
	v_pk_mul_f32 v[66:67], v[66:67], v[190:191] op_sel_hi:[1,0]
	v_pk_mul_f32 v[64:65], v[64:65], v[190:191] op_sel_hi:[1,0]
	v_pk_mul_f32 v[62:63], v[62:63], v[190:191] op_sel_hi:[1,0]
	v_pk_mul_f32 v[60:61], v[60:61], v[190:191] op_sel_hi:[1,0]
	v_pk_mul_f32 v[58:59], v[58:59], v[190:191] op_sel_hi:[1,0]
	v_pk_mul_f32 v[56:57], v[56:57], v[190:191] op_sel_hi:[1,0]
	v_pk_mul_f32 v[54:55], v[54:55], v[190:191] op_sel_hi:[1,0]
	v_pk_mul_f32 v[52:53], v[52:53], v[190:191] op_sel_hi:[1,0]
	v_pk_mul_f32 v[50:51], v[50:51], v[190:191] op_sel_hi:[1,0]
	v_pk_mul_f32 v[48:49], v[48:49], v[190:191] op_sel_hi:[1,0]
	v_pk_mul_f32 v[46:47], v[46:47], v[190:191] op_sel_hi:[1,0]
	v_pk_mul_f32 v[44:45], v[44:45], v[190:191] op_sel_hi:[1,0]
	v_pk_mul_f32 v[42:43], v[42:43], v[190:191] op_sel_hi:[1,0]
	v_pk_mul_f32 v[40:41], v[40:41], v[190:191] op_sel_hi:[1,0]
	v_pk_mul_f32 v[38:39], v[38:39], v[190:191] op_sel_hi:[1,0]
	v_pk_mul_f32 v[36:37], v[36:37], v[190:191] op_sel_hi:[1,0]
	v_pk_mul_f32 v[34:35], v[34:35], v[190:191] op_sel_hi:[1,0]
	v_pk_mul_f32 v[32:33], v[32:33], v[190:191] op_sel_hi:[1,0]
	v_pk_mul_f32 v[30:31], v[30:31], v[190:191] op_sel_hi:[1,0]
	v_pk_mul_f32 v[28:29], v[28:29], v[190:191] op_sel_hi:[1,0]
	v_pk_mul_f32 v[26:27], v[26:27], v[190:191] op_sel_hi:[1,0]
	v_pk_mul_f32 v[24:25], v[24:25], v[190:191] op_sel_hi:[1,0]
	v_pk_mul_f32 v[22:23], v[22:23], v[190:191] op_sel_hi:[1,0]
	v_pk_mul_f32 v[20:21], v[20:21], v[190:191] op_sel_hi:[1,0]
	v_pk_mul_f32 v[18:19], v[18:19], v[190:191] op_sel_hi:[1,0]
	v_pk_mul_f32 v[16:17], v[16:17], v[190:191] op_sel_hi:[1,0]
	v_pk_mul_f32 v[14:15], v[14:15], v[190:191] op_sel_hi:[1,0]
	v_pk_mul_f32 v[12:13], v[12:13], v[190:191] op_sel_hi:[1,0]
	v_pk_mul_f32 v[10:11], v[10:11], v[190:191] op_sel_hi:[1,0]
	v_pk_mul_f32 v[8:9], v[8:9], v[190:191] op_sel_hi:[1,0]
	v_pk_mul_f32 v[6:7], v[6:7], v[190:191] op_sel_hi:[1,0]
	v_pk_mul_f32 v[4:5], v[4:5], v[190:191] op_sel_hi:[1,0]
	v_pk_mul_f32 v[2:3], v[2:3], v[190:191] op_sel_hi:[1,0]
	v_pk_mul_f32 v[0:1], v[0:1], v[190:191] op_sel_hi:[1,0]
	v_mul_f32_e32 v195, v195, v190
	v_mov_b32_e32 v190, v246
.Latt_nr0_1s2:
	s_waitcnt lgkmcnt(3)
	v_mfma_f32_32x32x16_bf16 v[222:237], v[214:217], v[152:155], v[222:237]
	ds_read_b128 v[214:217], v202 offset:40960
	v_sub_f32_e32 v128, v128, v190
	v_exp_f32_e32 v128, v128
	v_sub_f32_e32 v129, v129, v190
	v_exp_f32_e32 v129, v129
	v_sub_f32_e32 v130, v130, v190
	s_waitcnt lgkmcnt(3)
	v_mfma_f32_32x32x16_bf16 v[222:237], v[238:241], v[156:159], v[222:237]
	ds_read_b128 v[238:241], v203 offset:40960
	v_add_f32_e32 v254, 0, v128
	v_exp_f32_e32 v130, v130
	v_sub_f32_e32 v131, v131, v190
	v_add_f32_e32 v254, v129, v254
	v_exp_f32_e32 v131, v131
	s_waitcnt lgkmcnt(3)
	v_mfma_f32_32x32x16_bf16 v[222:237], v[206:209], v[160:163], v[222:237]
	ds_read_b64_tr_b16 v[206:207], v205
	ds_read_b64_tr_b16 v[208:209], v205 offset:4096
	v_sub_f32_e32 v132, v132, v190
	v_add_f32_e32 v254, v130, v254
	v_exp_f32_e32 v132, v132
	v_sub_f32_e32 v133, v133, v190
	v_add_f32_e32 v254, v131, v254
	s_waitcnt lgkmcnt(4)
	v_mfma_f32_32x32x16_bf16 v[222:237], v[210:213], v[164:167], v[222:237]
	ds_read_b64_tr_b16 v[210:211], v218
	ds_read_b64_tr_b16 v[212:213], v218 offset:4096
	v_exp_f32_e32 v133, v133
	v_sub_f32_e32 v134, v134, v190
	v_add_f32_e32 v254, v132, v254
	v_exp_f32_e32 v134, v134
	s_waitcnt lgkmcnt(5)
	v_mfma_f32_32x32x16_bf16 v[222:237], v[214:217], v[168:171], v[222:237]
	ds_read_b64_tr_b16 v[214:215], v219
	ds_read_b64_tr_b16 v[216:217], v219 offset:4096
	v_sub_f32_e32 v135, v135, v190
	v_add_f32_e32 v254, v133, v254
	v_exp_f32_e32 v135, v135
	s_nop 0
	s_waitcnt lgkmcnt(6)
	v_mfma_f32_32x32x16_bf16 v[222:237], v[238:241], v[172:175], v[222:237]
	ds_read_b64_tr_b16 v[238:239], v221
	ds_read_b64_tr_b16 v[240:241], v221 offset:4096
	v_cvt_pk_bf16_f32 v242, v128, v129
	v_cvt_pk_bf16_f32 v243, v130, v131
	v_cvt_pk_bf16_f32 v244, v132, v133
	v_cvt_pk_bf16_f32 v245, v134, v135
	s_nop 1
	s_waitcnt lgkmcnt(6)
	v_mfma_f32_32x32x16_bf16 v[112:127], v[206:209], v[242:245], v[112:127]
	ds_read_b64_tr_b16 v[206:207], v205 offset:256
	ds_read_b64_tr_b16 v[208:209], v205 offset:4352
	v_sub_f32_e32 v136, v136, v190
	v_add_f32_e32 v254, v134, v254
	v_exp_f32_e32 v136, v136
	v_sub_f32_e32 v137, v137, v190
	v_add_f32_e32 v254, v135, v254
	s_waitcnt lgkmcnt(6)
	v_mfma_f32_32x32x16_bf16 v[96:111], v[210:213], v[242:245], v[96:111]
	ds_read_b64_tr_b16 v[210:211], v218 offset:256
	ds_read_b64_tr_b16 v[212:213], v218 offset:4352
	v_exp_f32_e32 v137, v137
	v_sub_f32_e32 v138, v138, v190
	v_add_f32_e32 v254, v136, v254
	v_exp_f32_e32 v138, v138
	v_sub_f32_e32 v139, v139, v190
	s_waitcnt lgkmcnt(6)
	v_mfma_f32_32x32x16_bf16 v[80:95], v[214:217], v[242:245], v[80:95]
	ds_read_b64_tr_b16 v[214:215], v219 offset:256
	ds_read_b64_tr_b16 v[216:217], v219 offset:4352
	v_add_f32_e32 v254, v137, v254
	v_exp_f32_e32 v139, v139
	v_sub_f32_e32 v140, v140, v190
	v_add_f32_e32 v254, v138, v254
	s_waitcnt lgkmcnt(6)
	v_mfma_f32_32x32x16_bf16 v[64:79], v[238:241], v[242:245], v[64:79]
	ds_read_b64_tr_b16 v[238:239], v221 offset:256
	ds_read_b64_tr_b16 v[240:241], v221 offset:4352
	v_exp_f32_e32 v140, v140
	v_sub_f32_e32 v141, v141, v190
	v_add_f32_e32 v254, v139, v254
	v_exp_f32_e32 v141, v141
	s_waitcnt lgkmcnt(6)
	v_mfma_f32_32x32x16_bf16 v[48:63], v[206:209], v[242:245], v[48:63]
	ds_read_b64_tr_b16 v[206:207], v205 offset:8192
	ds_read_b64_tr_b16 v[208:209], v205 offset:12288
	v_sub_f32_e32 v142, v142, v190
	v_add_f32_e32 v254, v140, v254
	v_exp_f32_e32 v142, v142
	v_sub_f32_e32 v143, v143, v190
	s_waitcnt lgkmcnt(6)
	v_mfma_f32_32x32x16_bf16 v[32:47], v[210:213], v[242:245], v[32:47]
	ds_read_b64_tr_b16 v[210:211], v218 offset:8192
	ds_read_b64_tr_b16 v[212:213], v218 offset:12288
	v_add_f32_e32 v254, v141, v254
	v_exp_f32_e32 v143, v143
	v_add_f32_e32 v254, v142, v254
	v_add_f32_e32 v254, v143, v254
	s_waitcnt lgkmcnt(6)
	v_mfma_f32_32x32x16_bf16 v[16:31], v[214:217], v[242:245], v[16:31]
	ds_read_b64_tr_b16 v[214:215], v219 offset:8192
	ds_read_b64_tr_b16 v[216:217], v219 offset:12288
	v_cvt_pk_bf16_f32 v250, v136, v137
	v_cvt_pk_bf16_f32 v251, v138, v139
	v_cvt_pk_bf16_f32 v252, v140, v141
	v_cvt_pk_bf16_f32 v253, v142, v143
	v_add_f32_e32 v195, v195, v254
	s_waitcnt lgkmcnt(6)
	v_mfma_f32_32x32x16_bf16 v[0:15], v[238:241], v[242:245], v[0:15]
	ds_read_b64_tr_b16 v[238:239], v221 offset:8192
	ds_read_b64_tr_b16 v[240:241], v221 offset:12288
	ds_read_b64_tr_b16 v[128:129], v205 offset:8448
	ds_read_b64_tr_b16 v[130:131], v205 offset:12544
	s_waitcnt lgkmcnt(8)
	v_mfma_f32_32x32x16_bf16 v[112:127], v[206:209], v[250:253], v[112:127]
	ds_read_b64_tr_b16 v[206:207], v218 offset:8448
	ds_read_b64_tr_b16 v[208:209], v218 offset:12544
	v_max3_f32 v246, v222, v223, v224
	v_max3_f32 v247, v225, v226, v227
	v_max3_f32 v246, v246, v228, v229
	v_max3_f32 v247, v247, v230, v231
	v_max3_f32 v246, v246, v232, v233
	s_waitcnt lgkmcnt(8)
	v_mfma_f32_32x32x16_bf16 v[96:111], v[210:213], v[250:253], v[96:111]
	ds_read_b64_tr_b16 v[210:211], v219 offset:8448
	ds_read_b64_tr_b16 v[212:213], v219 offset:12544
	v_max3_f32 v247, v247, v234, v235
	v_max3_f32 v246, v246, v236, v237
	v_max_f32_e32 v246, v246, v247
	v_mov_b32_e32 v247, v246
	v_add_f32_e32 v249, 0x41000000, v190
	s_waitcnt lgkmcnt(8)
	v_mfma_f32_32x32x16_bf16 v[80:95], v[214:217], v[250:253], v[80:95]
	ds_read_b64_tr_b16 v[214:215], v221 offset:8448
	ds_read_b64_tr_b16 v[216:217], v221 offset:12544
	s_nop 1
	v_permlane32_swap_b32_e32 v246, v247
	v_max_f32_e32 v246, v246, v247
	v_cmp_gt_f32_e32 vcc, v246, v249
	s_cbranch_vccnz .Latt_rs1_1s2
	s_waitcnt lgkmcnt(8)
	v_mfma_f32_32x32x16_bf16 v[64:79], v[238:241], v[250:253], v[64:79]
	ds_read_b64_tr_b16 v[238:239], v205 offset:16384
	ds_read_b64_tr_b16 v[240:241], v205 offset:20480
	v_sub_f32_e32 v222, v222, v190
	v_exp_f32_e32 v222, v222
	v_sub_f32_e32 v223, v223, v190
	v_exp_f32_e32 v223, v223
	v_sub_f32_e32 v224, v224, v190
	v_add_f32_e32 v254, 0, v222
	s_waitcnt lgkmcnt(8)
	v_mfma_f32_32x32x16_bf16 v[48:63], v[128:131], v[250:253], v[48:63]
	ds_read_b64_tr_b16 v[128:129], v218 offset:16384
	ds_read_b64_tr_b16 v[130:131], v218 offset:20480
	v_exp_f32_e32 v224, v224
	v_sub_f32_e32 v225, v225, v190
	v_add_f32_e32 v254, v223, v254
	v_exp_f32_e32 v225, v225
	v_sub_f32_e32 v226, v226, v190
	v_add_f32_e32 v254, v224, v254
	s_waitcnt lgkmcnt(8)
	v_mfma_f32_32x32x16_bf16 v[32:47], v[206:209], v[250:253], v[32:47]
	ds_read_b64_tr_b16 v[206:207], v219 offset:16384
	ds_read_b64_tr_b16 v[208:209], v219 offset:20480
	v_exp_f32_e32 v226, v226
	v_sub_f32_e32 v227, v227, v190
	v_add_f32_e32 v254, v225, v254
	v_exp_f32_e32 v227, v227
	v_sub_f32_e32 v228, v228, v190
	s_waitcnt lgkmcnt(8)
	v_mfma_f32_32x32x16_bf16 v[16:31], v[210:213], v[250:253], v[16:31]
	ds_read_b64_tr_b16 v[210:211], v221 offset:16384
	ds_read_b64_tr_b16 v[212:213], v221 offset:20480
	v_add_f32_e32 v254, v226, v254
	v_exp_f32_e32 v228, v228
	v_sub_f32_e32 v229, v229, v190
	v_add_f32_e32 v254, v227, v254
	v_exp_f32_e32 v229, v229
	s_waitcnt lgkmcnt(8)
	v_mfma_f32_32x32x16_bf16 v[0:15], v[214:217], v[250:253], v[0:15]
	ds_read_b64_tr_b16 v[214:215], v205 offset:16640
	ds_read_b64_tr_b16 v[216:217], v205 offset:20736
	s_nop 0
	v_cvt_pk_bf16_f32 v242, v222, v223
	v_cvt_pk_bf16_f32 v243, v224, v225
	v_cvt_pk_bf16_f32 v244, v226, v227
	v_cvt_pk_bf16_f32 v245, v228, v229
	s_nop 1
	s_waitcnt lgkmcnt(8)
	v_mfma_f32_32x32x16_bf16 v[112:127], v[238:241], v[242:245], v[112:127]
	ds_read_b64_tr_b16 v[238:239], v218 offset:16640
	ds_read_b64_tr_b16 v[240:241], v218 offset:20736
	v_sub_f32_e32 v230, v230, v190
	v_add_f32_e32 v254, v228, v254
	v_exp_f32_e32 v230, v230
	v_sub_f32_e32 v231, v231, v190
	v_add_f32_e32 v254, v229, v254
	s_waitcnt lgkmcnt(8)
	v_mfma_f32_32x32x16_bf16 v[96:111], v[128:131], v[242:245], v[96:111]
	ds_read_b64_tr_b16 v[128:129], v219 offset:16640
	ds_read_b64_tr_b16 v[130:131], v219 offset:20736
	v_exp_f32_e32 v231, v231
	v_sub_f32_e32 v232, v232, v190
	v_add_f32_e32 v254, v230, v254
	v_exp_f32_e32 v232, v232
	v_sub_f32_e32 v233, v233, v190
	s_waitcnt lgkmcnt(8)
	v_mfma_f32_32x32x16_bf16 v[80:95], v[206:209], v[242:245], v[80:95]
	ds_read_b64_tr_b16 v[206:207], v221 offset:16640
	ds_read_b64_tr_b16 v[208:209], v221 offset:20736
	v_add_f32_e32 v254, v231, v254
	v_exp_f32_e32 v233, v233
	v_sub_f32_e32 v234, v234, v190
	v_add_f32_e32 v254, v232, v254
	s_waitcnt lgkmcnt(8)
	v_mfma_f32_32x32x16_bf16 v[64:79], v[210:213], v[242:245], v[64:79]
	ds_read_b64_tr_b16 v[210:211], v205 offset:24576
	ds_read_b64_tr_b16 v[212:213], v205 offset:28672
	v_exp_f32_e32 v234, v234
	v_sub_f32_e32 v235, v235, v190
	v_add_f32_e32 v254, v233, v254
	v_exp_f32_e32 v235, v235
	s_waitcnt lgkmcnt(8)
	v_mfma_f32_32x32x16_bf16 v[48:63], v[214:217], v[242:245], v[48:63]
	ds_read_b64_tr_b16 v[214:215], v218 offset:24576
	ds_read_b64_tr_b16 v[216:217], v218 offset:28672
	v_sub_f32_e32 v236, v236, v190
	v_add_f32_e32 v254, v234, v254
	v_exp_f32_e32 v236, v236
	v_sub_f32_e32 v237, v237, v190
	s_waitcnt lgkmcnt(8)
	v_mfma_f32_32x32x16_bf16 v[32:47], v[238:241], v[242:245], v[32:47]
	ds_read_b64_tr_b16 v[238:239], v219 offset:24576
	ds_read_b64_tr_b16 v[240:241], v219 offset:28672
	v_add_f32_e32 v254, v235, v254
	v_exp_f32_e32 v237, v237
	v_add_f32_e32 v254, v236, v254
	v_add_f32_e32 v254, v237, v254
	s_waitcnt lgkmcnt(8)
	v_mfma_f32_32x32x16_bf16 v[16:31], v[128:131], v[242:245], v[16:31]
	ds_read_b64_tr_b16 v[128:129], v221 offset:24576
	ds_read_b64_tr_b16 v[130:131], v221 offset:28672
	v_cvt_pk_bf16_f32 v250, v230, v231
	v_cvt_pk_bf16_f32 v251, v232, v233
	v_cvt_pk_bf16_f32 v252, v234, v235
	v_cvt_pk_bf16_f32 v253, v236, v237
	v_add_f32_e32 v195, v195, v254
	s_waitcnt lgkmcnt(8)
	v_mfma_f32_32x32x16_bf16 v[0:15], v[206:209], v[242:245], v[0:15]
	ds_read_b64_tr_b16 v[206:207], v205 offset:24832
	ds_read_b64_tr_b16 v[208:209], v205 offset:28928
	s_waitcnt lgkmcnt(8)
	v_mfma_f32_32x32x16_bf16 v[112:127], v[210:213], v[250:253], v[112:127]
	ds_read_b64_tr_b16 v[210:211], v218 offset:24832
	ds_read_b64_tr_b16 v[212:213], v218 offset:28928
	s_waitcnt lgkmcnt(8)
	v_mfma_f32_32x32x16_bf16 v[96:111], v[214:217], v[250:253], v[96:111]
	ds_read_b64_tr_b16 v[214:215], v219 offset:24832
	ds_read_b64_tr_b16 v[216:217], v219 offset:28928
	s_waitcnt lgkmcnt(8)
	v_mfma_f32_32x32x16_bf16 v[80:95], v[238:241], v[250:253], v[80:95]
	ds_read_b64_tr_b16 v[238:239], v221 offset:24832
	ds_read_b64_tr_b16 v[240:241], v221 offset:28928
	s_waitcnt lgkmcnt(8)
	v_mfma_f32_32x32x16_bf16 v[64:79], v[128:131], v[250:253], v[64:79]
	s_waitcnt lgkmcnt(6)
	v_mfma_f32_32x32x16_bf16 v[48:63], v[206:209], v[250:253], v[48:63]
	s_waitcnt lgkmcnt(4)
	v_mfma_f32_32x32x16_bf16 v[32:47], v[210:213], v[250:253], v[32:47]
	s_waitcnt lgkmcnt(2)
	v_mfma_f32_32x32x16_bf16 v[16:31], v[214:217], v[250:253], v[16:31]
	s_waitcnt lgkmcnt(0)
	v_mfma_f32_32x32x16_bf16 v[0:15], v[238:241], v[250:253], v[0:15]
	ds_read_b128 v[206:209], v196
	ds_read_b128 v[210:213], v197
	ds_read_b128 v[214:217], v198
	ds_read_b128 v[238:241], v199
	ds_read_b128 v[242:245], v200
	ds_read_b128 v[250:253], v201
	ds_read_b128 v[222:225], v202
	ds_read_b128 v[226:229], v203
	s_branch .Latt_end_1
.Latt_rs1_1s2:
	s_waitcnt lgkmcnt(8)
	v_mfma_f32_32x32x16_bf16 v[64:79], v[238:241], v[250:253], v[64:79]
	ds_read_b64_tr_b16 v[238:239], v205 offset:16384
	ds_read_b64_tr_b16 v[240:241], v205 offset:20480
	s_waitcnt lgkmcnt(8)
	v_mfma_f32_32x32x16_bf16 v[48:63], v[128:131], v[250:253], v[48:63]
	ds_read_b64_tr_b16 v[128:129], v218 offset:16384
	ds_read_b64_tr_b16 v[130:131], v218 offset:20480
	s_waitcnt lgkmcnt(8)
	v_mfma_f32_32x32x16_bf16 v[32:47], v[206:209], v[250:253], v[32:47]
	ds_read_b64_tr_b16 v[206:207], v219 offset:16384
	ds_read_b64_tr_b16 v[208:209], v219 offset:20480
	s_waitcnt lgkmcnt(8)
	v_mfma_f32_32x32x16_bf16 v[16:31], v[210:213], v[250:253], v[16:31]
	ds_read_b64_tr_b16 v[210:211], v221 offset:16384
	ds_read_b64_tr_b16 v[212:213], v221 offset:20480
	s_waitcnt lgkmcnt(8)
	v_mfma_f32_32x32x16_bf16 v[0:15], v[214:217], v[250:253], v[0:15]
	ds_read_b64_tr_b16 v[214:215], v205 offset:16640
	ds_read_b64_tr_b16 v[216:217], v205 offset:20736
	s_nop 11
	v_max_f32_e32 v246, v190, v246
	v_sub_f32_e32 v190, v190, v246
	v_exp_f32_e32 v190, v190
	s_nop 0
	v_pk_mul_f32 v[126:127], v[126:127], v[190:191] op_sel_hi:[1,0]
	v_pk_mul_f32 v[124:125], v[124:125], v[190:191] op_sel_hi:[1,0]
	v_pk_mul_f32 v[122:123], v[122:123], v[190:191] op_sel_hi:[1,0]
	v_pk_mul_f32 v[120:121], v[120:121], v[190:191] op_sel_hi:[1,0]
	v_pk_mul_f32 v[118:119], v[118:119], v[190:191] op_sel_hi:[1,0]
	v_pk_mul_f32 v[116:117], v[116:117], v[190:191] op_sel_hi:[1,0]
	v_pk_mul_f32 v[114:115], v[114:115], v[190:191] op_sel_hi:[1,0]
	v_pk_mul_f32 v[112:113], v[112:113], v[190:191] op_sel_hi:[1,0]
	v_pk_mul_f32 v[110:111], v[110:111], v[190:191] op_sel_hi:[1,0]
	v_pk_mul_f32 v[108:109], v[108:109], v[190:191] op_sel_hi:[1,0]
	v_pk_mul_f32 v[106:107], v[106:107], v[190:191] op_sel_hi:[1,0]
	v_pk_mul_f32 v[104:105], v[104:105], v[190:191] op_sel_hi:[1,0]
	v_pk_mul_f32 v[102:103], v[102:103], v[190:191] op_sel_hi:[1,0]
	v_pk_mul_f32 v[100:101], v[100:101], v[190:191] op_sel_hi:[1,0]
	v_pk_mul_f32 v[98:99], v[98:99], v[190:191] op_sel_hi:[1,0]
	v_pk_mul_f32 v[96:97], v[96:97], v[190:191] op_sel_hi:[1,0]
	v_pk_mul_f32 v[94:95], v[94:95], v[190:191] op_sel_hi:[1,0]
	v_pk_mul_f32 v[92:93], v[92:93], v[190:191] op_sel_hi:[1,0]
	v_pk_mul_f32 v[90:91], v[90:91], v[190:191] op_sel_hi:[1,0]
	v_pk_mul_f32 v[88:89], v[88:89], v[190:191] op_sel_hi:[1,0]
	v_pk_mul_f32 v[86:87], v[86:87], v[190:191] op_sel_hi:[1,0]
	v_pk_mul_f32 v[84:85], v[84:85], v[190:191] op_sel_hi:[1,0]
	v_pk_mul_f32 v[82:83], v[82:83], v[190:191] op_sel_hi:[1,0]
	v_pk_mul_f32 v[80:81], v[80:81], v[190:191] op_sel_hi:[1,0]
	v_pk_mul_f32 v[78:79], v[78:79], v[190:191] op_sel_hi:[1,0]
	v_pk_mul_f32 v[76:77], v[76:77], v[190:191] op_sel_hi:[1,0]
	v_pk_mul_f32 v[74:75], v[74:75], v[190:191] op_sel_hi:[1,0]
	v_pk_mul_f32 v[72:73], v[72:73], v[190:191] op_sel_hi:[1,0]
	v_pk_mul_f32 v[70:71], v[70:71], v[190:191] op_sel_hi:[1,0]
	v_pk_mul_f32 v[68:69], v[68:69], v[190:191] op_sel_hi:[1,0]
	v_pk_mul_f32 v[66:67], v[66:67], v[190:191] op_sel_hi:[1,0]
	v_pk_mul_f32 v[64:65], v[64:65], v[190:191] op_sel_hi:[1,0]
	v_pk_mul_f32 v[62:63], v[62:63], v[190:191] op_sel_hi:[1,0]
	v_pk_mul_f32 v[60:61], v[60:61], v[190:191] op_sel_hi:[1,0]
	v_pk_mul_f32 v[58:59], v[58:59], v[190:191] op_sel_hi:[1,0]
	v_pk_mul_f32 v[56:57], v[56:57], v[190:191] op_sel_hi:[1,0]
	v_pk_mul_f32 v[54:55], v[54:55], v[190:191] op_sel_hi:[1,0]
	v_pk_mul_f32 v[52:53], v[52:53], v[190:191] op_sel_hi:[1,0]
	v_pk_mul_f32 v[50:51], v[50:51], v[190:191] op_sel_hi:[1,0]
	v_pk_mul_f32 v[48:49], v[48:49], v[190:191] op_sel_hi:[1,0]
	v_pk_mul_f32 v[46:47], v[46:47], v[190:191] op_sel_hi:[1,0]
	v_pk_mul_f32 v[44:45], v[44:45], v[190:191] op_sel_hi:[1,0]
	v_pk_mul_f32 v[42:43], v[42:43], v[190:191] op_sel_hi:[1,0]
	v_pk_mul_f32 v[40:41], v[40:41], v[190:191] op_sel_hi:[1,0]
	v_pk_mul_f32 v[38:39], v[38:39], v[190:191] op_sel_hi:[1,0]
	v_pk_mul_f32 v[36:37], v[36:37], v[190:191] op_sel_hi:[1,0]
	v_pk_mul_f32 v[34:35], v[34:35], v[190:191] op_sel_hi:[1,0]
	v_pk_mul_f32 v[32:33], v[32:33], v[190:191] op_sel_hi:[1,0]
	v_pk_mul_f32 v[30:31], v[30:31], v[190:191] op_sel_hi:[1,0]
	v_pk_mul_f32 v[28:29], v[28:29], v[190:191] op_sel_hi:[1,0]
	v_pk_mul_f32 v[26:27], v[26:27], v[190:191] op_sel_hi:[1,0]
	v_pk_mul_f32 v[24:25], v[24:25], v[190:191] op_sel_hi:[1,0]
	v_pk_mul_f32 v[22:23], v[22:23], v[190:191] op_sel_hi:[1,0]
	v_pk_mul_f32 v[20:21], v[20:21], v[190:191] op_sel_hi:[1,0]
	v_pk_mul_f32 v[18:19], v[18:19], v[190:191] op_sel_hi:[1,0]
	v_pk_mul_f32 v[16:17], v[16:17], v[190:191] op_sel_hi:[1,0]
	v_pk_mul_f32 v[14:15], v[14:15], v[190:191] op_sel_hi:[1,0]
	v_pk_mul_f32 v[12:13], v[12:13], v[190:191] op_sel_hi:[1,0]
	v_pk_mul_f32 v[10:11], v[10:11], v[190:191] op_sel_hi:[1,0]
	v_pk_mul_f32 v[8:9], v[8:9], v[190:191] op_sel_hi:[1,0]
	v_pk_mul_f32 v[6:7], v[6:7], v[190:191] op_sel_hi:[1,0]
	v_pk_mul_f32 v[4:5], v[4:5], v[190:191] op_sel_hi:[1,0]
	v_pk_mul_f32 v[2:3], v[2:3], v[190:191] op_sel_hi:[1,0]
	v_pk_mul_f32 v[0:1], v[0:1], v[190:191] op_sel_hi:[1,0]
	v_mul_f32_e32 v195, v195, v190
	v_mov_b32_e32 v190, v246
	v_sub_f32_e32 v222, v222, v190
	v_exp_f32_e32 v222, v222
	v_sub_f32_e32 v223, v223, v190
	v_exp_f32_e32 v223, v223
	v_sub_f32_e32 v224, v224, v190
	v_add_f32_e32 v254, 0, v222
	v_exp_f32_e32 v224, v224
	v_sub_f32_e32 v225, v225, v190
	v_add_f32_e32 v254, v223, v254
	v_exp_f32_e32 v225, v225
	v_sub_f32_e32 v226, v226, v190
	v_add_f32_e32 v254, v224, v254
	v_exp_f32_e32 v226, v226
	v_sub_f32_e32 v227, v227, v190
	v_add_f32_e32 v254, v225, v254
	v_exp_f32_e32 v227, v227
	v_sub_f32_e32 v228, v228, v190
	v_add_f32_e32 v254, v226, v254
	v_exp_f32_e32 v228, v228
	v_sub_f32_e32 v229, v229, v190
	v_add_f32_e32 v254, v227, v254
	v_exp_f32_e32 v229, v229
	v_sub_f32_e32 v230, v230, v190
	v_add_f32_e32 v254, v228, v254
	v_exp_f32_e32 v230, v230
	v_sub_f32_e32 v231, v231, v190
	v_add_f32_e32 v254, v229, v254
	v_exp_f32_e32 v231, v231
	v_sub_f32_e32 v232, v232, v190
	v_add_f32_e32 v254, v230, v254
	v_exp_f32_e32 v232, v232
	v_sub_f32_e32 v233, v233, v190
	v_add_f32_e32 v254, v231, v254
	v_exp_f32_e32 v233, v233
	v_sub_f32_e32 v234, v234, v190
	v_add_f32_e32 v254, v232, v254
	v_exp_f32_e32 v234, v234
	v_sub_f32_e32 v235, v235, v190
	v_add_f32_e32 v254, v233, v254
	v_exp_f32_e32 v235, v235
	v_sub_f32_e32 v236, v236, v190
	v_add_f32_e32 v254, v234, v254
	v_exp_f32_e32 v236, v236
	v_sub_f32_e32 v237, v237, v190
	v_add_f32_e32 v254, v235, v254
	v_exp_f32_e32 v237, v237
	v_add_f32_e32 v254, v236, v254
	v_add_f32_e32 v254, v237, v254
	v_cvt_pk_bf16_f32 v242, v222, v223
	v_cvt_pk_bf16_f32 v243, v224, v225
	v_cvt_pk_bf16_f32 v244, v226, v227
	v_cvt_pk_bf16_f32 v245, v228, v229
	v_cvt_pk_bf16_f32 v250, v230, v231
	v_cvt_pk_bf16_f32 v251, v232, v233
	v_cvt_pk_bf16_f32 v252, v234, v235
	v_cvt_pk_bf16_f32 v253, v236, v237
	v_add_f32_e32 v195, v195, v254
	s_nop 1
	s_waitcnt lgkmcnt(8)
	v_mfma_f32_32x32x16_bf16 v[112:127], v[238:241], v[242:245], v[112:127]
	ds_read_b64_tr_b16 v[238:239], v218 offset:16640
	ds_read_b64_tr_b16 v[240:241], v218 offset:20736
	s_waitcnt lgkmcnt(8)
	v_mfma_f32_32x32x16_bf16 v[96:111], v[128:131], v[242:245], v[96:111]
	ds_read_b64_tr_b16 v[222:223], v219 offset:16640
	ds_read_b64_tr_b16 v[224:225], v219 offset:20736
	s_waitcnt lgkmcnt(8)
	v_mfma_f32_32x32x16_bf16 v[80:95], v[206:209], v[242:245], v[80:95]
	ds_read_b64_tr_b16 v[206:207], v221 offset:16640
	ds_read_b64_tr_b16 v[208:209], v221 offset:20736
	s_waitcnt lgkmcnt(8)
	v_mfma_f32_32x32x16_bf16 v[64:79], v[210:213], v[242:245], v[64:79]
	ds_read_b64_tr_b16 v[210:211], v205 offset:24576
	ds_read_b64_tr_b16 v[212:213], v205 offset:28672
	s_waitcnt lgkmcnt(8)
	v_mfma_f32_32x32x16_bf16 v[48:63], v[214:217], v[242:245], v[48:63]
	ds_read_b64_tr_b16 v[214:215], v218 offset:24576
	ds_read_b64_tr_b16 v[216:217], v218 offset:28672
	s_waitcnt lgkmcnt(8)
	v_mfma_f32_32x32x16_bf16 v[32:47], v[238:241], v[242:245], v[32:47]
	ds_read_b64_tr_b16 v[238:239], v219 offset:24576
	ds_read_b64_tr_b16 v[240:241], v219 offset:28672
	s_waitcnt lgkmcnt(8)
	v_mfma_f32_32x32x16_bf16 v[16:31], v[222:225], v[242:245], v[16:31]
	ds_read_b64_tr_b16 v[222:223], v221 offset:24576
	ds_read_b64_tr_b16 v[224:225], v221 offset:28672
	s_waitcnt lgkmcnt(8)
	v_mfma_f32_32x32x16_bf16 v[0:15], v[206:209], v[242:245], v[0:15]
	ds_read_b64_tr_b16 v[206:207], v205 offset:24832
	ds_read_b64_tr_b16 v[208:209], v205 offset:28928
	s_waitcnt lgkmcnt(8)
	v_mfma_f32_32x32x16_bf16 v[112:127], v[210:213], v[250:253], v[112:127]
	ds_read_b64_tr_b16 v[210:211], v218 offset:24832
	ds_read_b64_tr_b16 v[212:213], v218 offset:28928
	s_waitcnt lgkmcnt(8)
	v_mfma_f32_32x32x16_bf16 v[96:111], v[214:217], v[250:253], v[96:111]
	ds_read_b64_tr_b16 v[214:215], v219 offset:24832
	ds_read_b64_tr_b16 v[216:217], v219 offset:28928
	s_waitcnt lgkmcnt(8)
	v_mfma_f32_32x32x16_bf16 v[80:95], v[238:241], v[250:253], v[80:95]
	ds_read_b64_tr_b16 v[238:239], v221 offset:24832
	ds_read_b64_tr_b16 v[240:241], v221 offset:28928
	s_waitcnt lgkmcnt(8)
	v_mfma_f32_32x32x16_bf16 v[64:79], v[222:225], v[250:253], v[64:79]
	s_waitcnt lgkmcnt(6)
	v_mfma_f32_32x32x16_bf16 v[48:63], v[206:209], v[250:253], v[48:63]
	s_waitcnt lgkmcnt(4)
	v_mfma_f32_32x32x16_bf16 v[32:47], v[210:213], v[250:253], v[32:47]
	s_waitcnt lgkmcnt(2)
	v_mfma_f32_32x32x16_bf16 v[16:31], v[214:217], v[250:253], v[16:31]
	s_waitcnt lgkmcnt(0)
	v_mfma_f32_32x32x16_bf16 v[0:15], v[238:241], v[250:253], v[0:15]
	ds_read_b128 v[206:209], v196
	ds_read_b128 v[210:213], v197
	ds_read_b128 v[214:217], v198
	ds_read_b128 v[238:241], v199
	ds_read_b128 v[242:245], v200
	ds_read_b128 v[250:253], v201
	ds_read_b128 v[222:225], v202
	ds_read_b128 v[226:229], v203
	s_branch .Latt_end_1
.Latt_slow_1s2:
.Latt_slow_1:
	s_waitcnt lgkmcnt(0)
	s_lshl_b32 s89, s33, 14
	s_add_i32 s90, s89, 0
	v_add_u32_e32 v207, s90, v196
	ds_read_b128 v[128:131], v207
	v_add_u32_e32 v208, s90, v197
	ds_read_b128 v[210:213], v208
	v_add_u32_e32 v209, s90, v198
	v_lshrrev_b32_e32 v205, 3, v204
	s_add_i32 s91, s4, 31
	v_and_or_b32 v206, v204, 31, s83
	s_cmp_le_i32 s91, s83
	s_waitcnt lgkmcnt(1)
	v_mfma_f32_32x32x16_bf16 v[128:143], v[128:131], v[144:147], 0
	s_waitcnt lgkmcnt(0)
	v_mfma_f32_32x32x16_bf16 v[128:143], v[210:213], v[148:151], v[128:143]
	ds_read_b128 v[212:215], v209
	v_add_u32_e32 v210, s90, v199
	v_add_u32_e32 v211, s90, v200
	s_waitcnt lgkmcnt(0)
	v_mfma_f32_32x32x16_bf16 v[128:143], v[212:215], v[152:155], v[128:143]
	ds_read_b128 v[212:215], v210
	s_waitcnt lgkmcnt(0)
	v_mfma_f32_32x32x16_bf16 v[128:143], v[212:215], v[156:159], v[128:143]
	ds_read_b128 v[214:217], v211
	v_add_u32_e32 v212, s90, v201
	v_add_u32_e32 v213, s90, v202
	s_waitcnt lgkmcnt(0)
	v_mfma_f32_32x32x16_bf16 v[128:143], v[214:217], v[160:163], v[128:143]
	ds_read_b128 v[214:217], v212
	s_waitcnt lgkmcnt(0)
	v_mfma_f32_32x32x16_bf16 v[128:143], v[214:217], v[164:167], v[128:143]
	ds_read_b128 v[216:219], v213
	v_add_u32_e32 v215, s90, v203
	v_and_b32_e32 v214, 4, v205
	s_waitcnt lgkmcnt(0)
	v_mfma_f32_32x32x16_bf16 v[128:143], v[216:219], v[168:171], v[128:143]
	ds_read_b128 v[216:219], v215
	s_waitcnt lgkmcnt(0)
	v_mfma_f32_32x32x16_bf16 v[128:143], v[216:219], v[172:175], v[128:143]
	s_cbranch_scc1 .LBB0_869
	v_add_u32_e32 v205, s4, v214
	v_cmp_lt_i32_e32 vcc, v205, v206
	v_add_u32_e32 v216, 2, v205
	s_nop 7
	v_cndmask_b32_e32 v129, v192, v129, vcc
	v_cmp_le_i32_e32 vcc, v205, v206
	s_nop 1
	v_cndmask_b32_e32 v128, v192, v128, vcc
	v_cmp_le_i32_e32 vcc, v216, v206
	v_add_u32_e32 v216, 3, v205
	s_nop 0
	v_cndmask_b32_e32 v130, v192, v130, vcc
	v_cmp_le_i32_e32 vcc, v216, v206
	v_add_u32_e32 v216, 8, v205
	s_nop 0
	v_cndmask_b32_e32 v131, v192, v131, vcc
	v_cmp_le_i32_e32 vcc, v216, v206
	v_add_u32_e32 v216, 9, v205
	s_nop 0
	v_cndmask_b32_e32 v132, v192, v132, vcc
	v_cmp_le_i32_e32 vcc, v216, v206
	v_add_u32_e32 v216, 10, v205
	s_nop 0
	v_cndmask_b32_e32 v133, v192, v133, vcc
	v_cmp_le_i32_e32 vcc, v216, v206
	v_add_u32_e32 v216, 11, v205
	s_nop 0
	v_cndmask_b32_e32 v134, v192, v134, vcc
	v_cmp_le_i32_e32 vcc, v216, v206
	v_add_u32_e32 v216, 16, v205
	s_nop 0
	v_cndmask_b32_e32 v135, v192, v135, vcc
	v_cmp_le_i32_e32 vcc, v216, v206
	v_add_u32_e32 v216, 17, v205
	s_nop 0
	v_cndmask_b32_e32 v136, v192, v136, vcc
	v_cmp_le_i32_e32 vcc, v216, v206
	v_add_u32_e32 v216, 18, v205
	s_nop 0
	v_cndmask_b32_e32 v137, v192, v137, vcc
	v_cmp_le_i32_e32 vcc, v216, v206
	v_add_u32_e32 v216, 19, v205
	s_nop 0
	v_cndmask_b32_e32 v138, v192, v138, vcc
	v_cmp_le_i32_e32 vcc, v216, v206
	v_add_u32_e32 v216, 24, v205
	s_nop 0
	v_cndmask_b32_e32 v139, v192, v139, vcc
	v_cmp_le_i32_e32 vcc, v216, v206
	v_add_u32_e32 v216, 25, v205
	s_nop 0
	v_cndmask_b32_e32 v140, v192, v140, vcc
	v_cmp_le_i32_e32 vcc, v216, v206
	v_add_u32_e32 v216, 26, v205
	v_add_u32_e32 v205, 27, v205
	v_cndmask_b32_e32 v141, v192, v141, vcc
	v_cmp_le_i32_e32 vcc, v216, v206
	s_nop 1
	v_cndmask_b32_e32 v142, v192, v142, vcc
	v_cmp_le_i32_e32 vcc, v205, v206
	s_nop 1
	v_cndmask_b32_e32 v143, v192, v143, vcc

.LBB0_876:
	v_sub_f32_e32 v128, v128, v190
	v_exp_f32_e32 v128, v128
	v_sub_f32_e32 v129, v129, v190
	v_exp_f32_e32 v129, v129
	v_sub_f32_e32 v130, v130, v190
	v_exp_f32_e32 v130, v130
	v_sub_f32_e32 v131, v131, v190
	v_exp_f32_e32 v131, v131
	v_sub_f32_e32 v132, v132, v190
	v_add_f32_e32 v206, 0, v128
	v_exp_f32_e32 v132, v132
	v_sub_f32_e32 v133, v133, v190
	v_add_f32_e32 v206, v129, v206
	v_exp_f32_e32 v133, v133
	v_sub_f32_e32 v134, v134, v190
	v_add_f32_e32 v206, v130, v206
	v_exp_f32_e32 v134, v134
	v_sub_f32_e32 v135, v135, v190
	v_add_f32_e32 v206, v131, v206
	v_exp_f32_e32 v135, v135
	v_sub_f32_e32 v136, v136, v190
	v_add_f32_e32 v206, v132, v206
	v_exp_f32_e32 v136, v136
	v_sub_f32_e32 v137, v137, v190
	v_add_f32_e32 v206, v133, v206
	v_exp_f32_e32 v137, v137
	v_sub_f32_e32 v138, v138, v190
	v_add_f32_e32 v206, v134, v206
	v_exp_f32_e32 v138, v138
	v_sub_f32_e32 v139, v139, v190
	v_add_f32_e32 v206, v135, v206
	v_exp_f32_e32 v139, v139
	v_sub_f32_e32 v140, v140, v190
	v_add_f32_e32 v206, v136, v206
	v_exp_f32_e32 v140, v140
	v_sub_f32_e32 v141, v141, v190
	v_add_f32_e32 v206, v137, v206
	v_exp_f32_e32 v141, v141
	v_sub_f32_e32 v142, v142, v190
	v_add_f32_e32 v206, v138, v206
	v_exp_f32_e32 v142, v142
	v_sub_f32_e32 v143, v143, v190
	v_add_f32_e32 v206, v139, v206
	v_exp_f32_e32 v143, v143
	v_add_f32_e32 v206, v140, v206
	v_add_f32_e32 v206, v141, v206
	v_add_f32_e32 v206, v142, v206
	v_add_u32_e32 v208, 0xc000, v216
	v_add_f32_e32 v216, v143, v206
	v_cvt_pk_bf16_f32 v128, v128, v129
	v_cvt_pk_bf16_f32 v129, v130, v131
	v_cvt_pk_bf16_f32 v130, v132, v133
	v_cvt_pk_bf16_f32 v131, v134, v135
	v_cvt_pk_bf16_f32 v132, v136, v137
	v_cvt_pk_bf16_f32 v133, v138, v139
	v_cvt_pk_bf16_f32 v134, v140, v141
	v_cvt_pk_bf16_f32 v135, v142, v143
	v_add_u32_e32 v219, v208, v205
	ds_read_b64_tr_b16 v[136:137], v219 offset:16384
	ds_read_b64_tr_b16 v[138:139], v219 offset:20480
	v_add_u32_e32 v221, v208, v204
	ds_read_b64_tr_b16 v[142:143], v219 offset:20736
	ds_read_b64_tr_b16 v[140:141], v219 offset:16640
	v_add_u32_e32 v217, v208, v217
	v_add_u32_e32 v218, v208, v218
	s_waitcnt lgkmcnt(2)
	v_mfma_f32_32x32x16_bf16 v[112:127], v[136:139], v[128:131], v[112:127]
	ds_read_b64_tr_b16 v[136:137], v221 offset:16384
	ds_read_b64_tr_b16 v[138:139], v221 offset:20480
	ds_read_b64_tr_b16 v[206:207], v221 offset:20736
	ds_read_b64_tr_b16 v[204:205], v221 offset:16640
	v_add_f32_e32 v195, v195, v216
	s_waitcnt lgkmcnt(2)
	v_mfma_f32_32x32x16_bf16 v[96:111], v[136:139], v[128:131], v[96:111]
	ds_read_b64_tr_b16 v[136:137], v217 offset:16384
	ds_read_b64_tr_b16 v[138:139], v217 offset:20480
	ds_read_b64_tr_b16 v[210:211], v217 offset:20736
	ds_read_b64_tr_b16 v[208:209], v217 offset:16640
	s_waitcnt lgkmcnt(2)
	v_mfma_f32_32x32x16_bf16 v[80:95], v[136:139], v[128:131], v[80:95]
	ds_read_b64_tr_b16 v[136:137], v218 offset:16384
	ds_read_b64_tr_b16 v[138:139], v218 offset:20480
	ds_read_b64_tr_b16 v[214:215], v218 offset:20736
	ds_read_b64_tr_b16 v[212:213], v218 offset:16640
	s_waitcnt lgkmcnt(2)
	v_mfma_f32_32x32x16_bf16 v[64:79], v[136:139], v[128:131], v[64:79]
	v_mfma_f32_32x32x16_bf16 v[48:63], v[140:143], v[128:131], v[48:63]
	v_mfma_f32_32x32x16_bf16 v[32:47], v[204:207], v[128:131], v[32:47]
	v_mfma_f32_32x32x16_bf16 v[16:31], v[208:211], v[128:131], v[16:31]
	s_waitcnt lgkmcnt(0)
	v_mfma_f32_32x32x16_bf16 v[0:15], v[212:215], v[128:131], v[0:15]
	ds_read_b64_tr_b16 v[128:129], v219 offset:24576
	ds_read_b64_tr_b16 v[130:131], v219 offset:28672
	ds_read_b64_tr_b16 v[138:139], v219 offset:28928
	ds_read_b64_tr_b16 v[136:137], v219 offset:24832
	s_waitcnt lgkmcnt(2)
	v_mfma_f32_32x32x16_bf16 v[112:127], v[128:131], v[132:135], v[112:127]
	ds_read_b64_tr_b16 v[128:129], v221 offset:24576
	ds_read_b64_tr_b16 v[130:131], v221 offset:28672
	ds_read_b64_tr_b16 v[142:143], v221 offset:28928
	ds_read_b64_tr_b16 v[140:141], v221 offset:24832
	s_waitcnt lgkmcnt(2)
	v_mfma_f32_32x32x16_bf16 v[96:111], v[128:131], v[132:135], v[96:111]
	ds_read_b64_tr_b16 v[128:129], v217 offset:24576
	ds_read_b64_tr_b16 v[130:131], v217 offset:28672
	ds_read_b64_tr_b16 v[206:207], v217 offset:28928
	ds_read_b64_tr_b16 v[204:205], v217 offset:24832
	s_waitcnt lgkmcnt(2)
	v_mfma_f32_32x32x16_bf16 v[80:95], v[128:131], v[132:135], v[80:95]
	ds_read_b64_tr_b16 v[128:129], v218 offset:24576
	ds_read_b64_tr_b16 v[130:131], v218 offset:28672
	ds_read_b64_tr_b16 v[210:211], v218 offset:28928
	ds_read_b64_tr_b16 v[208:209], v218 offset:24832
	s_waitcnt lgkmcnt(2)
	v_mfma_f32_32x32x16_bf16 v[64:79], v[128:131], v[132:135], v[64:79]
	v_mfma_f32_32x32x16_bf16 v[48:63], v[136:139], v[132:135], v[48:63]
	v_mfma_f32_32x32x16_bf16 v[32:47], v[140:143], v[132:135], v[32:47]
	v_mfma_f32_32x32x16_bf16 v[16:31], v[204:207], v[132:135], v[16:31]
	s_waitcnt lgkmcnt(0)
	v_mfma_f32_32x32x16_bf16 v[0:15], v[208:211], v[132:135], v[0:15]
.LBB0_877:
	s_waitcnt lgkmcnt(0)
.Latt_end_1:
	s_andn2_b64 vcc, exec, s[18:19]
	s_mov_b64 s[18:19], -1
	s_cbranch_vccnz .LBB0_879
	s_waitcnt vmcnt(0)
	s_mov_b64 s[18:19], 0

.LBB0_885:
	s_cmp_gt_i32 s84, s81
	s_cbranch_scc1 .LBB0_896
	s_add_i32 s100, s84, 63
	s_cmp_le_i32 s100, s80
	s_cbranch_scc0 .Latt_slow_2
	s_cmp_eq_u32 s38, 1
	s_cbranch_scc1 .Latt_slot1_2
	s_cmp_eq_u32 s38, 2
	s_cbranch_scc1 .Latt_slot2_2
	s_cmp_lg_u32 s84, 0
	s_cbranch_scc1 .Latt_vstep_2s0
	ds_read_b128 v[206:209], v195
	ds_read_b128 v[210:213], v196
	ds_read_b128 v[214:217], v197
	ds_read_b128 v[238:241], v198
	ds_read_b128 v[242:245], v199
	ds_read_b128 v[250:253], v200
	ds_read_b128 v[222:225], v201
	ds_read_b128 v[226:229], v202
	v_bfe_u32 v246, v204, 2, 2
	v_bfe_u32 v247, v204, 5, 1
	v_lshl_or_b32 v247, v247, 2, v246
	v_and_b32_e32 v249, 3, v204
	v_and_b32_e32 v254, 16, v204
	v_lshl_or_b32 v249, v249, 2, v254
	v_lshlrev_b32_e32 v249, 1, v249
	v_lshl_add_u32 v247, v247, 9, v249
	v_add_u32_e32 v247, 0xc000, v247
	v_lshlrev_b32_e32 v246, 6, v246
	v_add_u32_e32 v205, v247, v246
	v_xor_b32_e32 v249, 64, v246
	v_add_u32_e32 v218, v247, v249
	v_xor_b32_e32 v249, 0x80, v246
	v_add_u32_e32 v219, v247, v249
	v_xor_b32_e32 v249, 0xc0, v246
	v_add_u32_e32 v221, v247, v249
	s_branch .Latt_vdone_2s0

.Latt_vdone_2s0:
	s_waitcnt lgkmcnt(7)
	v_mfma_f32_32x32x16_bf16 v[128:143], v[206:209], v[144:147], 0
	ds_read_b128 v[206:209], v195 offset:8192
	s_cmp_lg_u64 s[12:13], 0
	s_cbranch_scc1 .Latt_nd0_2s0
	s_sub_i32 s100, s38, 1
	s_cmp_eq_u32 s38, 0
	s_cselect_b32 s100, 2, s100
	s_lshl_b32 s101, s100, 14
	s_add_i32 m0, s40, s101
	s_nop 0
	global_load_lds_dwordx4 v178, s[22:23]
.Latt_nd0_2s0:
	s_waitcnt lgkmcnt(7)
	v_mfma_f32_32x32x16_bf16 v[128:143], v[210:213], v[148:151], v[128:143]
	ds_read_b128 v[210:213], v196 offset:8192
	s_cmp_lg_u64 s[12:13], 0
	s_cbranch_scc1 .Latt_nd1_2s0
	s_add_i32 m0, m0, 0x400
	s_nop 0
	global_load_lds_dwordx4 v180, s[22:23]
.Latt_nd1_2s0:
	s_waitcnt lgkmcnt(7)
	v_mfma_f32_32x32x16_bf16 v[128:143], v[214:217], v[152:155], v[128:143]
	ds_read_b128 v[214:217], v197 offset:8192
	s_cmp_lg_u64 s[12:13], 0
	s_cbranch_scc1 .Latt_nd2_2s0
	s_lshl_b32 s101, s100, 15
	s_add_i32 m0, s41, s101
	s_add_u32 s100, s22, 0x1000
	s_addc_u32 s101, s23, 0
	global_load_lds_dwordx4 v182, s[100:101]
.Latt_nd2_2s0:
	s_waitcnt lgkmcnt(7)
	v_mfma_f32_32x32x16_bf16 v[128:143], v[238:241], v[156:159], v[128:143]
	ds_read_b128 v[238:241], v198 offset:8192
	s_cmp_lg_u64 s[12:13], 0
	s_cbranch_scc1 .Latt_nd3_2s0
	s_add_i32 m0, m0, 0x400
	s_nop 0
	global_load_lds_dwordx4 v184, s[100:101]
.Latt_nd3_2s0:
	s_waitcnt lgkmcnt(7)
	v_mfma_f32_32x32x16_bf16 v[128:143], v[242:245], v[160:163], v[128:143]
	s_cmp_lg_u64 s[12:13], 0
	s_cbranch_scc1 .Latt_nd4_2s0
	s_add_i32 m0, m0, 0x400
	s_nop 0
	global_load_lds_dwordx4 v186, s[100:101]
.Latt_nd4_2s0:
	s_waitcnt lgkmcnt(6)
	v_mfma_f32_32x32x16_bf16 v[128:143], v[250:253], v[164:167], v[128:143]
	s_cmp_lg_u64 s[12:13], 0
	s_cbranch_scc1 .Latt_nd5_2s0
	s_add_i32 m0, m0, 0x400
	s_nop 0
	global_load_lds_dwordx4 v188, s[100:101]
.Latt_nd5_2s0:
	s_waitcnt lgkmcnt(5)
	v_mfma_f32_32x32x16_bf16 v[128:143], v[222:225], v[168:171], v[128:143]
	s_waitcnt lgkmcnt(4)
	v_mfma_f32_32x32x16_bf16 v[128:143], v[226:229], v[172:175], v[128:143]
	s_waitcnt lgkmcnt(3)
	v_mfma_f32_32x32x16_bf16 v[222:237], v[206:209], v[144:147], 0
	ds_read_b128 v[206:209], v199 offset:8192
	s_nop 8
	v_max3_f32 v246, v128, v129, v130
	v_max3_f32 v247, v131, v132, v133
	v_max3_f32 v246, v246, v134, v135
	v_max3_f32 v247, v247, v136, v137
	v_max3_f32 v246, v246, v138, v139
	v_max3_f32 v247, v247, v140, v141
	v_max3_f32 v246, v246, v142, v143
	s_waitcnt lgkmcnt(3)
	v_mfma_f32_32x32x16_bf16 v[222:237], v[210:213], v[148:151], v[222:237]
	ds_read_b128 v[210:213], v200 offset:8192
	v_max_f32_e32 v246, v246, v247
	v_mov_b32_e32 v247, v246
	v_add_f32_e32 v249, 0x41000000, v190
	s_nop 1
	v_permlane32_swap_b32_e32 v246, v247
	v_max_f32_e32 v246, v246, v247
	v_cmp_gt_f32_e32 vcc, v246, v249
	s_cbranch_vccz .Latt_nr0_2s0
	v_max_f32_e32 v246, v190, v246
	v_sub_f32_e32 v190, v190, v246
	v_exp_f32_e32 v190, v190
	s_nop 0
	v_pk_mul_f32 v[126:127], v[126:127], v[190:191] op_sel_hi:[1,0]
	v_pk_mul_f32 v[124:125], v[124:125], v[190:191] op_sel_hi:[1,0]
	v_pk_mul_f32 v[122:123], v[122:123], v[190:191] op_sel_hi:[1,0]
	v_pk_mul_f32 v[120:121], v[120:121], v[190:191] op_sel_hi:[1,0]
	v_pk_mul_f32 v[118:119], v[118:119], v[190:191] op_sel_hi:[1,0]
	v_pk_mul_f32 v[116:117], v[116:117], v[190:191] op_sel_hi:[1,0]
	v_pk_mul_f32 v[114:115], v[114:115], v[190:191] op_sel_hi:[1,0]
	v_pk_mul_f32 v[112:113], v[112:113], v[190:191] op_sel_hi:[1,0]
	v_pk_mul_f32 v[110:111], v[110:111], v[190:191] op_sel_hi:[1,0]
	v_pk_mul_f32 v[108:109], v[108:109], v[190:191] op_sel_hi:[1,0]
	v_pk_mul_f32 v[106:107], v[106:107], v[190:191] op_sel_hi:[1,0]
	v_pk_mul_f32 v[104:105], v[104:105], v[190:191] op_sel_hi:[1,0]
	v_pk_mul_f32 v[102:103], v[102:103], v[190:191] op_sel_hi:[1,0]
	v_pk_mul_f32 v[100:101], v[100:101], v[190:191] op_sel_hi:[1,0]
	v_pk_mul_f32 v[98:99], v[98:99], v[190:191] op_sel_hi:[1,0]
	v_pk_mul_f32 v[96:97], v[96:97], v[190:191] op_sel_hi:[1,0]
	v_pk_mul_f32 v[94:95], v[94:95], v[190:191] op_sel_hi:[1,0]
	v_pk_mul_f32 v[92:93], v[92:93], v[190:191] op_sel_hi:[1,0]
	v_pk_mul_f32 v[90:91], v[90:91], v[190:191] op_sel_hi:[1,0]
	v_pk_mul_f32 v[88:89], v[88:89], v[190:191] op_sel_hi:[1,0]
	v_pk_mul_f32 v[86:87], v[86:87], v[190:191] op_sel_hi:[1,0]
	v_pk_mul_f32 v[84:85], v[84:85], v[190:191] op_sel_hi:[1,0]
	v_pk_mul_f32 v[82:83], v[82:83], v[190:191] op_sel_hi:[1,0]
	v_pk_mul_f32 v[80:81], v[80:81], v[190:191] op_sel_hi:[1,0]
	v_pk_mul_f32 v[78:79], v[78:79], v[190:191] op_sel_hi:[1,0]
	v_pk_mul_f32 v[76:77], v[76:77], v[190:191] op_sel_hi:[1,0]
	v_pk_mul_f32 v[74:75], v[74:75], v[190:191] op_sel_hi:[1,0]
	v_pk_mul_f32 v[72:73], v[72:73], v[190:191] op_sel_hi:[1,0]
	v_pk_mul_f32 v[70:71], v[70:71], v[190:191] op_sel_hi:[1,0]
	v_pk_mul_f32 v[68:69], v[68:69], v[190:191] op_sel_hi:[1,0]
	v_pk_mul_f32 v[66:67], v[66:67], v[190:191] op_sel_hi:[1,0]
	v_pk_mul_f32 v[64:65], v[64:65], v[190:191] op_sel_hi:[1,0]
	v_pk_mul_f32 v[62:63], v[62:63], v[190:191] op_sel_hi:[1,0]
	v_pk_mul_f32 v[60:61], v[60:61], v[190:191] op_sel_hi:[1,0]
	v_pk_mul_f32 v[58:59], v[58:59], v[190:191] op_sel_hi:[1,0]
	v_pk_mul_f32 v[56:57], v[56:57], v[190:191] op_sel_hi:[1,0]
	v_pk_mul_f32 v[54:55], v[54:55], v[190:191] op_sel_hi:[1,0]
	v_pk_mul_f32 v[52:53], v[52:53], v[190:191] op_sel_hi:[1,0]
	v_pk_mul_f32 v[50:51], v[50:51], v[190:191] op_sel_hi:[1,0]
	v_pk_mul_f32 v[48:49], v[48:49], v[190:191] op_sel_hi:[1,0]
	v_pk_mul_f32 v[46:47], v[46:47], v[190:191] op_sel_hi:[1,0]
	v_pk_mul_f32 v[44:45], v[44:45], v[190:191] op_sel_hi:[1,0]
	v_pk_mul_f32 v[42:43], v[42:43], v[190:191] op_sel_hi:[1,0]
	v_pk_mul_f32 v[40:41], v[40:41], v[190:191] op_sel_hi:[1,0]
	v_pk_mul_f32 v[38:39], v[38:39], v[190:191] op_sel_hi:[1,0]
	v_pk_mul_f32 v[36:37], v[36:37], v[190:191] op_sel_hi:[1,0]
	v_pk_mul_f32 v[34:35], v[34:35], v[190:191] op_sel_hi:[1,0]
	v_pk_mul_f32 v[32:33], v[32:33], v[190:191] op_sel_hi:[1,0]
	v_pk_mul_f32 v[30:31], v[30:31], v[190:191] op_sel_hi:[1,0]
	v_pk_mul_f32 v[28:29], v[28:29], v[190:191] op_sel_hi:[1,0]
	v_pk_mul_f32 v[26:27], v[26:27], v[190:191] op_sel_hi:[1,0]
	v_pk_mul_f32 v[24:25], v[24:25], v[190:191] op_sel_hi:[1,0]
	v_pk_mul_f32 v[22:23], v[22:23], v[190:191] op_sel_hi:[1,0]
	v_pk_mul_f32 v[20:21], v[20:21], v[190:191] op_sel_hi:[1,0]
	v_pk_mul_f32 v[18:19], v[18:19], v[190:191] op_sel_hi:[1,0]
	v_pk_mul_f32 v[16:17], v[16:17], v[190:191] op_sel_hi:[1,0]
	v_pk_mul_f32 v[14:15], v[14:15], v[190:191] op_sel_hi:[1,0]
	v_pk_mul_f32 v[12:13], v[12:13], v[190:191] op_sel_hi:[1,0]
	v_pk_mul_f32 v[10:11], v[10:11], v[190:191] op_sel_hi:[1,0]
	v_pk_mul_f32 v[8:9], v[8:9], v[190:191] op_sel_hi:[1,0]
	v_pk_mul_f32 v[6:7], v[6:7], v[190:191] op_sel_hi:[1,0]
	v_pk_mul_f32 v[4:5], v[4:5], v[190:191] op_sel_hi:[1,0]
	v_pk_mul_f32 v[2:3], v[2:3], v[190:191] op_sel_hi:[1,0]
	v_pk_mul_f32 v[0:1], v[0:1], v[190:191] op_sel_hi:[1,0]
	v_mul_f32_e32 v203, v203, v190
	v_mov_b32_e32 v190, v246
.Latt_nr0_2s0:
	s_waitcnt lgkmcnt(3)
	v_mfma_f32_32x32x16_bf16 v[222:237], v[214:217], v[152:155], v[222:237]
	ds_read_b128 v[214:217], v201 offset:8192
	v_sub_f32_e32 v128, v128, v190
	v_exp_f32_e32 v128, v128
	v_sub_f32_e32 v129, v129, v190
	v_exp_f32_e32 v129, v129
	v_sub_f32_e32 v130, v130, v190
	s_waitcnt lgkmcnt(3)
	v_mfma_f32_32x32x16_bf16 v[222:237], v[238:241], v[156:159], v[222:237]
	ds_read_b128 v[238:241], v202 offset:8192
	v_add_f32_e32 v254, 0, v128
	v_exp_f32_e32 v130, v130
	v_sub_f32_e32 v131, v131, v190
	v_add_f32_e32 v254, v129, v254
	v_exp_f32_e32 v131, v131
	s_waitcnt lgkmcnt(3)
	v_mfma_f32_32x32x16_bf16 v[222:237], v[206:209], v[160:163], v[222:237]
	ds_read_b64_tr_b16 v[206:207], v205
	ds_read_b64_tr_b16 v[208:209], v205 offset:4096
	v_sub_f32_e32 v132, v132, v190
	v_add_f32_e32 v254, v130, v254
	v_exp_f32_e32 v132, v132
	v_sub_f32_e32 v133, v133, v190
	v_add_f32_e32 v254, v131, v254
	s_waitcnt lgkmcnt(4)
	v_mfma_f32_32x32x16_bf16 v[222:237], v[210:213], v[164:167], v[222:237]
	ds_read_b64_tr_b16 v[210:211], v218
	ds_read_b64_tr_b16 v[212:213], v218 offset:4096
	v_exp_f32_e32 v133, v133
	v_sub_f32_e32 v134, v134, v190
	v_add_f32_e32 v254, v132, v254
	v_exp_f32_e32 v134, v134
	s_waitcnt lgkmcnt(5)
	v_mfma_f32_32x32x16_bf16 v[222:237], v[214:217], v[168:171], v[222:237]
	ds_read_b64_tr_b16 v[214:215], v219
	ds_read_b64_tr_b16 v[216:217], v219 offset:4096
	v_sub_f32_e32 v135, v135, v190
	v_add_f32_e32 v254, v133, v254
	v_exp_f32_e32 v135, v135
	s_nop 0
	s_waitcnt lgkmcnt(6)
	v_mfma_f32_32x32x16_bf16 v[222:237], v[238:241], v[172:175], v[222:237]
	ds_read_b64_tr_b16 v[238:239], v221
	ds_read_b64_tr_b16 v[240:241], v221 offset:4096
	v_cvt_pk_bf16_f32 v242, v128, v129
	v_cvt_pk_bf16_f32 v243, v130, v131
	v_cvt_pk_bf16_f32 v244, v132, v133
	v_cvt_pk_bf16_f32 v245, v134, v135
	s_nop 1
	s_waitcnt lgkmcnt(6)
	v_mfma_f32_32x32x16_bf16 v[112:127], v[206:209], v[242:245], v[112:127]
	ds_read_b64_tr_b16 v[206:207], v205 offset:256
	ds_read_b64_tr_b16 v[208:209], v205 offset:4352
	v_sub_f32_e32 v136, v136, v190
	v_add_f32_e32 v254, v134, v254
	v_exp_f32_e32 v136, v136
	v_sub_f32_e32 v137, v137, v190
	v_add_f32_e32 v254, v135, v254
	s_waitcnt lgkmcnt(6)
	v_mfma_f32_32x32x16_bf16 v[96:111], v[210:213], v[242:245], v[96:111]
	ds_read_b64_tr_b16 v[210:211], v218 offset:256
	ds_read_b64_tr_b16 v[212:213], v218 offset:4352
	v_exp_f32_e32 v137, v137
	v_sub_f32_e32 v138, v138, v190
	v_add_f32_e32 v254, v136, v254
	v_exp_f32_e32 v138, v138
	v_sub_f32_e32 v139, v139, v190
	s_waitcnt lgkmcnt(6)
	v_mfma_f32_32x32x16_bf16 v[80:95], v[214:217], v[242:245], v[80:95]
	ds_read_b64_tr_b16 v[214:215], v219 offset:256
	ds_read_b64_tr_b16 v[216:217], v219 offset:4352
	v_add_f32_e32 v254, v137, v254
	v_exp_f32_e32 v139, v139
	v_sub_f32_e32 v140, v140, v190
	v_add_f32_e32 v254, v138, v254
	s_waitcnt lgkmcnt(6)
	v_mfma_f32_32x32x16_bf16 v[64:79], v[238:241], v[242:245], v[64:79]
	ds_read_b64_tr_b16 v[238:239], v221 offset:256
	ds_read_b64_tr_b16 v[240:241], v221 offset:4352
	v_exp_f32_e32 v140, v140
	v_sub_f32_e32 v141, v141, v190
	v_add_f32_e32 v254, v139, v254
	v_exp_f32_e32 v141, v141
	s_waitcnt lgkmcnt(6)
	v_mfma_f32_32x32x16_bf16 v[48:63], v[206:209], v[242:245], v[48:63]
	ds_read_b64_tr_b16 v[206:207], v205 offset:8192
	ds_read_b64_tr_b16 v[208:209], v205 offset:12288
	v_sub_f32_e32 v142, v142, v190
	v_add_f32_e32 v254, v140, v254
	v_exp_f32_e32 v142, v142
	v_sub_f32_e32 v143, v143, v190
	s_waitcnt lgkmcnt(6)
	v_mfma_f32_32x32x16_bf16 v[32:47], v[210:213], v[242:245], v[32:47]
	ds_read_b64_tr_b16 v[210:211], v218 offset:8192
	ds_read_b64_tr_b16 v[212:213], v218 offset:12288
	v_add_f32_e32 v254, v141, v254
	v_exp_f32_e32 v143, v143
	v_add_f32_e32 v254, v142, v254
	v_add_f32_e32 v254, v143, v254
	s_waitcnt lgkmcnt(6)
	v_mfma_f32_32x32x16_bf16 v[16:31], v[214:217], v[242:245], v[16:31]
	ds_read_b64_tr_b16 v[214:215], v219 offset:8192
	ds_read_b64_tr_b16 v[216:217], v219 offset:12288
	v_cvt_pk_bf16_f32 v250, v136, v137
	v_cvt_pk_bf16_f32 v251, v138, v139
	v_cvt_pk_bf16_f32 v252, v140, v141
	v_cvt_pk_bf16_f32 v253, v142, v143
	v_add_f32_e32 v203, v203, v254
	s_waitcnt lgkmcnt(6)
	v_mfma_f32_32x32x16_bf16 v[0:15], v[238:241], v[242:245], v[0:15]
	ds_read_b64_tr_b16 v[238:239], v221 offset:8192
	ds_read_b64_tr_b16 v[240:241], v221 offset:12288
	ds_read_b64_tr_b16 v[128:129], v205 offset:8448
	ds_read_b64_tr_b16 v[130:131], v205 offset:12544
	s_waitcnt lgkmcnt(8)
	v_mfma_f32_32x32x16_bf16 v[112:127], v[206:209], v[250:253], v[112:127]
	ds_read_b64_tr_b16 v[206:207], v218 offset:8448
	ds_read_b64_tr_b16 v[208:209], v218 offset:12544
	v_max3_f32 v246, v222, v223, v224
	v_max3_f32 v247, v225, v226, v227
	v_max3_f32 v246, v246, v228, v229
	v_max3_f32 v247, v247, v230, v231
	v_max3_f32 v246, v246, v232, v233
	s_waitcnt lgkmcnt(8)
	v_mfma_f32_32x32x16_bf16 v[96:111], v[210:213], v[250:253], v[96:111]
	ds_read_b64_tr_b16 v[210:211], v219 offset:8448
	ds_read_b64_tr_b16 v[212:213], v219 offset:12544
	v_max3_f32 v247, v247, v234, v235
	v_max3_f32 v246, v246, v236, v237
	v_max_f32_e32 v246, v246, v247
	v_mov_b32_e32 v247, v246
	v_add_f32_e32 v249, 0x41000000, v190
	s_waitcnt lgkmcnt(8)
	v_mfma_f32_32x32x16_bf16 v[80:95], v[214:217], v[250:253], v[80:95]
	ds_read_b64_tr_b16 v[214:215], v221 offset:8448
	ds_read_b64_tr_b16 v[216:217], v221 offset:12544
	s_nop 1
	v_permlane32_swap_b32_e32 v246, v247
	v_max_f32_e32 v246, v246, v247
	v_cmp_gt_f32_e32 vcc, v246, v249
	s_cbranch_vccnz .Latt_rs1_2s0
	s_waitcnt lgkmcnt(8)
	v_mfma_f32_32x32x16_bf16 v[64:79], v[238:241], v[250:253], v[64:79]
	ds_read_b64_tr_b16 v[238:239], v205 offset:16384
	ds_read_b64_tr_b16 v[240:241], v205 offset:20480
	v_sub_f32_e32 v222, v222, v190
	v_exp_f32_e32 v222, v222
	v_sub_f32_e32 v223, v223, v190
	v_exp_f32_e32 v223, v223
	v_sub_f32_e32 v224, v224, v190
	v_add_f32_e32 v254, 0, v222
	s_waitcnt lgkmcnt(8)
	v_mfma_f32_32x32x16_bf16 v[48:63], v[128:131], v[250:253], v[48:63]
	ds_read_b64_tr_b16 v[128:129], v218 offset:16384
	ds_read_b64_tr_b16 v[130:131], v218 offset:20480
	v_exp_f32_e32 v224, v224
	v_sub_f32_e32 v225, v225, v190
	v_add_f32_e32 v254, v223, v254
	v_exp_f32_e32 v225, v225
	v_sub_f32_e32 v226, v226, v190
	v_add_f32_e32 v254, v224, v254
	s_waitcnt lgkmcnt(8)
	v_mfma_f32_32x32x16_bf16 v[32:47], v[206:209], v[250:253], v[32:47]
	ds_read_b64_tr_b16 v[206:207], v219 offset:16384
	ds_read_b64_tr_b16 v[208:209], v219 offset:20480
	v_exp_f32_e32 v226, v226
	v_sub_f32_e32 v227, v227, v190
	v_add_f32_e32 v254, v225, v254
	v_exp_f32_e32 v227, v227
	v_sub_f32_e32 v228, v228, v190
	s_waitcnt lgkmcnt(8)
	v_mfma_f32_32x32x16_bf16 v[16:31], v[210:213], v[250:253], v[16:31]
	ds_read_b64_tr_b16 v[210:211], v221 offset:16384
	ds_read_b64_tr_b16 v[212:213], v221 offset:20480
	v_add_f32_e32 v254, v226, v254
	v_exp_f32_e32 v228, v228
	v_sub_f32_e32 v229, v229, v190
	v_add_f32_e32 v254, v227, v254
	v_exp_f32_e32 v229, v229
	s_waitcnt lgkmcnt(8)
	v_mfma_f32_32x32x16_bf16 v[0:15], v[214:217], v[250:253], v[0:15]
	ds_read_b64_tr_b16 v[214:215], v205 offset:16640
	ds_read_b64_tr_b16 v[216:217], v205 offset:20736
	s_nop 0
	v_cvt_pk_bf16_f32 v242, v222, v223
	v_cvt_pk_bf16_f32 v243, v224, v225
	v_cvt_pk_bf16_f32 v244, v226, v227
	v_cvt_pk_bf16_f32 v245, v228, v229
	s_nop 1
	s_waitcnt lgkmcnt(8)
	v_mfma_f32_32x32x16_bf16 v[112:127], v[238:241], v[242:245], v[112:127]
	ds_read_b64_tr_b16 v[238:239], v218 offset:16640
	ds_read_b64_tr_b16 v[240:241], v218 offset:20736
	v_sub_f32_e32 v230, v230, v190
	v_add_f32_e32 v254, v228, v254
	v_exp_f32_e32 v230, v230
	v_sub_f32_e32 v231, v231, v190
	v_add_f32_e32 v254, v229, v254
	s_waitcnt lgkmcnt(8)
	v_mfma_f32_32x32x16_bf16 v[96:111], v[128:131], v[242:245], v[96:111]
	ds_read_b64_tr_b16 v[128:129], v219 offset:16640
	ds_read_b64_tr_b16 v[130:131], v219 offset:20736
	v_exp_f32_e32 v231, v231
	v_sub_f32_e32 v232, v232, v190
	v_add_f32_e32 v254, v230, v254
	v_exp_f32_e32 v232, v232
	v_sub_f32_e32 v233, v233, v190
	s_waitcnt lgkmcnt(8)
	v_mfma_f32_32x32x16_bf16 v[80:95], v[206:209], v[242:245], v[80:95]
	ds_read_b64_tr_b16 v[206:207], v221 offset:16640
	ds_read_b64_tr_b16 v[208:209], v221 offset:20736
	v_add_f32_e32 v254, v231, v254
	v_exp_f32_e32 v233, v233
	v_sub_f32_e32 v234, v234, v190
	v_add_f32_e32 v254, v232, v254
	s_waitcnt lgkmcnt(8)
	v_mfma_f32_32x32x16_bf16 v[64:79], v[210:213], v[242:245], v[64:79]
	ds_read_b64_tr_b16 v[210:211], v205 offset:24576
	ds_read_b64_tr_b16 v[212:213], v205 offset:28672
	v_exp_f32_e32 v234, v234
	v_sub_f32_e32 v235, v235, v190
	v_add_f32_e32 v254, v233, v254
	v_exp_f32_e32 v235, v235
	s_waitcnt lgkmcnt(8)
	v_mfma_f32_32x32x16_bf16 v[48:63], v[214:217], v[242:245], v[48:63]
	ds_read_b64_tr_b16 v[214:215], v218 offset:24576
	ds_read_b64_tr_b16 v[216:217], v218 offset:28672
	v_sub_f32_e32 v236, v236, v190
	v_add_f32_e32 v254, v234, v254
	v_exp_f32_e32 v236, v236
	v_sub_f32_e32 v237, v237, v190
	s_waitcnt lgkmcnt(8)
	v_mfma_f32_32x32x16_bf16 v[32:47], v[238:241], v[242:245], v[32:47]
	ds_read_b64_tr_b16 v[238:239], v219 offset:24576
	ds_read_b64_tr_b16 v[240:241], v219 offset:28672
	v_add_f32_e32 v254, v235, v254
	v_exp_f32_e32 v237, v237
	v_add_f32_e32 v254, v236, v254
	v_add_f32_e32 v254, v237, v254
	s_waitcnt lgkmcnt(8)
	v_mfma_f32_32x32x16_bf16 v[16:31], v[128:131], v[242:245], v[16:31]
	ds_read_b64_tr_b16 v[128:129], v221 offset:24576
	ds_read_b64_tr_b16 v[130:131], v221 offset:28672
	v_cvt_pk_bf16_f32 v250, v230, v231
	v_cvt_pk_bf16_f32 v251, v232, v233
	v_cvt_pk_bf16_f32 v252, v234, v235
	v_cvt_pk_bf16_f32 v253, v236, v237
	v_add_f32_e32 v203, v203, v254
	s_waitcnt lgkmcnt(8)
	v_mfma_f32_32x32x16_bf16 v[0:15], v[206:209], v[242:245], v[0:15]
	ds_read_b64_tr_b16 v[206:207], v205 offset:24832
	ds_read_b64_tr_b16 v[208:209], v205 offset:28928
	s_waitcnt lgkmcnt(8)
	v_mfma_f32_32x32x16_bf16 v[112:127], v[210:213], v[250:253], v[112:127]
	ds_read_b64_tr_b16 v[210:211], v218 offset:24832
	ds_read_b64_tr_b16 v[212:213], v218 offset:28928
	s_waitcnt lgkmcnt(8)
	v_mfma_f32_32x32x16_bf16 v[96:111], v[214:217], v[250:253], v[96:111]
	ds_read_b64_tr_b16 v[214:215], v219 offset:24832
	ds_read_b64_tr_b16 v[216:217], v219 offset:28928
	s_waitcnt lgkmcnt(8)
	v_mfma_f32_32x32x16_bf16 v[80:95], v[238:241], v[250:253], v[80:95]
	ds_read_b64_tr_b16 v[238:239], v221 offset:24832
	ds_read_b64_tr_b16 v[240:241], v221 offset:28928
	s_waitcnt lgkmcnt(8)
	v_mfma_f32_32x32x16_bf16 v[64:79], v[128:131], v[250:253], v[64:79]
	s_waitcnt lgkmcnt(6)
	v_mfma_f32_32x32x16_bf16 v[48:63], v[206:209], v[250:253], v[48:63]
	s_waitcnt lgkmcnt(4)
	v_mfma_f32_32x32x16_bf16 v[32:47], v[210:213], v[250:253], v[32:47]
	s_waitcnt lgkmcnt(2)
	v_mfma_f32_32x32x16_bf16 v[16:31], v[214:217], v[250:253], v[16:31]
	s_waitcnt lgkmcnt(0)
	v_mfma_f32_32x32x16_bf16 v[0:15], v[238:241], v[250:253], v[0:15]
	ds_read_b128 v[206:209], v195 offset:16384
	ds_read_b128 v[210:213], v196 offset:16384
	ds_read_b128 v[214:217], v197 offset:16384
	ds_read_b128 v[238:241], v198 offset:16384
	ds_read_b128 v[242:245], v199 offset:16384
	ds_read_b128 v[250:253], v200 offset:16384
	ds_read_b128 v[222:225], v201 offset:16384
	ds_read_b128 v[226:229], v202 offset:16384
	s_branch .Latt_end_2
.Latt_rs1_2s0:
	s_waitcnt lgkmcnt(8)
	v_mfma_f32_32x32x16_bf16 v[64:79], v[238:241], v[250:253], v[64:79]
	ds_read_b64_tr_b16 v[238:239], v205 offset:16384
	ds_read_b64_tr_b16 v[240:241], v205 offset:20480
	s_waitcnt lgkmcnt(8)
	v_mfma_f32_32x32x16_bf16 v[48:63], v[128:131], v[250:253], v[48:63]
	ds_read_b64_tr_b16 v[128:129], v218 offset:16384
	ds_read_b64_tr_b16 v[130:131], v218 offset:20480
	s_waitcnt lgkmcnt(8)
	v_mfma_f32_32x32x16_bf16 v[32:47], v[206:209], v[250:253], v[32:47]
	ds_read_b64_tr_b16 v[206:207], v219 offset:16384
	ds_read_b64_tr_b16 v[208:209], v219 offset:20480
	s_waitcnt lgkmcnt(8)
	v_mfma_f32_32x32x16_bf16 v[16:31], v[210:213], v[250:253], v[16:31]
	ds_read_b64_tr_b16 v[210:211], v221 offset:16384
	ds_read_b64_tr_b16 v[212:213], v221 offset:20480
	s_waitcnt lgkmcnt(8)
	v_mfma_f32_32x32x16_bf16 v[0:15], v[214:217], v[250:253], v[0:15]
	ds_read_b64_tr_b16 v[214:215], v205 offset:16640
	ds_read_b64_tr_b16 v[216:217], v205 offset:20736
	s_nop 11
	v_max_f32_e32 v246, v190, v246
	v_sub_f32_e32 v190, v190, v246
	v_exp_f32_e32 v190, v190
	s_nop 0
	v_pk_mul_f32 v[126:127], v[126:127], v[190:191] op_sel_hi:[1,0]
	v_pk_mul_f32 v[124:125], v[124:125], v[190:191] op_sel_hi:[1,0]
	v_pk_mul_f32 v[122:123], v[122:123], v[190:191] op_sel_hi:[1,0]
	v_pk_mul_f32 v[120:121], v[120:121], v[190:191] op_sel_hi:[1,0]
	v_pk_mul_f32 v[118:119], v[118:119], v[190:191] op_sel_hi:[1,0]
	v_pk_mul_f32 v[116:117], v[116:117], v[190:191] op_sel_hi:[1,0]
	v_pk_mul_f32 v[114:115], v[114:115], v[190:191] op_sel_hi:[1,0]
	v_pk_mul_f32 v[112:113], v[112:113], v[190:191] op_sel_hi:[1,0]
	v_pk_mul_f32 v[110:111], v[110:111], v[190:191] op_sel_hi:[1,0]
	v_pk_mul_f32 v[108:109], v[108:109], v[190:191] op_sel_hi:[1,0]
	v_pk_mul_f32 v[106:107], v[106:107], v[190:191] op_sel_hi:[1,0]
	v_pk_mul_f32 v[104:105], v[104:105], v[190:191] op_sel_hi:[1,0]
	v_pk_mul_f32 v[102:103], v[102:103], v[190:191] op_sel_hi:[1,0]
	v_pk_mul_f32 v[100:101], v[100:101], v[190:191] op_sel_hi:[1,0]
	v_pk_mul_f32 v[98:99], v[98:99], v[190:191] op_sel_hi:[1,0]
	v_pk_mul_f32 v[96:97], v[96:97], v[190:191] op_sel_hi:[1,0]
	v_pk_mul_f32 v[94:95], v[94:95], v[190:191] op_sel_hi:[1,0]
	v_pk_mul_f32 v[92:93], v[92:93], v[190:191] op_sel_hi:[1,0]
	v_pk_mul_f32 v[90:91], v[90:91], v[190:191] op_sel_hi:[1,0]
	v_pk_mul_f32 v[88:89], v[88:89], v[190:191] op_sel_hi:[1,0]
	v_pk_mul_f32 v[86:87], v[86:87], v[190:191] op_sel_hi:[1,0]
	v_pk_mul_f32 v[84:85], v[84:85], v[190:191] op_sel_hi:[1,0]
	v_pk_mul_f32 v[82:83], v[82:83], v[190:191] op_sel_hi:[1,0]
	v_pk_mul_f32 v[80:81], v[80:81], v[190:191] op_sel_hi:[1,0]
	v_pk_mul_f32 v[78:79], v[78:79], v[190:191] op_sel_hi:[1,0]
	v_pk_mul_f32 v[76:77], v[76:77], v[190:191] op_sel_hi:[1,0]
	v_pk_mul_f32 v[74:75], v[74:75], v[190:191] op_sel_hi:[1,0]
	v_pk_mul_f32 v[72:73], v[72:73], v[190:191] op_sel_hi:[1,0]
	v_pk_mul_f32 v[70:71], v[70:71], v[190:191] op_sel_hi:[1,0]
	v_pk_mul_f32 v[68:69], v[68:69], v[190:191] op_sel_hi:[1,0]
	v_pk_mul_f32 v[66:67], v[66:67], v[190:191] op_sel_hi:[1,0]
	v_pk_mul_f32 v[64:65], v[64:65], v[190:191] op_sel_hi:[1,0]
	v_pk_mul_f32 v[62:63], v[62:63], v[190:191] op_sel_hi:[1,0]
	v_pk_mul_f32 v[60:61], v[60:61], v[190:191] op_sel_hi:[1,0]
	v_pk_mul_f32 v[58:59], v[58:59], v[190:191] op_sel_hi:[1,0]
	v_pk_mul_f32 v[56:57], v[56:57], v[190:191] op_sel_hi:[1,0]
	v_pk_mul_f32 v[54:55], v[54:55], v[190:191] op_sel_hi:[1,0]
	v_pk_mul_f32 v[52:53], v[52:53], v[190:191] op_sel_hi:[1,0]
	v_pk_mul_f32 v[50:51], v[50:51], v[190:191] op_sel_hi:[1,0]
	v_pk_mul_f32 v[48:49], v[48:49], v[190:191] op_sel_hi:[1,0]
	v_pk_mul_f32 v[46:47], v[46:47], v[190:191] op_sel_hi:[1,0]
	v_pk_mul_f32 v[44:45], v[44:45], v[190:191] op_sel_hi:[1,0]
	v_pk_mul_f32 v[42:43], v[42:43], v[190:191] op_sel_hi:[1,0]
	v_pk_mul_f32 v[40:41], v[40:41], v[190:191] op_sel_hi:[1,0]
	v_pk_mul_f32 v[38:39], v[38:39], v[190:191] op_sel_hi:[1,0]
	v_pk_mul_f32 v[36:37], v[36:37], v[190:191] op_sel_hi:[1,0]
	v_pk_mul_f32 v[34:35], v[34:35], v[190:191] op_sel_hi:[1,0]
	v_pk_mul_f32 v[32:33], v[32:33], v[190:191] op_sel_hi:[1,0]
	v_pk_mul_f32 v[30:31], v[30:31], v[190:191] op_sel_hi:[1,0]
	v_pk_mul_f32 v[28:29], v[28:29], v[190:191] op_sel_hi:[1,0]
	v_pk_mul_f32 v[26:27], v[26:27], v[190:191] op_sel_hi:[1,0]
	v_pk_mul_f32 v[24:25], v[24:25], v[190:191] op_sel_hi:[1,0]
	v_pk_mul_f32 v[22:23], v[22:23], v[190:191] op_sel_hi:[1,0]
	v_pk_mul_f32 v[20:21], v[20:21], v[190:191] op_sel_hi:[1,0]
	v_pk_mul_f32 v[18:19], v[18:19], v[190:191] op_sel_hi:[1,0]
	v_pk_mul_f32 v[16:17], v[16:17], v[190:191] op_sel_hi:[1,0]
	v_pk_mul_f32 v[14:15], v[14:15], v[190:191] op_sel_hi:[1,0]
	v_pk_mul_f32 v[12:13], v[12:13], v[190:191] op_sel_hi:[1,0]
	v_pk_mul_f32 v[10:11], v[10:11], v[190:191] op_sel_hi:[1,0]
	v_pk_mul_f32 v[8:9], v[8:9], v[190:191] op_sel_hi:[1,0]
	v_pk_mul_f32 v[6:7], v[6:7], v[190:191] op_sel_hi:[1,0]
	v_pk_mul_f32 v[4:5], v[4:5], v[190:191] op_sel_hi:[1,0]
	v_pk_mul_f32 v[2:3], v[2:3], v[190:191] op_sel_hi:[1,0]
	v_pk_mul_f32 v[0:1], v[0:1], v[190:191] op_sel_hi:[1,0]
	v_mul_f32_e32 v203, v203, v190
	v_mov_b32_e32 v190, v246
	v_sub_f32_e32 v222, v222, v190
	v_exp_f32_e32 v222, v222
	v_sub_f32_e32 v223, v223, v190
	v_exp_f32_e32 v223, v223
	v_sub_f32_e32 v224, v224, v190
	v_add_f32_e32 v254, 0, v222
	v_exp_f32_e32 v224, v224
	v_sub_f32_e32 v225, v225, v190
	v_add_f32_e32 v254, v223, v254
	v_exp_f32_e32 v225, v225
	v_sub_f32_e32 v226, v226, v190
	v_add_f32_e32 v254, v224, v254
	v_exp_f32_e32 v226, v226
	v_sub_f32_e32 v227, v227, v190
	v_add_f32_e32 v254, v225, v254
	v_exp_f32_e32 v227, v227
	v_sub_f32_e32 v228, v228, v190
	v_add_f32_e32 v254, v226, v254
	v_exp_f32_e32 v228, v228
	v_sub_f32_e32 v229, v229, v190
	v_add_f32_e32 v254, v227, v254
	v_exp_f32_e32 v229, v229
	v_sub_f32_e32 v230, v230, v190
	v_add_f32_e32 v254, v228, v254
	v_exp_f32_e32 v230, v230
	v_sub_f32_e32 v231, v231, v190
	v_add_f32_e32 v254, v229, v254
	v_exp_f32_e32 v231, v231
	v_sub_f32_e32 v232, v232, v190
	v_add_f32_e32 v254, v230, v254
	v_exp_f32_e32 v232, v232
	v_sub_f32_e32 v233, v233, v190
	v_add_f32_e32 v254, v231, v254
	v_exp_f32_e32 v233, v233
	v_sub_f32_e32 v234, v234, v190
	v_add_f32_e32 v254, v232, v254
	v_exp_f32_e32 v234, v234
	v_sub_f32_e32 v235, v235, v190
	v_add_f32_e32 v254, v233, v254
	v_exp_f32_e32 v235, v235
	v_sub_f32_e32 v236, v236, v190
	v_add_f32_e32 v254, v234, v254
	v_exp_f32_e32 v236, v236
	v_sub_f32_e32 v237, v237, v190
	v_add_f32_e32 v254, v235, v254
	v_exp_f32_e32 v237, v237
	v_add_f32_e32 v254, v236, v254
	v_add_f32_e32 v254, v237, v254
	v_cvt_pk_bf16_f32 v242, v222, v223
	v_cvt_pk_bf16_f32 v243, v224, v225
	v_cvt_pk_bf16_f32 v244, v226, v227
	v_cvt_pk_bf16_f32 v245, v228, v229
	v_cvt_pk_bf16_f32 v250, v230, v231
	v_cvt_pk_bf16_f32 v251, v232, v233
	v_cvt_pk_bf16_f32 v252, v234, v235
	v_cvt_pk_bf16_f32 v253, v236, v237
	v_add_f32_e32 v203, v203, v254
	s_nop 1
	s_waitcnt lgkmcnt(8)
	v_mfma_f32_32x32x16_bf16 v[112:127], v[238:241], v[242:245], v[112:127]
	ds_read_b64_tr_b16 v[238:239], v218 offset:16640
	ds_read_b64_tr_b16 v[240:241], v218 offset:20736
	s_waitcnt lgkmcnt(8)
	v_mfma_f32_32x32x16_bf16 v[96:111], v[128:131], v[242:245], v[96:111]
	ds_read_b64_tr_b16 v[222:223], v219 offset:16640
	ds_read_b64_tr_b16 v[224:225], v219 offset:20736
	s_waitcnt lgkmcnt(8)
	v_mfma_f32_32x32x16_bf16 v[80:95], v[206:209], v[242:245], v[80:95]
	ds_read_b64_tr_b16 v[206:207], v221 offset:16640
	ds_read_b64_tr_b16 v[208:209], v221 offset:20736
	s_waitcnt lgkmcnt(8)
	v_mfma_f32_32x32x16_bf16 v[64:79], v[210:213], v[242:245], v[64:79]
	ds_read_b64_tr_b16 v[210:211], v205 offset:24576
	ds_read_b64_tr_b16 v[212:213], v205 offset:28672
	s_waitcnt lgkmcnt(8)
	v_mfma_f32_32x32x16_bf16 v[48:63], v[214:217], v[242:245], v[48:63]
	ds_read_b64_tr_b16 v[214:215], v218 offset:24576
	ds_read_b64_tr_b16 v[216:217], v218 offset:28672
	s_waitcnt lgkmcnt(8)
	v_mfma_f32_32x32x16_bf16 v[32:47], v[238:241], v[242:245], v[32:47]
	ds_read_b64_tr_b16 v[238:239], v219 offset:24576
	ds_read_b64_tr_b16 v[240:241], v219 offset:28672
	s_waitcnt lgkmcnt(8)
	v_mfma_f32_32x32x16_bf16 v[16:31], v[222:225], v[242:245], v[16:31]
	ds_read_b64_tr_b16 v[222:223], v221 offset:24576
	ds_read_b64_tr_b16 v[224:225], v221 offset:28672
	s_waitcnt lgkmcnt(8)
	v_mfma_f32_32x32x16_bf16 v[0:15], v[206:209], v[242:245], v[0:15]
	ds_read_b64_tr_b16 v[206:207], v205 offset:24832
	ds_read_b64_tr_b16 v[208:209], v205 offset:28928
	s_waitcnt lgkmcnt(8)
	v_mfma_f32_32x32x16_bf16 v[112:127], v[210:213], v[250:253], v[112:127]
	ds_read_b64_tr_b16 v[210:211], v218 offset:24832
	ds_read_b64_tr_b16 v[212:213], v218 offset:28928
	s_waitcnt lgkmcnt(8)
	v_mfma_f32_32x32x16_bf16 v[96:111], v[214:217], v[250:253], v[96:111]
	ds_read_b64_tr_b16 v[214:215], v219 offset:24832
	ds_read_b64_tr_b16 v[216:217], v219 offset:28928
	s_waitcnt lgkmcnt(8)
	v_mfma_f32_32x32x16_bf16 v[80:95], v[238:241], v[250:253], v[80:95]
	ds_read_b64_tr_b16 v[238:239], v221 offset:24832
	ds_read_b64_tr_b16 v[240:241], v221 offset:28928
	s_waitcnt lgkmcnt(8)
	v_mfma_f32_32x32x16_bf16 v[64:79], v[222:225], v[250:253], v[64:79]
	s_waitcnt lgkmcnt(6)
	v_mfma_f32_32x32x16_bf16 v[48:63], v[206:209], v[250:253], v[48:63]
	s_waitcnt lgkmcnt(4)
	v_mfma_f32_32x32x16_bf16 v[32:47], v[210:213], v[250:253], v[32:47]
	s_waitcnt lgkmcnt(2)
	v_mfma_f32_32x32x16_bf16 v[16:31], v[214:217], v[250:253], v[16:31]
	s_waitcnt lgkmcnt(0)
	v_mfma_f32_32x32x16_bf16 v[0:15], v[238:241], v[250:253], v[0:15]
	ds_read_b128 v[206:209], v195 offset:16384
	ds_read_b128 v[210:213], v196 offset:16384
	ds_read_b128 v[214:217], v197 offset:16384
	ds_read_b128 v[238:241], v198 offset:16384
	ds_read_b128 v[242:245], v199 offset:16384
	ds_read_b128 v[250:253], v200 offset:16384
	ds_read_b128 v[222:225], v201 offset:16384
	ds_read_b128 v[226:229], v202 offset:16384
	s_branch .Latt_end_2
.Latt_slow_2s0:
.Latt_slot1_2:
	v_add_u32_e32 v205, 0x8000, v205
	v_add_u32_e32 v218, 0x8000, v218
	v_add_u32_e32 v219, 0x8000, v219
	v_add_u32_e32 v221, 0x8000, v221
	s_waitcnt lgkmcnt(7)
	v_mfma_f32_32x32x16_bf16 v[128:143], v[206:209], v[144:147], 0
	ds_read_b128 v[206:209], v195 offset:24576
	s_cmp_lg_u64 s[12:13], 0
	s_cbranch_scc1 .Latt_nd0_2s1
	s_sub_i32 s100, s38, 1
	s_cmp_eq_u32 s38, 0
	s_cselect_b32 s100, 2, s100
	s_lshl_b32 s101, s100, 14
	s_add_i32 m0, s40, s101
	s_nop 0
	global_load_lds_dwordx4 v178, s[22:23]
.Latt_nd0_2s1:
	s_waitcnt lgkmcnt(7)
	v_mfma_f32_32x32x16_bf16 v[128:143], v[210:213], v[148:151], v[128:143]
	ds_read_b128 v[210:213], v196 offset:24576
	s_cmp_lg_u64 s[12:13], 0
	s_cbranch_scc1 .Latt_nd1_2s1
	s_add_i32 m0, m0, 0x400
	s_nop 0
	global_load_lds_dwordx4 v180, s[22:23]
.Latt_nd1_2s1:
	s_waitcnt lgkmcnt(7)
	v_mfma_f32_32x32x16_bf16 v[128:143], v[214:217], v[152:155], v[128:143]
	ds_read_b128 v[214:217], v197 offset:24576
	s_cmp_lg_u64 s[12:13], 0
	s_cbranch_scc1 .Latt_nd2_2s1
	s_lshl_b32 s101, s100, 15
	s_add_i32 m0, s41, s101
	s_add_u32 s100, s22, 0x1000
	s_addc_u32 s101, s23, 0
	global_load_lds_dwordx4 v182, s[100:101]
.Latt_nd2_2s1:
	s_waitcnt lgkmcnt(7)
	v_mfma_f32_32x32x16_bf16 v[128:143], v[238:241], v[156:159], v[128:143]
	ds_read_b128 v[238:241], v198 offset:24576
	s_cmp_lg_u64 s[12:13], 0
	s_cbranch_scc1 .Latt_nd3_2s1
	s_add_i32 m0, m0, 0x400
	s_nop 0
	global_load_lds_dwordx4 v184, s[100:101]

.Latt_nd5_2s1:
	s_waitcnt lgkmcnt(5)
	v_mfma_f32_32x32x16_bf16 v[128:143], v[222:225], v[168:171], v[128:143]
	s_waitcnt lgkmcnt(4)
	v_mfma_f32_32x32x16_bf16 v[128:143], v[226:229], v[172:175], v[128:143]
	s_waitcnt lgkmcnt(3)
	v_mfma_f32_32x32x16_bf16 v[222:237], v[206:209], v[144:147], 0
	ds_read_b128 v[206:209], v199 offset:24576
	s_nop 8
	v_max3_f32 v246, v128, v129, v130
	v_max3_f32 v247, v131, v132, v133
	v_max3_f32 v246, v246, v134, v135
	v_max3_f32 v247, v247, v136, v137
	v_max3_f32 v246, v246, v138, v139
	v_max3_f32 v247, v247, v140, v141
	v_max3_f32 v246, v246, v142, v143
	s_waitcnt lgkmcnt(3)
	v_mfma_f32_32x32x16_bf16 v[222:237], v[210:213], v[148:151], v[222:237]
	ds_read_b128 v[210:213], v200 offset:24576
	v_max_f32_e32 v246, v246, v247
	v_mov_b32_e32 v247, v246
	v_add_f32_e32 v249, 0x41000000, v190
	s_nop 1
	v_permlane32_swap_b32_e32 v246, v247
	v_max_f32_e32 v246, v246, v247
	v_cmp_gt_f32_e32 vcc, v246, v249
	s_cbranch_vccz .Latt_nr0_2s1
	v_max_f32_e32 v246, v190, v246
	v_sub_f32_e32 v190, v190, v246
	v_exp_f32_e32 v190, v190
	s_nop 0
	v_pk_mul_f32 v[126:127], v[126:127], v[190:191] op_sel_hi:[1,0]
	v_pk_mul_f32 v[124:125], v[124:125], v[190:191] op_sel_hi:[1,0]
	v_pk_mul_f32 v[122:123], v[122:123], v[190:191] op_sel_hi:[1,0]
	v_pk_mul_f32 v[120:121], v[120:121], v[190:191] op_sel_hi:[1,0]
	v_pk_mul_f32 v[118:119], v[118:119], v[190:191] op_sel_hi:[1,0]
	v_pk_mul_f32 v[116:117], v[116:117], v[190:191] op_sel_hi:[1,0]
	v_pk_mul_f32 v[114:115], v[114:115], v[190:191] op_sel_hi:[1,0]
	v_pk_mul_f32 v[112:113], v[112:113], v[190:191] op_sel_hi:[1,0]
	v_pk_mul_f32 v[110:111], v[110:111], v[190:191] op_sel_hi:[1,0]
	v_pk_mul_f32 v[108:109], v[108:109], v[190:191] op_sel_hi:[1,0]
	v_pk_mul_f32 v[106:107], v[106:107], v[190:191] op_sel_hi:[1,0]
	v_pk_mul_f32 v[104:105], v[104:105], v[190:191] op_sel_hi:[1,0]
	v_pk_mul_f32 v[102:103], v[102:103], v[190:191] op_sel_hi:[1,0]
	v_pk_mul_f32 v[100:101], v[100:101], v[190:191] op_sel_hi:[1,0]
	v_pk_mul_f32 v[98:99], v[98:99], v[190:191] op_sel_hi:[1,0]
	v_pk_mul_f32 v[96:97], v[96:97], v[190:191] op_sel_hi:[1,0]
	v_pk_mul_f32 v[94:95], v[94:95], v[190:191] op_sel_hi:[1,0]
	v_pk_mul_f32 v[92:93], v[92:93], v[190:191] op_sel_hi:[1,0]
	v_pk_mul_f32 v[90:91], v[90:91], v[190:191] op_sel_hi:[1,0]
	v_pk_mul_f32 v[88:89], v[88:89], v[190:191] op_sel_hi:[1,0]
	v_pk_mul_f32 v[86:87], v[86:87], v[190:191] op_sel_hi:[1,0]
	v_pk_mul_f32 v[84:85], v[84:85], v[190:191] op_sel_hi:[1,0]
	v_pk_mul_f32 v[82:83], v[82:83], v[190:191] op_sel_hi:[1,0]
	v_pk_mul_f32 v[80:81], v[80:81], v[190:191] op_sel_hi:[1,0]
	v_pk_mul_f32 v[78:79], v[78:79], v[190:191] op_sel_hi:[1,0]
	v_pk_mul_f32 v[76:77], v[76:77], v[190:191] op_sel_hi:[1,0]
	v_pk_mul_f32 v[74:75], v[74:75], v[190:191] op_sel_hi:[1,0]
	v_pk_mul_f32 v[72:73], v[72:73], v[190:191] op_sel_hi:[1,0]
	v_pk_mul_f32 v[70:71], v[70:71], v[190:191] op_sel_hi:[1,0]
	v_pk_mul_f32 v[68:69], v[68:69], v[190:191] op_sel_hi:[1,0]
	v_pk_mul_f32 v[66:67], v[66:67], v[190:191] op_sel_hi:[1,0]
	v_pk_mul_f32 v[64:65], v[64:65], v[190:191] op_sel_hi:[1,0]
	v_pk_mul_f32 v[62:63], v[62:63], v[190:191] op_sel_hi:[1,0]
	v_pk_mul_f32 v[60:61], v[60:61], v[190:191] op_sel_hi:[1,0]
	v_pk_mul_f32 v[58:59], v[58:59], v[190:191] op_sel_hi:[1,0]
	v_pk_mul_f32 v[56:57], v[56:57], v[190:191] op_sel_hi:[1,0]
	v_pk_mul_f32 v[54:55], v[54:55], v[190:191] op_sel_hi:[1,0]
	v_pk_mul_f32 v[52:53], v[52:53], v[190:191] op_sel_hi:[1,0]
	v_pk_mul_f32 v[50:51], v[50:51], v[190:191] op_sel_hi:[1,0]
	v_pk_mul_f32 v[48:49], v[48:49], v[190:191] op_sel_hi:[1,0]
	v_pk_mul_f32 v[46:47], v[46:47], v[190:191] op_sel_hi:[1,0]
	v_pk_mul_f32 v[44:45], v[44:45], v[190:191] op_sel_hi:[1,0]
	v_pk_mul_f32 v[42:43], v[42:43], v[190:191] op_sel_hi:[1,0]
	v_pk_mul_f32 v[40:41], v[40:41], v[190:191] op_sel_hi:[1,0]
	v_pk_mul_f32 v[38:39], v[38:39], v[190:191] op_sel_hi:[1,0]
	v_pk_mul_f32 v[36:37], v[36:37], v[190:191] op_sel_hi:[1,0]
	v_pk_mul_f32 v[34:35], v[34:35], v[190:191] op_sel_hi:[1,0]
	v_pk_mul_f32 v[32:33], v[32:33], v[190:191] op_sel_hi:[1,0]
	v_pk_mul_f32 v[30:31], v[30:31], v[190:191] op_sel_hi:[1,0]
	v_pk_mul_f32 v[28:29], v[28:29], v[190:191] op_sel_hi:[1,0]
	v_pk_mul_f32 v[26:27], v[26:27], v[190:191] op_sel_hi:[1,0]
	v_pk_mul_f32 v[24:25], v[24:25], v[190:191] op_sel_hi:[1,0]
	v_pk_mul_f32 v[22:23], v[22:23], v[190:191] op_sel_hi:[1,0]
	v_pk_mul_f32 v[20:21], v[20:21], v[190:191] op_sel_hi:[1,0]
	v_pk_mul_f32 v[18:19], v[18:19], v[190:191] op_sel_hi:[1,0]
	v_pk_mul_f32 v[16:17], v[16:17], v[190:191] op_sel_hi:[1,0]
	v_pk_mul_f32 v[14:15], v[14:15], v[190:191] op_sel_hi:[1,0]
	v_pk_mul_f32 v[12:13], v[12:13], v[190:191] op_sel_hi:[1,0]
	v_pk_mul_f32 v[10:11], v[10:11], v[190:191] op_sel_hi:[1,0]
	v_pk_mul_f32 v[8:9], v[8:9], v[190:191] op_sel_hi:[1,0]
	v_pk_mul_f32 v[6:7], v[6:7], v[190:191] op_sel_hi:[1,0]
	v_pk_mul_f32 v[4:5], v[4:5], v[190:191] op_sel_hi:[1,0]
	v_pk_mul_f32 v[2:3], v[2:3], v[190:191] op_sel_hi:[1,0]
	v_pk_mul_f32 v[0:1], v[0:1], v[190:191] op_sel_hi:[1,0]
	v_mul_f32_e32 v203, v203, v190
	v_mov_b32_e32 v190, v246
.Latt_nr0_2s1:
	s_waitcnt lgkmcnt(3)
	v_mfma_f32_32x32x16_bf16 v[222:237], v[214:217], v[152:155], v[222:237]
	ds_read_b128 v[214:217], v201 offset:24576
	v_sub_f32_e32 v128, v128, v190
	v_exp_f32_e32 v128, v128
	v_sub_f32_e32 v129, v129, v190
	v_exp_f32_e32 v129, v129
	v_sub_f32_e32 v130, v130, v190
	s_waitcnt lgkmcnt(3)
	v_mfma_f32_32x32x16_bf16 v[222:237], v[238:241], v[156:159], v[222:237]
	ds_read_b128 v[238:241], v202 offset:24576
	v_add_f32_e32 v254, 0, v128
	v_exp_f32_e32 v130, v130
	v_sub_f32_e32 v131, v131, v190
	v_add_f32_e32 v254, v129, v254
	v_exp_f32_e32 v131, v131
	s_waitcnt lgkmcnt(3)
	v_mfma_f32_32x32x16_bf16 v[222:237], v[206:209], v[160:163], v[222:237]
	ds_read_b64_tr_b16 v[206:207], v205
	ds_read_b64_tr_b16 v[208:209], v205 offset:4096
	v_sub_f32_e32 v132, v132, v190
	v_add_f32_e32 v254, v130, v254
	v_exp_f32_e32 v132, v132
	v_sub_f32_e32 v133, v133, v190
	v_add_f32_e32 v254, v131, v254
	s_waitcnt lgkmcnt(4)
	v_mfma_f32_32x32x16_bf16 v[222:237], v[210:213], v[164:167], v[222:237]
	ds_read_b64_tr_b16 v[210:211], v218
	ds_read_b64_tr_b16 v[212:213], v218 offset:4096
	v_exp_f32_e32 v133, v133
	v_sub_f32_e32 v134, v134, v190
	v_add_f32_e32 v254, v132, v254
	v_exp_f32_e32 v134, v134
	s_waitcnt lgkmcnt(5)
	v_mfma_f32_32x32x16_bf16 v[222:237], v[214:217], v[168:171], v[222:237]
	ds_read_b64_tr_b16 v[214:215], v219
	ds_read_b64_tr_b16 v[216:217], v219 offset:4096
	v_sub_f32_e32 v135, v135, v190
	v_add_f32_e32 v254, v133, v254
	v_exp_f32_e32 v135, v135
	s_nop 0
	s_waitcnt lgkmcnt(6)
	v_mfma_f32_32x32x16_bf16 v[222:237], v[238:241], v[172:175], v[222:237]
	ds_read_b64_tr_b16 v[238:239], v221
	ds_read_b64_tr_b16 v[240:241], v221 offset:4096
	v_cvt_pk_bf16_f32 v242, v128, v129
	v_cvt_pk_bf16_f32 v243, v130, v131
	v_cvt_pk_bf16_f32 v244, v132, v133
	v_cvt_pk_bf16_f32 v245, v134, v135
	s_nop 1
	s_waitcnt lgkmcnt(6)
	v_mfma_f32_32x32x16_bf16 v[112:127], v[206:209], v[242:245], v[112:127]
	ds_read_b64_tr_b16 v[206:207], v205 offset:256
	ds_read_b64_tr_b16 v[208:209], v205 offset:4352
	v_sub_f32_e32 v136, v136, v190
	v_add_f32_e32 v254, v134, v254
	v_exp_f32_e32 v136, v136
	v_sub_f32_e32 v137, v137, v190
	v_add_f32_e32 v254, v135, v254
	s_waitcnt lgkmcnt(6)
	v_mfma_f32_32x32x16_bf16 v[96:111], v[210:213], v[242:245], v[96:111]
	ds_read_b64_tr_b16 v[210:211], v218 offset:256
	ds_read_b64_tr_b16 v[212:213], v218 offset:4352
	v_exp_f32_e32 v137, v137
	v_sub_f32_e32 v138, v138, v190
	v_add_f32_e32 v254, v136, v254
	v_exp_f32_e32 v138, v138
	v_sub_f32_e32 v139, v139, v190
	s_waitcnt lgkmcnt(6)
	v_mfma_f32_32x32x16_bf16 v[80:95], v[214:217], v[242:245], v[80:95]
	ds_read_b64_tr_b16 v[214:215], v219 offset:256
	ds_read_b64_tr_b16 v[216:217], v219 offset:4352
	v_add_f32_e32 v254, v137, v254
	v_exp_f32_e32 v139, v139
	v_sub_f32_e32 v140, v140, v190
	v_add_f32_e32 v254, v138, v254
	s_waitcnt lgkmcnt(6)
	v_mfma_f32_32x32x16_bf16 v[64:79], v[238:241], v[242:245], v[64:79]
	ds_read_b64_tr_b16 v[238:239], v221 offset:256
	ds_read_b64_tr_b16 v[240:241], v221 offset:4352
	v_exp_f32_e32 v140, v140
	v_sub_f32_e32 v141, v141, v190
	v_add_f32_e32 v254, v139, v254
	v_exp_f32_e32 v141, v141
	s_waitcnt lgkmcnt(6)
	v_mfma_f32_32x32x16_bf16 v[48:63], v[206:209], v[242:245], v[48:63]
	ds_read_b64_tr_b16 v[206:207], v205 offset:8192
	ds_read_b64_tr_b16 v[208:209], v205 offset:12288
	v_sub_f32_e32 v142, v142, v190
	v_add_f32_e32 v254, v140, v254
	v_exp_f32_e32 v142, v142
	v_sub_f32_e32 v143, v143, v190
	s_waitcnt lgkmcnt(6)
	v_mfma_f32_32x32x16_bf16 v[32:47], v[210:213], v[242:245], v[32:47]
	ds_read_b64_tr_b16 v[210:211], v218 offset:8192
	ds_read_b64_tr_b16 v[212:213], v218 offset:12288
	v_add_f32_e32 v254, v141, v254
	v_exp_f32_e32 v143, v143
	v_add_f32_e32 v254, v142, v254
	v_add_f32_e32 v254, v143, v254
	s_waitcnt lgkmcnt(6)
	v_mfma_f32_32x32x16_bf16 v[16:31], v[214:217], v[242:245], v[16:31]
	ds_read_b64_tr_b16 v[214:215], v219 offset:8192
	ds_read_b64_tr_b16 v[216:217], v219 offset:12288
	v_cvt_pk_bf16_f32 v250, v136, v137
	v_cvt_pk_bf16_f32 v251, v138, v139
	v_cvt_pk_bf16_f32 v252, v140, v141
	v_cvt_pk_bf16_f32 v253, v142, v143
	v_add_f32_e32 v203, v203, v254
	s_waitcnt lgkmcnt(6)
	v_mfma_f32_32x32x16_bf16 v[0:15], v[238:241], v[242:245], v[0:15]
	ds_read_b64_tr_b16 v[238:239], v221 offset:8192
	ds_read_b64_tr_b16 v[240:241], v221 offset:12288
	ds_read_b64_tr_b16 v[128:129], v205 offset:8448
	ds_read_b64_tr_b16 v[130:131], v205 offset:12544
	s_waitcnt lgkmcnt(8)
	v_mfma_f32_32x32x16_bf16 v[112:127], v[206:209], v[250:253], v[112:127]
	ds_read_b64_tr_b16 v[206:207], v218 offset:8448
	ds_read_b64_tr_b16 v[208:209], v218 offset:12544
	v_max3_f32 v246, v222, v223, v224
	v_max3_f32 v247, v225, v226, v227
	v_max3_f32 v246, v246, v228, v229
	v_max3_f32 v247, v247, v230, v231
	v_max3_f32 v246, v246, v232, v233
	s_waitcnt lgkmcnt(8)
	v_mfma_f32_32x32x16_bf16 v[96:111], v[210:213], v[250:253], v[96:111]
	ds_read_b64_tr_b16 v[210:211], v219 offset:8448
	ds_read_b64_tr_b16 v[212:213], v219 offset:12544
	v_max3_f32 v247, v247, v234, v235
	v_max3_f32 v246, v246, v236, v237
	v_max_f32_e32 v246, v246, v247
	v_mov_b32_e32 v247, v246
	v_add_f32_e32 v249, 0x41000000, v190
	s_waitcnt lgkmcnt(8)
	v_mfma_f32_32x32x16_bf16 v[80:95], v[214:217], v[250:253], v[80:95]
	ds_read_b64_tr_b16 v[214:215], v221 offset:8448
	ds_read_b64_tr_b16 v[216:217], v221 offset:12544
	s_nop 1
	v_permlane32_swap_b32_e32 v246, v247
	v_max_f32_e32 v246, v246, v247
	v_cmp_gt_f32_e32 vcc, v246, v249
	s_cbranch_vccnz .Latt_rs1_2s1
	s_waitcnt lgkmcnt(8)
	v_mfma_f32_32x32x16_bf16 v[64:79], v[238:241], v[250:253], v[64:79]
	ds_read_b64_tr_b16 v[238:239], v205 offset:16384
	ds_read_b64_tr_b16 v[240:241], v205 offset:20480
	v_sub_f32_e32 v222, v222, v190
	v_exp_f32_e32 v222, v222
	v_sub_f32_e32 v223, v223, v190
	v_exp_f32_e32 v223, v223
	v_sub_f32_e32 v224, v224, v190
	v_add_f32_e32 v254, 0, v222
	s_waitcnt lgkmcnt(8)
	v_mfma_f32_32x32x16_bf16 v[48:63], v[128:131], v[250:253], v[48:63]
	ds_read_b64_tr_b16 v[128:129], v218 offset:16384
	ds_read_b64_tr_b16 v[130:131], v218 offset:20480
	v_exp_f32_e32 v224, v224
	v_sub_f32_e32 v225, v225, v190
	v_add_f32_e32 v254, v223, v254
	v_exp_f32_e32 v225, v225
	v_sub_f32_e32 v226, v226, v190
	v_add_f32_e32 v254, v224, v254
	s_waitcnt lgkmcnt(8)
	v_mfma_f32_32x32x16_bf16 v[32:47], v[206:209], v[250:253], v[32:47]
	ds_read_b64_tr_b16 v[206:207], v219 offset:16384
	ds_read_b64_tr_b16 v[208:209], v219 offset:20480
	v_exp_f32_e32 v226, v226
	v_sub_f32_e32 v227, v227, v190
	v_add_f32_e32 v254, v225, v254
	v_exp_f32_e32 v227, v227
	v_sub_f32_e32 v228, v228, v190
	s_waitcnt lgkmcnt(8)
	v_mfma_f32_32x32x16_bf16 v[16:31], v[210:213], v[250:253], v[16:31]
	ds_read_b64_tr_b16 v[210:211], v221 offset:16384
	ds_read_b64_tr_b16 v[212:213], v221 offset:20480
	v_add_f32_e32 v254, v226, v254
	v_exp_f32_e32 v228, v228
	v_sub_f32_e32 v229, v229, v190
	v_add_f32_e32 v254, v227, v254
	v_exp_f32_e32 v229, v229
	s_waitcnt lgkmcnt(8)
	v_mfma_f32_32x32x16_bf16 v[0:15], v[214:217], v[250:253], v[0:15]
	ds_read_b64_tr_b16 v[214:215], v205 offset:16640
	ds_read_b64_tr_b16 v[216:217], v205 offset:20736
	s_nop 0
	v_cvt_pk_bf16_f32 v242, v222, v223
	v_cvt_pk_bf16_f32 v243, v224, v225
	v_cvt_pk_bf16_f32 v244, v226, v227
	v_cvt_pk_bf16_f32 v245, v228, v229
	s_nop 1
	s_waitcnt lgkmcnt(8)
	v_mfma_f32_32x32x16_bf16 v[112:127], v[238:241], v[242:245], v[112:127]
	ds_read_b64_tr_b16 v[238:239], v218 offset:16640
	ds_read_b64_tr_b16 v[240:241], v218 offset:20736
	v_sub_f32_e32 v230, v230, v190
	v_add_f32_e32 v254, v228, v254
	v_exp_f32_e32 v230, v230
	v_sub_f32_e32 v231, v231, v190
	v_add_f32_e32 v254, v229, v254
	s_waitcnt lgkmcnt(8)
	v_mfma_f32_32x32x16_bf16 v[96:111], v[128:131], v[242:245], v[96:111]
	ds_read_b64_tr_b16 v[128:129], v219 offset:16640
	ds_read_b64_tr_b16 v[130:131], v219 offset:20736
	v_exp_f32_e32 v231, v231
	v_sub_f32_e32 v232, v232, v190
	v_add_f32_e32 v254, v230, v254
	v_exp_f32_e32 v232, v232
	v_sub_f32_e32 v233, v233, v190
	s_waitcnt lgkmcnt(8)
	v_mfma_f32_32x32x16_bf16 v[80:95], v[206:209], v[242:245], v[80:95]
	ds_read_b64_tr_b16 v[206:207], v221 offset:16640
	ds_read_b64_tr_b16 v[208:209], v221 offset:20736
	v_add_f32_e32 v254, v231, v254
	v_exp_f32_e32 v233, v233
	v_sub_f32_e32 v234, v234, v190
	v_add_f32_e32 v254, v232, v254
	s_waitcnt lgkmcnt(8)
	v_mfma_f32_32x32x16_bf16 v[64:79], v[210:213], v[242:245], v[64:79]
	ds_read_b64_tr_b16 v[210:211], v205 offset:24576
	ds_read_b64_tr_b16 v[212:213], v205 offset:28672
	v_exp_f32_e32 v234, v234
	v_sub_f32_e32 v235, v235, v190
	v_add_f32_e32 v254, v233, v254
	v_exp_f32_e32 v235, v235
	s_waitcnt lgkmcnt(8)
	v_mfma_f32_32x32x16_bf16 v[48:63], v[214:217], v[242:245], v[48:63]
	ds_read_b64_tr_b16 v[214:215], v218 offset:24576
	ds_read_b64_tr_b16 v[216:217], v218 offset:28672
	v_sub_f32_e32 v236, v236, v190
	v_add_f32_e32 v254, v234, v254
	v_exp_f32_e32 v236, v236
	v_sub_f32_e32 v237, v237, v190
	s_waitcnt lgkmcnt(8)
	v_mfma_f32_32x32x16_bf16 v[32:47], v[238:241], v[242:245], v[32:47]
	ds_read_b64_tr_b16 v[238:239], v219 offset:24576
	ds_read_b64_tr_b16 v[240:241], v219 offset:28672
	v_add_f32_e32 v254, v235, v254
	v_exp_f32_e32 v237, v237
	v_add_f32_e32 v254, v236, v254
	v_add_f32_e32 v254, v237, v254
	s_waitcnt lgkmcnt(8)
	v_mfma_f32_32x32x16_bf16 v[16:31], v[128:131], v[242:245], v[16:31]
	ds_read_b64_tr_b16 v[128:129], v221 offset:24576
	ds_read_b64_tr_b16 v[130:131], v221 offset:28672
	v_cvt_pk_bf16_f32 v250, v230, v231
	v_cvt_pk_bf16_f32 v251, v232, v233
	v_cvt_pk_bf16_f32 v252, v234, v235
	v_cvt_pk_bf16_f32 v253, v236, v237
	v_add_f32_e32 v203, v203, v254
	s_waitcnt lgkmcnt(8)
	v_mfma_f32_32x32x16_bf16 v[0:15], v[206:209], v[242:245], v[0:15]
	ds_read_b64_tr_b16 v[206:207], v205 offset:24832
	ds_read_b64_tr_b16 v[208:209], v205 offset:28928
	s_waitcnt lgkmcnt(8)
	v_mfma_f32_32x32x16_bf16 v[112:127], v[210:213], v[250:253], v[112:127]
	ds_read_b64_tr_b16 v[210:211], v218 offset:24832
	ds_read_b64_tr_b16 v[212:213], v218 offset:28928
	s_waitcnt lgkmcnt(8)
	v_mfma_f32_32x32x16_bf16 v[96:111], v[214:217], v[250:253], v[96:111]
	ds_read_b64_tr_b16 v[214:215], v219 offset:24832
	ds_read_b64_tr_b16 v[216:217], v219 offset:28928
	s_waitcnt lgkmcnt(8)
	v_mfma_f32_32x32x16_bf16 v[80:95], v[238:241], v[250:253], v[80:95]
	ds_read_b64_tr_b16 v[238:239], v221 offset:24832
	ds_read_b64_tr_b16 v[240:241], v221 offset:28928
	s_waitcnt lgkmcnt(8)
	v_mfma_f32_32x32x16_bf16 v[64:79], v[128:131], v[250:253], v[64:79]
	s_waitcnt lgkmcnt(6)
	v_mfma_f32_32x32x16_bf16 v[48:63], v[206:209], v[250:253], v[48:63]
	s_waitcnt lgkmcnt(4)
	v_mfma_f32_32x32x16_bf16 v[32:47], v[210:213], v[250:253], v[32:47]
	s_waitcnt lgkmcnt(2)
	v_mfma_f32_32x32x16_bf16 v[16:31], v[214:217], v[250:253], v[16:31]
	s_waitcnt lgkmcnt(0)
	v_mfma_f32_32x32x16_bf16 v[0:15], v[238:241], v[250:253], v[0:15]
	ds_read_b128 v[206:209], v195 offset:32768
	ds_read_b128 v[210:213], v196 offset:32768
	ds_read_b128 v[214:217], v197 offset:32768
	ds_read_b128 v[238:241], v198 offset:32768
	ds_read_b128 v[242:245], v199 offset:32768
	ds_read_b128 v[250:253], v200 offset:32768
	ds_read_b128 v[222:225], v201 offset:32768
	ds_read_b128 v[226:229], v202 offset:32768
	s_branch .Latt_end_2
.Latt_rs1_2s1:
	s_waitcnt lgkmcnt(8)
	v_mfma_f32_32x32x16_bf16 v[64:79], v[238:241], v[250:253], v[64:79]
	ds_read_b64_tr_b16 v[238:239], v205 offset:16384
	ds_read_b64_tr_b16 v[240:241], v205 offset:20480
	s_waitcnt lgkmcnt(8)
	v_mfma_f32_32x32x16_bf16 v[48:63], v[128:131], v[250:253], v[48:63]
	ds_read_b64_tr_b16 v[128:129], v218 offset:16384
	ds_read_b64_tr_b16 v[130:131], v218 offset:20480
	s_waitcnt lgkmcnt(8)
	v_mfma_f32_32x32x16_bf16 v[32:47], v[206:209], v[250:253], v[32:47]
	ds_read_b64_tr_b16 v[206:207], v219 offset:16384
	ds_read_b64_tr_b16 v[208:209], v219 offset:20480
	s_waitcnt lgkmcnt(8)
	v_mfma_f32_32x32x16_bf16 v[16:31], v[210:213], v[250:253], v[16:31]
	ds_read_b64_tr_b16 v[210:211], v221 offset:16384
	ds_read_b64_tr_b16 v[212:213], v221 offset:20480
	s_waitcnt lgkmcnt(8)
	v_mfma_f32_32x32x16_bf16 v[0:15], v[214:217], v[250:253], v[0:15]
	ds_read_b64_tr_b16 v[214:215], v205 offset:16640
	ds_read_b64_tr_b16 v[216:217], v205 offset:20736
	s_nop 11
	v_max_f32_e32 v246, v190, v246
	v_sub_f32_e32 v190, v190, v246
	v_exp_f32_e32 v190, v190
	s_nop 0
	v_pk_mul_f32 v[126:127], v[126:127], v[190:191] op_sel_hi:[1,0]
	v_pk_mul_f32 v[124:125], v[124:125], v[190:191] op_sel_hi:[1,0]
	v_pk_mul_f32 v[122:123], v[122:123], v[190:191] op_sel_hi:[1,0]
	v_pk_mul_f32 v[120:121], v[120:121], v[190:191] op_sel_hi:[1,0]
	v_pk_mul_f32 v[118:119], v[118:119], v[190:191] op_sel_hi:[1,0]
	v_pk_mul_f32 v[116:117], v[116:117], v[190:191] op_sel_hi:[1,0]
	v_pk_mul_f32 v[114:115], v[114:115], v[190:191] op_sel_hi:[1,0]
	v_pk_mul_f32 v[112:113], v[112:113], v[190:191] op_sel_hi:[1,0]
	v_pk_mul_f32 v[110:111], v[110:111], v[190:191] op_sel_hi:[1,0]
	v_pk_mul_f32 v[108:109], v[108:109], v[190:191] op_sel_hi:[1,0]
	v_pk_mul_f32 v[106:107], v[106:107], v[190:191] op_sel_hi:[1,0]
	v_pk_mul_f32 v[104:105], v[104:105], v[190:191] op_sel_hi:[1,0]
	v_pk_mul_f32 v[102:103], v[102:103], v[190:191] op_sel_hi:[1,0]
	v_pk_mul_f32 v[100:101], v[100:101], v[190:191] op_sel_hi:[1,0]
	v_pk_mul_f32 v[98:99], v[98:99], v[190:191] op_sel_hi:[1,0]
	v_pk_mul_f32 v[96:97], v[96:97], v[190:191] op_sel_hi:[1,0]
	v_pk_mul_f32 v[94:95], v[94:95], v[190:191] op_sel_hi:[1,0]
	v_pk_mul_f32 v[92:93], v[92:93], v[190:191] op_sel_hi:[1,0]
	v_pk_mul_f32 v[90:91], v[90:91], v[190:191] op_sel_hi:[1,0]
	v_pk_mul_f32 v[88:89], v[88:89], v[190:191] op_sel_hi:[1,0]
	v_pk_mul_f32 v[86:87], v[86:87], v[190:191] op_sel_hi:[1,0]
	v_pk_mul_f32 v[84:85], v[84:85], v[190:191] op_sel_hi:[1,0]
	v_pk_mul_f32 v[82:83], v[82:83], v[190:191] op_sel_hi:[1,0]
	v_pk_mul_f32 v[80:81], v[80:81], v[190:191] op_sel_hi:[1,0]
	v_pk_mul_f32 v[78:79], v[78:79], v[190:191] op_sel_hi:[1,0]
	v_pk_mul_f32 v[76:77], v[76:77], v[190:191] op_sel_hi:[1,0]
	v_pk_mul_f32 v[74:75], v[74:75], v[190:191] op_sel_hi:[1,0]
	v_pk_mul_f32 v[72:73], v[72:73], v[190:191] op_sel_hi:[1,0]
	v_pk_mul_f32 v[70:71], v[70:71], v[190:191] op_sel_hi:[1,0]
	v_pk_mul_f32 v[68:69], v[68:69], v[190:191] op_sel_hi:[1,0]
	v_pk_mul_f32 v[66:67], v[66:67], v[190:191] op_sel_hi:[1,0]
	v_pk_mul_f32 v[64:65], v[64:65], v[190:191] op_sel_hi:[1,0]
	v_pk_mul_f32 v[62:63], v[62:63], v[190:191] op_sel_hi:[1,0]
	v_pk_mul_f32 v[60:61], v[60:61], v[190:191] op_sel_hi:[1,0]
	v_pk_mul_f32 v[58:59], v[58:59], v[190:191] op_sel_hi:[1,0]
	v_pk_mul_f32 v[56:57], v[56:57], v[190:191] op_sel_hi:[1,0]
	v_pk_mul_f32 v[54:55], v[54:55], v[190:191] op_sel_hi:[1,0]
	v_pk_mul_f32 v[52:53], v[52:53], v[190:191] op_sel_hi:[1,0]
	v_pk_mul_f32 v[50:51], v[50:51], v[190:191] op_sel_hi:[1,0]
	v_pk_mul_f32 v[48:49], v[48:49], v[190:191] op_sel_hi:[1,0]
	v_pk_mul_f32 v[46:47], v[46:47], v[190:191] op_sel_hi:[1,0]
	v_pk_mul_f32 v[44:45], v[44:45], v[190:191] op_sel_hi:[1,0]
	v_pk_mul_f32 v[42:43], v[42:43], v[190:191] op_sel_hi:[1,0]
	v_pk_mul_f32 v[40:41], v[40:41], v[190:191] op_sel_hi:[1,0]
	v_pk_mul_f32 v[38:39], v[38:39], v[190:191] op_sel_hi:[1,0]
	v_pk_mul_f32 v[36:37], v[36:37], v[190:191] op_sel_hi:[1,0]
	v_pk_mul_f32 v[34:35], v[34:35], v[190:191] op_sel_hi:[1,0]
	v_pk_mul_f32 v[32:33], v[32:33], v[190:191] op_sel_hi:[1,0]
	v_pk_mul_f32 v[30:31], v[30:31], v[190:191] op_sel_hi:[1,0]
	v_pk_mul_f32 v[28:29], v[28:29], v[190:191] op_sel_hi:[1,0]
	v_pk_mul_f32 v[26:27], v[26:27], v[190:191] op_sel_hi:[1,0]
	v_pk_mul_f32 v[24:25], v[24:25], v[190:191] op_sel_hi:[1,0]
	v_pk_mul_f32 v[22:23], v[22:23], v[190:191] op_sel_hi:[1,0]
	v_pk_mul_f32 v[20:21], v[20:21], v[190:191] op_sel_hi:[1,0]
	v_pk_mul_f32 v[18:19], v[18:19], v[190:191] op_sel_hi:[1,0]
	v_pk_mul_f32 v[16:17], v[16:17], v[190:191] op_sel_hi:[1,0]
	v_pk_mul_f32 v[14:15], v[14:15], v[190:191] op_sel_hi:[1,0]
	v_pk_mul_f32 v[12:13], v[12:13], v[190:191] op_sel_hi:[1,0]
	v_pk_mul_f32 v[10:11], v[10:11], v[190:191] op_sel_hi:[1,0]
	v_pk_mul_f32 v[8:9], v[8:9], v[190:191] op_sel_hi:[1,0]
	v_pk_mul_f32 v[6:7], v[6:7], v[190:191] op_sel_hi:[1,0]
	v_pk_mul_f32 v[4:5], v[4:5], v[190:191] op_sel_hi:[1,0]
	v_pk_mul_f32 v[2:3], v[2:3], v[190:191] op_sel_hi:[1,0]
	v_pk_mul_f32 v[0:1], v[0:1], v[190:191] op_sel_hi:[1,0]
	v_mul_f32_e32 v203, v203, v190
	v_mov_b32_e32 v190, v246
	v_sub_f32_e32 v222, v222, v190
	v_exp_f32_e32 v222, v222
	v_sub_f32_e32 v223, v223, v190
	v_exp_f32_e32 v223, v223
	v_sub_f32_e32 v224, v224, v190
	v_add_f32_e32 v254, 0, v222
	v_exp_f32_e32 v224, v224
	v_sub_f32_e32 v225, v225, v190
	v_add_f32_e32 v254, v223, v254
	v_exp_f32_e32 v225, v225
	v_sub_f32_e32 v226, v226, v190
	v_add_f32_e32 v254, v224, v254
	v_exp_f32_e32 v226, v226
	v_sub_f32_e32 v227, v227, v190
	v_add_f32_e32 v254, v225, v254
	v_exp_f32_e32 v227, v227
	v_sub_f32_e32 v228, v228, v190
	v_add_f32_e32 v254, v226, v254
	v_exp_f32_e32 v228, v228
	v_sub_f32_e32 v229, v229, v190
	v_add_f32_e32 v254, v227, v254
	v_exp_f32_e32 v229, v229
	v_sub_f32_e32 v230, v230, v190
	v_add_f32_e32 v254, v228, v254
	v_exp_f32_e32 v230, v230
	v_sub_f32_e32 v231, v231, v190
	v_add_f32_e32 v254, v229, v254
	v_exp_f32_e32 v231, v231
	v_sub_f32_e32 v232, v232, v190
	v_add_f32_e32 v254, v230, v254
	v_exp_f32_e32 v232, v232
	v_sub_f32_e32 v233, v233, v190
	v_add_f32_e32 v254, v231, v254
	v_exp_f32_e32 v233, v233
	v_sub_f32_e32 v234, v234, v190
	v_add_f32_e32 v254, v232, v254
	v_exp_f32_e32 v234, v234
	v_sub_f32_e32 v235, v235, v190
	v_add_f32_e32 v254, v233, v254
	v_exp_f32_e32 v235, v235
	v_sub_f32_e32 v236, v236, v190
	v_add_f32_e32 v254, v234, v254
	v_exp_f32_e32 v236, v236
	v_sub_f32_e32 v237, v237, v190
	v_add_f32_e32 v254, v235, v254
	v_exp_f32_e32 v237, v237
	v_add_f32_e32 v254, v236, v254
	v_add_f32_e32 v254, v237, v254
	v_cvt_pk_bf16_f32 v242, v222, v223
	v_cvt_pk_bf16_f32 v243, v224, v225
	v_cvt_pk_bf16_f32 v244, v226, v227
	v_cvt_pk_bf16_f32 v245, v228, v229
	v_cvt_pk_bf16_f32 v250, v230, v231
	v_cvt_pk_bf16_f32 v251, v232, v233
	v_cvt_pk_bf16_f32 v252, v234, v235
	v_cvt_pk_bf16_f32 v253, v236, v237
	v_add_f32_e32 v203, v203, v254
	s_nop 1
	s_waitcnt lgkmcnt(8)
	v_mfma_f32_32x32x16_bf16 v[112:127], v[238:241], v[242:245], v[112:127]
	ds_read_b64_tr_b16 v[238:239], v218 offset:16640
	ds_read_b64_tr_b16 v[240:241], v218 offset:20736
	s_waitcnt lgkmcnt(8)
	v_mfma_f32_32x32x16_bf16 v[96:111], v[128:131], v[242:245], v[96:111]
	ds_read_b64_tr_b16 v[222:223], v219 offset:16640
	ds_read_b64_tr_b16 v[224:225], v219 offset:20736
	s_waitcnt lgkmcnt(8)
	v_mfma_f32_32x32x16_bf16 v[80:95], v[206:209], v[242:245], v[80:95]
	ds_read_b64_tr_b16 v[206:207], v221 offset:16640
	ds_read_b64_tr_b16 v[208:209], v221 offset:20736
	s_waitcnt lgkmcnt(8)
	v_mfma_f32_32x32x16_bf16 v[64:79], v[210:213], v[242:245], v[64:79]
	ds_read_b64_tr_b16 v[210:211], v205 offset:24576
	ds_read_b64_tr_b16 v[212:213], v205 offset:28672
	s_waitcnt lgkmcnt(8)
	v_mfma_f32_32x32x16_bf16 v[48:63], v[214:217], v[242:245], v[48:63]
	ds_read_b64_tr_b16 v[214:215], v218 offset:24576
	ds_read_b64_tr_b16 v[216:217], v218 offset:28672
	s_waitcnt lgkmcnt(8)
	v_mfma_f32_32x32x16_bf16 v[32:47], v[238:241], v[242:245], v[32:47]
	ds_read_b64_tr_b16 v[238:239], v219 offset:24576
	ds_read_b64_tr_b16 v[240:241], v219 offset:28672
	s_waitcnt lgkmcnt(8)
	v_mfma_f32_32x32x16_bf16 v[16:31], v[222:225], v[242:245], v[16:31]
	ds_read_b64_tr_b16 v[222:223], v221 offset:24576
	ds_read_b64_tr_b16 v[224:225], v221 offset:28672
	s_waitcnt lgkmcnt(8)
	v_mfma_f32_32x32x16_bf16 v[0:15], v[206:209], v[242:245], v[0:15]
	ds_read_b64_tr_b16 v[206:207], v205 offset:24832
	ds_read_b64_tr_b16 v[208:209], v205 offset:28928
	s_waitcnt lgkmcnt(8)
	v_mfma_f32_32x32x16_bf16 v[112:127], v[210:213], v[250:253], v[112:127]
	ds_read_b64_tr_b16 v[210:211], v218 offset:24832
	ds_read_b64_tr_b16 v[212:213], v218 offset:28928
	s_waitcnt lgkmcnt(8)
	v_mfma_f32_32x32x16_bf16 v[96:111], v[214:217], v[250:253], v[96:111]
	ds_read_b64_tr_b16 v[214:215], v219 offset:24832
	ds_read_b64_tr_b16 v[216:217], v219 offset:28928
	s_waitcnt lgkmcnt(8)
	v_mfma_f32_32x32x16_bf16 v[80:95], v[238:241], v[250:253], v[80:95]
	ds_read_b64_tr_b16 v[238:239], v221 offset:24832
	ds_read_b64_tr_b16 v[240:241], v221 offset:28928
	s_waitcnt lgkmcnt(8)
	v_mfma_f32_32x32x16_bf16 v[64:79], v[222:225], v[250:253], v[64:79]
	s_waitcnt lgkmcnt(6)
	v_mfma_f32_32x32x16_bf16 v[48:63], v[206:209], v[250:253], v[48:63]
	s_waitcnt lgkmcnt(4)
	v_mfma_f32_32x32x16_bf16 v[32:47], v[210:213], v[250:253], v[32:47]
	s_waitcnt lgkmcnt(2)
	v_mfma_f32_32x32x16_bf16 v[16:31], v[214:217], v[250:253], v[16:31]
	s_waitcnt lgkmcnt(0)
	v_mfma_f32_32x32x16_bf16 v[0:15], v[238:241], v[250:253], v[0:15]
	ds_read_b128 v[206:209], v195 offset:32768
	ds_read_b128 v[210:213], v196 offset:32768
	ds_read_b128 v[214:217], v197 offset:32768
	ds_read_b128 v[238:241], v198 offset:32768
	ds_read_b128 v[242:245], v199 offset:32768
	ds_read_b128 v[250:253], v200 offset:32768
	ds_read_b128 v[222:225], v201 offset:32768
	ds_read_b128 v[226:229], v202 offset:32768
	s_branch .Latt_end_2
.Latt_slow_2s1:
.Latt_slot2_2:
	v_add_u32_e32 v205, 0x8000, v205
	v_add_u32_e32 v218, 0x8000, v218
	v_add_u32_e32 v219, 0x8000, v219
	v_add_u32_e32 v221, 0x8000, v221
	s_waitcnt lgkmcnt(7)
	v_mfma_f32_32x32x16_bf16 v[128:143], v[206:209], v[144:147], 0
	ds_read_b128 v[206:209], v195 offset:40960
	s_cmp_lg_u64 s[12:13], 0
	s_cbranch_scc1 .Latt_nd0_2s2
	s_sub_i32 s100, s38, 1
	s_cmp_eq_u32 s38, 0
	s_cselect_b32 s100, 2, s100
	s_lshl_b32 s101, s100, 14
	s_add_i32 m0, s40, s101
	s_nop 0
	global_load_lds_dwordx4 v178, s[22:23]
.Latt_nd0_2s2:
	s_waitcnt lgkmcnt(7)
	v_mfma_f32_32x32x16_bf16 v[128:143], v[210:213], v[148:151], v[128:143]
	ds_read_b128 v[210:213], v196 offset:40960
	s_cmp_lg_u64 s[12:13], 0
	s_cbranch_scc1 .Latt_nd1_2s2
	s_add_i32 m0, m0, 0x400
	s_nop 0
	global_load_lds_dwordx4 v180, s[22:23]
.Latt_nd1_2s2:
	s_waitcnt lgkmcnt(7)
	v_mfma_f32_32x32x16_bf16 v[128:143], v[214:217], v[152:155], v[128:143]
	ds_read_b128 v[214:217], v197 offset:40960
	s_cmp_lg_u64 s[12:13], 0
	s_cbranch_scc1 .Latt_nd2_2s2
	s_lshl_b32 s101, s100, 15
	s_add_i32 m0, s41, s101
	s_add_u32 s100, s22, 0x1000
	s_addc_u32 s101, s23, 0
	global_load_lds_dwordx4 v182, s[100:101]
.Latt_nd2_2s2:
	s_waitcnt lgkmcnt(7)
	v_mfma_f32_32x32x16_bf16 v[128:143], v[238:241], v[156:159], v[128:143]
	ds_read_b128 v[238:241], v198 offset:40960
	s_cmp_lg_u64 s[12:13], 0
	s_cbranch_scc1 .Latt_nd3_2s2
	s_add_i32 m0, m0, 0x400
	s_nop 0
	global_load_lds_dwordx4 v184, s[100:101]

.Latt_nd5_2s2:
	s_waitcnt lgkmcnt(5)
	v_mfma_f32_32x32x16_bf16 v[128:143], v[222:225], v[168:171], v[128:143]
	s_waitcnt lgkmcnt(4)
	v_mfma_f32_32x32x16_bf16 v[128:143], v[226:229], v[172:175], v[128:143]
	s_waitcnt lgkmcnt(3)
	v_mfma_f32_32x32x16_bf16 v[222:237], v[206:209], v[144:147], 0
	ds_read_b128 v[206:209], v199 offset:40960
	s_nop 8
	v_max3_f32 v246, v128, v129, v130
	v_max3_f32 v247, v131, v132, v133
	v_max3_f32 v246, v246, v134, v135
	v_max3_f32 v247, v247, v136, v137
	v_max3_f32 v246, v246, v138, v139
	v_max3_f32 v247, v247, v140, v141
	v_max3_f32 v246, v246, v142, v143
	s_waitcnt lgkmcnt(3)
	v_mfma_f32_32x32x16_bf16 v[222:237], v[210:213], v[148:151], v[222:237]
	ds_read_b128 v[210:213], v200 offset:40960
	v_max_f32_e32 v246, v246, v247
	v_mov_b32_e32 v247, v246
	v_add_f32_e32 v249, 0x41000000, v190
	s_nop 1
	v_permlane32_swap_b32_e32 v246, v247
	v_max_f32_e32 v246, v246, v247
	v_cmp_gt_f32_e32 vcc, v246, v249
	s_cbranch_vccz .Latt_nr0_2s2
	v_max_f32_e32 v246, v190, v246
	v_sub_f32_e32 v190, v190, v246
	v_exp_f32_e32 v190, v190
	s_nop 0
	v_pk_mul_f32 v[126:127], v[126:127], v[190:191] op_sel_hi:[1,0]
	v_pk_mul_f32 v[124:125], v[124:125], v[190:191] op_sel_hi:[1,0]
	v_pk_mul_f32 v[122:123], v[122:123], v[190:191] op_sel_hi:[1,0]
	v_pk_mul_f32 v[120:121], v[120:121], v[190:191] op_sel_hi:[1,0]
	v_pk_mul_f32 v[118:119], v[118:119], v[190:191] op_sel_hi:[1,0]
	v_pk_mul_f32 v[116:117], v[116:117], v[190:191] op_sel_hi:[1,0]
	v_pk_mul_f32 v[114:115], v[114:115], v[190:191] op_sel_hi:[1,0]
	v_pk_mul_f32 v[112:113], v[112:113], v[190:191] op_sel_hi:[1,0]
	v_pk_mul_f32 v[110:111], v[110:111], v[190:191] op_sel_hi:[1,0]
	v_pk_mul_f32 v[108:109], v[108:109], v[190:191] op_sel_hi:[1,0]
	v_pk_mul_f32 v[106:107], v[106:107], v[190:191] op_sel_hi:[1,0]
	v_pk_mul_f32 v[104:105], v[104:105], v[190:191] op_sel_hi:[1,0]
	v_pk_mul_f32 v[102:103], v[102:103], v[190:191] op_sel_hi:[1,0]
	v_pk_mul_f32 v[100:101], v[100:101], v[190:191] op_sel_hi:[1,0]
	v_pk_mul_f32 v[98:99], v[98:99], v[190:191] op_sel_hi:[1,0]
	v_pk_mul_f32 v[96:97], v[96:97], v[190:191] op_sel_hi:[1,0]
	v_pk_mul_f32 v[94:95], v[94:95], v[190:191] op_sel_hi:[1,0]
	v_pk_mul_f32 v[92:93], v[92:93], v[190:191] op_sel_hi:[1,0]
	v_pk_mul_f32 v[90:91], v[90:91], v[190:191] op_sel_hi:[1,0]
	v_pk_mul_f32 v[88:89], v[88:89], v[190:191] op_sel_hi:[1,0]
	v_pk_mul_f32 v[86:87], v[86:87], v[190:191] op_sel_hi:[1,0]
	v_pk_mul_f32 v[84:85], v[84:85], v[190:191] op_sel_hi:[1,0]
	v_pk_mul_f32 v[82:83], v[82:83], v[190:191] op_sel_hi:[1,0]
	v_pk_mul_f32 v[80:81], v[80:81], v[190:191] op_sel_hi:[1,0]
	v_pk_mul_f32 v[78:79], v[78:79], v[190:191] op_sel_hi:[1,0]
	v_pk_mul_f32 v[76:77], v[76:77], v[190:191] op_sel_hi:[1,0]
	v_pk_mul_f32 v[74:75], v[74:75], v[190:191] op_sel_hi:[1,0]
	v_pk_mul_f32 v[72:73], v[72:73], v[190:191] op_sel_hi:[1,0]
	v_pk_mul_f32 v[70:71], v[70:71], v[190:191] op_sel_hi:[1,0]
	v_pk_mul_f32 v[68:69], v[68:69], v[190:191] op_sel_hi:[1,0]
	v_pk_mul_f32 v[66:67], v[66:67], v[190:191] op_sel_hi:[1,0]
	v_pk_mul_f32 v[64:65], v[64:65], v[190:191] op_sel_hi:[1,0]
	v_pk_mul_f32 v[62:63], v[62:63], v[190:191] op_sel_hi:[1,0]
	v_pk_mul_f32 v[60:61], v[60:61], v[190:191] op_sel_hi:[1,0]
	v_pk_mul_f32 v[58:59], v[58:59], v[190:191] op_sel_hi:[1,0]
	v_pk_mul_f32 v[56:57], v[56:57], v[190:191] op_sel_hi:[1,0]
	v_pk_mul_f32 v[54:55], v[54:55], v[190:191] op_sel_hi:[1,0]
	v_pk_mul_f32 v[52:53], v[52:53], v[190:191] op_sel_hi:[1,0]
	v_pk_mul_f32 v[50:51], v[50:51], v[190:191] op_sel_hi:[1,0]
	v_pk_mul_f32 v[48:49], v[48:49], v[190:191] op_sel_hi:[1,0]
	v_pk_mul_f32 v[46:47], v[46:47], v[190:191] op_sel_hi:[1,0]
	v_pk_mul_f32 v[44:45], v[44:45], v[190:191] op_sel_hi:[1,0]
	v_pk_mul_f32 v[42:43], v[42:43], v[190:191] op_sel_hi:[1,0]
	v_pk_mul_f32 v[40:41], v[40:41], v[190:191] op_sel_hi:[1,0]
	v_pk_mul_f32 v[38:39], v[38:39], v[190:191] op_sel_hi:[1,0]
	v_pk_mul_f32 v[36:37], v[36:37], v[190:191] op_sel_hi:[1,0]
	v_pk_mul_f32 v[34:35], v[34:35], v[190:191] op_sel_hi:[1,0]
	v_pk_mul_f32 v[32:33], v[32:33], v[190:191] op_sel_hi:[1,0]
	v_pk_mul_f32 v[30:31], v[30:31], v[190:191] op_sel_hi:[1,0]
	v_pk_mul_f32 v[28:29], v[28:29], v[190:191] op_sel_hi:[1,0]
	v_pk_mul_f32 v[26:27], v[26:27], v[190:191] op_sel_hi:[1,0]
	v_pk_mul_f32 v[24:25], v[24:25], v[190:191] op_sel_hi:[1,0]
	v_pk_mul_f32 v[22:23], v[22:23], v[190:191] op_sel_hi:[1,0]
	v_pk_mul_f32 v[20:21], v[20:21], v[190:191] op_sel_hi:[1,0]
	v_pk_mul_f32 v[18:19], v[18:19], v[190:191] op_sel_hi:[1,0]
	v_pk_mul_f32 v[16:17], v[16:17], v[190:191] op_sel_hi:[1,0]
	v_pk_mul_f32 v[14:15], v[14:15], v[190:191] op_sel_hi:[1,0]
	v_pk_mul_f32 v[12:13], v[12:13], v[190:191] op_sel_hi:[1,0]
	v_pk_mul_f32 v[10:11], v[10:11], v[190:191] op_sel_hi:[1,0]
	v_pk_mul_f32 v[8:9], v[8:9], v[190:191] op_sel_hi:[1,0]
	v_pk_mul_f32 v[6:7], v[6:7], v[190:191] op_sel_hi:[1,0]
	v_pk_mul_f32 v[4:5], v[4:5], v[190:191] op_sel_hi:[1,0]
	v_pk_mul_f32 v[2:3], v[2:3], v[190:191] op_sel_hi:[1,0]
	v_pk_mul_f32 v[0:1], v[0:1], v[190:191] op_sel_hi:[1,0]
	v_mul_f32_e32 v203, v203, v190
	v_mov_b32_e32 v190, v246
.Latt_nr0_2s2:
	s_waitcnt lgkmcnt(3)
	v_mfma_f32_32x32x16_bf16 v[222:237], v[214:217], v[152:155], v[222:237]
	ds_read_b128 v[214:217], v201 offset:40960
	v_sub_f32_e32 v128, v128, v190
	v_exp_f32_e32 v128, v128
	v_sub_f32_e32 v129, v129, v190
	v_exp_f32_e32 v129, v129
	v_sub_f32_e32 v130, v130, v190
	s_waitcnt lgkmcnt(3)
	v_mfma_f32_32x32x16_bf16 v[222:237], v[238:241], v[156:159], v[222:237]
	ds_read_b128 v[238:241], v202 offset:40960
	v_add_f32_e32 v254, 0, v128
	v_exp_f32_e32 v130, v130
	v_sub_f32_e32 v131, v131, v190
	v_add_f32_e32 v254, v129, v254
	v_exp_f32_e32 v131, v131
	s_waitcnt lgkmcnt(3)
	v_mfma_f32_32x32x16_bf16 v[222:237], v[206:209], v[160:163], v[222:237]
	ds_read_b64_tr_b16 v[206:207], v205
	ds_read_b64_tr_b16 v[208:209], v205 offset:4096
	v_sub_f32_e32 v132, v132, v190
	v_add_f32_e32 v254, v130, v254
	v_exp_f32_e32 v132, v132
	v_sub_f32_e32 v133, v133, v190
	v_add_f32_e32 v254, v131, v254
	s_waitcnt lgkmcnt(4)
	v_mfma_f32_32x32x16_bf16 v[222:237], v[210:213], v[164:167], v[222:237]
	ds_read_b64_tr_b16 v[210:211], v218
	ds_read_b64_tr_b16 v[212:213], v218 offset:4096
	v_exp_f32_e32 v133, v133
	v_sub_f32_e32 v134, v134, v190
	v_add_f32_e32 v254, v132, v254
	v_exp_f32_e32 v134, v134
	s_waitcnt lgkmcnt(5)
	v_mfma_f32_32x32x16_bf16 v[222:237], v[214:217], v[168:171], v[222:237]
	ds_read_b64_tr_b16 v[214:215], v219
	ds_read_b64_tr_b16 v[216:217], v219 offset:4096
	v_sub_f32_e32 v135, v135, v190
	v_add_f32_e32 v254, v133, v254
	v_exp_f32_e32 v135, v135
	s_nop 0
	s_waitcnt lgkmcnt(6)
	v_mfma_f32_32x32x16_bf16 v[222:237], v[238:241], v[172:175], v[222:237]
	ds_read_b64_tr_b16 v[238:239], v221
	ds_read_b64_tr_b16 v[240:241], v221 offset:4096
	v_cvt_pk_bf16_f32 v242, v128, v129
	v_cvt_pk_bf16_f32 v243, v130, v131
	v_cvt_pk_bf16_f32 v244, v132, v133
	v_cvt_pk_bf16_f32 v245, v134, v135
	s_nop 1
	s_waitcnt lgkmcnt(6)
	v_mfma_f32_32x32x16_bf16 v[112:127], v[206:209], v[242:245], v[112:127]
	ds_read_b64_tr_b16 v[206:207], v205 offset:256
	ds_read_b64_tr_b16 v[208:209], v205 offset:4352
	v_sub_f32_e32 v136, v136, v190
	v_add_f32_e32 v254, v134, v254
	v_exp_f32_e32 v136, v136
	v_sub_f32_e32 v137, v137, v190
	v_add_f32_e32 v254, v135, v254
	s_waitcnt lgkmcnt(6)
	v_mfma_f32_32x32x16_bf16 v[96:111], v[210:213], v[242:245], v[96:111]
	ds_read_b64_tr_b16 v[210:211], v218 offset:256
	ds_read_b64_tr_b16 v[212:213], v218 offset:4352
	v_exp_f32_e32 v137, v137
	v_sub_f32_e32 v138, v138, v190
	v_add_f32_e32 v254, v136, v254
	v_exp_f32_e32 v138, v138
	v_sub_f32_e32 v139, v139, v190
	s_waitcnt lgkmcnt(6)
	v_mfma_f32_32x32x16_bf16 v[80:95], v[214:217], v[242:245], v[80:95]
	ds_read_b64_tr_b16 v[214:215], v219 offset:256
	ds_read_b64_tr_b16 v[216:217], v219 offset:4352
	v_add_f32_e32 v254, v137, v254
	v_exp_f32_e32 v139, v139
	v_sub_f32_e32 v140, v140, v190
	v_add_f32_e32 v254, v138, v254
	s_waitcnt lgkmcnt(6)
	v_mfma_f32_32x32x16_bf16 v[64:79], v[238:241], v[242:245], v[64:79]
	ds_read_b64_tr_b16 v[238:239], v221 offset:256
	ds_read_b64_tr_b16 v[240:241], v221 offset:4352
	v_exp_f32_e32 v140, v140
	v_sub_f32_e32 v141, v141, v190
	v_add_f32_e32 v254, v139, v254
	v_exp_f32_e32 v141, v141
	s_waitcnt lgkmcnt(6)
	v_mfma_f32_32x32x16_bf16 v[48:63], v[206:209], v[242:245], v[48:63]
	ds_read_b64_tr_b16 v[206:207], v205 offset:8192
	ds_read_b64_tr_b16 v[208:209], v205 offset:12288
	v_sub_f32_e32 v142, v142, v190
	v_add_f32_e32 v254, v140, v254
	v_exp_f32_e32 v142, v142
	v_sub_f32_e32 v143, v143, v190
	s_waitcnt lgkmcnt(6)
	v_mfma_f32_32x32x16_bf16 v[32:47], v[210:213], v[242:245], v[32:47]
	ds_read_b64_tr_b16 v[210:211], v218 offset:8192
	ds_read_b64_tr_b16 v[212:213], v218 offset:12288
	v_add_f32_e32 v254, v141, v254
	v_exp_f32_e32 v143, v143
	v_add_f32_e32 v254, v142, v254
	v_add_f32_e32 v254, v143, v254
	s_waitcnt lgkmcnt(6)
	v_mfma_f32_32x32x16_bf16 v[16:31], v[214:217], v[242:245], v[16:31]
	ds_read_b64_tr_b16 v[214:215], v219 offset:8192
	ds_read_b64_tr_b16 v[216:217], v219 offset:12288
	v_cvt_pk_bf16_f32 v250, v136, v137
	v_cvt_pk_bf16_f32 v251, v138, v139
	v_cvt_pk_bf16_f32 v252, v140, v141
	v_cvt_pk_bf16_f32 v253, v142, v143
	v_add_f32_e32 v203, v203, v254
	s_waitcnt lgkmcnt(6)
	v_mfma_f32_32x32x16_bf16 v[0:15], v[238:241], v[242:245], v[0:15]
	ds_read_b64_tr_b16 v[238:239], v221 offset:8192
	ds_read_b64_tr_b16 v[240:241], v221 offset:12288
	ds_read_b64_tr_b16 v[128:129], v205 offset:8448
	ds_read_b64_tr_b16 v[130:131], v205 offset:12544
	s_waitcnt lgkmcnt(8)
	v_mfma_f32_32x32x16_bf16 v[112:127], v[206:209], v[250:253], v[112:127]
	ds_read_b64_tr_b16 v[206:207], v218 offset:8448
	ds_read_b64_tr_b16 v[208:209], v218 offset:12544
	v_max3_f32 v246, v222, v223, v224
	v_max3_f32 v247, v225, v226, v227
	v_max3_f32 v246, v246, v228, v229
	v_max3_f32 v247, v247, v230, v231
	v_max3_f32 v246, v246, v232, v233
	s_waitcnt lgkmcnt(8)
	v_mfma_f32_32x32x16_bf16 v[96:111], v[210:213], v[250:253], v[96:111]
	ds_read_b64_tr_b16 v[210:211], v219 offset:8448
	ds_read_b64_tr_b16 v[212:213], v219 offset:12544
	v_max3_f32 v247, v247, v234, v235
	v_max3_f32 v246, v246, v236, v237
	v_max_f32_e32 v246, v246, v247
	v_mov_b32_e32 v247, v246
	v_add_f32_e32 v249, 0x41000000, v190
	s_waitcnt lgkmcnt(8)
	v_mfma_f32_32x32x16_bf16 v[80:95], v[214:217], v[250:253], v[80:95]
	ds_read_b64_tr_b16 v[214:215], v221 offset:8448
	ds_read_b64_tr_b16 v[216:217], v221 offset:12544
	s_nop 1
	v_permlane32_swap_b32_e32 v246, v247
	v_max_f32_e32 v246, v246, v247
	v_cmp_gt_f32_e32 vcc, v246, v249
	s_cbranch_vccnz .Latt_rs1_2s2
	s_waitcnt lgkmcnt(8)
	v_mfma_f32_32x32x16_bf16 v[64:79], v[238:241], v[250:253], v[64:79]
	ds_read_b64_tr_b16 v[238:239], v205 offset:16384
	ds_read_b64_tr_b16 v[240:241], v205 offset:20480
	v_sub_f32_e32 v222, v222, v190
	v_exp_f32_e32 v222, v222
	v_sub_f32_e32 v223, v223, v190
	v_exp_f32_e32 v223, v223
	v_sub_f32_e32 v224, v224, v190
	v_add_f32_e32 v254, 0, v222
	s_waitcnt lgkmcnt(8)
	v_mfma_f32_32x32x16_bf16 v[48:63], v[128:131], v[250:253], v[48:63]
	ds_read_b64_tr_b16 v[128:129], v218 offset:16384
	ds_read_b64_tr_b16 v[130:131], v218 offset:20480
	v_exp_f32_e32 v224, v224
	v_sub_f32_e32 v225, v225, v190
	v_add_f32_e32 v254, v223, v254
	v_exp_f32_e32 v225, v225
	v_sub_f32_e32 v226, v226, v190
	v_add_f32_e32 v254, v224, v254
	s_waitcnt lgkmcnt(8)
	v_mfma_f32_32x32x16_bf16 v[32:47], v[206:209], v[250:253], v[32:47]
	ds_read_b64_tr_b16 v[206:207], v219 offset:16384
	ds_read_b64_tr_b16 v[208:209], v219 offset:20480
	v_exp_f32_e32 v226, v226
	v_sub_f32_e32 v227, v227, v190
	v_add_f32_e32 v254, v225, v254
	v_exp_f32_e32 v227, v227
	v_sub_f32_e32 v228, v228, v190
	s_waitcnt lgkmcnt(8)
	v_mfma_f32_32x32x16_bf16 v[16:31], v[210:213], v[250:253], v[16:31]
	ds_read_b64_tr_b16 v[210:211], v221 offset:16384
	ds_read_b64_tr_b16 v[212:213], v221 offset:20480
	v_add_f32_e32 v254, v226, v254
	v_exp_f32_e32 v228, v228
	v_sub_f32_e32 v229, v229, v190
	v_add_f32_e32 v254, v227, v254
	v_exp_f32_e32 v229, v229
	s_waitcnt lgkmcnt(8)
	v_mfma_f32_32x32x16_bf16 v[0:15], v[214:217], v[250:253], v[0:15]
	ds_read_b64_tr_b16 v[214:215], v205 offset:16640
	ds_read_b64_tr_b16 v[216:217], v205 offset:20736
	s_nop 0
	v_cvt_pk_bf16_f32 v242, v222, v223
	v_cvt_pk_bf16_f32 v243, v224, v225
	v_cvt_pk_bf16_f32 v244, v226, v227
	v_cvt_pk_bf16_f32 v245, v228, v229
	s_nop 1
	s_waitcnt lgkmcnt(8)
	v_mfma_f32_32x32x16_bf16 v[112:127], v[238:241], v[242:245], v[112:127]
	ds_read_b64_tr_b16 v[238:239], v218 offset:16640
	ds_read_b64_tr_b16 v[240:241], v218 offset:20736
	v_sub_f32_e32 v230, v230, v190
	v_add_f32_e32 v254, v228, v254
	v_exp_f32_e32 v230, v230
	v_sub_f32_e32 v231, v231, v190
	v_add_f32_e32 v254, v229, v254
	s_waitcnt lgkmcnt(8)
	v_mfma_f32_32x32x16_bf16 v[96:111], v[128:131], v[242:245], v[96:111]
	ds_read_b64_tr_b16 v[128:129], v219 offset:16640
	ds_read_b64_tr_b16 v[130:131], v219 offset:20736
	v_exp_f32_e32 v231, v231
	v_sub_f32_e32 v232, v232, v190
	v_add_f32_e32 v254, v230, v254
	v_exp_f32_e32 v232, v232
	v_sub_f32_e32 v233, v233, v190
	s_waitcnt lgkmcnt(8)
	v_mfma_f32_32x32x16_bf16 v[80:95], v[206:209], v[242:245], v[80:95]
	ds_read_b64_tr_b16 v[206:207], v221 offset:16640
	ds_read_b64_tr_b16 v[208:209], v221 offset:20736
	v_add_f32_e32 v254, v231, v254
	v_exp_f32_e32 v233, v233
	v_sub_f32_e32 v234, v234, v190
	v_add_f32_e32 v254, v232, v254
	s_waitcnt lgkmcnt(8)
	v_mfma_f32_32x32x16_bf16 v[64:79], v[210:213], v[242:245], v[64:79]
	ds_read_b64_tr_b16 v[210:211], v205 offset:24576
	ds_read_b64_tr_b16 v[212:213], v205 offset:28672
	v_exp_f32_e32 v234, v234
	v_sub_f32_e32 v235, v235, v190
	v_add_f32_e32 v254, v233, v254
	v_exp_f32_e32 v235, v235
	s_waitcnt lgkmcnt(8)
	v_mfma_f32_32x32x16_bf16 v[48:63], v[214:217], v[242:245], v[48:63]
	ds_read_b64_tr_b16 v[214:215], v218 offset:24576
	ds_read_b64_tr_b16 v[216:217], v218 offset:28672
	v_sub_f32_e32 v236, v236, v190
	v_add_f32_e32 v254, v234, v254
	v_exp_f32_e32 v236, v236
	v_sub_f32_e32 v237, v237, v190
	s_waitcnt lgkmcnt(8)
	v_mfma_f32_32x32x16_bf16 v[32:47], v[238:241], v[242:245], v[32:47]
	ds_read_b64_tr_b16 v[238:239], v219 offset:24576
	ds_read_b64_tr_b16 v[240:241], v219 offset:28672
	v_add_f32_e32 v254, v235, v254
	v_exp_f32_e32 v237, v237
	v_add_f32_e32 v254, v236, v254
	v_add_f32_e32 v254, v237, v254
	s_waitcnt lgkmcnt(8)
	v_mfma_f32_32x32x16_bf16 v[16:31], v[128:131], v[242:245], v[16:31]
	ds_read_b64_tr_b16 v[128:129], v221 offset:24576
	ds_read_b64_tr_b16 v[130:131], v221 offset:28672
	v_cvt_pk_bf16_f32 v250, v230, v231
	v_cvt_pk_bf16_f32 v251, v232, v233
	v_cvt_pk_bf16_f32 v252, v234, v235
	v_cvt_pk_bf16_f32 v253, v236, v237
	v_add_f32_e32 v203, v203, v254
	s_waitcnt lgkmcnt(8)
	v_mfma_f32_32x32x16_bf16 v[0:15], v[206:209], v[242:245], v[0:15]
	ds_read_b64_tr_b16 v[206:207], v205 offset:24832
	ds_read_b64_tr_b16 v[208:209], v205 offset:28928
	s_waitcnt lgkmcnt(8)
	v_mfma_f32_32x32x16_bf16 v[112:127], v[210:213], v[250:253], v[112:127]
	ds_read_b64_tr_b16 v[210:211], v218 offset:24832
	ds_read_b64_tr_b16 v[212:213], v218 offset:28928
	s_waitcnt lgkmcnt(8)
	v_mfma_f32_32x32x16_bf16 v[96:111], v[214:217], v[250:253], v[96:111]
	ds_read_b64_tr_b16 v[214:215], v219 offset:24832
	ds_read_b64_tr_b16 v[216:217], v219 offset:28928
	s_waitcnt lgkmcnt(8)
	v_mfma_f32_32x32x16_bf16 v[80:95], v[238:241], v[250:253], v[80:95]
	ds_read_b64_tr_b16 v[238:239], v221 offset:24832
	ds_read_b64_tr_b16 v[240:241], v221 offset:28928
	s_waitcnt lgkmcnt(8)
	v_mfma_f32_32x32x16_bf16 v[64:79], v[128:131], v[250:253], v[64:79]
	s_waitcnt lgkmcnt(6)
	v_mfma_f32_32x32x16_bf16 v[48:63], v[206:209], v[250:253], v[48:63]
	s_waitcnt lgkmcnt(4)
	v_mfma_f32_32x32x16_bf16 v[32:47], v[210:213], v[250:253], v[32:47]
	s_waitcnt lgkmcnt(2)
	v_mfma_f32_32x32x16_bf16 v[16:31], v[214:217], v[250:253], v[16:31]
	s_waitcnt lgkmcnt(0)
	v_mfma_f32_32x32x16_bf16 v[0:15], v[238:241], v[250:253], v[0:15]
	ds_read_b128 v[206:209], v195
	ds_read_b128 v[210:213], v196
	ds_read_b128 v[214:217], v197
	ds_read_b128 v[238:241], v198
	ds_read_b128 v[242:245], v199
	ds_read_b128 v[250:253], v200
	ds_read_b128 v[222:225], v201
	ds_read_b128 v[226:229], v202
	s_branch .Latt_end_2
.Latt_rs1_2s2:
	s_waitcnt lgkmcnt(8)
	v_mfma_f32_32x32x16_bf16 v[64:79], v[238:241], v[250:253], v[64:79]
	ds_read_b64_tr_b16 v[238:239], v205 offset:16384
	ds_read_b64_tr_b16 v[240:241], v205 offset:20480
	s_waitcnt lgkmcnt(8)
	v_mfma_f32_32x32x16_bf16 v[48:63], v[128:131], v[250:253], v[48:63]
	ds_read_b64_tr_b16 v[128:129], v218 offset:16384
	ds_read_b64_tr_b16 v[130:131], v218 offset:20480
	s_waitcnt lgkmcnt(8)
	v_mfma_f32_32x32x16_bf16 v[32:47], v[206:209], v[250:253], v[32:47]
	ds_read_b64_tr_b16 v[206:207], v219 offset:16384
	ds_read_b64_tr_b16 v[208:209], v219 offset:20480
	s_waitcnt lgkmcnt(8)
	v_mfma_f32_32x32x16_bf16 v[16:31], v[210:213], v[250:253], v[16:31]
	ds_read_b64_tr_b16 v[210:211], v221 offset:16384
	ds_read_b64_tr_b16 v[212:213], v221 offset:20480
	s_waitcnt lgkmcnt(8)
	v_mfma_f32_32x32x16_bf16 v[0:15], v[214:217], v[250:253], v[0:15]
	ds_read_b64_tr_b16 v[214:215], v205 offset:16640
	ds_read_b64_tr_b16 v[216:217], v205 offset:20736
	s_nop 11
	v_max_f32_e32 v246, v190, v246
	v_sub_f32_e32 v190, v190, v246
	v_exp_f32_e32 v190, v190
	s_nop 0
	v_pk_mul_f32 v[126:127], v[126:127], v[190:191] op_sel_hi:[1,0]
	v_pk_mul_f32 v[124:125], v[124:125], v[190:191] op_sel_hi:[1,0]
	v_pk_mul_f32 v[122:123], v[122:123], v[190:191] op_sel_hi:[1,0]
	v_pk_mul_f32 v[120:121], v[120:121], v[190:191] op_sel_hi:[1,0]
	v_pk_mul_f32 v[118:119], v[118:119], v[190:191] op_sel_hi:[1,0]
	v_pk_mul_f32 v[116:117], v[116:117], v[190:191] op_sel_hi:[1,0]
	v_pk_mul_f32 v[114:115], v[114:115], v[190:191] op_sel_hi:[1,0]
	v_pk_mul_f32 v[112:113], v[112:113], v[190:191] op_sel_hi:[1,0]
	v_pk_mul_f32 v[110:111], v[110:111], v[190:191] op_sel_hi:[1,0]
	v_pk_mul_f32 v[108:109], v[108:109], v[190:191] op_sel_hi:[1,0]
	v_pk_mul_f32 v[106:107], v[106:107], v[190:191] op_sel_hi:[1,0]
	v_pk_mul_f32 v[104:105], v[104:105], v[190:191] op_sel_hi:[1,0]
	v_pk_mul_f32 v[102:103], v[102:103], v[190:191] op_sel_hi:[1,0]
	v_pk_mul_f32 v[100:101], v[100:101], v[190:191] op_sel_hi:[1,0]
	v_pk_mul_f32 v[98:99], v[98:99], v[190:191] op_sel_hi:[1,0]
	v_pk_mul_f32 v[96:97], v[96:97], v[190:191] op_sel_hi:[1,0]
	v_pk_mul_f32 v[94:95], v[94:95], v[190:191] op_sel_hi:[1,0]
	v_pk_mul_f32 v[92:93], v[92:93], v[190:191] op_sel_hi:[1,0]
	v_pk_mul_f32 v[90:91], v[90:91], v[190:191] op_sel_hi:[1,0]
	v_pk_mul_f32 v[88:89], v[88:89], v[190:191] op_sel_hi:[1,0]
	v_pk_mul_f32 v[86:87], v[86:87], v[190:191] op_sel_hi:[1,0]
	v_pk_mul_f32 v[84:85], v[84:85], v[190:191] op_sel_hi:[1,0]
	v_pk_mul_f32 v[82:83], v[82:83], v[190:191] op_sel_hi:[1,0]
	v_pk_mul_f32 v[80:81], v[80:81], v[190:191] op_sel_hi:[1,0]
	v_pk_mul_f32 v[78:79], v[78:79], v[190:191] op_sel_hi:[1,0]
	v_pk_mul_f32 v[76:77], v[76:77], v[190:191] op_sel_hi:[1,0]
	v_pk_mul_f32 v[74:75], v[74:75], v[190:191] op_sel_hi:[1,0]
	v_pk_mul_f32 v[72:73], v[72:73], v[190:191] op_sel_hi:[1,0]
	v_pk_mul_f32 v[70:71], v[70:71], v[190:191] op_sel_hi:[1,0]
	v_pk_mul_f32 v[68:69], v[68:69], v[190:191] op_sel_hi:[1,0]
	v_pk_mul_f32 v[66:67], v[66:67], v[190:191] op_sel_hi:[1,0]
	v_pk_mul_f32 v[64:65], v[64:65], v[190:191] op_sel_hi:[1,0]
	v_pk_mul_f32 v[62:63], v[62:63], v[190:191] op_sel_hi:[1,0]
	v_pk_mul_f32 v[60:61], v[60:61], v[190:191] op_sel_hi:[1,0]
	v_pk_mul_f32 v[58:59], v[58:59], v[190:191] op_sel_hi:[1,0]
	v_pk_mul_f32 v[56:57], v[56:57], v[190:191] op_sel_hi:[1,0]
	v_pk_mul_f32 v[54:55], v[54:55], v[190:191] op_sel_hi:[1,0]
	v_pk_mul_f32 v[52:53], v[52:53], v[190:191] op_sel_hi:[1,0]
	v_pk_mul_f32 v[50:51], v[50:51], v[190:191] op_sel_hi:[1,0]
	v_pk_mul_f32 v[48:49], v[48:49], v[190:191] op_sel_hi:[1,0]
	v_pk_mul_f32 v[46:47], v[46:47], v[190:191] op_sel_hi:[1,0]
	v_pk_mul_f32 v[44:45], v[44:45], v[190:191] op_sel_hi:[1,0]
	v_pk_mul_f32 v[42:43], v[42:43], v[190:191] op_sel_hi:[1,0]
	v_pk_mul_f32 v[40:41], v[40:41], v[190:191] op_sel_hi:[1,0]
	v_pk_mul_f32 v[38:39], v[38:39], v[190:191] op_sel_hi:[1,0]
	v_pk_mul_f32 v[36:37], v[36:37], v[190:191] op_sel_hi:[1,0]
	v_pk_mul_f32 v[34:35], v[34:35], v[190:191] op_sel_hi:[1,0]
	v_pk_mul_f32 v[32:33], v[32:33], v[190:191] op_sel_hi:[1,0]
	v_pk_mul_f32 v[30:31], v[30:31], v[190:191] op_sel_hi:[1,0]
	v_pk_mul_f32 v[28:29], v[28:29], v[190:191] op_sel_hi:[1,0]
	v_pk_mul_f32 v[26:27], v[26:27], v[190:191] op_sel_hi:[1,0]
	v_pk_mul_f32 v[24:25], v[24:25], v[190:191] op_sel_hi:[1,0]
	v_pk_mul_f32 v[22:23], v[22:23], v[190:191] op_sel_hi:[1,0]
	v_pk_mul_f32 v[20:21], v[20:21], v[190:191] op_sel_hi:[1,0]
	v_pk_mul_f32 v[18:19], v[18:19], v[190:191] op_sel_hi:[1,0]
	v_pk_mul_f32 v[16:17], v[16:17], v[190:191] op_sel_hi:[1,0]
	v_pk_mul_f32 v[14:15], v[14:15], v[190:191] op_sel_hi:[1,0]
	v_pk_mul_f32 v[12:13], v[12:13], v[190:191] op_sel_hi:[1,0]
	v_pk_mul_f32 v[10:11], v[10:11], v[190:191] op_sel_hi:[1,0]
	v_pk_mul_f32 v[8:9], v[8:9], v[190:191] op_sel_hi:[1,0]
	v_pk_mul_f32 v[6:7], v[6:7], v[190:191] op_sel_hi:[1,0]
	v_pk_mul_f32 v[4:5], v[4:5], v[190:191] op_sel_hi:[1,0]
	v_pk_mul_f32 v[2:3], v[2:3], v[190:191] op_sel_hi:[1,0]
	v_pk_mul_f32 v[0:1], v[0:1], v[190:191] op_sel_hi:[1,0]
	v_mul_f32_e32 v203, v203, v190
	v_mov_b32_e32 v190, v246
	v_sub_f32_e32 v222, v222, v190
	v_exp_f32_e32 v222, v222
	v_sub_f32_e32 v223, v223, v190
	v_exp_f32_e32 v223, v223
	v_sub_f32_e32 v224, v224, v190
	v_add_f32_e32 v254, 0, v222
	v_exp_f32_e32 v224, v224
	v_sub_f32_e32 v225, v225, v190
	v_add_f32_e32 v254, v223, v254
	v_exp_f32_e32 v225, v225
	v_sub_f32_e32 v226, v226, v190
	v_add_f32_e32 v254, v224, v254
	v_exp_f32_e32 v226, v226
	v_sub_f32_e32 v227, v227, v190
	v_add_f32_e32 v254, v225, v254
	v_exp_f32_e32 v227, v227
	v_sub_f32_e32 v228, v228, v190
	v_add_f32_e32 v254, v226, v254
	v_exp_f32_e32 v228, v228
	v_sub_f32_e32 v229, v229, v190
	v_add_f32_e32 v254, v227, v254
	v_exp_f32_e32 v229, v229
	v_sub_f32_e32 v230, v230, v190
	v_add_f32_e32 v254, v228, v254
	v_exp_f32_e32 v230, v230
	v_sub_f32_e32 v231, v231, v190
	v_add_f32_e32 v254, v229, v254
	v_exp_f32_e32 v231, v231
	v_sub_f32_e32 v232, v232, v190
	v_add_f32_e32 v254, v230, v254
	v_exp_f32_e32 v232, v232
	v_sub_f32_e32 v233, v233, v190
	v_add_f32_e32 v254, v231, v254
	v_exp_f32_e32 v233, v233
	v_sub_f32_e32 v234, v234, v190
	v_add_f32_e32 v254, v232, v254
	v_exp_f32_e32 v234, v234
	v_sub_f32_e32 v235, v235, v190
	v_add_f32_e32 v254, v233, v254
	v_exp_f32_e32 v235, v235
	v_sub_f32_e32 v236, v236, v190
	v_add_f32_e32 v254, v234, v254
	v_exp_f32_e32 v236, v236
	v_sub_f32_e32 v237, v237, v190
	v_add_f32_e32 v254, v235, v254
	v_exp_f32_e32 v237, v237
	v_add_f32_e32 v254, v236, v254
	v_add_f32_e32 v254, v237, v254
	v_cvt_pk_bf16_f32 v242, v222, v223
	v_cvt_pk_bf16_f32 v243, v224, v225
	v_cvt_pk_bf16_f32 v244, v226, v227
	v_cvt_pk_bf16_f32 v245, v228, v229
	v_cvt_pk_bf16_f32 v250, v230, v231
	v_cvt_pk_bf16_f32 v251, v232, v233
	v_cvt_pk_bf16_f32 v252, v234, v235
	v_cvt_pk_bf16_f32 v253, v236, v237
	v_add_f32_e32 v203, v203, v254
	s_nop 1
	s_waitcnt lgkmcnt(8)
	v_mfma_f32_32x32x16_bf16 v[112:127], v[238:241], v[242:245], v[112:127]
	ds_read_b64_tr_b16 v[238:239], v218 offset:16640
	ds_read_b64_tr_b16 v[240:241], v218 offset:20736
	s_waitcnt lgkmcnt(8)
	v_mfma_f32_32x32x16_bf16 v[96:111], v[128:131], v[242:245], v[96:111]
	ds_read_b64_tr_b16 v[222:223], v219 offset:16640
	ds_read_b64_tr_b16 v[224:225], v219 offset:20736
	s_waitcnt lgkmcnt(8)
	v_mfma_f32_32x32x16_bf16 v[80:95], v[206:209], v[242:245], v[80:95]
	ds_read_b64_tr_b16 v[206:207], v221 offset:16640
	ds_read_b64_tr_b16 v[208:209], v221 offset:20736
	s_waitcnt lgkmcnt(8)
	v_mfma_f32_32x32x16_bf16 v[64:79], v[210:213], v[242:245], v[64:79]
	ds_read_b64_tr_b16 v[210:211], v205 offset:24576
	ds_read_b64_tr_b16 v[212:213], v205 offset:28672
	s_waitcnt lgkmcnt(8)
	v_mfma_f32_32x32x16_bf16 v[48:63], v[214:217], v[242:245], v[48:63]
	ds_read_b64_tr_b16 v[214:215], v218 offset:24576
	ds_read_b64_tr_b16 v[216:217], v218 offset:28672
	s_waitcnt lgkmcnt(8)
	v_mfma_f32_32x32x16_bf16 v[32:47], v[238:241], v[242:245], v[32:47]
	ds_read_b64_tr_b16 v[238:239], v219 offset:24576
	ds_read_b64_tr_b16 v[240:241], v219 offset:28672
	s_waitcnt lgkmcnt(8)
	v_mfma_f32_32x32x16_bf16 v[16:31], v[222:225], v[242:245], v[16:31]
	ds_read_b64_tr_b16 v[222:223], v221 offset:24576
	ds_read_b64_tr_b16 v[224:225], v221 offset:28672
	s_waitcnt lgkmcnt(8)
	v_mfma_f32_32x32x16_bf16 v[0:15], v[206:209], v[242:245], v[0:15]
	ds_read_b64_tr_b16 v[206:207], v205 offset:24832
	ds_read_b64_tr_b16 v[208:209], v205 offset:28928
	s_waitcnt lgkmcnt(8)
	v_mfma_f32_32x32x16_bf16 v[112:127], v[210:213], v[250:253], v[112:127]
	ds_read_b64_tr_b16 v[210:211], v218 offset:24832
	ds_read_b64_tr_b16 v[212:213], v218 offset:28928
	s_waitcnt lgkmcnt(8)
	v_mfma_f32_32x32x16_bf16 v[96:111], v[214:217], v[250:253], v[96:111]
	ds_read_b64_tr_b16 v[214:215], v219 offset:24832
	ds_read_b64_tr_b16 v[216:217], v219 offset:28928
	s_waitcnt lgkmcnt(8)
	v_mfma_f32_32x32x16_bf16 v[80:95], v[238:241], v[250:253], v[80:95]
	ds_read_b64_tr_b16 v[238:239], v221 offset:24832
	ds_read_b64_tr_b16 v[240:241], v221 offset:28928
	s_waitcnt lgkmcnt(8)
	v_mfma_f32_32x32x16_bf16 v[64:79], v[222:225], v[250:253], v[64:79]
	s_waitcnt lgkmcnt(6)
	v_mfma_f32_32x32x16_bf16 v[48:63], v[206:209], v[250:253], v[48:63]
	s_waitcnt lgkmcnt(4)
	v_mfma_f32_32x32x16_bf16 v[32:47], v[210:213], v[250:253], v[32:47]
	s_waitcnt lgkmcnt(2)
	v_mfma_f32_32x32x16_bf16 v[16:31], v[214:217], v[250:253], v[16:31]
	s_waitcnt lgkmcnt(0)
	v_mfma_f32_32x32x16_bf16 v[0:15], v[238:241], v[250:253], v[0:15]
	ds_read_b128 v[206:209], v195
	ds_read_b128 v[210:213], v196
	ds_read_b128 v[214:217], v197
	ds_read_b128 v[238:241], v198
	ds_read_b128 v[242:245], v199
	ds_read_b128 v[250:253], v200
	ds_read_b128 v[222:225], v201
	ds_read_b128 v[226:229], v202
	s_branch .Latt_end_2
.Latt_slow_2s2:
.Latt_slow_2:
	s_waitcnt lgkmcnt(0)
	s_lshl_b32 s14, s38, 14
	s_add_i32 s15, s14, 0
	v_add_u32_e32 v207, s15, v195
	ds_read_b128 v[128:131], v207
	v_add_u32_e32 v208, s15, v196
	ds_read_b128 v[210:213], v208
	v_add_u32_e32 v209, s15, v197
	v_lshrrev_b32_e32 v205, 3, v204
	s_add_i32 s39, s84, 31
	v_and_or_b32 v206, v204, 31, s80
	s_cmp_le_i32 s39, s80
	s_waitcnt lgkmcnt(1)
	v_mfma_f32_32x32x16_bf16 v[128:143], v[128:131], v[144:147], 0
	s_waitcnt lgkmcnt(0)
	v_mfma_f32_32x32x16_bf16 v[128:143], v[210:213], v[148:151], v[128:143]
	ds_read_b128 v[212:215], v209
	v_add_u32_e32 v210, s15, v198
	ds_read_b128 v[216:219], v210
	v_add_u32_e32 v211, s15, v199
	s_waitcnt lgkmcnt(1)
	v_mfma_f32_32x32x16_bf16 v[128:143], v[212:215], v[152:155], v[128:143]
	v_add_u32_e32 v213, s15, v200
	v_and_b32_e32 v212, 4, v205
	ds_read_b128 v[222:225], v213
	s_waitcnt lgkmcnt(1)
	v_mfma_f32_32x32x16_bf16 v[128:143], v[216:219], v[156:159], v[128:143]
	ds_read_b128 v[214:217], v211
	s_waitcnt lgkmcnt(0)
	v_mfma_f32_32x32x16_bf16 v[128:143], v[214:217], v[160:163], v[128:143]
	v_add_u32_e32 v214, s15, v201
	ds_read_b128 v[216:219], v214
	v_add_u32_e32 v215, s15, v202
	v_mfma_f32_32x32x16_bf16 v[128:143], v[222:225], v[164:167], v[128:143]
	ds_read_b128 v[222:225], v215
	s_waitcnt lgkmcnt(1)
	v_mfma_f32_32x32x16_bf16 v[128:143], v[216:219], v[168:171], v[128:143]
	s_waitcnt lgkmcnt(0)
	v_mfma_f32_32x32x16_bf16 v[128:143], v[222:225], v[172:175], v[128:143]
	s_cbranch_scc1 .LBB0_888
	v_add_u32_e32 v205, s84, v212
	v_cmp_lt_i32_e32 vcc, v205, v206
	v_add_u32_e32 v216, 2, v205
	s_nop 7
	v_cndmask_b32_e32 v129, v192, v129, vcc
	v_cmp_le_i32_e32 vcc, v205, v206
	s_nop 1
	v_cndmask_b32_e32 v128, v192, v128, vcc
	v_cmp_le_i32_e32 vcc, v216, v206
	v_add_u32_e32 v216, 3, v205
	s_nop 0
	v_cndmask_b32_e32 v130, v192, v130, vcc
	v_cmp_le_i32_e32 vcc, v216, v206
	v_add_u32_e32 v216, 8, v205
	s_nop 0
	v_cndmask_b32_e32 v131, v192, v131, vcc
	v_cmp_le_i32_e32 vcc, v216, v206
	v_add_u32_e32 v216, 9, v205
	s_nop 0
	v_cndmask_b32_e32 v132, v192, v132, vcc
	v_cmp_le_i32_e32 vcc, v216, v206
	v_add_u32_e32 v216, 10, v205
	s_nop 0
	v_cndmask_b32_e32 v133, v192, v133, vcc
	v_cmp_le_i32_e32 vcc, v216, v206
	v_add_u32_e32 v216, 11, v205
	s_nop 0
	v_cndmask_b32_e32 v134, v192, v134, vcc
	v_cmp_le_i32_e32 vcc, v216, v206
	v_add_u32_e32 v216, 16, v205
	s_nop 0
	v_cndmask_b32_e32 v135, v192, v135, vcc
	v_cmp_le_i32_e32 vcc, v216, v206
	v_add_u32_e32 v216, 17, v205
	s_nop 0
	v_cndmask_b32_e32 v136, v192, v136, vcc
	v_cmp_le_i32_e32 vcc, v216, v206
	v_add_u32_e32 v216, 18, v205
	s_nop 0
	v_cndmask_b32_e32 v137, v192, v137, vcc
	v_cmp_le_i32_e32 vcc, v216, v206
	v_add_u32_e32 v216, 19, v205
	s_nop 0
	v_cndmask_b32_e32 v138, v192, v138, vcc
	v_cmp_le_i32_e32 vcc, v216, v206
	v_add_u32_e32 v216, 24, v205
	s_nop 0
	v_cndmask_b32_e32 v139, v192, v139, vcc
	v_cmp_le_i32_e32 vcc, v216, v206
	v_add_u32_e32 v216, 25, v205
	s_nop 0
	v_cndmask_b32_e32 v140, v192, v140, vcc
	v_cmp_le_i32_e32 vcc, v216, v206
	v_add_u32_e32 v216, 26, v205
	v_add_u32_e32 v205, 27, v205
	v_cndmask_b32_e32 v141, v192, v141, vcc
	v_cmp_le_i32_e32 vcc, v216, v206
	s_nop 1
	v_cndmask_b32_e32 v142, v192, v142, vcc
	v_cmp_le_i32_e32 vcc, v205, v206
	s_nop 1
	v_cndmask_b32_e32 v143, v192, v143, vcc

.LBB0_895:
	v_sub_f32_e32 v128, v128, v190
	v_exp_f32_e32 v128, v128
	v_sub_f32_e32 v129, v129, v190
	v_exp_f32_e32 v129, v129
	v_sub_f32_e32 v130, v130, v190
	v_exp_f32_e32 v130, v130
	v_sub_f32_e32 v131, v131, v190
	v_exp_f32_e32 v131, v131
	v_sub_f32_e32 v132, v132, v190
	v_add_f32_e32 v206, 0, v128
	v_exp_f32_e32 v132, v132
	v_sub_f32_e32 v133, v133, v190
	v_add_f32_e32 v206, v129, v206
	v_exp_f32_e32 v133, v133
	v_sub_f32_e32 v134, v134, v190
	v_add_f32_e32 v206, v130, v206
	v_exp_f32_e32 v134, v134
	v_sub_f32_e32 v135, v135, v190
	v_add_f32_e32 v206, v131, v206
	v_exp_f32_e32 v135, v135
	v_sub_f32_e32 v136, v136, v190
	v_add_f32_e32 v206, v132, v206
	v_exp_f32_e32 v136, v136
	v_sub_f32_e32 v137, v137, v190
	v_add_f32_e32 v206, v133, v206
	v_exp_f32_e32 v137, v137
	v_sub_f32_e32 v138, v138, v190
	v_add_f32_e32 v206, v134, v206
	v_exp_f32_e32 v138, v138
	v_sub_f32_e32 v139, v139, v190
	v_add_f32_e32 v206, v135, v206
	v_exp_f32_e32 v139, v139
	v_sub_f32_e32 v140, v140, v190
	v_add_f32_e32 v206, v136, v206
	v_exp_f32_e32 v140, v140
	v_sub_f32_e32 v141, v141, v190
	v_add_f32_e32 v206, v137, v206
	v_exp_f32_e32 v141, v141
	v_sub_f32_e32 v142, v142, v190
	v_add_f32_e32 v206, v138, v206
	v_exp_f32_e32 v142, v142
	v_sub_f32_e32 v143, v143, v190
	v_add_f32_e32 v206, v139, v206
	v_exp_f32_e32 v143, v143
	v_add_f32_e32 v206, v140, v206
	v_add_f32_e32 v206, v141, v206
	v_add_f32_e32 v206, v142, v206
	v_add_u32_e32 v208, 0xc000, v216
	v_add_f32_e32 v216, v143, v206
	v_cvt_pk_bf16_f32 v128, v128, v129
	v_cvt_pk_bf16_f32 v129, v130, v131
	v_cvt_pk_bf16_f32 v130, v132, v133
	v_cvt_pk_bf16_f32 v131, v134, v135
	v_cvt_pk_bf16_f32 v132, v136, v137
	v_cvt_pk_bf16_f32 v133, v138, v139
	v_cvt_pk_bf16_f32 v134, v140, v141
	v_cvt_pk_bf16_f32 v135, v142, v143
	v_add_u32_e32 v219, v208, v205
	ds_read_b64_tr_b16 v[136:137], v219 offset:16384
	ds_read_b64_tr_b16 v[138:139], v219 offset:20480
	v_add_u32_e32 v221, v208, v204
	ds_read_b64_tr_b16 v[142:143], v219 offset:20736
	ds_read_b64_tr_b16 v[140:141], v219 offset:16640
	v_add_u32_e32 v217, v208, v217
	v_add_u32_e32 v218, v208, v218
	s_waitcnt lgkmcnt(2)
	v_mfma_f32_32x32x16_bf16 v[112:127], v[136:139], v[128:131], v[112:127]
	ds_read_b64_tr_b16 v[136:137], v221 offset:16384
	ds_read_b64_tr_b16 v[138:139], v221 offset:20480
	ds_read_b64_tr_b16 v[206:207], v221 offset:20736
	ds_read_b64_tr_b16 v[204:205], v221 offset:16640
	v_add_f32_e32 v203, v203, v216
	s_waitcnt lgkmcnt(2)
	v_mfma_f32_32x32x16_bf16 v[96:111], v[136:139], v[128:131], v[96:111]
	ds_read_b64_tr_b16 v[136:137], v217 offset:16384
	ds_read_b64_tr_b16 v[138:139], v217 offset:20480
	ds_read_b64_tr_b16 v[210:211], v217 offset:20736
	ds_read_b64_tr_b16 v[208:209], v217 offset:16640
	s_waitcnt lgkmcnt(2)
	v_mfma_f32_32x32x16_bf16 v[80:95], v[136:139], v[128:131], v[80:95]
	ds_read_b64_tr_b16 v[136:137], v218 offset:16384
	ds_read_b64_tr_b16 v[138:139], v218 offset:20480
	ds_read_b64_tr_b16 v[214:215], v218 offset:20736
	ds_read_b64_tr_b16 v[212:213], v218 offset:16640
	s_waitcnt lgkmcnt(2)
	v_mfma_f32_32x32x16_bf16 v[64:79], v[136:139], v[128:131], v[64:79]
	v_mfma_f32_32x32x16_bf16 v[48:63], v[140:143], v[128:131], v[48:63]
	v_mfma_f32_32x32x16_bf16 v[32:47], v[204:207], v[128:131], v[32:47]
	v_mfma_f32_32x32x16_bf16 v[16:31], v[208:211], v[128:131], v[16:31]
	s_waitcnt lgkmcnt(0)
	v_mfma_f32_32x32x16_bf16 v[0:15], v[212:215], v[128:131], v[0:15]
	ds_read_b64_tr_b16 v[128:129], v219 offset:24576
	ds_read_b64_tr_b16 v[130:131], v219 offset:28672
	ds_read_b64_tr_b16 v[138:139], v219 offset:28928
	ds_read_b64_tr_b16 v[136:137], v219 offset:24832
	s_waitcnt lgkmcnt(2)
	v_mfma_f32_32x32x16_bf16 v[112:127], v[128:131], v[132:135], v[112:127]
	ds_read_b64_tr_b16 v[128:129], v221 offset:24576
	ds_read_b64_tr_b16 v[130:131], v221 offset:28672
	ds_read_b64_tr_b16 v[142:143], v221 offset:28928
	ds_read_b64_tr_b16 v[140:141], v221 offset:24832
	s_waitcnt lgkmcnt(2)
	v_mfma_f32_32x32x16_bf16 v[96:111], v[128:131], v[132:135], v[96:111]
	ds_read_b64_tr_b16 v[128:129], v217 offset:24576
	ds_read_b64_tr_b16 v[130:131], v217 offset:28672
	ds_read_b64_tr_b16 v[206:207], v217 offset:28928
	ds_read_b64_tr_b16 v[204:205], v217 offset:24832
	s_waitcnt lgkmcnt(2)
	v_mfma_f32_32x32x16_bf16 v[80:95], v[128:131], v[132:135], v[80:95]
	ds_read_b64_tr_b16 v[128:129], v218 offset:24576
	ds_read_b64_tr_b16 v[130:131], v218 offset:28672
	ds_read_b64_tr_b16 v[210:211], v218 offset:28928
	ds_read_b64_tr_b16 v[208:209], v218 offset:24832
	s_waitcnt lgkmcnt(2)
	v_mfma_f32_32x32x16_bf16 v[64:79], v[128:131], v[132:135], v[64:79]
	v_mfma_f32_32x32x16_bf16 v[48:63], v[136:139], v[132:135], v[48:63]
	v_mfma_f32_32x32x16_bf16 v[32:47], v[140:143], v[132:135], v[32:47]
	v_mfma_f32_32x32x16_bf16 v[16:31], v[204:207], v[132:135], v[16:31]
	s_waitcnt lgkmcnt(0)
	v_mfma_f32_32x32x16_bf16 v[0:15], v[208:211], v[132:135], v[0:15]
.LBB0_896:
	s_waitcnt lgkmcnt(0)
.Latt_end_2:
	s_mov_b64 s[14:15], -1
	s_and_b64 vcc, exec, s[12:13]
	s_cbranch_vccz .LBB0_898
	s_waitcnt vmcnt(0)
	s_mov_b64 s[14:15], 0

.LBB0_904:
	s_cmp_gt_i32 s14, s81
	s_cbranch_scc1 .LBB0_915
	s_add_i32 s100, s14, 63
	s_cmp_le_i32 s100, s80
	s_cbranch_scc0 .Latt_slow_3
	s_cmp_eq_u32 s11, 1
	s_cbranch_scc1 .Latt_slot1_3
	s_cmp_eq_u32 s11, 2
	s_cbranch_scc1 .Latt_slot2_3
	s_cmp_lg_u32 s14, 0
	s_cbranch_scc1 .Latt_vstep_3s0
	ds_read_b128 v[206:209], v196
	ds_read_b128 v[210:213], v197
	ds_read_b128 v[214:217], v198
	ds_read_b128 v[238:241], v199
	ds_read_b128 v[242:245], v200
	ds_read_b128 v[250:253], v201
	ds_read_b128 v[222:225], v202
	ds_read_b128 v[226:229], v203
	v_bfe_u32 v246, v204, 2, 2
	v_bfe_u32 v247, v204, 5, 1
	v_lshl_or_b32 v247, v247, 2, v246
	v_and_b32_e32 v249, 3, v204
	v_and_b32_e32 v254, 16, v204
	v_lshl_or_b32 v249, v249, 2, v254
	v_lshlrev_b32_e32 v249, 1, v249
	v_lshl_add_u32 v247, v247, 9, v249
	v_add_u32_e32 v247, 0xc000, v247
	v_lshlrev_b32_e32 v246, 6, v246
	v_add_u32_e32 v205, v247, v246
	v_xor_b32_e32 v249, 64, v246
	v_add_u32_e32 v218, v247, v249
	v_xor_b32_e32 v249, 0x80, v246
	v_add_u32_e32 v219, v247, v249
	v_xor_b32_e32 v249, 0xc0, v246
	v_add_u32_e32 v221, v247, v249
	s_branch .Latt_vdone_3s0

.Latt_vdone_3s0:
	s_waitcnt lgkmcnt(7)
	v_mfma_f32_32x32x16_bf16 v[128:143], v[206:209], v[144:147], 0
	ds_read_b128 v[206:209], v196 offset:8192
	s_cmp_lg_u64 s[8:9], 0
	s_cbranch_scc1 .Latt_nd0_3s0
	s_sub_i32 s100, s11, 1
	s_cmp_eq_u32 s11, 0
	s_cselect_b32 s100, 2, s100
	s_lshl_b32 s101, s100, 14
	s_add_i32 m0, s40, s101
	s_nop 0
	global_load_lds_dwordx4 v178, s[34:35]
.Latt_nd0_3s0:
	s_waitcnt lgkmcnt(7)
	v_mfma_f32_32x32x16_bf16 v[128:143], v[210:213], v[148:151], v[128:143]
	ds_read_b128 v[210:213], v197 offset:8192
	s_cmp_lg_u64 s[8:9], 0
	s_cbranch_scc1 .Latt_nd1_3s0
	s_add_i32 m0, m0, 0x400
	s_nop 0
	global_load_lds_dwordx4 v180, s[34:35]
.Latt_nd1_3s0:
	s_waitcnt lgkmcnt(7)
	v_mfma_f32_32x32x16_bf16 v[128:143], v[214:217], v[152:155], v[128:143]
	ds_read_b128 v[214:217], v198 offset:8192
	s_cmp_lg_u64 s[8:9], 0
	s_cbranch_scc1 .Latt_nd2_3s0
	s_lshl_b32 s101, s100, 15
	s_add_i32 m0, s41, s101
	s_add_u32 s100, s34, 0xf00
	s_addc_u32 s101, s35, 0
	global_load_lds_dwordx4 v182, s[100:101]
.Latt_nd2_3s0:
	s_waitcnt lgkmcnt(7)
	v_mfma_f32_32x32x16_bf16 v[128:143], v[238:241], v[156:159], v[128:143]
	ds_read_b128 v[238:241], v199 offset:8192
	s_cmp_lg_u64 s[8:9], 0
	s_cbranch_scc1 .Latt_nd3_3s0
	s_add_i32 m0, m0, 0x400
	s_nop 0
	global_load_lds_dwordx4 v184, s[100:101]
.Latt_nd3_3s0:
	s_waitcnt lgkmcnt(7)
	v_mfma_f32_32x32x16_bf16 v[128:143], v[242:245], v[160:163], v[128:143]
	s_cmp_lg_u64 s[8:9], 0
	s_cbranch_scc1 .Latt_nd4_3s0
	s_add_i32 m0, m0, 0x400
	s_nop 0
	global_load_lds_dwordx4 v186, s[100:101]
.Latt_nd4_3s0:
	s_waitcnt lgkmcnt(6)
	v_mfma_f32_32x32x16_bf16 v[128:143], v[250:253], v[164:167], v[128:143]
	s_cmp_lg_u64 s[8:9], 0
	s_cbranch_scc1 .Latt_nd5_3s0
	s_add_i32 m0, m0, 0x400
	s_nop 0
	global_load_lds_dwordx4 v188, s[100:101]

.Latt_slow_3s0:
.Latt_slot1_3:
	v_add_u32_e32 v205, 0x8000, v205
	v_add_u32_e32 v218, 0x8000, v218
	v_add_u32_e32 v219, 0x8000, v219
	v_add_u32_e32 v221, 0x8000, v221
	s_waitcnt lgkmcnt(7)
	v_mfma_f32_32x32x16_bf16 v[128:143], v[206:209], v[144:147], 0
	ds_read_b128 v[206:209], v196 offset:24576
	s_cmp_lg_u64 s[8:9], 0
	s_cbranch_scc1 .Latt_nd0_3s1
	s_sub_i32 s100, s11, 1
	s_cmp_eq_u32 s11, 0
	s_cselect_b32 s100, 2, s100
	s_lshl_b32 s101, s100, 14
	s_add_i32 m0, s40, s101
	s_nop 0
	global_load_lds_dwordx4 v178, s[34:35]
.Latt_nd0_3s1:
	s_waitcnt lgkmcnt(7)
	v_mfma_f32_32x32x16_bf16 v[128:143], v[210:213], v[148:151], v[128:143]
	ds_read_b128 v[210:213], v197 offset:24576
	s_cmp_lg_u64 s[8:9], 0
	s_cbranch_scc1 .Latt_nd1_3s1
	s_add_i32 m0, m0, 0x400
	s_nop 0
	global_load_lds_dwordx4 v180, s[34:35]
.Latt_nd1_3s1:
	s_waitcnt lgkmcnt(7)
	v_mfma_f32_32x32x16_bf16 v[128:143], v[214:217], v[152:155], v[128:143]
	ds_read_b128 v[214:217], v198 offset:24576
	s_cmp_lg_u64 s[8:9], 0
	s_cbranch_scc1 .Latt_nd2_3s1
	s_lshl_b32 s101, s100, 15
	s_add_i32 m0, s41, s101
	s_add_u32 s100, s34, 0xf00
	s_addc_u32 s101, s35, 0
	global_load_lds_dwordx4 v182, s[100:101]
.Latt_nd2_3s1:
	s_waitcnt lgkmcnt(7)
	v_mfma_f32_32x32x16_bf16 v[128:143], v[238:241], v[156:159], v[128:143]
	ds_read_b128 v[238:241], v199 offset:24576
	s_cmp_lg_u64 s[8:9], 0
	s_cbranch_scc1 .Latt_nd3_3s1
	s_add_i32 m0, m0, 0x400
	s_nop 0
	global_load_lds_dwordx4 v184, s[100:101]

.Latt_slow_3s1:
.Latt_slot2_3:
	v_add_u32_e32 v205, 0x8000, v205
	v_add_u32_e32 v218, 0x8000, v218
	v_add_u32_e32 v219, 0x8000, v219
	v_add_u32_e32 v221, 0x8000, v221
	s_waitcnt lgkmcnt(7)
	v_mfma_f32_32x32x16_bf16 v[128:143], v[206:209], v[144:147], 0
	ds_read_b128 v[206:209], v196 offset:40960
	s_cmp_lg_u64 s[8:9], 0
	s_cbranch_scc1 .Latt_nd0_3s2
	s_sub_i32 s100, s11, 1
	s_cmp_eq_u32 s11, 0
	s_cselect_b32 s100, 2, s100
	s_lshl_b32 s101, s100, 14
	s_add_i32 m0, s40, s101
	s_nop 0
	global_load_lds_dwordx4 v178, s[34:35]
.Latt_nd0_3s2:
	s_waitcnt lgkmcnt(7)
	v_mfma_f32_32x32x16_bf16 v[128:143], v[210:213], v[148:151], v[128:143]
	ds_read_b128 v[210:213], v197 offset:40960
	s_cmp_lg_u64 s[8:9], 0
	s_cbranch_scc1 .Latt_nd1_3s2
	s_add_i32 m0, m0, 0x400
	s_nop 0
	global_load_lds_dwordx4 v180, s[34:35]
.Latt_nd1_3s2:
	s_waitcnt lgkmcnt(7)
	v_mfma_f32_32x32x16_bf16 v[128:143], v[214:217], v[152:155], v[128:143]
	ds_read_b128 v[214:217], v198 offset:40960
	s_cmp_lg_u64 s[8:9], 0
	s_cbranch_scc1 .Latt_nd2_3s2
	s_lshl_b32 s101, s100, 15
	s_add_i32 m0, s41, s101
	s_add_u32 s100, s34, 0xf00
	s_addc_u32 s101, s35, 0
	global_load_lds_dwordx4 v182, s[100:101]
.Latt_nd2_3s2:
	s_waitcnt lgkmcnt(7)
	v_mfma_f32_32x32x16_bf16 v[128:143], v[238:241], v[156:159], v[128:143]
	ds_read_b128 v[238:241], v199 offset:40960
	s_cmp_lg_u64 s[8:9], 0
	s_cbranch_scc1 .Latt_nd3_3s2
	s_add_i32 m0, m0, 0x400
	s_nop 0
	global_load_lds_dwordx4 v184, s[100:101]

.Latt_slow_3s2:
.Latt_slow_3:
	s_waitcnt lgkmcnt(0)
	s_lshl_b32 s15, s11, 14
	s_add_i32 s16, s15, 0
	v_add_u32_e32 v207, s16, v196
	ds_read_b128 v[128:131], v207
	v_add_u32_e32 v208, s16, v197
	ds_read_b128 v[210:213], v208
	v_add_u32_e32 v209, s16, v198
	v_lshrrev_b32_e32 v205, 3, v204
	s_add_i32 s17, s14, 31
	v_and_or_b32 v206, v204, 31, s80
	s_cmp_le_i32 s17, s80
	s_waitcnt lgkmcnt(1)
	v_mfma_f32_32x32x16_bf16 v[128:143], v[128:131], v[144:147], 0
	s_waitcnt lgkmcnt(0)
	v_mfma_f32_32x32x16_bf16 v[128:143], v[210:213], v[148:151], v[128:143]
	ds_read_b128 v[212:215], v209
	v_add_u32_e32 v210, s16, v199
	ds_read_b128 v[216:219], v210
	v_add_u32_e32 v211, s16, v200
	s_waitcnt lgkmcnt(1)
	v_mfma_f32_32x32x16_bf16 v[128:143], v[212:215], v[152:155], v[128:143]
	v_add_u32_e32 v213, s16, v201
	v_and_b32_e32 v212, 4, v205
	ds_read_b128 v[222:225], v213
	s_waitcnt lgkmcnt(1)
	v_mfma_f32_32x32x16_bf16 v[128:143], v[216:219], v[156:159], v[128:143]
	ds_read_b128 v[214:217], v211
	s_waitcnt lgkmcnt(0)
	v_mfma_f32_32x32x16_bf16 v[128:143], v[214:217], v[160:163], v[128:143]
	v_add_u32_e32 v214, s16, v202
	ds_read_b128 v[216:219], v214
	v_add_u32_e32 v215, s16, v203
	v_mfma_f32_32x32x16_bf16 v[128:143], v[222:225], v[164:167], v[128:143]
	ds_read_b128 v[222:225], v215
	s_waitcnt lgkmcnt(1)
	v_mfma_f32_32x32x16_bf16 v[128:143], v[216:219], v[168:171], v[128:143]
	s_waitcnt lgkmcnt(0)
	v_mfma_f32_32x32x16_bf16 v[128:143], v[222:225], v[172:175], v[128:143]
	s_cbranch_scc1 .LBB0_907
	v_add_u32_e32 v205, s14, v212
	v_cmp_lt_i32_e32 vcc, v205, v206
	v_add_u32_e32 v216, 2, v205
	s_nop 7
	v_cndmask_b32_e32 v129, v192, v129, vcc
	v_cmp_le_i32_e32 vcc, v205, v206
	s_nop 1
	v_cndmask_b32_e32 v128, v192, v128, vcc
	v_cmp_le_i32_e32 vcc, v216, v206
	v_add_u32_e32 v216, 3, v205
	s_nop 0
	v_cndmask_b32_e32 v130, v192, v130, vcc
	v_cmp_le_i32_e32 vcc, v216, v206
	v_add_u32_e32 v216, 8, v205
	s_nop 0
	v_cndmask_b32_e32 v131, v192, v131, vcc
	v_cmp_le_i32_e32 vcc, v216, v206
	v_add_u32_e32 v216, 9, v205
	s_nop 0
	v_cndmask_b32_e32 v132, v192, v132, vcc
	v_cmp_le_i32_e32 vcc, v216, v206
	v_add_u32_e32 v216, 10, v205
	s_nop 0
	v_cndmask_b32_e32 v133, v192, v133, vcc
	v_cmp_le_i32_e32 vcc, v216, v206
	v_add_u32_e32 v216, 11, v205
	s_nop 0
	v_cndmask_b32_e32 v134, v192, v134, vcc
	v_cmp_le_i32_e32 vcc, v216, v206
	v_add_u32_e32 v216, 16, v205
	s_nop 0
	v_cndmask_b32_e32 v135, v192, v135, vcc
	v_cmp_le_i32_e32 vcc, v216, v206
	v_add_u32_e32 v216, 17, v205
	s_nop 0
	v_cndmask_b32_e32 v136, v192, v136, vcc
	v_cmp_le_i32_e32 vcc, v216, v206
	v_add_u32_e32 v216, 18, v205
	s_nop 0
	v_cndmask_b32_e32 v137, v192, v137, vcc
	v_cmp_le_i32_e32 vcc, v216, v206
	v_add_u32_e32 v216, 19, v205
	s_nop 0
	v_cndmask_b32_e32 v138, v192, v138, vcc
	v_cmp_le_i32_e32 vcc, v216, v206
	v_add_u32_e32 v216, 24, v205
	s_nop 0
	v_cndmask_b32_e32 v139, v192, v139, vcc
	v_cmp_le_i32_e32 vcc, v216, v206
	v_add_u32_e32 v216, 25, v205
	s_nop 0
	v_cndmask_b32_e32 v140, v192, v140, vcc
	v_cmp_le_i32_e32 vcc, v216, v206
	v_add_u32_e32 v216, 26, v205
	v_add_u32_e32 v205, 27, v205
	v_cndmask_b32_e32 v141, v192, v141, vcc
	v_cmp_le_i32_e32 vcc, v216, v206
	s_nop 1
	v_cndmask_b32_e32 v142, v192, v142, vcc
	v_cmp_le_i32_e32 vcc, v205, v206
	s_nop 1
	v_cndmask_b32_e32 v143, v192, v143, vcc

.LBB0_914:
	v_sub_f32_e32 v128, v128, v190
	v_exp_f32_e32 v128, v128
	v_sub_f32_e32 v129, v129, v190
	v_exp_f32_e32 v129, v129
	v_sub_f32_e32 v130, v130, v190
	v_exp_f32_e32 v130, v130
	v_sub_f32_e32 v131, v131, v190
	v_exp_f32_e32 v131, v131
	v_sub_f32_e32 v132, v132, v190
	v_add_f32_e32 v206, 0, v128
	v_exp_f32_e32 v132, v132
	v_sub_f32_e32 v133, v133, v190
	v_add_f32_e32 v206, v129, v206
	v_exp_f32_e32 v133, v133
	v_sub_f32_e32 v134, v134, v190
	v_add_f32_e32 v206, v130, v206
	v_exp_f32_e32 v134, v134
	v_sub_f32_e32 v135, v135, v190
	v_add_f32_e32 v206, v131, v206
	v_exp_f32_e32 v135, v135
	v_sub_f32_e32 v136, v136, v190
	v_add_f32_e32 v206, v132, v206
	v_exp_f32_e32 v136, v136
	v_sub_f32_e32 v137, v137, v190
	v_add_f32_e32 v206, v133, v206
	v_exp_f32_e32 v137, v137
	v_sub_f32_e32 v138, v138, v190
	v_add_f32_e32 v206, v134, v206
	v_exp_f32_e32 v138, v138
	v_sub_f32_e32 v139, v139, v190
	v_add_f32_e32 v206, v135, v206
	v_exp_f32_e32 v139, v139
	v_sub_f32_e32 v140, v140, v190
	v_add_f32_e32 v206, v136, v206
	v_exp_f32_e32 v140, v140
	v_sub_f32_e32 v141, v141, v190
	v_add_f32_e32 v206, v137, v206
	v_exp_f32_e32 v141, v141
	v_sub_f32_e32 v142, v142, v190
	v_add_f32_e32 v206, v138, v206
	v_exp_f32_e32 v142, v142
	v_sub_f32_e32 v143, v143, v190
	v_add_f32_e32 v206, v139, v206
	v_exp_f32_e32 v143, v143
	v_add_f32_e32 v206, v140, v206
	v_add_f32_e32 v206, v141, v206
	v_add_f32_e32 v206, v142, v206
	v_add_u32_e32 v208, 0xc000, v216
	v_add_f32_e32 v216, v143, v206
	v_cvt_pk_bf16_f32 v128, v128, v129
	v_cvt_pk_bf16_f32 v129, v130, v131
	v_cvt_pk_bf16_f32 v130, v132, v133
	v_cvt_pk_bf16_f32 v131, v134, v135
	v_cvt_pk_bf16_f32 v132, v136, v137
	v_cvt_pk_bf16_f32 v133, v138, v139
	v_cvt_pk_bf16_f32 v134, v140, v141
	v_cvt_pk_bf16_f32 v135, v142, v143
	v_add_u32_e32 v219, v208, v205
	ds_read_b64_tr_b16 v[136:137], v219 offset:16384
	ds_read_b64_tr_b16 v[138:139], v219 offset:20480
	v_add_u32_e32 v221, v208, v204
	ds_read_b64_tr_b16 v[142:143], v219 offset:20736
	ds_read_b64_tr_b16 v[140:141], v219 offset:16640
	v_add_u32_e32 v217, v208, v217
	v_add_u32_e32 v218, v208, v218
	s_waitcnt lgkmcnt(2)
	v_mfma_f32_32x32x16_bf16 v[112:127], v[136:139], v[128:131], v[112:127]
	ds_read_b64_tr_b16 v[136:137], v221 offset:16384
	ds_read_b64_tr_b16 v[138:139], v221 offset:20480
	ds_read_b64_tr_b16 v[206:207], v221 offset:20736
	ds_read_b64_tr_b16 v[204:205], v221 offset:16640
	v_add_f32_e32 v195, v195, v216
	s_waitcnt lgkmcnt(2)
	v_mfma_f32_32x32x16_bf16 v[96:111], v[136:139], v[128:131], v[96:111]
	ds_read_b64_tr_b16 v[136:137], v217 offset:16384
	ds_read_b64_tr_b16 v[138:139], v217 offset:20480
	ds_read_b64_tr_b16 v[210:211], v217 offset:20736
	ds_read_b64_tr_b16 v[208:209], v217 offset:16640
	s_waitcnt lgkmcnt(2)
	v_mfma_f32_32x32x16_bf16 v[80:95], v[136:139], v[128:131], v[80:95]
	ds_read_b64_tr_b16 v[136:137], v218 offset:16384
	ds_read_b64_tr_b16 v[138:139], v218 offset:20480
	ds_read_b64_tr_b16 v[214:215], v218 offset:20736
	ds_read_b64_tr_b16 v[212:213], v218 offset:16640
	s_waitcnt lgkmcnt(2)
	v_mfma_f32_32x32x16_bf16 v[64:79], v[136:139], v[128:131], v[64:79]
	v_mfma_f32_32x32x16_bf16 v[48:63], v[140:143], v[128:131], v[48:63]
	v_mfma_f32_32x32x16_bf16 v[32:47], v[204:207], v[128:131], v[32:47]
	v_mfma_f32_32x32x16_bf16 v[16:31], v[208:211], v[128:131], v[16:31]
	s_waitcnt lgkmcnt(0)
	v_mfma_f32_32x32x16_bf16 v[0:15], v[212:215], v[128:131], v[0:15]
	ds_read_b64_tr_b16 v[128:129], v219 offset:24576
	ds_read_b64_tr_b16 v[130:131], v219 offset:28672
	ds_read_b64_tr_b16 v[138:139], v219 offset:28928
	ds_read_b64_tr_b16 v[136:137], v219 offset:24832
	s_waitcnt lgkmcnt(2)
	v_mfma_f32_32x32x16_bf16 v[112:127], v[128:131], v[132:135], v[112:127]
	ds_read_b64_tr_b16 v[128:129], v221 offset:24576
	ds_read_b64_tr_b16 v[130:131], v221 offset:28672
	ds_read_b64_tr_b16 v[142:143], v221 offset:28928
	ds_read_b64_tr_b16 v[140:141], v221 offset:24832
	s_waitcnt lgkmcnt(2)
	v_mfma_f32_32x32x16_bf16 v[96:111], v[128:131], v[132:135], v[96:111]
	ds_read_b64_tr_b16 v[128:129], v217 offset:24576
	ds_read_b64_tr_b16 v[130:131], v217 offset:28672
	ds_read_b64_tr_b16 v[206:207], v217 offset:28928
	ds_read_b64_tr_b16 v[204:205], v217 offset:24832
	s_waitcnt lgkmcnt(2)
	v_mfma_f32_32x32x16_bf16 v[80:95], v[128:131], v[132:135], v[80:95]
	ds_read_b64_tr_b16 v[128:129], v218 offset:24576
	ds_read_b64_tr_b16 v[130:131], v218 offset:28672
	ds_read_b64_tr_b16 v[210:211], v218 offset:28928
	ds_read_b64_tr_b16 v[208:209], v218 offset:24832
	s_waitcnt lgkmcnt(2)
	v_mfma_f32_32x32x16_bf16 v[64:79], v[128:131], v[132:135], v[64:79]
	v_mfma_f32_32x32x16_bf16 v[48:63], v[136:139], v[132:135], v[48:63]
	v_mfma_f32_32x32x16_bf16 v[32:47], v[140:143], v[132:135], v[32:47]
	v_mfma_f32_32x32x16_bf16 v[16:31], v[204:207], v[132:135], v[16:31]
	s_waitcnt lgkmcnt(0)
	v_mfma_f32_32x32x16_bf16 v[0:15], v[208:211], v[132:135], v[0:15]
.LBB0_915:
	s_waitcnt lgkmcnt(0)
.Latt_end_3:
	s_andn2_b64 vcc, exec, s[8:9]
	s_mov_b64 s[8:9], -1
	s_cbranch_vccnz .LBB0_917
	s_waitcnt vmcnt(0)
	s_mov_b64 s[8:9], 0

.LBB0_1801:
	s_cmp_gt_i32 s39, s72
	s_cbranch_scc1 .LBB0_1812
	s_add_i32 s100, s39, 63
	s_cmp_le_i32 s100, s71
	s_cbranch_scc0 .Latt_slow_4
	s_cmp_eq_u32 s76, 1
	s_cbranch_scc1 .Latt_slot1_4
	s_cmp_eq_u32 s76, 2
	s_cbranch_scc1 .Latt_slot2_4
	s_cmp_lg_u32 s39, 0
	s_cbranch_scc1 .Latt_vstep_4s0
	ds_read_b128 v[206:209], v194
	ds_read_b128 v[210:213], v195
	ds_read_b128 v[214:217], v196
	ds_read_b128 v[238:241], v197
	ds_read_b128 v[242:245], v198
	ds_read_b128 v[250:253], v199
	ds_read_b128 v[222:225], v200
	ds_read_b128 v[226:229], v201
	v_bfe_u32 v246, v203, 2, 2
	v_bfe_u32 v247, v203, 5, 1
	v_lshl_or_b32 v247, v247, 2, v246
	v_and_b32_e32 v249, 3, v203
	v_and_b32_e32 v254, 16, v203
	v_lshl_or_b32 v249, v249, 2, v254
	v_lshlrev_b32_e32 v249, 1, v249
	v_lshl_add_u32 v247, v247, 9, v249
	v_add_u32_e32 v247, 0xc000, v247
	v_lshlrev_b32_e32 v246, 6, v246
	v_add_u32_e32 v205, v247, v246
	v_xor_b32_e32 v249, 64, v246
	v_add_u32_e32 v218, v247, v249
	v_xor_b32_e32 v249, 0x80, v246
	v_add_u32_e32 v219, v247, v249
	v_xor_b32_e32 v249, 0xc0, v246
	v_add_u32_e32 v221, v247, v249
	s_branch .Latt_vdone_4s0

.Latt_vdone_4s0:
	s_waitcnt lgkmcnt(7)
	v_mfma_f32_32x32x16_bf16 v[128:143], v[206:209], v[144:147], 0
	ds_read_b128 v[206:209], v194 offset:8192
	s_cmp_lg_u64 s[18:19], 0
	s_cbranch_scc1 .Latt_nd0_4s0
	s_sub_i32 s100, s76, 1
	s_cmp_eq_u32 s76, 0
	s_cselect_b32 s100, 2, s100
	s_lshl_b32 s101, s100, 14
	s_add_i32 m0, s73, s101
	s_nop 0
	global_load_lds_dwordx4 v178, s[14:15]

.Latt_nd1_4s0:
	s_waitcnt lgkmcnt(7)
	v_mfma_f32_32x32x16_bf16 v[128:143], v[214:217], v[152:155], v[128:143]
	ds_read_b128 v[214:217], v196 offset:8192
	s_cmp_lg_u64 s[18:19], 0
	s_cbranch_scc1 .Latt_nd2_4s0
	s_lshl_b32 s101, s100, 15
	s_add_i32 m0, s74, s101
	s_add_u32 s100, s14, 0x1000
	s_addc_u32 s101, s15, 0
	global_load_lds_dwordx4 v182, s[100:101]

.Latt_slow_4s0:
.Latt_slot1_4:
	v_add_u32_e32 v205, 0x8000, v205
	v_add_u32_e32 v218, 0x8000, v218
	v_add_u32_e32 v219, 0x8000, v219
	v_add_u32_e32 v221, 0x8000, v221
	s_waitcnt lgkmcnt(7)
	v_mfma_f32_32x32x16_bf16 v[128:143], v[206:209], v[144:147], 0
	ds_read_b128 v[206:209], v194 offset:24576
	s_cmp_lg_u64 s[18:19], 0
	s_cbranch_scc1 .Latt_nd0_4s1
	s_sub_i32 s100, s76, 1
	s_cmp_eq_u32 s76, 0
	s_cselect_b32 s100, 2, s100
	s_lshl_b32 s101, s100, 14
	s_add_i32 m0, s73, s101
	s_nop 0
	global_load_lds_dwordx4 v178, s[14:15]

.Latt_nd1_4s1:
	s_waitcnt lgkmcnt(7)
	v_mfma_f32_32x32x16_bf16 v[128:143], v[214:217], v[152:155], v[128:143]
	ds_read_b128 v[214:217], v196 offset:24576
	s_cmp_lg_u64 s[18:19], 0
	s_cbranch_scc1 .Latt_nd2_4s1
	s_lshl_b32 s101, s100, 15
	s_add_i32 m0, s74, s101
	s_add_u32 s100, s14, 0x1000
	s_addc_u32 s101, s15, 0
	global_load_lds_dwordx4 v182, s[100:101]

.Latt_slow_4s1:
.Latt_slot2_4:
	v_add_u32_e32 v205, 0x8000, v205
	v_add_u32_e32 v218, 0x8000, v218
	v_add_u32_e32 v219, 0x8000, v219
	v_add_u32_e32 v221, 0x8000, v221
	s_waitcnt lgkmcnt(7)
	v_mfma_f32_32x32x16_bf16 v[128:143], v[206:209], v[144:147], 0
	ds_read_b128 v[206:209], v194 offset:40960
	s_cmp_lg_u64 s[18:19], 0
	s_cbranch_scc1 .Latt_nd0_4s2
	s_sub_i32 s100, s76, 1
	s_cmp_eq_u32 s76, 0
	s_cselect_b32 s100, 2, s100
	s_lshl_b32 s101, s100, 14
	s_add_i32 m0, s73, s101
	s_nop 0
	global_load_lds_dwordx4 v178, s[14:15]

.Latt_nd1_4s2:
	s_waitcnt lgkmcnt(7)
	v_mfma_f32_32x32x16_bf16 v[128:143], v[214:217], v[152:155], v[128:143]
	ds_read_b128 v[214:217], v196 offset:40960
	s_cmp_lg_u64 s[18:19], 0
	s_cbranch_scc1 .Latt_nd2_4s2
	s_lshl_b32 s101, s100, 15
	s_add_i32 m0, s74, s101
	s_add_u32 s100, s14, 0x1000
	s_addc_u32 s101, s15, 0
	global_load_lds_dwordx4 v182, s[100:101]

.Latt_slow_4s2:
.Latt_slow_4:
	s_waitcnt lgkmcnt(0)
	s_lshl_b32 s22, s76, 14
	s_add_i32 s23, s22, 0
	v_add_u32_e32 v206, s23, v194
	ds_read_b128 v[128:131], v206
	v_add_u32_e32 v207, s23, v195
	ds_read_b128 v[210:213], v207
	v_add_u32_e32 v208, s23, v196
	v_add_u32_e32 v209, s23, v197
	v_lshrrev_b32_e32 v204, 3, v203
	s_add_i32 s77, s39, 31
	v_and_or_b32 v205, v203, 31, s71
	s_cmp_le_i32 s77, s71
	s_waitcnt lgkmcnt(1)
	v_mfma_f32_32x32x16_bf16 v[128:143], v[128:131], v[144:147], 0
	ds_read_b128 v[214:217], v209
	s_waitcnt lgkmcnt(1)
	v_mfma_f32_32x32x16_bf16 v[128:143], v[210:213], v[148:151], v[128:143]
	ds_read_b128 v[210:213], v208
	s_waitcnt lgkmcnt(0)
	v_mfma_f32_32x32x16_bf16 v[128:143], v[210:213], v[152:155], v[128:143]
	v_add_u32_e32 v210, s23, v198
	v_add_u32_e32 v212, s23, v199
	v_add_u32_e32 v213, s23, v200
	v_and_b32_e32 v211, 4, v204
	ds_read_b128 v[222:225], v212
	v_mfma_f32_32x32x16_bf16 v[128:143], v[214:217], v[156:159], v[128:143]
	ds_read_b128 v[214:217], v210
	s_waitcnt lgkmcnt(0)
	v_mfma_f32_32x32x16_bf16 v[128:143], v[214:217], v[160:163], v[128:143]
	ds_read_b128 v[216:219], v213
	v_add_u32_e32 v214, s23, v201
	v_mfma_f32_32x32x16_bf16 v[128:143], v[222:225], v[164:167], v[128:143]
	ds_read_b128 v[222:225], v214
	s_waitcnt lgkmcnt(1)
	v_mfma_f32_32x32x16_bf16 v[128:143], v[216:219], v[168:171], v[128:143]
	s_waitcnt lgkmcnt(0)
	v_mfma_f32_32x32x16_bf16 v[128:143], v[222:225], v[172:175], v[128:143]
	s_cbranch_scc1 .LBB0_1804
	v_add_u32_e32 v204, s39, v211
	v_cmp_lt_i32_e32 vcc, v204, v205
	v_add_u32_e32 v215, 2, v204
	s_nop 7
	v_cndmask_b32_e32 v129, v192, v129, vcc
	v_cmp_le_i32_e32 vcc, v204, v205
	s_nop 1
	v_cndmask_b32_e32 v128, v192, v128, vcc
	v_cmp_le_i32_e32 vcc, v215, v205
	v_add_u32_e32 v215, 3, v204
	s_nop 0
	v_cndmask_b32_e32 v130, v192, v130, vcc
	v_cmp_le_i32_e32 vcc, v215, v205
	v_add_u32_e32 v215, 8, v204
	s_nop 0
	v_cndmask_b32_e32 v131, v192, v131, vcc
	v_cmp_le_i32_e32 vcc, v215, v205
	v_add_u32_e32 v215, 9, v204
	s_nop 0
	v_cndmask_b32_e32 v132, v192, v132, vcc
	v_cmp_le_i32_e32 vcc, v215, v205
	v_add_u32_e32 v215, 10, v204
	s_nop 0
	v_cndmask_b32_e32 v133, v192, v133, vcc
	v_cmp_le_i32_e32 vcc, v215, v205
	v_add_u32_e32 v215, 11, v204
	s_nop 0
	v_cndmask_b32_e32 v134, v192, v134, vcc
	v_cmp_le_i32_e32 vcc, v215, v205
	v_add_u32_e32 v215, 16, v204
	s_nop 0
	v_cndmask_b32_e32 v135, v192, v135, vcc
	v_cmp_le_i32_e32 vcc, v215, v205
	v_add_u32_e32 v215, 17, v204
	s_nop 0
	v_cndmask_b32_e32 v136, v192, v136, vcc
	v_cmp_le_i32_e32 vcc, v215, v205
	v_add_u32_e32 v215, 18, v204
	s_nop 0
	v_cndmask_b32_e32 v137, v192, v137, vcc
	v_cmp_le_i32_e32 vcc, v215, v205
	v_add_u32_e32 v215, 19, v204
	s_nop 0
	v_cndmask_b32_e32 v138, v192, v138, vcc
	v_cmp_le_i32_e32 vcc, v215, v205
	v_add_u32_e32 v215, 24, v204
	s_nop 0
	v_cndmask_b32_e32 v139, v192, v139, vcc
	v_cmp_le_i32_e32 vcc, v215, v205
	v_add_u32_e32 v215, 25, v204
	s_nop 0
	v_cndmask_b32_e32 v140, v192, v140, vcc
	v_cmp_le_i32_e32 vcc, v215, v205
	v_add_u32_e32 v215, 26, v204
	v_add_u32_e32 v204, 27, v204
	v_cndmask_b32_e32 v141, v192, v141, vcc
	v_cmp_le_i32_e32 vcc, v215, v205
	s_nop 1
	v_cndmask_b32_e32 v142, v192, v142, vcc
	v_cmp_le_i32_e32 vcc, v204, v205
	s_nop 1
	v_cndmask_b32_e32 v143, v192, v143, vcc

.LBB0_1811:
	v_sub_f32_e32 v128, v128, v190
	v_exp_f32_e32 v128, v128
	v_sub_f32_e32 v129, v129, v190
	v_exp_f32_e32 v129, v129
	v_sub_f32_e32 v130, v130, v190
	v_exp_f32_e32 v130, v130
	v_sub_f32_e32 v131, v131, v190
	v_exp_f32_e32 v131, v131
	v_sub_f32_e32 v132, v132, v190
	v_add_f32_e32 v205, 0, v128
	v_exp_f32_e32 v132, v132
	v_sub_f32_e32 v133, v133, v190
	v_add_f32_e32 v205, v129, v205
	v_exp_f32_e32 v133, v133
	v_sub_f32_e32 v134, v134, v190
	v_add_f32_e32 v205, v130, v205
	v_exp_f32_e32 v134, v134
	v_sub_f32_e32 v135, v135, v190
	v_add_f32_e32 v205, v131, v205
	v_exp_f32_e32 v135, v135
	v_sub_f32_e32 v136, v136, v190
	v_add_f32_e32 v205, v132, v205
	v_exp_f32_e32 v136, v136
	v_sub_f32_e32 v137, v137, v190
	v_add_f32_e32 v205, v133, v205
	v_exp_f32_e32 v137, v137
	v_sub_f32_e32 v138, v138, v190
	v_add_f32_e32 v205, v134, v205
	v_exp_f32_e32 v138, v138
	v_sub_f32_e32 v139, v139, v190
	v_add_f32_e32 v205, v135, v205
	v_exp_f32_e32 v139, v139
	v_sub_f32_e32 v140, v140, v190
	v_add_f32_e32 v205, v136, v205
	v_exp_f32_e32 v140, v140
	v_sub_f32_e32 v141, v141, v190
	v_add_f32_e32 v205, v137, v205
	v_exp_f32_e32 v141, v141
	v_sub_f32_e32 v142, v142, v190
	v_add_f32_e32 v205, v138, v205
	v_exp_f32_e32 v142, v142
	v_sub_f32_e32 v143, v143, v190
	v_add_f32_e32 v205, v139, v205
	v_exp_f32_e32 v143, v143
	v_add_f32_e32 v205, v140, v205
	v_add_f32_e32 v205, v141, v205
	v_add_f32_e32 v205, v142, v205
	v_add_u32_e32 v208, 0xc000, v216
	v_add_f32_e32 v216, v143, v205
	v_cvt_pk_bf16_f32 v128, v128, v129
	v_cvt_pk_bf16_f32 v129, v130, v131
	v_cvt_pk_bf16_f32 v130, v132, v133
	v_cvt_pk_bf16_f32 v131, v134, v135
	v_cvt_pk_bf16_f32 v132, v136, v137
	v_cvt_pk_bf16_f32 v133, v138, v139
	v_cvt_pk_bf16_f32 v134, v140, v141
	v_cvt_pk_bf16_f32 v135, v142, v143
	v_add_u32_e32 v219, v208, v204
	ds_read_b64_tr_b16 v[136:137], v219 offset:16384
	ds_read_b64_tr_b16 v[138:139], v219 offset:20480
	v_add_u32_e32 v203, v208, v203
	ds_read_b64_tr_b16 v[142:143], v219 offset:20736
	ds_read_b64_tr_b16 v[140:141], v219 offset:16640
	v_add_u32_e32 v217, v208, v217
	v_add_u32_e32 v218, v208, v218
	s_waitcnt lgkmcnt(2)
	v_mfma_f32_32x32x16_bf16 v[112:127], v[136:139], v[128:131], v[112:127]
	ds_read_b64_tr_b16 v[136:137], v203 offset:16384
	ds_read_b64_tr_b16 v[138:139], v203 offset:20480
	ds_read_b64_tr_b16 v[206:207], v203 offset:20736
	ds_read_b64_tr_b16 v[204:205], v203 offset:16640
	v_add_f32_e32 v202, v202, v216
	s_waitcnt lgkmcnt(2)
	v_mfma_f32_32x32x16_bf16 v[96:111], v[136:139], v[128:131], v[96:111]
	ds_read_b64_tr_b16 v[136:137], v217 offset:16384
	ds_read_b64_tr_b16 v[138:139], v217 offset:20480
	ds_read_b64_tr_b16 v[210:211], v217 offset:20736
	ds_read_b64_tr_b16 v[208:209], v217 offset:16640
	s_waitcnt lgkmcnt(2)
	v_mfma_f32_32x32x16_bf16 v[80:95], v[136:139], v[128:131], v[80:95]
	ds_read_b64_tr_b16 v[136:137], v218 offset:16384
	ds_read_b64_tr_b16 v[138:139], v218 offset:20480
	ds_read_b64_tr_b16 v[214:215], v218 offset:20736
	ds_read_b64_tr_b16 v[212:213], v218 offset:16640
	s_waitcnt lgkmcnt(2)
	v_mfma_f32_32x32x16_bf16 v[64:79], v[136:139], v[128:131], v[64:79]
	v_mfma_f32_32x32x16_bf16 v[48:63], v[140:143], v[128:131], v[48:63]
	v_mfma_f32_32x32x16_bf16 v[32:47], v[204:207], v[128:131], v[32:47]
	v_mfma_f32_32x32x16_bf16 v[16:31], v[208:211], v[128:131], v[16:31]
	s_waitcnt lgkmcnt(0)
	v_mfma_f32_32x32x16_bf16 v[0:15], v[212:215], v[128:131], v[0:15]
	ds_read_b64_tr_b16 v[128:129], v219 offset:24576
	ds_read_b64_tr_b16 v[130:131], v219 offset:28672
	ds_read_b64_tr_b16 v[138:139], v219 offset:28928
	ds_read_b64_tr_b16 v[136:137], v219 offset:24832
	s_waitcnt lgkmcnt(2)
	v_mfma_f32_32x32x16_bf16 v[112:127], v[128:131], v[132:135], v[112:127]
	ds_read_b64_tr_b16 v[128:129], v203 offset:24576
	ds_read_b64_tr_b16 v[130:131], v203 offset:28672
	ds_read_b64_tr_b16 v[142:143], v203 offset:28928
	ds_read_b64_tr_b16 v[140:141], v203 offset:24832
	s_waitcnt lgkmcnt(2)
	v_mfma_f32_32x32x16_bf16 v[96:111], v[128:131], v[132:135], v[96:111]
	ds_read_b64_tr_b16 v[128:129], v217 offset:24576
	ds_read_b64_tr_b16 v[130:131], v217 offset:28672
	ds_read_b64_tr_b16 v[206:207], v217 offset:28928
	ds_read_b64_tr_b16 v[204:205], v217 offset:24832
	s_waitcnt lgkmcnt(2)
	v_mfma_f32_32x32x16_bf16 v[80:95], v[128:131], v[132:135], v[80:95]
	ds_read_b64_tr_b16 v[128:129], v218 offset:24576
	ds_read_b64_tr_b16 v[130:131], v218 offset:28672
	ds_read_b64_tr_b16 v[210:211], v218 offset:28928
	ds_read_b64_tr_b16 v[208:209], v218 offset:24832
	s_waitcnt lgkmcnt(2)
	v_mfma_f32_32x32x16_bf16 v[64:79], v[128:131], v[132:135], v[64:79]
	v_mfma_f32_32x32x16_bf16 v[48:63], v[136:139], v[132:135], v[48:63]
	v_mfma_f32_32x32x16_bf16 v[32:47], v[140:143], v[132:135], v[32:47]
	v_mfma_f32_32x32x16_bf16 v[16:31], v[204:207], v[132:135], v[16:31]
	s_waitcnt lgkmcnt(0)
	v_mfma_f32_32x32x16_bf16 v[0:15], v[208:211], v[132:135], v[0:15]
.LBB0_1812:
	s_waitcnt lgkmcnt(0)
.Latt_end_4:
	s_mov_b64 s[22:23], -1
	s_and_b64 vcc, exec, s[18:19]
	s_cbranch_vccz .LBB0_1814
	s_waitcnt vmcnt(0)
	s_mov_b64 s[22:23], 0

.LBB0_1820:
	s_cmp_gt_i32 s4, s72
	s_cbranch_scc1 .LBB0_1831
	s_add_i32 s100, s4, 63
	s_cmp_le_i32 s100, s71
	s_cbranch_scc0 .Latt_slow_5
	s_cmp_eq_u32 s33, 1
	s_cbranch_scc1 .Latt_slot1_5
	s_cmp_eq_u32 s33, 2
	s_cbranch_scc1 .Latt_slot2_5
	s_cmp_lg_u32 s4, 0
	s_cbranch_scc1 .Latt_vstep_5s0
	ds_read_b128 v[206:209], v196
	ds_read_b128 v[210:213], v197
	ds_read_b128 v[214:217], v198
	ds_read_b128 v[238:241], v199
	ds_read_b128 v[242:245], v200
	ds_read_b128 v[250:253], v201
	ds_read_b128 v[222:225], v202
	ds_read_b128 v[226:229], v203
	v_bfe_u32 v246, v204, 2, 2
	v_bfe_u32 v247, v204, 5, 1
	v_lshl_or_b32 v247, v247, 2, v246
	v_and_b32_e32 v249, 3, v204
	v_and_b32_e32 v254, 16, v204
	v_lshl_or_b32 v249, v249, 2, v254
	v_lshlrev_b32_e32 v249, 1, v249
	v_lshl_add_u32 v247, v247, 9, v249
	v_add_u32_e32 v247, 0xc000, v247
	v_lshlrev_b32_e32 v246, 6, v246
	v_add_u32_e32 v205, v247, v246
	v_xor_b32_e32 v249, 64, v246
	v_add_u32_e32 v218, v247, v249
	v_xor_b32_e32 v249, 0x80, v246
	v_add_u32_e32 v219, v247, v249
	v_xor_b32_e32 v249, 0xc0, v246
	v_add_u32_e32 v221, v247, v249
	s_branch .Latt_vdone_5s0

.Latt_vdone_5s0:
	s_waitcnt lgkmcnt(7)
	v_mfma_f32_32x32x16_bf16 v[128:143], v[206:209], v[144:147], 0
	ds_read_b128 v[206:209], v196 offset:8192
	s_cmp_lg_u64 s[18:19], 0
	s_cbranch_scc1 .Latt_nd0_5s0
	s_sub_i32 s100, s33, 1
	s_cmp_eq_u32 s33, 0
	s_cselect_b32 s100, 2, s100
	s_lshl_b32 s101, s100, 14
	s_add_i32 m0, s73, s101
	s_nop 0
	global_load_lds_dwordx4 v178, s[12:13]

.Latt_nd1_5s0:
	s_waitcnt lgkmcnt(7)
	v_mfma_f32_32x32x16_bf16 v[128:143], v[214:217], v[152:155], v[128:143]
	ds_read_b128 v[214:217], v198 offset:8192
	s_cmp_lg_u64 s[18:19], 0
	s_cbranch_scc1 .Latt_nd2_5s0
	s_lshl_b32 s101, s100, 15
	s_add_i32 m0, s74, s101
	s_add_u32 s100, s12, 0xf00
	s_addc_u32 s101, s13, 0
	global_load_lds_dwordx4 v182, s[100:101]

.Latt_slow_5s0:
.Latt_slot1_5:
	v_add_u32_e32 v205, 0x8000, v205
	v_add_u32_e32 v218, 0x8000, v218
	v_add_u32_e32 v219, 0x8000, v219
	v_add_u32_e32 v221, 0x8000, v221
	s_waitcnt lgkmcnt(7)
	v_mfma_f32_32x32x16_bf16 v[128:143], v[206:209], v[144:147], 0
	ds_read_b128 v[206:209], v196 offset:24576
	s_cmp_lg_u64 s[18:19], 0
	s_cbranch_scc1 .Latt_nd0_5s1
	s_sub_i32 s100, s33, 1
	s_cmp_eq_u32 s33, 0
	s_cselect_b32 s100, 2, s100
	s_lshl_b32 s101, s100, 14
	s_add_i32 m0, s73, s101
	s_nop 0
	global_load_lds_dwordx4 v178, s[12:13]

.Latt_nd1_5s1:
	s_waitcnt lgkmcnt(7)
	v_mfma_f32_32x32x16_bf16 v[128:143], v[214:217], v[152:155], v[128:143]
	ds_read_b128 v[214:217], v198 offset:24576
	s_cmp_lg_u64 s[18:19], 0
	s_cbranch_scc1 .Latt_nd2_5s1
	s_lshl_b32 s101, s100, 15
	s_add_i32 m0, s74, s101
	s_add_u32 s100, s12, 0xf00
	s_addc_u32 s101, s13, 0
	global_load_lds_dwordx4 v182, s[100:101]

.Latt_slow_5s1:
.Latt_slot2_5:
	v_add_u32_e32 v205, 0x8000, v205
	v_add_u32_e32 v218, 0x8000, v218
	v_add_u32_e32 v219, 0x8000, v219
	v_add_u32_e32 v221, 0x8000, v221
	s_waitcnt lgkmcnt(7)
	v_mfma_f32_32x32x16_bf16 v[128:143], v[206:209], v[144:147], 0
	ds_read_b128 v[206:209], v196 offset:40960
	s_cmp_lg_u64 s[18:19], 0
	s_cbranch_scc1 .Latt_nd0_5s2
	s_sub_i32 s100, s33, 1
	s_cmp_eq_u32 s33, 0
	s_cselect_b32 s100, 2, s100
	s_lshl_b32 s101, s100, 14
	s_add_i32 m0, s73, s101
	s_nop 0
	global_load_lds_dwordx4 v178, s[12:13]

.Latt_nd1_5s2:
	s_waitcnt lgkmcnt(7)
	v_mfma_f32_32x32x16_bf16 v[128:143], v[214:217], v[152:155], v[128:143]
	ds_read_b128 v[214:217], v198 offset:40960
	s_cmp_lg_u64 s[18:19], 0
	s_cbranch_scc1 .Latt_nd2_5s2
	s_lshl_b32 s101, s100, 15
	s_add_i32 m0, s74, s101
	s_add_u32 s100, s12, 0xf00
	s_addc_u32 s101, s13, 0
	global_load_lds_dwordx4 v182, s[100:101]

.Latt_slow_5s2:
.Latt_slow_5:
	s_waitcnt lgkmcnt(0)
	s_lshl_b32 s77, s33, 14
	s_add_i32 s78, s77, 0
	v_add_u32_e32 v207, s78, v196
	ds_read_b128 v[128:131], v207
	v_add_u32_e32 v208, s78, v197
	ds_read_b128 v[210:213], v208
	v_add_u32_e32 v209, s78, v198
	v_lshrrev_b32_e32 v205, 3, v204
	s_add_i32 s79, s4, 31
	v_and_or_b32 v206, v204, 31, s71
	s_cmp_le_i32 s79, s71
	s_waitcnt lgkmcnt(1)
	v_mfma_f32_32x32x16_bf16 v[128:143], v[128:131], v[144:147], 0
	s_waitcnt lgkmcnt(0)
	v_mfma_f32_32x32x16_bf16 v[128:143], v[210:213], v[148:151], v[128:143]
	ds_read_b128 v[212:215], v209
	v_add_u32_e32 v210, s78, v199
	ds_read_b128 v[216:219], v210
	v_add_u32_e32 v211, s78, v200
	s_waitcnt lgkmcnt(1)
	v_mfma_f32_32x32x16_bf16 v[128:143], v[212:215], v[152:155], v[128:143]
	v_add_u32_e32 v213, s78, v201
	v_and_b32_e32 v212, 4, v205
	ds_read_b128 v[222:225], v213
	s_waitcnt lgkmcnt(1)
	v_mfma_f32_32x32x16_bf16 v[128:143], v[216:219], v[156:159], v[128:143]
	ds_read_b128 v[214:217], v211
	s_waitcnt lgkmcnt(0)
	v_mfma_f32_32x32x16_bf16 v[128:143], v[214:217], v[160:163], v[128:143]
	v_add_u32_e32 v214, s78, v202
	ds_read_b128 v[216:219], v214
	v_add_u32_e32 v215, s78, v203
	v_mfma_f32_32x32x16_bf16 v[128:143], v[222:225], v[164:167], v[128:143]
	ds_read_b128 v[222:225], v215
	s_waitcnt lgkmcnt(1)
	v_mfma_f32_32x32x16_bf16 v[128:143], v[216:219], v[168:171], v[128:143]
	s_waitcnt lgkmcnt(0)
	v_mfma_f32_32x32x16_bf16 v[128:143], v[222:225], v[172:175], v[128:143]
	s_cbranch_scc1 .LBB0_1823
	v_add_u32_e32 v205, s4, v212
	v_cmp_lt_i32_e32 vcc, v205, v206
	v_add_u32_e32 v216, 2, v205
	s_nop 7
	v_cndmask_b32_e32 v129, v192, v129, vcc
	v_cmp_le_i32_e32 vcc, v205, v206
	s_nop 1
	v_cndmask_b32_e32 v128, v192, v128, vcc
	v_cmp_le_i32_e32 vcc, v216, v206
	v_add_u32_e32 v216, 3, v205
	s_nop 0
	v_cndmask_b32_e32 v130, v192, v130, vcc
	v_cmp_le_i32_e32 vcc, v216, v206
	v_add_u32_e32 v216, 8, v205
	s_nop 0
	v_cndmask_b32_e32 v131, v192, v131, vcc
	v_cmp_le_i32_e32 vcc, v216, v206
	v_add_u32_e32 v216, 9, v205
	s_nop 0
	v_cndmask_b32_e32 v132, v192, v132, vcc
	v_cmp_le_i32_e32 vcc, v216, v206
	v_add_u32_e32 v216, 10, v205
	s_nop 0
	v_cndmask_b32_e32 v133, v192, v133, vcc
	v_cmp_le_i32_e32 vcc, v216, v206
	v_add_u32_e32 v216, 11, v205
	s_nop 0
	v_cndmask_b32_e32 v134, v192, v134, vcc
	v_cmp_le_i32_e32 vcc, v216, v206
	v_add_u32_e32 v216, 16, v205
	s_nop 0
	v_cndmask_b32_e32 v135, v192, v135, vcc
	v_cmp_le_i32_e32 vcc, v216, v206
	v_add_u32_e32 v216, 17, v205
	s_nop 0
	v_cndmask_b32_e32 v136, v192, v136, vcc
	v_cmp_le_i32_e32 vcc, v216, v206
	v_add_u32_e32 v216, 18, v205
	s_nop 0
	v_cndmask_b32_e32 v137, v192, v137, vcc
	v_cmp_le_i32_e32 vcc, v216, v206
	v_add_u32_e32 v216, 19, v205
	s_nop 0
	v_cndmask_b32_e32 v138, v192, v138, vcc
	v_cmp_le_i32_e32 vcc, v216, v206
	v_add_u32_e32 v216, 24, v205
	s_nop 0
	v_cndmask_b32_e32 v139, v192, v139, vcc
	v_cmp_le_i32_e32 vcc, v216, v206
	v_add_u32_e32 v216, 25, v205
	s_nop 0
	v_cndmask_b32_e32 v140, v192, v140, vcc
	v_cmp_le_i32_e32 vcc, v216, v206
	v_add_u32_e32 v216, 26, v205
	v_add_u32_e32 v205, 27, v205
	v_cndmask_b32_e32 v141, v192, v141, vcc
	v_cmp_le_i32_e32 vcc, v216, v206
	s_nop 1
	v_cndmask_b32_e32 v142, v192, v142, vcc
	v_cmp_le_i32_e32 vcc, v205, v206
	s_nop 1
	v_cndmask_b32_e32 v143, v192, v143, vcc

.LBB0_1830:
	v_sub_f32_e32 v128, v128, v190
	v_exp_f32_e32 v128, v128
	v_sub_f32_e32 v129, v129, v190
	v_exp_f32_e32 v129, v129
	v_sub_f32_e32 v130, v130, v190
	v_exp_f32_e32 v130, v130
	v_sub_f32_e32 v131, v131, v190
	v_exp_f32_e32 v131, v131
	v_sub_f32_e32 v132, v132, v190
	v_add_f32_e32 v206, 0, v128
	v_exp_f32_e32 v132, v132
	v_sub_f32_e32 v133, v133, v190
	v_add_f32_e32 v206, v129, v206
	v_exp_f32_e32 v133, v133
	v_sub_f32_e32 v134, v134, v190
	v_add_f32_e32 v206, v130, v206
	v_exp_f32_e32 v134, v134
	v_sub_f32_e32 v135, v135, v190
	v_add_f32_e32 v206, v131, v206
	v_exp_f32_e32 v135, v135
	v_sub_f32_e32 v136, v136, v190
	v_add_f32_e32 v206, v132, v206
	v_exp_f32_e32 v136, v136
	v_sub_f32_e32 v137, v137, v190
	v_add_f32_e32 v206, v133, v206
	v_exp_f32_e32 v137, v137
	v_sub_f32_e32 v138, v138, v190
	v_add_f32_e32 v206, v134, v206
	v_exp_f32_e32 v138, v138
	v_sub_f32_e32 v139, v139, v190
	v_add_f32_e32 v206, v135, v206
	v_exp_f32_e32 v139, v139
	v_sub_f32_e32 v140, v140, v190
	v_add_f32_e32 v206, v136, v206
	v_exp_f32_e32 v140, v140
	v_sub_f32_e32 v141, v141, v190
	v_add_f32_e32 v206, v137, v206
	v_exp_f32_e32 v141, v141
	v_sub_f32_e32 v142, v142, v190
	v_add_f32_e32 v206, v138, v206
	v_exp_f32_e32 v142, v142
	v_sub_f32_e32 v143, v143, v190
	v_add_f32_e32 v206, v139, v206
	v_exp_f32_e32 v143, v143
	v_add_f32_e32 v206, v140, v206
	v_add_f32_e32 v206, v141, v206
	v_add_f32_e32 v206, v142, v206
	v_add_u32_e32 v208, 0xc000, v216
	v_add_f32_e32 v216, v143, v206
	v_cvt_pk_bf16_f32 v128, v128, v129
	v_cvt_pk_bf16_f32 v129, v130, v131
	v_cvt_pk_bf16_f32 v130, v132, v133
	v_cvt_pk_bf16_f32 v131, v134, v135
	v_cvt_pk_bf16_f32 v132, v136, v137
	v_cvt_pk_bf16_f32 v133, v138, v139
	v_cvt_pk_bf16_f32 v134, v140, v141
	v_cvt_pk_bf16_f32 v135, v142, v143
	v_add_u32_e32 v219, v208, v205
	ds_read_b64_tr_b16 v[136:137], v219 offset:16384
	ds_read_b64_tr_b16 v[138:139], v219 offset:20480
	v_add_u32_e32 v221, v208, v204
	ds_read_b64_tr_b16 v[142:143], v219 offset:20736
	ds_read_b64_tr_b16 v[140:141], v219 offset:16640
	v_add_u32_e32 v217, v208, v217
	v_add_u32_e32 v218, v208, v218
	s_waitcnt lgkmcnt(2)
	v_mfma_f32_32x32x16_bf16 v[112:127], v[136:139], v[128:131], v[112:127]
	ds_read_b64_tr_b16 v[136:137], v221 offset:16384
	ds_read_b64_tr_b16 v[138:139], v221 offset:20480
	ds_read_b64_tr_b16 v[206:207], v221 offset:20736
	ds_read_b64_tr_b16 v[204:205], v221 offset:16640
	v_add_f32_e32 v195, v195, v216
	s_waitcnt lgkmcnt(2)
	v_mfma_f32_32x32x16_bf16 v[96:111], v[136:139], v[128:131], v[96:111]
	ds_read_b64_tr_b16 v[136:137], v217 offset:16384
	ds_read_b64_tr_b16 v[138:139], v217 offset:20480
	ds_read_b64_tr_b16 v[210:211], v217 offset:20736
	ds_read_b64_tr_b16 v[208:209], v217 offset:16640
	s_waitcnt lgkmcnt(2)
	v_mfma_f32_32x32x16_bf16 v[80:95], v[136:139], v[128:131], v[80:95]
	ds_read_b64_tr_b16 v[136:137], v218 offset:16384
	ds_read_b64_tr_b16 v[138:139], v218 offset:20480
	ds_read_b64_tr_b16 v[214:215], v218 offset:20736
	ds_read_b64_tr_b16 v[212:213], v218 offset:16640
	s_waitcnt lgkmcnt(2)
	v_mfma_f32_32x32x16_bf16 v[64:79], v[136:139], v[128:131], v[64:79]
	v_mfma_f32_32x32x16_bf16 v[48:63], v[140:143], v[128:131], v[48:63]
	v_mfma_f32_32x32x16_bf16 v[32:47], v[204:207], v[128:131], v[32:47]
	v_mfma_f32_32x32x16_bf16 v[16:31], v[208:211], v[128:131], v[16:31]
	s_waitcnt lgkmcnt(0)
	v_mfma_f32_32x32x16_bf16 v[0:15], v[212:215], v[128:131], v[0:15]
	ds_read_b64_tr_b16 v[128:129], v219 offset:24576
	ds_read_b64_tr_b16 v[130:131], v219 offset:28672
	ds_read_b64_tr_b16 v[138:139], v219 offset:28928
	ds_read_b64_tr_b16 v[136:137], v219 offset:24832
	s_waitcnt lgkmcnt(2)
	v_mfma_f32_32x32x16_bf16 v[112:127], v[128:131], v[132:135], v[112:127]
	ds_read_b64_tr_b16 v[128:129], v221 offset:24576
	ds_read_b64_tr_b16 v[130:131], v221 offset:28672
	ds_read_b64_tr_b16 v[142:143], v221 offset:28928
	ds_read_b64_tr_b16 v[140:141], v221 offset:24832
	s_waitcnt lgkmcnt(2)
	v_mfma_f32_32x32x16_bf16 v[96:111], v[128:131], v[132:135], v[96:111]
	ds_read_b64_tr_b16 v[128:129], v217 offset:24576
	ds_read_b64_tr_b16 v[130:131], v217 offset:28672
	ds_read_b64_tr_b16 v[206:207], v217 offset:28928
	ds_read_b64_tr_b16 v[204:205], v217 offset:24832
	s_waitcnt lgkmcnt(2)
	v_mfma_f32_32x32x16_bf16 v[80:95], v[128:131], v[132:135], v[80:95]
	ds_read_b64_tr_b16 v[128:129], v218 offset:24576
	ds_read_b64_tr_b16 v[130:131], v218 offset:28672
	ds_read_b64_tr_b16 v[210:211], v218 offset:28928
	ds_read_b64_tr_b16 v[208:209], v218 offset:24832
	s_waitcnt lgkmcnt(2)
	v_mfma_f32_32x32x16_bf16 v[64:79], v[128:131], v[132:135], v[64:79]
	v_mfma_f32_32x32x16_bf16 v[48:63], v[136:139], v[132:135], v[48:63]
	v_mfma_f32_32x32x16_bf16 v[32:47], v[140:143], v[132:135], v[32:47]
	v_mfma_f32_32x32x16_bf16 v[16:31], v[204:207], v[132:135], v[16:31]
	s_waitcnt lgkmcnt(0)
	v_mfma_f32_32x32x16_bf16 v[0:15], v[208:211], v[132:135], v[0:15]
.LBB0_1831:
	s_waitcnt lgkmcnt(0)
.Latt_end_5:
	s_andn2_b64 vcc, exec, s[18:19]
	s_mov_b64 s[18:19], -1
	s_cbranch_vccnz .LBB0_1833
	s_waitcnt vmcnt(0)
	s_mov_b64 s[18:19], 0

.LBB0_1839:
	s_cmp_gt_i32 s72, s69
	s_cbranch_scc1 .LBB0_1850
	s_add_i32 s100, s72, 63
	s_cmp_le_i32 s100, s68
	s_cbranch_scc0 .Latt_slow_6
	s_cmp_eq_u32 s34, 1
	s_cbranch_scc1 .Latt_slot1_6
	s_cmp_eq_u32 s34, 2
	s_cbranch_scc1 .Latt_slot2_6
	s_cmp_lg_u32 s72, 0
	s_cbranch_scc1 .Latt_vstep_6s0
	ds_read_b128 v[206:209], v195
	ds_read_b128 v[210:213], v196
	ds_read_b128 v[214:217], v197
	ds_read_b128 v[238:241], v198
	ds_read_b128 v[242:245], v199
	ds_read_b128 v[250:253], v200
	ds_read_b128 v[222:225], v201
	ds_read_b128 v[226:229], v202
	v_bfe_u32 v246, v204, 2, 2
	v_bfe_u32 v247, v204, 5, 1
	v_lshl_or_b32 v247, v247, 2, v246
	v_and_b32_e32 v249, 3, v204
	v_and_b32_e32 v254, 16, v204
	v_lshl_or_b32 v249, v249, 2, v254
	v_lshlrev_b32_e32 v249, 1, v249
	v_lshl_add_u32 v247, v247, 9, v249
	v_add_u32_e32 v247, 0xc000, v247
	v_lshlrev_b32_e32 v246, 6, v246
	v_add_u32_e32 v205, v247, v246
	v_xor_b32_e32 v249, 64, v246
	v_add_u32_e32 v218, v247, v249
	v_xor_b32_e32 v249, 0x80, v246
	v_add_u32_e32 v219, v247, v249
	v_xor_b32_e32 v249, 0xc0, v246
	v_add_u32_e32 v221, v247, v249
	s_branch .Latt_vdone_6s0

.Latt_vdone_6s0:
	s_waitcnt lgkmcnt(7)
	v_mfma_f32_32x32x16_bf16 v[128:143], v[206:209], v[144:147], 0
	ds_read_b128 v[206:209], v195 offset:8192
	s_cmp_lg_u64 s[12:13], 0
	s_cbranch_scc1 .Latt_nd0_6s0
	s_sub_i32 s100, s34, 1
	s_cmp_eq_u32 s34, 0
	s_cselect_b32 s100, 2, s100
	s_lshl_b32 s101, s100, 14
	s_add_i32 m0, s36, s101
	s_nop 0
	global_load_lds_dwordx4 v178, s[20:21]
.Latt_nd0_6s0:
	s_waitcnt lgkmcnt(7)
	v_mfma_f32_32x32x16_bf16 v[128:143], v[210:213], v[148:151], v[128:143]
	ds_read_b128 v[210:213], v196 offset:8192
	s_cmp_lg_u64 s[12:13], 0
	s_cbranch_scc1 .Latt_nd1_6s0
	s_add_i32 m0, m0, 0x400
	s_nop 0
	global_load_lds_dwordx4 v180, s[20:21]
.Latt_nd1_6s0:
	s_waitcnt lgkmcnt(7)
	v_mfma_f32_32x32x16_bf16 v[128:143], v[214:217], v[152:155], v[128:143]
	ds_read_b128 v[214:217], v197 offset:8192
	s_cmp_lg_u64 s[12:13], 0
	s_cbranch_scc1 .Latt_nd2_6s0
	s_lshl_b32 s101, s100, 15
	s_add_i32 m0, s37, s101
	s_add_u32 s100, s20, 0x1000
	s_addc_u32 s101, s21, 0
	global_load_lds_dwordx4 v182, s[100:101]

.Latt_slow_6s0:
.Latt_slot1_6:
	v_add_u32_e32 v205, 0x8000, v205
	v_add_u32_e32 v218, 0x8000, v218
	v_add_u32_e32 v219, 0x8000, v219
	v_add_u32_e32 v221, 0x8000, v221
	s_waitcnt lgkmcnt(7)
	v_mfma_f32_32x32x16_bf16 v[128:143], v[206:209], v[144:147], 0
	ds_read_b128 v[206:209], v195 offset:24576
	s_cmp_lg_u64 s[12:13], 0
	s_cbranch_scc1 .Latt_nd0_6s1
	s_sub_i32 s100, s34, 1
	s_cmp_eq_u32 s34, 0
	s_cselect_b32 s100, 2, s100
	s_lshl_b32 s101, s100, 14
	s_add_i32 m0, s36, s101
	s_nop 0
	global_load_lds_dwordx4 v178, s[20:21]
.Latt_nd0_6s1:
	s_waitcnt lgkmcnt(7)
	v_mfma_f32_32x32x16_bf16 v[128:143], v[210:213], v[148:151], v[128:143]
	ds_read_b128 v[210:213], v196 offset:24576
	s_cmp_lg_u64 s[12:13], 0
	s_cbranch_scc1 .Latt_nd1_6s1
	s_add_i32 m0, m0, 0x400
	s_nop 0
	global_load_lds_dwordx4 v180, s[20:21]
.Latt_nd1_6s1:
	s_waitcnt lgkmcnt(7)
	v_mfma_f32_32x32x16_bf16 v[128:143], v[214:217], v[152:155], v[128:143]
	ds_read_b128 v[214:217], v197 offset:24576
	s_cmp_lg_u64 s[12:13], 0
	s_cbranch_scc1 .Latt_nd2_6s1
	s_lshl_b32 s101, s100, 15
	s_add_i32 m0, s37, s101
	s_add_u32 s100, s20, 0x1000
	s_addc_u32 s101, s21, 0
	global_load_lds_dwordx4 v182, s[100:101]

.Latt_slow_6s1:
.Latt_slot2_6:
	v_add_u32_e32 v205, 0x8000, v205
	v_add_u32_e32 v218, 0x8000, v218
	v_add_u32_e32 v219, 0x8000, v219
	v_add_u32_e32 v221, 0x8000, v221
	s_waitcnt lgkmcnt(7)
	v_mfma_f32_32x32x16_bf16 v[128:143], v[206:209], v[144:147], 0
	ds_read_b128 v[206:209], v195 offset:40960
	s_cmp_lg_u64 s[12:13], 0
	s_cbranch_scc1 .Latt_nd0_6s2
	s_sub_i32 s100, s34, 1
	s_cmp_eq_u32 s34, 0
	s_cselect_b32 s100, 2, s100
	s_lshl_b32 s101, s100, 14
	s_add_i32 m0, s36, s101
	s_nop 0
	global_load_lds_dwordx4 v178, s[20:21]
.Latt_nd0_6s2:
	s_waitcnt lgkmcnt(7)
	v_mfma_f32_32x32x16_bf16 v[128:143], v[210:213], v[148:151], v[128:143]
	ds_read_b128 v[210:213], v196 offset:40960
	s_cmp_lg_u64 s[12:13], 0
	s_cbranch_scc1 .Latt_nd1_6s2
	s_add_i32 m0, m0, 0x400
	s_nop 0
	global_load_lds_dwordx4 v180, s[20:21]
.Latt_nd1_6s2:
	s_waitcnt lgkmcnt(7)
	v_mfma_f32_32x32x16_bf16 v[128:143], v[214:217], v[152:155], v[128:143]
	ds_read_b128 v[214:217], v197 offset:40960
	s_cmp_lg_u64 s[12:13], 0
	s_cbranch_scc1 .Latt_nd2_6s2
	s_lshl_b32 s101, s100, 15
	s_add_i32 m0, s37, s101
	s_add_u32 s100, s20, 0x1000
	s_addc_u32 s101, s21, 0
	global_load_lds_dwordx4 v182, s[100:101]

.Latt_slow_6s2:
.Latt_slow_6:
	s_waitcnt lgkmcnt(0)
	s_lshl_b32 s14, s34, 14
	s_add_i32 s15, s14, 0
	v_add_u32_e32 v207, s15, v195
	ds_read_b128 v[128:131], v207
	v_add_u32_e32 v208, s15, v196
	ds_read_b128 v[210:213], v208
	v_add_u32_e32 v209, s15, v197
	v_lshrrev_b32_e32 v205, 3, v204
	s_add_i32 s35, s72, 31
	v_and_or_b32 v206, v204, 31, s68
	s_cmp_le_i32 s35, s68
	s_waitcnt lgkmcnt(1)
	v_mfma_f32_32x32x16_bf16 v[128:143], v[128:131], v[144:147], 0
	s_waitcnt lgkmcnt(0)
	v_mfma_f32_32x32x16_bf16 v[128:143], v[210:213], v[148:151], v[128:143]
	ds_read_b128 v[212:215], v209
	v_add_u32_e32 v210, s15, v198
	ds_read_b128 v[216:219], v210
	v_add_u32_e32 v211, s15, v199
	s_waitcnt lgkmcnt(1)
	v_mfma_f32_32x32x16_bf16 v[128:143], v[212:215], v[152:155], v[128:143]
	v_add_u32_e32 v213, s15, v200
	v_and_b32_e32 v212, 4, v205
	ds_read_b128 v[222:225], v213
	s_waitcnt lgkmcnt(1)
	v_mfma_f32_32x32x16_bf16 v[128:143], v[216:219], v[156:159], v[128:143]
	ds_read_b128 v[214:217], v211
	s_waitcnt lgkmcnt(0)
	v_mfma_f32_32x32x16_bf16 v[128:143], v[214:217], v[160:163], v[128:143]
	v_add_u32_e32 v214, s15, v201
	ds_read_b128 v[216:219], v214
	v_add_u32_e32 v215, s15, v202
	v_mfma_f32_32x32x16_bf16 v[128:143], v[222:225], v[164:167], v[128:143]
	ds_read_b128 v[222:225], v215
	s_waitcnt lgkmcnt(1)
	v_mfma_f32_32x32x16_bf16 v[128:143], v[216:219], v[168:171], v[128:143]
	s_waitcnt lgkmcnt(0)
	v_mfma_f32_32x32x16_bf16 v[128:143], v[222:225], v[172:175], v[128:143]
	s_cbranch_scc1 .LBB0_1842
	v_add_u32_e32 v205, s72, v212
	v_cmp_lt_i32_e32 vcc, v205, v206
	v_add_u32_e32 v216, 2, v205
	s_nop 7
	v_cndmask_b32_e32 v129, v192, v129, vcc
	v_cmp_le_i32_e32 vcc, v205, v206
	s_nop 1
	v_cndmask_b32_e32 v128, v192, v128, vcc
	v_cmp_le_i32_e32 vcc, v216, v206
	v_add_u32_e32 v216, 3, v205
	s_nop 0
	v_cndmask_b32_e32 v130, v192, v130, vcc
	v_cmp_le_i32_e32 vcc, v216, v206
	v_add_u32_e32 v216, 8, v205
	s_nop 0
	v_cndmask_b32_e32 v131, v192, v131, vcc
	v_cmp_le_i32_e32 vcc, v216, v206
	v_add_u32_e32 v216, 9, v205
	s_nop 0
	v_cndmask_b32_e32 v132, v192, v132, vcc
	v_cmp_le_i32_e32 vcc, v216, v206
	v_add_u32_e32 v216, 10, v205
	s_nop 0
	v_cndmask_b32_e32 v133, v192, v133, vcc
	v_cmp_le_i32_e32 vcc, v216, v206
	v_add_u32_e32 v216, 11, v205
	s_nop 0
	v_cndmask_b32_e32 v134, v192, v134, vcc
	v_cmp_le_i32_e32 vcc, v216, v206
	v_add_u32_e32 v216, 16, v205
	s_nop 0
	v_cndmask_b32_e32 v135, v192, v135, vcc
	v_cmp_le_i32_e32 vcc, v216, v206
	v_add_u32_e32 v216, 17, v205
	s_nop 0
	v_cndmask_b32_e32 v136, v192, v136, vcc
	v_cmp_le_i32_e32 vcc, v216, v206
	v_add_u32_e32 v216, 18, v205
	s_nop 0
	v_cndmask_b32_e32 v137, v192, v137, vcc
	v_cmp_le_i32_e32 vcc, v216, v206
	v_add_u32_e32 v216, 19, v205
	s_nop 0
	v_cndmask_b32_e32 v138, v192, v138, vcc
	v_cmp_le_i32_e32 vcc, v216, v206
	v_add_u32_e32 v216, 24, v205
	s_nop 0
	v_cndmask_b32_e32 v139, v192, v139, vcc
	v_cmp_le_i32_e32 vcc, v216, v206
	v_add_u32_e32 v216, 25, v205
	s_nop 0
	v_cndmask_b32_e32 v140, v192, v140, vcc
	v_cmp_le_i32_e32 vcc, v216, v206
	v_add_u32_e32 v216, 26, v205
	v_add_u32_e32 v205, 27, v205
	v_cndmask_b32_e32 v141, v192, v141, vcc
	v_cmp_le_i32_e32 vcc, v216, v206
	s_nop 1
	v_cndmask_b32_e32 v142, v192, v142, vcc
	v_cmp_le_i32_e32 vcc, v205, v206
	s_nop 1
	v_cndmask_b32_e32 v143, v192, v143, vcc

.LBB0_1849:
	v_sub_f32_e32 v128, v128, v190
	v_exp_f32_e32 v128, v128
	v_sub_f32_e32 v129, v129, v190
	v_exp_f32_e32 v129, v129
	v_sub_f32_e32 v130, v130, v190
	v_exp_f32_e32 v130, v130
	v_sub_f32_e32 v131, v131, v190
	v_exp_f32_e32 v131, v131
	v_sub_f32_e32 v132, v132, v190
	v_add_f32_e32 v206, 0, v128
	v_exp_f32_e32 v132, v132
	v_sub_f32_e32 v133, v133, v190
	v_add_f32_e32 v206, v129, v206
	v_exp_f32_e32 v133, v133
	v_sub_f32_e32 v134, v134, v190
	v_add_f32_e32 v206, v130, v206
	v_exp_f32_e32 v134, v134
	v_sub_f32_e32 v135, v135, v190
	v_add_f32_e32 v206, v131, v206
	v_exp_f32_e32 v135, v135
	v_sub_f32_e32 v136, v136, v190
	v_add_f32_e32 v206, v132, v206
	v_exp_f32_e32 v136, v136
	v_sub_f32_e32 v137, v137, v190
	v_add_f32_e32 v206, v133, v206
	v_exp_f32_e32 v137, v137
	v_sub_f32_e32 v138, v138, v190
	v_add_f32_e32 v206, v134, v206
	v_exp_f32_e32 v138, v138
	v_sub_f32_e32 v139, v139, v190
	v_add_f32_e32 v206, v135, v206
	v_exp_f32_e32 v139, v139
	v_sub_f32_e32 v140, v140, v190
	v_add_f32_e32 v206, v136, v206
	v_exp_f32_e32 v140, v140
	v_sub_f32_e32 v141, v141, v190
	v_add_f32_e32 v206, v137, v206
	v_exp_f32_e32 v141, v141
	v_sub_f32_e32 v142, v142, v190
	v_add_f32_e32 v206, v138, v206
	v_exp_f32_e32 v142, v142
	v_sub_f32_e32 v143, v143, v190
	v_add_f32_e32 v206, v139, v206
	v_exp_f32_e32 v143, v143
	v_add_f32_e32 v206, v140, v206
	v_add_f32_e32 v206, v141, v206
	v_add_f32_e32 v206, v142, v206
	v_add_u32_e32 v208, 0xc000, v216
	v_add_f32_e32 v216, v143, v206
	v_cvt_pk_bf16_f32 v128, v128, v129
	v_cvt_pk_bf16_f32 v129, v130, v131
	v_cvt_pk_bf16_f32 v130, v132, v133
	v_cvt_pk_bf16_f32 v131, v134, v135
	v_cvt_pk_bf16_f32 v132, v136, v137
	v_cvt_pk_bf16_f32 v133, v138, v139
	v_cvt_pk_bf16_f32 v134, v140, v141
	v_cvt_pk_bf16_f32 v135, v142, v143
	v_add_u32_e32 v219, v208, v205
	ds_read_b64_tr_b16 v[136:137], v219 offset:16384
	ds_read_b64_tr_b16 v[138:139], v219 offset:20480
	v_add_u32_e32 v221, v208, v204
	ds_read_b64_tr_b16 v[142:143], v219 offset:20736
	ds_read_b64_tr_b16 v[140:141], v219 offset:16640
	v_add_u32_e32 v217, v208, v217
	v_add_u32_e32 v218, v208, v218
	s_waitcnt lgkmcnt(2)
	v_mfma_f32_32x32x16_bf16 v[112:127], v[136:139], v[128:131], v[112:127]
	ds_read_b64_tr_b16 v[136:137], v221 offset:16384
	ds_read_b64_tr_b16 v[138:139], v221 offset:20480
	ds_read_b64_tr_b16 v[206:207], v221 offset:20736
	ds_read_b64_tr_b16 v[204:205], v221 offset:16640
	v_add_f32_e32 v203, v203, v216
	s_waitcnt lgkmcnt(2)
	v_mfma_f32_32x32x16_bf16 v[96:111], v[136:139], v[128:131], v[96:111]
	ds_read_b64_tr_b16 v[136:137], v217 offset:16384
	ds_read_b64_tr_b16 v[138:139], v217 offset:20480
	ds_read_b64_tr_b16 v[210:211], v217 offset:20736
	ds_read_b64_tr_b16 v[208:209], v217 offset:16640
	s_waitcnt lgkmcnt(2)
	v_mfma_f32_32x32x16_bf16 v[80:95], v[136:139], v[128:131], v[80:95]
	ds_read_b64_tr_b16 v[136:137], v218 offset:16384
	ds_read_b64_tr_b16 v[138:139], v218 offset:20480
	ds_read_b64_tr_b16 v[214:215], v218 offset:20736
	ds_read_b64_tr_b16 v[212:213], v218 offset:16640
	s_waitcnt lgkmcnt(2)
	v_mfma_f32_32x32x16_bf16 v[64:79], v[136:139], v[128:131], v[64:79]
	v_mfma_f32_32x32x16_bf16 v[48:63], v[140:143], v[128:131], v[48:63]
	v_mfma_f32_32x32x16_bf16 v[32:47], v[204:207], v[128:131], v[32:47]
	v_mfma_f32_32x32x16_bf16 v[16:31], v[208:211], v[128:131], v[16:31]
	s_waitcnt lgkmcnt(0)
	v_mfma_f32_32x32x16_bf16 v[0:15], v[212:215], v[128:131], v[0:15]
	ds_read_b64_tr_b16 v[128:129], v219 offset:24576
	ds_read_b64_tr_b16 v[130:131], v219 offset:28672
	ds_read_b64_tr_b16 v[138:139], v219 offset:28928
	ds_read_b64_tr_b16 v[136:137], v219 offset:24832
	s_waitcnt lgkmcnt(2)
	v_mfma_f32_32x32x16_bf16 v[112:127], v[128:131], v[132:135], v[112:127]
	ds_read_b64_tr_b16 v[128:129], v221 offset:24576
	ds_read_b64_tr_b16 v[130:131], v221 offset:28672
	ds_read_b64_tr_b16 v[142:143], v221 offset:28928
	ds_read_b64_tr_b16 v[140:141], v221 offset:24832
	s_waitcnt lgkmcnt(2)
	v_mfma_f32_32x32x16_bf16 v[96:111], v[128:131], v[132:135], v[96:111]
	ds_read_b64_tr_b16 v[128:129], v217 offset:24576
	ds_read_b64_tr_b16 v[130:131], v217 offset:28672
	ds_read_b64_tr_b16 v[206:207], v217 offset:28928
	ds_read_b64_tr_b16 v[204:205], v217 offset:24832
	s_waitcnt lgkmcnt(2)
	v_mfma_f32_32x32x16_bf16 v[80:95], v[128:131], v[132:135], v[80:95]
	ds_read_b64_tr_b16 v[128:129], v218 offset:24576
	ds_read_b64_tr_b16 v[130:131], v218 offset:28672
	ds_read_b64_tr_b16 v[210:211], v218 offset:28928
	ds_read_b64_tr_b16 v[208:209], v218 offset:24832
	s_waitcnt lgkmcnt(2)
	v_mfma_f32_32x32x16_bf16 v[64:79], v[128:131], v[132:135], v[64:79]
	v_mfma_f32_32x32x16_bf16 v[48:63], v[136:139], v[132:135], v[48:63]
	v_mfma_f32_32x32x16_bf16 v[32:47], v[140:143], v[132:135], v[32:47]
	v_mfma_f32_32x32x16_bf16 v[16:31], v[204:207], v[132:135], v[16:31]
	s_waitcnt lgkmcnt(0)
	v_mfma_f32_32x32x16_bf16 v[0:15], v[208:211], v[132:135], v[0:15]
.LBB0_1850:
	s_waitcnt lgkmcnt(0)
.Latt_end_6:
	s_mov_b64 s[14:15], -1
	s_and_b64 vcc, exec, s[12:13]
	s_cbranch_vccz .LBB0_1852
	s_waitcnt vmcnt(0)
	s_mov_b64 s[14:15], 0

.LBB0_1858:
	s_cmp_gt_i32 s14, s69
	s_cbranch_scc1 .LBB0_1869
	s_add_i32 s100, s14, 63
	s_cmp_le_i32 s100, s68
	s_cbranch_scc0 .Latt_slow_7
	s_cmp_eq_u32 s11, 1
	s_cbranch_scc1 .Latt_slot1_7
	s_cmp_eq_u32 s11, 2
	s_cbranch_scc1 .Latt_slot2_7
	s_cmp_lg_u32 s14, 0
	s_cbranch_scc1 .Latt_vstep_7s0
	ds_read_b128 v[206:209], v196
	ds_read_b128 v[210:213], v197
	ds_read_b128 v[214:217], v198
	ds_read_b128 v[238:241], v199
	ds_read_b128 v[242:245], v200
	ds_read_b128 v[250:253], v201
	ds_read_b128 v[222:225], v202
	ds_read_b128 v[226:229], v203
	v_bfe_u32 v246, v204, 2, 2
	v_bfe_u32 v247, v204, 5, 1
	v_lshl_or_b32 v247, v247, 2, v246
	v_and_b32_e32 v249, 3, v204
	v_and_b32_e32 v254, 16, v204
	v_lshl_or_b32 v249, v249, 2, v254
	v_lshlrev_b32_e32 v249, 1, v249
	v_lshl_add_u32 v247, v247, 9, v249
	v_add_u32_e32 v247, 0xc000, v247
	v_lshlrev_b32_e32 v246, 6, v246
	v_add_u32_e32 v205, v247, v246
	v_xor_b32_e32 v249, 64, v246
	v_add_u32_e32 v218, v247, v249
	v_xor_b32_e32 v249, 0x80, v246
	v_add_u32_e32 v219, v247, v249
	v_xor_b32_e32 v249, 0xc0, v246
	v_add_u32_e32 v221, v247, v249
	s_branch .Latt_vdone_7s0

.Latt_vdone_7s0:
	s_waitcnt lgkmcnt(7)
	v_mfma_f32_32x32x16_bf16 v[128:143], v[206:209], v[144:147], 0
	ds_read_b128 v[206:209], v196 offset:8192
	s_cmp_lg_u64 s[8:9], 0
	s_cbranch_scc1 .Latt_nd0_7s0
	s_sub_i32 s100, s11, 1
	s_cmp_eq_u32 s11, 0
	s_cselect_b32 s100, 2, s100
	s_lshl_b32 s101, s100, 14
	s_add_i32 m0, s36, s101
	s_nop 0
	global_load_lds_dwordx4 v178, s[22:23]
.Latt_nd0_7s0:
	s_waitcnt lgkmcnt(7)
	v_mfma_f32_32x32x16_bf16 v[128:143], v[210:213], v[148:151], v[128:143]
	ds_read_b128 v[210:213], v197 offset:8192
	s_cmp_lg_u64 s[8:9], 0
	s_cbranch_scc1 .Latt_nd1_7s0
	s_add_i32 m0, m0, 0x400
	s_nop 0
	global_load_lds_dwordx4 v180, s[22:23]
.Latt_nd1_7s0:
	s_waitcnt lgkmcnt(7)
	v_mfma_f32_32x32x16_bf16 v[128:143], v[214:217], v[152:155], v[128:143]
	ds_read_b128 v[214:217], v198 offset:8192
	s_cmp_lg_u64 s[8:9], 0
	s_cbranch_scc1 .Latt_nd2_7s0
	s_lshl_b32 s101, s100, 15
	s_add_i32 m0, s37, s101
	s_add_u32 s100, s22, 0xf00
	s_addc_u32 s101, s23, 0
	global_load_lds_dwordx4 v182, s[100:101]

.Latt_slow_7s0:
.Latt_slot1_7:
	v_add_u32_e32 v205, 0x8000, v205
	v_add_u32_e32 v218, 0x8000, v218
	v_add_u32_e32 v219, 0x8000, v219
	v_add_u32_e32 v221, 0x8000, v221
	s_waitcnt lgkmcnt(7)
	v_mfma_f32_32x32x16_bf16 v[128:143], v[206:209], v[144:147], 0
	ds_read_b128 v[206:209], v196 offset:24576
	s_cmp_lg_u64 s[8:9], 0
	s_cbranch_scc1 .Latt_nd0_7s1
	s_sub_i32 s100, s11, 1
	s_cmp_eq_u32 s11, 0
	s_cselect_b32 s100, 2, s100
	s_lshl_b32 s101, s100, 14
	s_add_i32 m0, s36, s101
	s_nop 0
	global_load_lds_dwordx4 v178, s[22:23]
.Latt_nd0_7s1:
	s_waitcnt lgkmcnt(7)
	v_mfma_f32_32x32x16_bf16 v[128:143], v[210:213], v[148:151], v[128:143]
	ds_read_b128 v[210:213], v197 offset:24576
	s_cmp_lg_u64 s[8:9], 0
	s_cbranch_scc1 .Latt_nd1_7s1
	s_add_i32 m0, m0, 0x400
	s_nop 0
	global_load_lds_dwordx4 v180, s[22:23]
.Latt_nd1_7s1:
	s_waitcnt lgkmcnt(7)
	v_mfma_f32_32x32x16_bf16 v[128:143], v[214:217], v[152:155], v[128:143]
	ds_read_b128 v[214:217], v198 offset:24576
	s_cmp_lg_u64 s[8:9], 0
	s_cbranch_scc1 .Latt_nd2_7s1
	s_lshl_b32 s101, s100, 15
	s_add_i32 m0, s37, s101
	s_add_u32 s100, s22, 0xf00
	s_addc_u32 s101, s23, 0
	global_load_lds_dwordx4 v182, s[100:101]

.Latt_slow_7s1:
.Latt_slot2_7:
	v_add_u32_e32 v205, 0x8000, v205
	v_add_u32_e32 v218, 0x8000, v218
	v_add_u32_e32 v219, 0x8000, v219
	v_add_u32_e32 v221, 0x8000, v221
	s_waitcnt lgkmcnt(7)
	v_mfma_f32_32x32x16_bf16 v[128:143], v[206:209], v[144:147], 0
	ds_read_b128 v[206:209], v196 offset:40960
	s_cmp_lg_u64 s[8:9], 0
	s_cbranch_scc1 .Latt_nd0_7s2
	s_sub_i32 s100, s11, 1
	s_cmp_eq_u32 s11, 0
	s_cselect_b32 s100, 2, s100
	s_lshl_b32 s101, s100, 14
	s_add_i32 m0, s36, s101
	s_nop 0
	global_load_lds_dwordx4 v178, s[22:23]
.Latt_nd0_7s2:
	s_waitcnt lgkmcnt(7)
	v_mfma_f32_32x32x16_bf16 v[128:143], v[210:213], v[148:151], v[128:143]
	ds_read_b128 v[210:213], v197 offset:40960
	s_cmp_lg_u64 s[8:9], 0
	s_cbranch_scc1 .Latt_nd1_7s2
	s_add_i32 m0, m0, 0x400
	s_nop 0
	global_load_lds_dwordx4 v180, s[22:23]
.Latt_nd1_7s2:
	s_waitcnt lgkmcnt(7)
	v_mfma_f32_32x32x16_bf16 v[128:143], v[214:217], v[152:155], v[128:143]
	ds_read_b128 v[214:217], v198 offset:40960
	s_cmp_lg_u64 s[8:9], 0
	s_cbranch_scc1 .Latt_nd2_7s2
	s_lshl_b32 s101, s100, 15
	s_add_i32 m0, s37, s101
	s_add_u32 s100, s22, 0xf00
	s_addc_u32 s101, s23, 0
	global_load_lds_dwordx4 v182, s[100:101]

.Latt_slow_7s2:
.Latt_slow_7:
	s_waitcnt lgkmcnt(0)
	s_lshl_b32 s15, s11, 14
	s_add_i32 s16, s15, 0
	v_add_u32_e32 v207, s16, v196
	ds_read_b128 v[128:131], v207
	v_add_u32_e32 v208, s16, v197
	ds_read_b128 v[210:213], v208
	v_add_u32_e32 v209, s16, v198
	v_lshrrev_b32_e32 v205, 3, v204
	s_add_i32 s17, s14, 31
	v_and_or_b32 v206, v204, 31, s68
	s_cmp_le_i32 s17, s68
	s_waitcnt lgkmcnt(1)
	v_mfma_f32_32x32x16_bf16 v[128:143], v[128:131], v[144:147], 0
	s_waitcnt lgkmcnt(0)
	v_mfma_f32_32x32x16_bf16 v[128:143], v[210:213], v[148:151], v[128:143]
	ds_read_b128 v[212:215], v209
	v_add_u32_e32 v210, s16, v199
	ds_read_b128 v[216:219], v210
	v_add_u32_e32 v211, s16, v200
	s_waitcnt lgkmcnt(1)
	v_mfma_f32_32x32x16_bf16 v[128:143], v[212:215], v[152:155], v[128:143]
	v_add_u32_e32 v213, s16, v201
	v_and_b32_e32 v212, 4, v205
	ds_read_b128 v[222:225], v213
	s_waitcnt lgkmcnt(1)
	v_mfma_f32_32x32x16_bf16 v[128:143], v[216:219], v[156:159], v[128:143]
	ds_read_b128 v[214:217], v211
	s_waitcnt lgkmcnt(0)
	v_mfma_f32_32x32x16_bf16 v[128:143], v[214:217], v[160:163], v[128:143]
	v_add_u32_e32 v214, s16, v202
	ds_read_b128 v[216:219], v214
	v_add_u32_e32 v215, s16, v203
	v_mfma_f32_32x32x16_bf16 v[128:143], v[222:225], v[164:167], v[128:143]
	ds_read_b128 v[222:225], v215
	s_waitcnt lgkmcnt(1)
	v_mfma_f32_32x32x16_bf16 v[128:143], v[216:219], v[168:171], v[128:143]
	s_waitcnt lgkmcnt(0)
	v_mfma_f32_32x32x16_bf16 v[128:143], v[222:225], v[172:175], v[128:143]
	s_cbranch_scc1 .LBB0_1861
	v_add_u32_e32 v205, s14, v212
	v_cmp_lt_i32_e32 vcc, v205, v206
	v_add_u32_e32 v216, 2, v205
	s_nop 7
	v_cndmask_b32_e32 v129, v192, v129, vcc
	v_cmp_le_i32_e32 vcc, v205, v206
	s_nop 1
	v_cndmask_b32_e32 v128, v192, v128, vcc
	v_cmp_le_i32_e32 vcc, v216, v206
	v_add_u32_e32 v216, 3, v205
	s_nop 0
	v_cndmask_b32_e32 v130, v192, v130, vcc
	v_cmp_le_i32_e32 vcc, v216, v206
	v_add_u32_e32 v216, 8, v205
	s_nop 0
	v_cndmask_b32_e32 v131, v192, v131, vcc
	v_cmp_le_i32_e32 vcc, v216, v206
	v_add_u32_e32 v216, 9, v205
	s_nop 0
	v_cndmask_b32_e32 v132, v192, v132, vcc
	v_cmp_le_i32_e32 vcc, v216, v206
	v_add_u32_e32 v216, 10, v205
	s_nop 0
	v_cndmask_b32_e32 v133, v192, v133, vcc
	v_cmp_le_i32_e32 vcc, v216, v206
	v_add_u32_e32 v216, 11, v205
	s_nop 0
	v_cndmask_b32_e32 v134, v192, v134, vcc
	v_cmp_le_i32_e32 vcc, v216, v206
	v_add_u32_e32 v216, 16, v205
	s_nop 0
	v_cndmask_b32_e32 v135, v192, v135, vcc
	v_cmp_le_i32_e32 vcc, v216, v206
	v_add_u32_e32 v216, 17, v205
	s_nop 0
	v_cndmask_b32_e32 v136, v192, v136, vcc
	v_cmp_le_i32_e32 vcc, v216, v206
	v_add_u32_e32 v216, 18, v205
	s_nop 0
	v_cndmask_b32_e32 v137, v192, v137, vcc
	v_cmp_le_i32_e32 vcc, v216, v206
	v_add_u32_e32 v216, 19, v205
	s_nop 0
	v_cndmask_b32_e32 v138, v192, v138, vcc
	v_cmp_le_i32_e32 vcc, v216, v206
	v_add_u32_e32 v216, 24, v205
	s_nop 0
	v_cndmask_b32_e32 v139, v192, v139, vcc
	v_cmp_le_i32_e32 vcc, v216, v206
	v_add_u32_e32 v216, 25, v205
	s_nop 0
	v_cndmask_b32_e32 v140, v192, v140, vcc
	v_cmp_le_i32_e32 vcc, v216, v206
	v_add_u32_e32 v216, 26, v205
	v_add_u32_e32 v205, 27, v205
	v_cndmask_b32_e32 v141, v192, v141, vcc
	v_cmp_le_i32_e32 vcc, v216, v206
	s_nop 1
	v_cndmask_b32_e32 v142, v192, v142, vcc
	v_cmp_le_i32_e32 vcc, v205, v206
	s_nop 1
	v_cndmask_b32_e32 v143, v192, v143, vcc

.LBB0_1868:
	v_sub_f32_e32 v128, v128, v190
	v_exp_f32_e32 v128, v128
	v_sub_f32_e32 v129, v129, v190
	v_exp_f32_e32 v129, v129
	v_sub_f32_e32 v130, v130, v190
	v_exp_f32_e32 v130, v130
	v_sub_f32_e32 v131, v131, v190
	v_exp_f32_e32 v131, v131
	v_sub_f32_e32 v132, v132, v190
	v_add_f32_e32 v206, 0, v128
	v_exp_f32_e32 v132, v132
	v_sub_f32_e32 v133, v133, v190
	v_add_f32_e32 v206, v129, v206
	v_exp_f32_e32 v133, v133
	v_sub_f32_e32 v134, v134, v190
	v_add_f32_e32 v206, v130, v206
	v_exp_f32_e32 v134, v134
	v_sub_f32_e32 v135, v135, v190
	v_add_f32_e32 v206, v131, v206
	v_exp_f32_e32 v135, v135
	v_sub_f32_e32 v136, v136, v190
	v_add_f32_e32 v206, v132, v206
	v_exp_f32_e32 v136, v136
	v_sub_f32_e32 v137, v137, v190
	v_add_f32_e32 v206, v133, v206
	v_exp_f32_e32 v137, v137
	v_sub_f32_e32 v138, v138, v190
	v_add_f32_e32 v206, v134, v206
	v_exp_f32_e32 v138, v138
	v_sub_f32_e32 v139, v139, v190
	v_add_f32_e32 v206, v135, v206
	v_exp_f32_e32 v139, v139
	v_sub_f32_e32 v140, v140, v190
	v_add_f32_e32 v206, v136, v206
	v_exp_f32_e32 v140, v140
	v_sub_f32_e32 v141, v141, v190
	v_add_f32_e32 v206, v137, v206
	v_exp_f32_e32 v141, v141
	v_sub_f32_e32 v142, v142, v190
	v_add_f32_e32 v206, v138, v206
	v_exp_f32_e32 v142, v142
	v_sub_f32_e32 v143, v143, v190
	v_add_f32_e32 v206, v139, v206
	v_exp_f32_e32 v143, v143
	v_add_f32_e32 v206, v140, v206
	v_add_f32_e32 v206, v141, v206
	v_add_f32_e32 v206, v142, v206
	v_add_u32_e32 v208, 0xc000, v216
	v_add_f32_e32 v216, v143, v206
	v_cvt_pk_bf16_f32 v128, v128, v129
	v_cvt_pk_bf16_f32 v129, v130, v131
	v_cvt_pk_bf16_f32 v130, v132, v133
	v_cvt_pk_bf16_f32 v131, v134, v135
	v_cvt_pk_bf16_f32 v132, v136, v137
	v_cvt_pk_bf16_f32 v133, v138, v139
	v_cvt_pk_bf16_f32 v134, v140, v141
	v_cvt_pk_bf16_f32 v135, v142, v143
	v_add_u32_e32 v219, v208, v205
	ds_read_b64_tr_b16 v[136:137], v219 offset:16384
	ds_read_b64_tr_b16 v[138:139], v219 offset:20480
	v_add_u32_e32 v221, v208, v204
	ds_read_b64_tr_b16 v[142:143], v219 offset:20736
	ds_read_b64_tr_b16 v[140:141], v219 offset:16640
	v_add_u32_e32 v217, v208, v217
	v_add_u32_e32 v218, v208, v218
	s_waitcnt lgkmcnt(2)
	v_mfma_f32_32x32x16_bf16 v[112:127], v[136:139], v[128:131], v[112:127]
	ds_read_b64_tr_b16 v[136:137], v221 offset:16384
	ds_read_b64_tr_b16 v[138:139], v221 offset:20480
	ds_read_b64_tr_b16 v[206:207], v221 offset:20736
	ds_read_b64_tr_b16 v[204:205], v221 offset:16640
	v_add_f32_e32 v195, v195, v216
	s_waitcnt lgkmcnt(2)
	v_mfma_f32_32x32x16_bf16 v[96:111], v[136:139], v[128:131], v[96:111]
	ds_read_b64_tr_b16 v[136:137], v217 offset:16384
	ds_read_b64_tr_b16 v[138:139], v217 offset:20480
	ds_read_b64_tr_b16 v[210:211], v217 offset:20736
	ds_read_b64_tr_b16 v[208:209], v217 offset:16640
	s_waitcnt lgkmcnt(2)
	v_mfma_f32_32x32x16_bf16 v[80:95], v[136:139], v[128:131], v[80:95]
	ds_read_b64_tr_b16 v[136:137], v218 offset:16384
	ds_read_b64_tr_b16 v[138:139], v218 offset:20480
	ds_read_b64_tr_b16 v[214:215], v218 offset:20736
	ds_read_b64_tr_b16 v[212:213], v218 offset:16640
	s_waitcnt lgkmcnt(2)
	v_mfma_f32_32x32x16_bf16 v[64:79], v[136:139], v[128:131], v[64:79]
	v_mfma_f32_32x32x16_bf16 v[48:63], v[140:143], v[128:131], v[48:63]
	v_mfma_f32_32x32x16_bf16 v[32:47], v[204:207], v[128:131], v[32:47]
	v_mfma_f32_32x32x16_bf16 v[16:31], v[208:211], v[128:131], v[16:31]
	s_waitcnt lgkmcnt(0)
	v_mfma_f32_32x32x16_bf16 v[0:15], v[212:215], v[128:131], v[0:15]
	ds_read_b64_tr_b16 v[128:129], v219 offset:24576
	ds_read_b64_tr_b16 v[130:131], v219 offset:28672
	ds_read_b64_tr_b16 v[138:139], v219 offset:28928
	ds_read_b64_tr_b16 v[136:137], v219 offset:24832
	s_waitcnt lgkmcnt(2)
	v_mfma_f32_32x32x16_bf16 v[112:127], v[128:131], v[132:135], v[112:127]
	ds_read_b64_tr_b16 v[128:129], v221 offset:24576
	ds_read_b64_tr_b16 v[130:131], v221 offset:28672
	ds_read_b64_tr_b16 v[142:143], v221 offset:28928
	ds_read_b64_tr_b16 v[140:141], v221 offset:24832
	s_waitcnt lgkmcnt(2)
	v_mfma_f32_32x32x16_bf16 v[96:111], v[128:131], v[132:135], v[96:111]
	ds_read_b64_tr_b16 v[128:129], v217 offset:24576
	ds_read_b64_tr_b16 v[130:131], v217 offset:28672
	ds_read_b64_tr_b16 v[206:207], v217 offset:28928
	ds_read_b64_tr_b16 v[204:205], v217 offset:24832
	s_waitcnt lgkmcnt(2)
	v_mfma_f32_32x32x16_bf16 v[80:95], v[128:131], v[132:135], v[80:95]
	ds_read_b64_tr_b16 v[128:129], v218 offset:24576
	ds_read_b64_tr_b16 v[130:131], v218 offset:28672
	ds_read_b64_tr_b16 v[210:211], v218 offset:28928
	ds_read_b64_tr_b16 v[208:209], v218 offset:24832
	s_waitcnt lgkmcnt(2)
	v_mfma_f32_32x32x16_bf16 v[64:79], v[128:131], v[132:135], v[64:79]
	v_mfma_f32_32x32x16_bf16 v[48:63], v[136:139], v[132:135], v[48:63]
	v_mfma_f32_32x32x16_bf16 v[32:47], v[140:143], v[132:135], v[32:47]
	v_mfma_f32_32x32x16_bf16 v[16:31], v[204:207], v[132:135], v[16:31]
	s_waitcnt lgkmcnt(0)
	v_mfma_f32_32x32x16_bf16 v[0:15], v[208:211], v[132:135], v[0:15]
.LBB0_1869:
	s_waitcnt lgkmcnt(0)
.Latt_end_7:
	s_andn2_b64 vcc, exec, s[8:9]
	s_mov_b64 s[8:9], -1
	s_cbranch_vccnz .LBB0_1871
	s_waitcnt vmcnt(0)
	s_mov_b64 s[8:9], 0
